# packed f32 VALU ops (v_pk_add/mul/fma_f32) in P6-P8 split into their two single f32 ops (bit-identical), on top of v017
# speedup vs baseline: 1.0056x; 1.0056x over previous
.LBB0_1426:
	s_or_b64 exec, exec, s[56:57]
	s_waitcnt vmcnt(13)
	v_add_f32_e32 v12, v12, v24
	v_add_f32_e32 v13, v13, v25
	v_add_f32_e32 v10, v10, v22
	v_add_f32_e32 v11, v11, v23
	v_add_f32_e32 v4, v4, v24
	v_add_f32_e32 v5, v5, v25
	v_add_f32_e32 v2, v2, v22
	v_add_f32_e32 v3, v3, v23
	v_cvt_pk_bf16_f32 v10, v10, v11
	v_cvt_pk_bf16_f32 v11, v12, v13
	v_add_f32_e32 v12, v16, v24
	v_add_f32_e32 v13, v17, v25
	v_add_f32_e32 v14, v14, v22
	v_add_f32_e32 v15, v15, v23
	v_cvt_pk_bf16_f32 v2, v2, v3
	v_cvt_pk_bf16_f32 v3, v4, v5
	v_add_f32_e32 v4, v8, v24
	v_add_f32_e32 v5, v9, v25
	v_add_f32_e32 v6, v6, v22
	v_add_f32_e32 v7, v7, v23
	v_cvt_pk_bf16_f32 v14, v14, v15
	v_cvt_pk_bf16_f32 v15, v12, v13
	v_cvt_pk_bf16_f32 v6, v6, v7
	v_cvt_pk_bf16_f32 v7, v4, v5
	v_add_u32_e32 v197, s3, v206
	s_waitcnt lgkmcnt(0)
	s_barrier
	ds_write2st64_b64 v205, v[10:11], v[14:15] offset1:8
	ds_write2st64_b64 v205, v[2:3], v[6:7] offset0:16 offset1:24
	s_waitcnt vmcnt(12)
	ds_write_b128 v228, v[18:21] offset:20480
	s_waitcnt vmcnt(11)
	ds_write_b128 v228, v[26:29] offset:28672
	s_waitcnt vmcnt(10)
	ds_write_b128 v228, v[30:33] offset:36864
	s_waitcnt vmcnt(9)
	ds_write_b128 v228, v[34:37] offset:45056
	s_and_saveexec_b64 s[56:57], s[6:7]
	s_cbranch_execz .LBB0_1428
	v_lshlrev_b32_e32 v2, 16, v86
	v_and_b32_e32 v3, 0xffff0000, v86
	v_lshlrev_b32_e32 v4, 16, v87
	v_and_b32_e32 v5, 0xffff0000, v87
	v_lshlrev_b32_e32 v6, 16, v88
	v_and_b32_e32 v7, 0xffff0000, v88
	v_lshlrev_b32_e32 v8, 16, v89
	v_and_b32_e32 v9, 0xffff0000, v89
	v_add_f32_e32 v4, v104, v4
	v_add_f32_e32 v5, v105, v5
	v_add_f32_e32 v2, v102, v2
	v_add_f32_e32 v3, v103, v3
	v_add_f32_e32 v8, v100, v8
	v_add_f32_e32 v9, v101, v9
	v_add_f32_e32 v6, v98, v6
	v_add_f32_e32 v7, v99, v7
	v_cvt_pk_bf16_f32 v2, v2, v3
	v_cvt_pk_bf16_f32 v3, v4, v5
	v_cvt_pk_bf16_f32 v4, v6, v7
	v_cvt_pk_bf16_f32 v5, v8, v9
	ds_write_b128 v197, v[2:5] offset:16384

; #define LAS __attribute__((address_space(3)))
; #define MFMA32(a, b, c) __builtin_amdgcn_mfma_f32_32x32x16_bf16((a), (b), (c), 0, 0, 0)
; __device__ __forceinline__ void cmp1_fused(const P& p, Frame& F) {
;     ...
;         for (int s2 = 0; s2 < 64; s2 += 2) {
; #pragma unroll
;             for (int u = 0; u < 2; ++u) { const int s = s2 + u;
;                 const LAS unsigned char* A_ = L + u * CS_BUF; const LAS unsigned char* B_ = A_ + CS_A; const int sw = ql & 7;
; #pragma unroll
;                 for (int ks = 0; ks < 4; ++ks) { const int off = ((2 * ks + half) ^ sw) << 4; const bf16x8 bfr = *(const LAS bf16x8*)(B_ + (32 * wave + ql) * 128 + off);
; #pragma unroll
;                     for (int mt = 0; mt < 5; ++mt) { const bf16x8 afr = *(const LAS bf16x8*)(A_ + (32 * mt + ql) * 128 + off); acc[mt] = MFMA32(bfr, afr, acc[mt]); } }
;                 if (s + 1 < 64) C1_PUT(u ^ 1, u ^ 1);
;                 if (s + 3 < 64) C1_LOAD(u ^ 1, s + 3);
;                 __syncthreads();
;             }
.LBB0_1431:
	v_add_u32_e32 v180, v207, v208
	ds_read_b128 v[236:239], v180 offset:20480
	ds_read_b128 v[240:243], v209
	v_add_u32_e32 v180, v207, v210
	s_waitcnt vmcnt(4)
	v_add_f32_e32 v200, v108, v124
	v_add_f32_e32 v201, v109, v125
	s_waitcnt lgkmcnt(0)
	v_mfma_f32_32x32x16_bf16 v[66:81], v[236:239], v[240:243], v[66:81]
	ds_read_b128 v[240:243], v209 offset:4096
	s_waitcnt lgkmcnt(0)
	v_mfma_f32_32x32x16_bf16 v[50:65], v[236:239], v[240:243], v[50:65]
	ds_read_b128 v[240:243], v209 offset:8192
	s_waitcnt lgkmcnt(0)
	v_mfma_f32_32x32x16_bf16 v[34:49], v[236:239], v[240:243], v[34:49]
	ds_read_b128 v[240:243], v209 offset:12288
	s_waitcnt lgkmcnt(0)
	v_mfma_f32_32x32x16_bf16 v[18:33], v[236:239], v[240:243], v[18:33]
	ds_read_b128 v[240:243], v209 offset:16384
	s_waitcnt lgkmcnt(0)
	v_mfma_f32_32x32x16_bf16 v[2:17], v[236:239], v[240:243], v[2:17]
	ds_read_b128 v[236:239], v180 offset:20480
	ds_read_b128 v[240:243], v211
	v_add_u32_e32 v180, v207, v212
	s_waitcnt lgkmcnt(0)
	v_mfma_f32_32x32x16_bf16 v[66:81], v[236:239], v[240:243], v[66:81]
	ds_read_b128 v[240:243], v211 offset:4096
	s_waitcnt lgkmcnt(0)
	v_mfma_f32_32x32x16_bf16 v[50:65], v[236:239], v[240:243], v[50:65]
	ds_read_b128 v[240:243], v211 offset:8192
	s_waitcnt lgkmcnt(0)
	v_mfma_f32_32x32x16_bf16 v[34:49], v[236:239], v[240:243], v[34:49]
	ds_read_b128 v[240:243], v211 offset:12288
	s_waitcnt lgkmcnt(0)
	v_mfma_f32_32x32x16_bf16 v[18:33], v[236:239], v[240:243], v[18:33]
	ds_read_b128 v[240:243], v211 offset:16384
	s_waitcnt lgkmcnt(0)
	v_mfma_f32_32x32x16_bf16 v[2:17], v[236:239], v[240:243], v[2:17]
	ds_read_b128 v[236:239], v180 offset:20480
	ds_read_b128 v[240:243], v213
	v_add_u32_e32 v180, v207, v214
	s_waitcnt lgkmcnt(0)
	v_mfma_f32_32x32x16_bf16 v[66:81], v[236:239], v[240:243], v[66:81]
	ds_read_b128 v[240:243], v213 offset:4096
	s_waitcnt lgkmcnt(0)
	v_mfma_f32_32x32x16_bf16 v[50:65], v[236:239], v[240:243], v[50:65]
	ds_read_b128 v[240:243], v213 offset:8192
	s_waitcnt lgkmcnt(0)
	v_mfma_f32_32x32x16_bf16 v[34:49], v[236:239], v[240:243], v[34:49]
	ds_read_b128 v[240:243], v213 offset:12288
	s_waitcnt lgkmcnt(0)
	v_mfma_f32_32x32x16_bf16 v[18:33], v[236:239], v[240:243], v[18:33]
	ds_read_b128 v[240:243], v213 offset:16384
	s_waitcnt lgkmcnt(0)
	v_mfma_f32_32x32x16_bf16 v[2:17], v[236:239], v[240:243], v[2:17]
	ds_read_b128 v[236:239], v180 offset:20480
	ds_read_b128 v[240:243], v215
	s_waitcnt lgkmcnt(0)
	v_mfma_f32_32x32x16_bf16 v[66:81], v[236:239], v[240:243], v[66:81]
	ds_read_b128 v[240:243], v215 offset:4096
	s_waitcnt lgkmcnt(0)
	v_mfma_f32_32x32x16_bf16 v[50:65], v[236:239], v[240:243], v[50:65]
	ds_read_b128 v[240:243], v215 offset:8192
	s_waitcnt lgkmcnt(0)
	v_mfma_f32_32x32x16_bf16 v[34:49], v[236:239], v[240:243], v[34:49]
	ds_read_b128 v[240:243], v215 offset:12288
	s_waitcnt lgkmcnt(0)
	v_mfma_f32_32x32x16_bf16 v[18:33], v[236:239], v[240:243], v[18:33]
	ds_read_b128 v[240:243], v215 offset:16384
	s_waitcnt lgkmcnt(0)
	v_mfma_f32_32x32x16_bf16 v[2:17], v[236:239], v[240:243], v[2:17]
	v_add_f32_e64 v236, v106, v122
	v_add_f32_e64 v237, v107, v123
	v_add_f32_e64 v238, v110, v122
	v_add_f32_e64 v239, v111, v123
	v_cvt_pk_bf16_f32 v236, v236, v237
	v_cvt_pk_bf16_f32 v237, v200, v201
	v_add_f32_e32 v200, v112, v124
	v_add_f32_e32 v201, v113, v125
	v_cvt_pk_bf16_f32 v238, v238, v239
	v_cvt_pk_bf16_f32 v239, v200, v201
	ds_write2st64_b64 v205, v[236:237], v[238:239] offset0:104 offset1:112
	v_add_f32_e32 v200, v116, v124
	v_add_f32_e32 v201, v117, v125
	v_add_f32_e32 v236, v114, v122
	v_add_f32_e32 v237, v115, v123
	s_nop 0
	v_cvt_pk_bf16_f32 v236, v236, v237
	v_cvt_pk_bf16_f32 v237, v200, v201
	ds_write_b64 v205, v[236:237] offset:61440
	v_add_f32_e32 v200, v120, v124
	v_add_f32_e32 v201, v121, v125
	v_add_f32_e32 v236, v118, v122
	v_add_f32_e32 v237, v119, v123
	s_nop 0
	v_cvt_pk_bf16_f32 v236, v236, v237
	v_cvt_pk_bf16_f32 v237, v200, v201
	ds_write_b64 v216, v[236:237] offset:12288
	s_waitcnt vmcnt(3)
	ds_write_b128 v227, v[126:129]
	s_waitcnt vmcnt(2)
	ds_write_b128 v227, v[130:133] offset:8192
	s_waitcnt vmcnt(1)
	ds_write_b128 v227, v[134:137] offset:16384
	s_waitcnt vmcnt(0)
	ds_write_b128 v227, v[138:141] offset:24576
	s_and_saveexec_b64 s[28:29], s[6:7]
	s_cbranch_execz .LBB0_1433
	v_lshlrev_b32_e32 v236, 16, v83
	v_and_b32_e32 v237, 0xffff0000, v83
	v_lshlrev_b32_e32 v200, 16, v82
	v_and_b32_e32 v201, 0xffff0000, v82
	v_add_f32_e32 v238, v92, v236
	v_add_f32_e32 v239, v93, v237
	v_lshlrev_b32_e32 v236, 16, v84
	v_and_b32_e32 v237, 0xffff0000, v84
	v_lshlrev_b32_e32 v240, 16, v85
	v_and_b32_e32 v241, 0xffff0000, v85
	v_add_f32_e32 v200, v90, v200
	v_add_f32_e32 v201, v91, v201
	v_add_f32_e32 v240, v96, v240
	v_add_f32_e32 v241, v97, v241
	v_add_f32_e32 v242, v94, v236
	v_add_f32_e32 v243, v95, v237
	v_cvt_pk_bf16_f32 v236, v200, v201
	v_cvt_pk_bf16_f32 v237, v238, v239
	v_cvt_pk_bf16_f32 v238, v242, v243
	v_cvt_pk_bf16_f32 v239, v240, v241
	v_add_u32_e32 v180, s4, v206
	ds_write_b128 v180, v[236:239] offset:16384

; #define LAS __attribute__((address_space(3)))
; #define MFMA32(a, b, c) __builtin_amdgcn_mfma_f32_32x32x16_bf16((a), (b), (c), 0, 0, 0)
; __device__ __forceinline__ void cmp1_fused(const P& p, Frame& F) {
;     ...
;         for (int s2 = 0; s2 < 64; s2 += 2) {
; #pragma unroll
;             for (int u = 0; u < 2; ++u) { const int s = s2 + u;
;                 const LAS unsigned char* A_ = L + u * CS_BUF; const LAS unsigned char* B_ = A_ + CS_A; const int sw = ql & 7;
; #pragma unroll
;                 for (int ks = 0; ks < 4; ++ks) { const int off = ((2 * ks + half) ^ sw) << 4; const bf16x8 bfr = *(const LAS bf16x8*)(B_ + (32 * wave + ql) * 128 + off);
; #pragma unroll
;                     for (int mt = 0; mt < 5; ++mt) { const bf16x8 afr = *(const LAS bf16x8*)(A_ + (32 * mt + ql) * 128 + off); acc[mt] = MFMA32(bfr, afr, acc[mt]); } }
;                 if (s + 1 < 64) C1_PUT(u ^ 1, u ^ 1);
;                 if (s + 3 < 64) C1_LOAD(u ^ 1, s + 3);
;                 __syncthreads();
;             }
.LBB0_1437:
	v_add_u32_e32 v180, v217, v208
	s_waitcnt lgkmcnt(0)
	s_barrier
	ds_read_b128 v[240:243], v180
	ds_read_b128 v[244:247], v209 offset:53248
	v_add_u32_e32 v180, v217, v210
	s_waitcnt lgkmcnt(0)
	v_mfma_f32_32x32x16_bf16 v[66:81], v[240:243], v[244:247], v[66:81]
	ds_read_b128 v[244:247], v209 offset:57344
	s_add_i32 s56, s53, 1
	s_cmp_gt_u32 s56, 62
	s_waitcnt lgkmcnt(0)
	v_mfma_f32_32x32x16_bf16 v[50:65], v[240:243], v[244:247], v[50:65]
	ds_read_b128 v[244:247], v209 offset:61440
	s_waitcnt lgkmcnt(0)
	v_mfma_f32_32x32x16_bf16 v[34:49], v[240:243], v[244:247], v[34:49]
	ds_read_b128 v[244:247], v218 offset:12288
	s_waitcnt lgkmcnt(0)
	v_mfma_f32_32x32x16_bf16 v[18:33], v[240:243], v[244:247], v[18:33]
	ds_read_b128 v[244:247], v218 offset:16384
	s_waitcnt lgkmcnt(0)
	v_mfma_f32_32x32x16_bf16 v[2:17], v[240:243], v[244:247], v[2:17]
	ds_read_b128 v[240:243], v180
	ds_read_b128 v[244:247], v211 offset:53248
	v_add_u32_e32 v180, v217, v212
	s_waitcnt lgkmcnt(0)
	v_mfma_f32_32x32x16_bf16 v[66:81], v[240:243], v[244:247], v[66:81]
	ds_read_b128 v[244:247], v211 offset:57344
	s_waitcnt lgkmcnt(0)
	v_mfma_f32_32x32x16_bf16 v[50:65], v[240:243], v[244:247], v[50:65]
	ds_read_b128 v[244:247], v211 offset:61440
	s_waitcnt lgkmcnt(0)
	v_mfma_f32_32x32x16_bf16 v[34:49], v[240:243], v[244:247], v[34:49]
	ds_read_b128 v[244:247], v219 offset:12288
	s_waitcnt lgkmcnt(0)
	v_mfma_f32_32x32x16_bf16 v[18:33], v[240:243], v[244:247], v[18:33]
	ds_read_b128 v[244:247], v219 offset:16384
	s_waitcnt lgkmcnt(0)
	v_mfma_f32_32x32x16_bf16 v[2:17], v[240:243], v[244:247], v[2:17]
	ds_read_b128 v[240:243], v180
	ds_read_b128 v[244:247], v213 offset:53248
	v_add_u32_e32 v180, v217, v214
	s_waitcnt lgkmcnt(0)
	v_mfma_f32_32x32x16_bf16 v[66:81], v[240:243], v[244:247], v[66:81]
	ds_read_b128 v[244:247], v213 offset:57344
	s_waitcnt lgkmcnt(0)
	v_mfma_f32_32x32x16_bf16 v[50:65], v[240:243], v[244:247], v[50:65]
	ds_read_b128 v[244:247], v213 offset:61440
	s_waitcnt lgkmcnt(0)
	v_mfma_f32_32x32x16_bf16 v[34:49], v[240:243], v[244:247], v[34:49]
	ds_read_b128 v[244:247], v220 offset:12288
	s_waitcnt lgkmcnt(0)
	v_mfma_f32_32x32x16_bf16 v[18:33], v[240:243], v[244:247], v[18:33]
	ds_read_b128 v[244:247], v220 offset:16384
	s_waitcnt lgkmcnt(0)
	v_mfma_f32_32x32x16_bf16 v[2:17], v[240:243], v[244:247], v[2:17]
	ds_read_b128 v[240:243], v180
	ds_read_b128 v[244:247], v215 offset:53248
	s_waitcnt lgkmcnt(0)
	v_mfma_f32_32x32x16_bf16 v[66:81], v[240:243], v[244:247], v[66:81]
	ds_read_b128 v[244:247], v215 offset:57344
	s_waitcnt lgkmcnt(0)
	v_mfma_f32_32x32x16_bf16 v[50:65], v[240:243], v[244:247], v[50:65]
	ds_read_b128 v[244:247], v215 offset:61440
	s_waitcnt lgkmcnt(0)
	v_mfma_f32_32x32x16_bf16 v[34:49], v[240:243], v[244:247], v[34:49]
	ds_read_b128 v[244:247], v221 offset:12288
	s_waitcnt lgkmcnt(0)
	v_mfma_f32_32x32x16_bf16 v[18:33], v[240:243], v[244:247], v[18:33]
	ds_read_b128 v[244:247], v221 offset:16384
	s_waitcnt lgkmcnt(0)
	v_mfma_f32_32x32x16_bf16 v[2:17], v[240:243], v[244:247], v[2:17]
	s_cbranch_scc1 .LBB0_1441
	s_waitcnt vmcnt(4)
	v_add_f32_e32 v240, v144, v160
	v_add_f32_e32 v241, v145, v161
	v_add_f32_e32 v242, v142, v158
	v_add_f32_e32 v243, v143, v159
	v_add_f32_e32 v244, v146, v158
	v_add_f32_e32 v245, v147, v159
	v_cvt_pk_bf16_f32 v242, v242, v243
	v_cvt_pk_bf16_f32 v243, v240, v241
	v_add_f32_e32 v240, v148, v160
	v_add_f32_e32 v241, v149, v161
	v_cvt_pk_bf16_f32 v244, v244, v245
	v_cvt_pk_bf16_f32 v245, v240, v241
	ds_write2st64_b64 v205, v[242:243], v[244:245] offset1:8
	v_add_f32_e32 v240, v152, v160
	v_add_f32_e32 v241, v153, v161
	v_add_f32_e32 v242, v150, v158
	v_add_f32_e32 v243, v151, v159
	v_add_f32_e32 v244, v154, v158
	v_add_f32_e32 v245, v155, v159
	v_cvt_pk_bf16_f32 v242, v242, v243
	v_cvt_pk_bf16_f32 v243, v240, v241
	v_add_f32_e32 v240, v156, v160
	v_add_f32_e32 v241, v157, v161
	v_cvt_pk_bf16_f32 v244, v244, v245
	v_cvt_pk_bf16_f32 v245, v240, v241
	ds_write2st64_b64 v205, v[242:243], v[244:245] offset0:16 offset1:24
	s_waitcnt vmcnt(3)
	ds_write_b128 v228, v[162:165] offset:20480
	s_waitcnt vmcnt(2)
	ds_write_b128 v228, v[166:169] offset:28672
	s_waitcnt vmcnt(1)
	ds_write_b128 v228, v[170:173] offset:36864
	s_waitcnt vmcnt(0)
	ds_write_b128 v228, v[174:177] offset:45056
	s_and_saveexec_b64 s[28:29], s[6:7]
	s_cbranch_execz .LBB0_1440
	v_lshlrev_b32_e32 v240, 16, v86
	v_and_b32_e32 v241, 0xffff0000, v86
	v_lshlrev_b32_e32 v242, 16, v87
	v_and_b32_e32 v243, 0xffff0000, v87
	v_lshlrev_b32_e32 v244, 16, v88
	v_and_b32_e32 v245, 0xffff0000, v88
	v_lshlrev_b32_e32 v246, 16, v89
	v_and_b32_e32 v247, 0xffff0000, v89
	v_add_f32_e32 v242, v104, v242
	v_add_f32_e32 v243, v105, v243
	v_add_f32_e32 v240, v102, v240
	v_add_f32_e32 v241, v103, v241
	v_add_f32_e32 v246, v100, v246
	v_add_f32_e32 v247, v101, v247
	v_add_f32_e32 v244, v98, v244
	v_add_f32_e32 v245, v99, v245
	v_cvt_pk_bf16_f32 v240, v240, v241
	v_cvt_pk_bf16_f32 v241, v242, v243
	v_cvt_pk_bf16_f32 v242, v244, v245
	v_cvt_pk_bf16_f32 v243, v246, v247
	ds_write_b128 v197, v[240:243] offset:16384

; __device__ __forceinline__ unsigned pk2(float lo, float hi) { const bfx2 b = __builtin_convertvector((f32x2){lo, hi}, bfx2); return __builtin_bit_cast(unsigned, b); }
; __device__ __forceinline__ float gelu_tanh(float x) { const float u = 0.7978845608028654f * (x + 0.044715f * x * x * x); const float th = 1.0f - 2.0f / (1.0f + __expf(2.0f * u)); return 0.5f * x * (1.0f + th); }
; __device__ __forceinline__ void cmp1_fused(const P& p, Frame& F) {
;     ...
; #pragma unroll
;         for (int mt = 0; mt < 5; ++mt) { const int rl = 32 * mt + ql; if (rl < 136) { const size_t row = (size_t)kv * CMPROWS + (rl < 128 ? 1024 + blk * 128 + rl : blk * 8 + (rl - 128));
; #pragma unroll
;                 for (int g = 0; g < 4; ++g) { u32x2 w; w.x = pk2(gelu_tanh(acc[mt][4 * g]), gelu_tanh(acc[mt][4 * g + 1])); w.y = pk2(gelu_tanh(acc[mt][4 * g + 2]), gelu_tanh(acc[mt][4 * g + 3]));
;                     *(u32x2*)(HID + row * 256 + 32 * wave + 8 * g + 4 * half) = w; } } }
.LBB0_1447:
	s_waitcnt vmcnt(8)
	v_mul_f32_e32 v108, 0x3d372713, v66
	v_mul_f32_e32 v109, 0x3d372713, v67
	v_mul_f32_e32 v108, v66, v108
	v_mul_f32_e32 v109, v67, v109
	v_fma_f32 v108, v66, v108, v66
	v_fma_f32 v109, v67, v109, v67
	v_mul_f32_e32 v108, 0x3f4c422a, v108
	v_mul_f32_e32 v109, 0x3f4c422a, v109
	v_add_f32_e32 v108, v108, v108
	v_add_f32_e32 v109, v109, v109
	v_mul_f32_e32 v108, 0x3fb8aa3b, v108
	v_mul_f32_e32 v109, 0x3fb8aa3b, v109
	v_exp_f32_e32 v108, v108
	v_exp_f32_e32 v109, v109
	v_mul_f32_e32 v66, 0.5, v66
	v_mul_f32_e32 v67, 0.5, v67
	s_addk_i32 s45, 0x400
	v_or_b32_e32 v180, s45, v189
	v_add_f32_e32 v108, 1.0, v108
	v_add_f32_e32 v109, 1.0, v109
	v_mad_i64_i32 v[106:107], s[24:25], s0, v179, v[180:181]
	s_waitcnt vmcnt(7)
	v_div_scale_f32 v110, s[24:25], v109, v109, 2.0
	v_rcp_f32_e32 v111, v110
	v_lshlrev_b64 v[106:107], 9, v[106:107]
	v_lshl_add_u64 v[106:107], v[190:191], 0, v[106:107]
	v_fma_f32 v112, -v110, v111, 1.0
	v_fmac_f32_e32 v111, v112, v111
	v_div_scale_f32 v112, vcc, 2.0, v109, 2.0
	v_mul_f32_e32 v113, v112, v111
	s_waitcnt vmcnt(6)
	v_fma_f32 v114, -v110, v113, v112
	v_fmac_f32_e32 v113, v114, v111
	v_fma_f32 v110, -v110, v113, v112
	v_div_fmas_f32 v110, v110, v111, v113
	v_div_fixup_f32 v109, v110, v109, 2.0
	v_div_scale_f32 v110, s[24:25], v108, v108, 2.0
	v_rcp_f32_e32 v111, v110
	s_nop 0
	v_fma_f32 v112, -v110, v111, 1.0
	v_fmac_f32_e32 v111, v112, v111
	v_div_scale_f32 v112, vcc, 2.0, v108, 2.0
	v_mul_f32_e32 v113, v112, v111
	v_fma_f32 v114, -v110, v113, v112
	v_fmac_f32_e32 v113, v114, v111
	v_fma_f32 v110, -v110, v113, v112
	v_div_fmas_f32 v110, v110, v111, v113
	v_div_fixup_f32 v108, v110, v108, 2.0
	v_sub_f32_e32 v108, 1.0, v108
	v_sub_f32_e32 v109, 1.0, v109
	s_nop 0
	v_add_f32_e32 v108, 1.0, v108
	v_add_f32_e32 v109, 1.0, v109
	s_nop 0
	v_mul_f32_e32 v66, v66, v108
	v_mul_f32_e32 v67, v67, v109
	s_nop 0
	v_cvt_pk_bf16_f32 v66, v66, v67
	v_mul_f32_e32 v67, 0x3d372713, v68
	v_mul_f32_e32 v67, v68, v67
	v_fma_f32 v67, v68, v67, v68
	v_mul_f32_e32 v67, 0x3f4c422a, v67
	v_add_f32_e32 v67, v67, v67
	v_mul_f32_e32 v67, 0x3fb8aa3b, v67
	v_exp_f32_e32 v108, v67
	v_mul_f32_e32 v67, 0x3d372713, v69
	v_mul_f32_e32 v67, v69, v67
	v_fma_f32 v67, v69, v67, v69
	v_mul_f32_e32 v67, 0x3f4c422a, v67
	v_add_f32_e32 v67, v67, v67
	v_mul_f32_e32 v67, 0x3fb8aa3b, v67
	v_exp_f32_e32 v109, v67
	v_mul_f32_e32 v68, 0.5, v68
	v_mul_f32_e32 v69, 0.5, v69
	v_add_f32_e32 v108, 1.0, v108
	v_add_f32_e32 v109, 1.0, v109
	s_nop 0
	v_div_scale_f32 v67, s[24:25], v109, v109, 2.0
	v_rcp_f32_e32 v110, v67
	s_nop 0
	v_fma_f32 v111, -v67, v110, 1.0
	v_fmac_f32_e32 v110, v111, v110
	v_div_scale_f32 v111, vcc, 2.0, v109, 2.0
	v_mul_f32_e32 v112, v111, v110
	v_fma_f32 v113, -v67, v112, v111
	v_fmac_f32_e32 v112, v113, v110
	v_fma_f32 v67, -v67, v112, v111
	v_div_fmas_f32 v67, v67, v110, v112
	v_div_fixup_f32 v109, v67, v109, 2.0
	v_div_scale_f32 v67, s[24:25], v108, v108, 2.0
	v_rcp_f32_e32 v110, v67
	s_nop 0
	v_fma_f32 v111, -v67, v110, 1.0
	v_fmac_f32_e32 v110, v111, v110
	v_div_scale_f32 v111, vcc, 2.0, v108, 2.0
	v_mul_f32_e32 v112, v111, v110
	v_fma_f32 v113, -v67, v112, v111
	v_fmac_f32_e32 v112, v113, v110
	v_fma_f32 v67, -v67, v112, v111
	v_div_fmas_f32 v67, v67, v110, v112
	v_div_fixup_f32 v108, v67, v108, 2.0
	v_sub_f32_e32 v108, 1.0, v108
	v_sub_f32_e32 v109, 1.0, v109
	s_nop 0
	v_add_f32_e32 v108, 1.0, v108
	v_add_f32_e32 v109, 1.0, v109
	s_nop 0
	v_mul_f32_e32 v68, v68, v108
	v_mul_f32_e32 v69, v69, v109
	s_nop 0
	v_cvt_pk_bf16_f32 v67, v68, v69
	global_store_dwordx2 v[106:107], v[66:67], off
	v_mul_f32_e32 v66, 0x3d372713, v70
	v_mul_f32_e32 v67, 0x3d372713, v71
	v_mul_f32_e32 v66, v70, v66
	v_mul_f32_e32 v67, v71, v67
	v_fma_f32 v66, v70, v66, v70
	v_fma_f32 v67, v71, v67, v71
	v_mul_f32_e32 v66, 0x3f4c422a, v66
	v_mul_f32_e32 v67, 0x3f4c422a, v67
	v_add_f32_e32 v66, v66, v66
	v_add_f32_e32 v67, v67, v67
	v_mul_f32_e32 v66, 0x3fb8aa3b, v66
	v_mul_f32_e32 v67, 0x3fb8aa3b, v67
	v_exp_f32_e32 v66, v66
	v_exp_f32_e32 v67, v67
	s_nop 0
	v_add_f32_e32 v66, 1.0, v66
	v_add_f32_e32 v67, 1.0, v67
	s_nop 0
	v_div_scale_f32 v68, s[24:25], v67, v67, 2.0
	v_rcp_f32_e32 v69, v68
	s_nop 0
	v_fma_f32 v108, -v68, v69, 1.0
	v_fmac_f32_e32 v69, v108, v69
	v_div_scale_f32 v108, vcc, 2.0, v67, 2.0
	v_mul_f32_e32 v109, v108, v69
	v_fma_f32 v110, -v68, v109, v108
	v_fmac_f32_e32 v109, v110, v69
	v_fma_f32 v68, -v68, v109, v108
	v_div_fmas_f32 v68, v68, v69, v109
	v_div_fixup_f32 v67, v68, v67, 2.0
	v_div_scale_f32 v68, s[24:25], v66, v66, 2.0
	v_rcp_f32_e32 v69, v68
	s_nop 0
	v_fma_f32 v108, -v68, v69, 1.0
	v_fmac_f32_e32 v69, v108, v69
	v_div_scale_f32 v108, vcc, 2.0, v66, 2.0
	v_mul_f32_e32 v109, v108, v69
	v_fma_f32 v110, -v68, v109, v108
	v_fmac_f32_e32 v109, v110, v69
	v_fma_f32 v68, -v68, v109, v108
	v_div_fmas_f32 v68, v68, v69, v109
	v_div_fixup_f32 v66, v68, v66, 2.0
	v_sub_f32_e32 v66, 1.0, v66
	v_sub_f32_e32 v67, 1.0, v67
	v_mul_f32_e32 v68, 0.5, v70
	v_mul_f32_e32 v69, 0.5, v71
	v_add_f32_e32 v66, 1.0, v66
	v_add_f32_e32 v67, 1.0, v67
	s_nop 0
	v_mul_f32_e32 v66, v68, v66
	v_mul_f32_e32 v67, v69, v67
	s_nop 0
	v_cvt_pk_bf16_f32 v66, v66, v67
	v_mul_f32_e32 v67, 0x3d372713, v72
	v_mul_f32_e32 v67, v72, v67
	v_fma_f32 v67, v72, v67, v72
	v_mul_f32_e32 v67, 0x3f4c422a, v67
	v_add_f32_e32 v67, v67, v67
	v_mul_f32_e32 v67, 0x3fb8aa3b, v67
	v_exp_f32_e32 v68, v67
	v_mul_f32_e32 v67, 0x3d372713, v73
	v_mul_f32_e32 v67, v73, v67
	v_fma_f32 v67, v73, v67, v73
	v_mul_f32_e32 v67, 0x3f4c422a, v67
	v_add_f32_e32 v67, v67, v67
	v_mul_f32_e32 v67, 0x3fb8aa3b, v67
	v_exp_f32_e32 v69, v67
	s_nop 0
	v_add_f32_e32 v68, 1.0, v68
	v_add_f32_e32 v69, 1.0, v69
; __device__ __forceinline__ unsigned pk2(float lo, float hi) { const bfx2 b = __builtin_convertvector((f32x2){lo, hi}, bfx2); return __builtin_bit_cast(unsigned, b); }
; __device__ __forceinline__ float gelu_tanh(float x) { const float u = 0.7978845608028654f * (x + 0.044715f * x * x * x); const float th = 1.0f - 2.0f / (1.0f + __expf(2.0f * u)); return 0.5f * x * (1.0f + th); }
; __device__ __forceinline__ void cmp1_fused(const P& p, Frame& F) {
;     ...
; #pragma unroll
;         for (int mt = 0; mt < 5; ++mt) { const int rl = 32 * mt + ql; if (rl < 136) { const size_t row = (size_t)kv * CMPROWS + (rl < 128 ? 1024 + blk * 128 + rl : blk * 8 + (rl - 128));
; #pragma unroll
;                 for (int g = 0; g < 4; ++g) { u32x2 w; w.x = pk2(gelu_tanh(acc[mt][4 * g]), gelu_tanh(acc[mt][4 * g + 1])); w.y = pk2(gelu_tanh(acc[mt][4 * g + 2]), gelu_tanh(acc[mt][4 * g + 3]));
;                     *(u32x2*)(HID + row * 256 + 32 * wave + 8 * g + 4 * half) = w; } } }
	s_nop 0
	v_div_scale_f32 v67, s[24:25], v69, v69, 2.0
	v_rcp_f32_e32 v70, v67
	s_nop 0
	v_fma_f32 v71, -v67, v70, 1.0
	v_fmac_f32_e32 v70, v71, v70
	v_div_scale_f32 v71, vcc, 2.0, v69, 2.0
	v_mul_f32_e32 v108, v71, v70
	v_fma_f32 v109, -v67, v108, v71
	v_fmac_f32_e32 v108, v109, v70
	v_fma_f32 v67, -v67, v108, v71
	v_div_fmas_f32 v67, v67, v70, v108
	v_div_fixup_f32 v69, v67, v69, 2.0
	v_div_scale_f32 v67, s[24:25], v68, v68, 2.0
	v_rcp_f32_e32 v70, v67
	s_nop 0
	v_fma_f32 v71, -v67, v70, 1.0
	v_fmac_f32_e32 v70, v71, v70
	v_div_scale_f32 v71, vcc, 2.0, v68, 2.0
	v_mul_f32_e32 v108, v71, v70
	v_fma_f32 v109, -v67, v108, v71
	v_fmac_f32_e32 v108, v109, v70
	v_fma_f32 v67, -v67, v108, v71
	v_div_fmas_f32 v67, v67, v70, v108
	v_div_fixup_f32 v68, v67, v68, 2.0
	v_sub_f32_e32 v68, 1.0, v68
	v_sub_f32_e32 v69, 1.0, v69
	v_mul_f32_e32 v70, 0.5, v72
	v_mul_f32_e32 v71, 0.5, v73
	v_add_f32_e32 v68, 1.0, v68
	v_add_f32_e32 v69, 1.0, v69
	s_nop 0
	v_mul_f32_e32 v68, v70, v68
	v_mul_f32_e32 v69, v71, v69
	s_nop 0
	v_cvt_pk_bf16_f32 v67, v68, v69
	global_store_dwordx2 v[106:107], v[66:67], off offset:16
	v_mul_f32_e32 v66, 0x3d372713, v74
	v_mul_f32_e32 v67, 0x3d372713, v75
	v_mul_f32_e32 v66, v74, v66
	v_mul_f32_e32 v67, v75, v67
	v_fma_f32 v66, v74, v66, v74
	v_fma_f32 v67, v75, v67, v75
	v_mul_f32_e32 v66, 0x3f4c422a, v66
	v_mul_f32_e32 v67, 0x3f4c422a, v67
	v_add_f32_e32 v66, v66, v66
	v_add_f32_e32 v67, v67, v67
	v_mul_f32_e32 v66, 0x3fb8aa3b, v66
	v_mul_f32_e32 v67, 0x3fb8aa3b, v67
	v_exp_f32_e32 v66, v66
	v_exp_f32_e32 v67, v67
	s_nop 0
	v_add_f32_e32 v66, 1.0, v66
	v_add_f32_e32 v67, 1.0, v67
	s_nop 0
	v_div_scale_f32 v68, s[24:25], v67, v67, 2.0
	v_rcp_f32_e32 v69, v68
	s_nop 0
	v_fma_f32 v70, -v68, v69, 1.0
	v_fmac_f32_e32 v69, v70, v69
	v_div_scale_f32 v70, vcc, 2.0, v67, 2.0
	v_mul_f32_e32 v71, v70, v69
	v_fma_f32 v72, -v68, v71, v70
	v_fmac_f32_e32 v71, v72, v69
	v_fma_f32 v68, -v68, v71, v70
	v_div_fmas_f32 v68, v68, v69, v71
	v_div_fixup_f32 v67, v68, v67, 2.0
	v_div_scale_f32 v68, s[24:25], v66, v66, 2.0
	v_rcp_f32_e32 v69, v68
	s_nop 0
	v_fma_f32 v70, -v68, v69, 1.0
	v_fmac_f32_e32 v69, v70, v69
	v_div_scale_f32 v70, vcc, 2.0, v66, 2.0
	v_mul_f32_e32 v71, v70, v69
	v_fma_f32 v72, -v68, v71, v70
	v_fmac_f32_e32 v71, v72, v69
	v_fma_f32 v68, -v68, v71, v70
	v_div_fmas_f32 v68, v68, v69, v71
	v_div_fixup_f32 v66, v68, v66, 2.0
	v_sub_f32_e32 v66, 1.0, v66
	v_sub_f32_e32 v67, 1.0, v67
	v_mul_f32_e32 v68, 0.5, v74
	v_mul_f32_e32 v69, 0.5, v75
	v_add_f32_e32 v66, 1.0, v66
	v_add_f32_e32 v67, 1.0, v67
	s_nop 0
	v_mul_f32_e32 v66, v68, v66
	v_mul_f32_e32 v67, v69, v67
	s_nop 0
	v_cvt_pk_bf16_f32 v66, v66, v67
	v_mul_f32_e32 v67, 0x3d372713, v76
	v_mul_f32_e32 v67, v76, v67
	v_fma_f32 v67, v76, v67, v76
	v_mul_f32_e32 v67, 0x3f4c422a, v67
	v_add_f32_e32 v67, v67, v67
	v_mul_f32_e32 v67, 0x3fb8aa3b, v67
	v_exp_f32_e32 v68, v67
	v_mul_f32_e32 v67, 0x3d372713, v77
	v_mul_f32_e32 v67, v77, v67
	v_fma_f32 v67, v77, v67, v77
	v_mul_f32_e32 v67, 0x3f4c422a, v67
	v_add_f32_e32 v67, v67, v67
	v_mul_f32_e32 v67, 0x3fb8aa3b, v67
	v_exp_f32_e32 v69, v67
	s_nop 0
	v_add_f32_e32 v68, 1.0, v68
	v_add_f32_e32 v69, 1.0, v69
	s_nop 0
	v_div_scale_f32 v67, s[24:25], v69, v69, 2.0
	v_rcp_f32_e32 v70, v67
	s_nop 0
	v_fma_f32 v71, -v67, v70, 1.0
	v_fmac_f32_e32 v70, v71, v70
	v_div_scale_f32 v71, vcc, 2.0, v69, 2.0
	v_mul_f32_e32 v72, v71, v70
	v_fma_f32 v73, -v67, v72, v71
	v_fmac_f32_e32 v72, v73, v70
	v_fma_f32 v67, -v67, v72, v71
	v_div_fmas_f32 v67, v67, v70, v72
	v_div_fixup_f32 v69, v67, v69, 2.0
	v_div_scale_f32 v67, s[24:25], v68, v68, 2.0
	v_rcp_f32_e32 v70, v67
	s_nop 0
	v_fma_f32 v71, -v67, v70, 1.0
	v_fmac_f32_e32 v70, v71, v70
	v_div_scale_f32 v71, vcc, 2.0, v68, 2.0
	v_mul_f32_e32 v72, v71, v70
	v_fma_f32 v73, -v67, v72, v71
	v_fmac_f32_e32 v72, v73, v70
	v_fma_f32 v67, -v67, v72, v71
	v_div_fmas_f32 v67, v67, v70, v72
	v_div_fixup_f32 v68, v67, v68, 2.0
	v_sub_f32_e32 v68, 1.0, v68
	v_sub_f32_e32 v69, 1.0, v69
	v_mul_f32_e32 v70, 0.5, v76
	v_mul_f32_e32 v71, 0.5, v77
	v_add_f32_e32 v68, 1.0, v68
	v_add_f32_e32 v69, 1.0, v69
	s_nop 0
	v_mul_f32_e32 v68, v70, v68
	v_mul_f32_e32 v69, v71, v69
	s_nop 0
	v_cvt_pk_bf16_f32 v67, v68, v69
	global_store_dwordx2 v[106:107], v[66:67], off offset:32
	v_mul_f32_e32 v66, 0x3d372713, v78
	v_mul_f32_e32 v67, 0x3d372713, v79
	v_mul_f32_e32 v66, v78, v66
	v_mul_f32_e32 v67, v79, v67
	v_fma_f32 v66, v78, v66, v78
	v_fma_f32 v67, v79, v67, v79
	v_mul_f32_e32 v66, 0x3f4c422a, v66
	v_mul_f32_e32 v67, 0x3f4c422a, v67
	v_add_f32_e32 v66, v66, v66
	v_add_f32_e32 v67, v67, v67
	v_mul_f32_e32 v66, 0x3fb8aa3b, v66
	v_mul_f32_e32 v67, 0x3fb8aa3b, v67
	v_exp_f32_e32 v66, v66
	v_exp_f32_e32 v67, v67
	s_nop 0
	v_add_f32_e32 v66, 1.0, v66
	v_add_f32_e32 v67, 1.0, v67
	s_nop 0
	v_div_scale_f32 v68, s[24:25], v67, v67, 2.0
	v_rcp_f32_e32 v69, v68
	s_nop 0
	v_fma_f32 v70, -v68, v69, 1.0
	v_fmac_f32_e32 v69, v70, v69
	v_div_scale_f32 v70, vcc, 2.0, v67, 2.0
	v_mul_f32_e32 v71, v70, v69
	v_fma_f32 v72, -v68, v71, v70
	v_fmac_f32_e32 v71, v72, v69
	v_fma_f32 v68, -v68, v71, v70
	v_div_fmas_f32 v68, v68, v69, v71
	v_div_fixup_f32 v67, v68, v67, 2.0
	v_div_scale_f32 v68, s[24:25], v66, v66, 2.0
	v_rcp_f32_e32 v69, v68
	s_nop 0
	v_fma_f32 v70, -v68, v69, 1.0
	v_fmac_f32_e32 v69, v70, v69
	v_div_scale_f32 v70, vcc, 2.0, v66, 2.0
	v_mul_f32_e32 v71, v70, v69
	v_fma_f32 v72, -v68, v71, v70
	v_fmac_f32_e32 v71, v72, v69
	v_fma_f32 v68, -v68, v71, v70
	v_div_fmas_f32 v68, v68, v69, v71
	v_div_fixup_f32 v66, v68, v66, 2.0
	v_sub_f32_e32 v66, 1.0, v66
	v_sub_f32_e32 v67, 1.0, v67
	v_mul_f32_e32 v68, 0.5, v78
	v_mul_f32_e32 v69, 0.5, v79
; __device__ __forceinline__ unsigned pk2(float lo, float hi) { const bfx2 b = __builtin_convertvector((f32x2){lo, hi}, bfx2); return __builtin_bit_cast(unsigned, b); }
; __device__ __forceinline__ float gelu_tanh(float x) { const float u = 0.7978845608028654f * (x + 0.044715f * x * x * x); const float th = 1.0f - 2.0f / (1.0f + __expf(2.0f * u)); return 0.5f * x * (1.0f + th); }
; __device__ __forceinline__ void cmp1_fused(const P& p, Frame& F) {
;     ...
; #pragma unroll
;         for (int mt = 0; mt < 5; ++mt) { const int rl = 32 * mt + ql; if (rl < 136) { const size_t row = (size_t)kv * CMPROWS + (rl < 128 ? 1024 + blk * 128 + rl : blk * 8 + (rl - 128));
; #pragma unroll
;                 for (int g = 0; g < 4; ++g) { u32x2 w; w.x = pk2(gelu_tanh(acc[mt][4 * g]), gelu_tanh(acc[mt][4 * g + 1])); w.y = pk2(gelu_tanh(acc[mt][4 * g + 2]), gelu_tanh(acc[mt][4 * g + 3]));
;                     *(u32x2*)(HID + row * 256 + 32 * wave + 8 * g + 4 * half) = w; } } }
	v_add_f32_e32 v66, 1.0, v66
	v_add_f32_e32 v67, 1.0, v67
	s_nop 0
	v_mul_f32_e32 v66, v68, v66
	v_mul_f32_e32 v67, v69, v67
	s_nop 0
	v_cvt_pk_bf16_f32 v66, v66, v67
	v_mul_f32_e32 v67, 0x3d372713, v80
	v_mul_f32_e32 v67, v80, v67
	v_fma_f32 v67, v80, v67, v80
	v_mul_f32_e32 v67, 0x3f4c422a, v67
	v_add_f32_e32 v67, v67, v67
	v_mul_f32_e32 v67, 0x3fb8aa3b, v67
	v_exp_f32_e32 v68, v67
	v_mul_f32_e32 v67, 0x3d372713, v81
	v_mul_f32_e32 v67, v81, v67
	v_fma_f32 v67, v81, v67, v81
	v_mul_f32_e32 v67, 0x3f4c422a, v67
	v_add_f32_e32 v67, v67, v67
	v_mul_f32_e32 v67, 0x3fb8aa3b, v67
	v_exp_f32_e32 v69, v67
	s_nop 0
	v_add_f32_e32 v68, 1.0, v68
	v_add_f32_e32 v69, 1.0, v69
	s_nop 0
	v_div_scale_f32 v67, s[24:25], v69, v69, 2.0
	v_rcp_f32_e32 v70, v67
	s_nop 0
	v_fma_f32 v71, -v67, v70, 1.0
	v_fmac_f32_e32 v70, v71, v70
	v_div_scale_f32 v71, vcc, 2.0, v69, 2.0
	v_mul_f32_e32 v72, v71, v70
	v_fma_f32 v73, -v67, v72, v71
	v_fmac_f32_e32 v72, v73, v70
	v_fma_f32 v67, -v67, v72, v71
	v_div_fmas_f32 v67, v67, v70, v72
	v_div_fixup_f32 v69, v67, v69, 2.0
	v_div_scale_f32 v67, s[24:25], v68, v68, 2.0
	v_rcp_f32_e32 v70, v67
	s_nop 0
	v_fma_f32 v71, -v67, v70, 1.0
	v_fmac_f32_e32 v70, v71, v70
	v_div_scale_f32 v71, vcc, 2.0, v68, 2.0
	v_mul_f32_e32 v72, v71, v70
	v_fma_f32 v73, -v67, v72, v71
	v_fmac_f32_e32 v72, v73, v70
	v_fma_f32 v67, -v67, v72, v71
	v_div_fmas_f32 v67, v67, v70, v72
	v_div_fixup_f32 v68, v67, v68, 2.0
	v_sub_f32_e32 v68, 1.0, v68
	v_sub_f32_e32 v69, 1.0, v69
	v_mul_f32_e32 v70, 0.5, v80
	v_mul_f32_e32 v71, 0.5, v81
	v_add_f32_e32 v68, 1.0, v68
	v_add_f32_e32 v69, 1.0, v69
	s_nop 0
	v_mul_f32_e32 v68, v70, v68
	v_mul_f32_e32 v69, v71, v69
	s_nop 0
	v_cvt_pk_bf16_f32 v67, v68, v69
	v_mul_f32_e32 v68, 0x3d372713, v50
	v_mul_f32_e32 v69, 0x3d372713, v51
	v_mul_f32_e32 v68, v50, v68
	v_mul_f32_e32 v69, v51, v69
	v_fma_f32 v68, v50, v68, v50
	v_fma_f32 v69, v51, v69, v51
	v_mul_f32_e32 v68, 0x3f4c422a, v68
	v_mul_f32_e32 v69, 0x3f4c422a, v69
	v_add_f32_e32 v68, v68, v68
	v_add_f32_e32 v69, v69, v69
	v_mul_f32_e32 v68, 0x3fb8aa3b, v68
	v_mul_f32_e32 v69, 0x3fb8aa3b, v69
	v_exp_f32_e32 v68, v68
	v_exp_f32_e32 v69, v69
	v_mul_f32_e32 v50, 0.5, v50
	v_mul_f32_e32 v51, 0.5, v51
	global_store_dwordx2 v[106:107], v[66:67], off offset:48
	v_or_b32_e32 v66, 32, v180
	v_add_f32_e32 v68, 1.0, v68
	v_add_f32_e32 v69, 1.0, v69
	v_mov_b32_e32 v67, v181
	v_div_scale_f32 v70, s[24:25], v69, v69, 2.0
	v_rcp_f32_e32 v71, v70
	v_mad_i64_i32 v[66:67], s[24:25], s0, v179, v[66:67]
	v_lshlrev_b64 v[66:67], 9, v[66:67]
	v_fma_f32 v72, -v70, v71, 1.0
	v_fmac_f32_e32 v71, v72, v71
	v_div_scale_f32 v72, vcc, 2.0, v69, 2.0
	v_mul_f32_e32 v73, v72, v71
	v_fma_f32 v74, -v70, v73, v72
	v_fmac_f32_e32 v73, v74, v71
	v_fma_f32 v70, -v70, v73, v72
	v_div_fmas_f32 v70, v70, v71, v73
	v_div_fixup_f32 v69, v70, v69, 2.0
	v_div_scale_f32 v70, s[24:25], v68, v68, 2.0
	v_rcp_f32_e32 v71, v70
	v_lshl_add_u64 v[66:67], v[190:191], 0, v[66:67]
	v_fma_f32 v72, -v70, v71, 1.0
	v_fmac_f32_e32 v71, v72, v71
	v_div_scale_f32 v72, vcc, 2.0, v68, 2.0
	v_mul_f32_e32 v73, v72, v71
	v_fma_f32 v74, -v70, v73, v72
	v_fmac_f32_e32 v73, v74, v71
	v_fma_f32 v70, -v70, v73, v72
	v_div_fmas_f32 v70, v70, v71, v73
	v_div_fixup_f32 v68, v70, v68, 2.0
	v_sub_f32_e32 v68, 1.0, v68
	v_sub_f32_e32 v69, 1.0, v69
	s_nop 0
	v_add_f32_e32 v68, 1.0, v68
	v_add_f32_e32 v69, 1.0, v69
	s_nop 0
	v_mul_f32_e32 v50, v50, v68
	v_mul_f32_e32 v51, v51, v69
	s_nop 0
	v_cvt_pk_bf16_f32 v50, v50, v51
	v_mul_f32_e32 v51, 0x3d372713, v52
	v_mul_f32_e32 v51, v52, v51
	v_fma_f32 v51, v52, v51, v52
	v_mul_f32_e32 v51, 0x3f4c422a, v51
	v_add_f32_e32 v51, v51, v51
	v_mul_f32_e32 v51, 0x3fb8aa3b, v51
	v_exp_f32_e32 v68, v51
	v_mul_f32_e32 v51, 0x3d372713, v53
	v_mul_f32_e32 v51, v53, v51
	v_fma_f32 v51, v53, v51, v53
	v_mul_f32_e32 v51, 0x3f4c422a, v51
	v_add_f32_e32 v51, v51, v51
	v_mul_f32_e32 v51, 0x3fb8aa3b, v51
	v_exp_f32_e32 v69, v51
	v_mul_f32_e32 v52, 0.5, v52
	v_mul_f32_e32 v53, 0.5, v53
	v_add_f32_e32 v68, 1.0, v68
	v_add_f32_e32 v69, 1.0, v69
	s_nop 0
	v_div_scale_f32 v51, s[24:25], v69, v69, 2.0
	v_rcp_f32_e32 v70, v51
	s_nop 0
	v_fma_f32 v71, -v51, v70, 1.0
	v_fmac_f32_e32 v70, v71, v70
	v_div_scale_f32 v71, vcc, 2.0, v69, 2.0
	v_mul_f32_e32 v72, v71, v70
	v_fma_f32 v73, -v51, v72, v71
	v_fmac_f32_e32 v72, v73, v70
	v_fma_f32 v51, -v51, v72, v71
	v_div_fmas_f32 v51, v51, v70, v72
	v_div_fixup_f32 v69, v51, v69, 2.0
	v_div_scale_f32 v51, s[24:25], v68, v68, 2.0
	v_rcp_f32_e32 v70, v51
	s_nop 0
	v_fma_f32 v71, -v51, v70, 1.0
	v_fmac_f32_e32 v70, v71, v70
	v_div_scale_f32 v71, vcc, 2.0, v68, 2.0
	v_mul_f32_e32 v72, v71, v70
	v_fma_f32 v73, -v51, v72, v71
	v_fmac_f32_e32 v72, v73, v70
	v_fma_f32 v51, -v51, v72, v71
	v_div_fmas_f32 v51, v51, v70, v72
	v_div_fixup_f32 v68, v51, v68, 2.0
	v_sub_f32_e32 v68, 1.0, v68
	v_sub_f32_e32 v69, 1.0, v69
	s_nop 0
	v_add_f32_e32 v68, 1.0, v68
	v_add_f32_e32 v69, 1.0, v69
	s_nop 0
	v_mul_f32_e32 v52, v52, v68
	v_mul_f32_e32 v53, v53, v69
	s_nop 0
	v_cvt_pk_bf16_f32 v51, v52, v53
	global_store_dwordx2 v[66:67], v[50:51], off
	v_mul_f32_e32 v50, 0x3d372713, v54
	v_mul_f32_e32 v51, 0x3d372713, v55
	v_mul_f32_e32 v50, v54, v50
	v_mul_f32_e32 v51, v55, v51
	v_fma_f32 v50, v54, v50, v54
	v_fma_f32 v51, v55, v51, v55
	v_mul_f32_e32 v50, 0x3f4c422a, v50
	v_mul_f32_e32 v51, 0x3f4c422a, v51
	v_add_f32_e32 v50, v50, v50
	v_add_f32_e32 v51, v51, v51
	v_mul_f32_e32 v50, 0x3fb8aa3b, v50
	v_mul_f32_e32 v51, 0x3fb8aa3b, v51
	v_exp_f32_e32 v50, v50
	v_exp_f32_e32 v51, v51
	s_nop 0
	v_add_f32_e32 v50, 1.0, v50
	v_add_f32_e32 v51, 1.0, v51
	s_nop 0
	v_div_scale_f32 v52, s[24:25], v51, v51, 2.0
; __device__ __forceinline__ unsigned pk2(float lo, float hi) { const bfx2 b = __builtin_convertvector((f32x2){lo, hi}, bfx2); return __builtin_bit_cast(unsigned, b); }
; __device__ __forceinline__ float gelu_tanh(float x) { const float u = 0.7978845608028654f * (x + 0.044715f * x * x * x); const float th = 1.0f - 2.0f / (1.0f + __expf(2.0f * u)); return 0.5f * x * (1.0f + th); }
; __device__ __forceinline__ void cmp1_fused(const P& p, Frame& F) {
;     ...
; #pragma unroll
;         for (int mt = 0; mt < 5; ++mt) { const int rl = 32 * mt + ql; if (rl < 136) { const size_t row = (size_t)kv * CMPROWS + (rl < 128 ? 1024 + blk * 128 + rl : blk * 8 + (rl - 128));
; #pragma unroll
;                 for (int g = 0; g < 4; ++g) { u32x2 w; w.x = pk2(gelu_tanh(acc[mt][4 * g]), gelu_tanh(acc[mt][4 * g + 1])); w.y = pk2(gelu_tanh(acc[mt][4 * g + 2]), gelu_tanh(acc[mt][4 * g + 3]));
;                     *(u32x2*)(HID + row * 256 + 32 * wave + 8 * g + 4 * half) = w; } } }
	v_rcp_f32_e32 v53, v52
	s_nop 0
	v_fma_f32 v68, -v52, v53, 1.0
	v_fmac_f32_e32 v53, v68, v53
	v_div_scale_f32 v68, vcc, 2.0, v51, 2.0
	v_mul_f32_e32 v69, v68, v53
	v_fma_f32 v70, -v52, v69, v68
	v_fmac_f32_e32 v69, v70, v53
	v_fma_f32 v52, -v52, v69, v68
	v_div_fmas_f32 v52, v52, v53, v69
	v_div_fixup_f32 v51, v52, v51, 2.0
	v_div_scale_f32 v52, s[24:25], v50, v50, 2.0
	v_rcp_f32_e32 v53, v52
	s_nop 0
	v_fma_f32 v68, -v52, v53, 1.0
	v_fmac_f32_e32 v53, v68, v53
	v_div_scale_f32 v68, vcc, 2.0, v50, 2.0
	v_mul_f32_e32 v69, v68, v53
	v_fma_f32 v70, -v52, v69, v68
	v_fmac_f32_e32 v69, v70, v53
	v_fma_f32 v52, -v52, v69, v68
	v_div_fmas_f32 v52, v52, v53, v69
	v_div_fixup_f32 v50, v52, v50, 2.0
	v_sub_f32_e32 v50, 1.0, v50
	v_sub_f32_e32 v51, 1.0, v51
	v_mul_f32_e32 v52, 0.5, v54
	v_mul_f32_e32 v53, 0.5, v55
	v_add_f32_e32 v50, 1.0, v50
	v_add_f32_e32 v51, 1.0, v51
	s_nop 0
	v_mul_f32_e32 v50, v52, v50
	v_mul_f32_e32 v51, v53, v51
	s_nop 0
	v_cvt_pk_bf16_f32 v50, v50, v51
	v_mul_f32_e32 v51, 0x3d372713, v56
	v_mul_f32_e32 v51, v56, v51
	v_fma_f32 v51, v56, v51, v56
	v_mul_f32_e32 v51, 0x3f4c422a, v51
	v_add_f32_e32 v51, v51, v51
	v_mul_f32_e32 v51, 0x3fb8aa3b, v51
	v_exp_f32_e32 v52, v51
	v_mul_f32_e32 v51, 0x3d372713, v57
	v_mul_f32_e32 v51, v57, v51
	v_fma_f32 v51, v57, v51, v57
	v_mul_f32_e32 v51, 0x3f4c422a, v51
	v_add_f32_e32 v51, v51, v51
	v_mul_f32_e32 v51, 0x3fb8aa3b, v51
	v_exp_f32_e32 v53, v51
	s_nop 0
	v_add_f32_e32 v52, 1.0, v52
	v_add_f32_e32 v53, 1.0, v53
	s_nop 0
	v_div_scale_f32 v51, s[24:25], v53, v53, 2.0
	v_rcp_f32_e32 v54, v51
	s_nop 0
	v_fma_f32 v55, -v51, v54, 1.0
	v_fmac_f32_e32 v54, v55, v54
	v_div_scale_f32 v55, vcc, 2.0, v53, 2.0
	v_mul_f32_e32 v68, v55, v54
	v_fma_f32 v69, -v51, v68, v55
	v_fmac_f32_e32 v68, v69, v54
	v_fma_f32 v51, -v51, v68, v55
	v_div_fmas_f32 v51, v51, v54, v68
	v_div_fixup_f32 v53, v51, v53, 2.0
	v_div_scale_f32 v51, s[24:25], v52, v52, 2.0
	v_rcp_f32_e32 v54, v51
	s_nop 0
	v_fma_f32 v55, -v51, v54, 1.0
	v_fmac_f32_e32 v54, v55, v54
	v_div_scale_f32 v55, vcc, 2.0, v52, 2.0
	v_mul_f32_e32 v68, v55, v54
	v_fma_f32 v69, -v51, v68, v55
	v_fmac_f32_e32 v68, v69, v54
	v_fma_f32 v51, -v51, v68, v55
	v_div_fmas_f32 v51, v51, v54, v68
	v_div_fixup_f32 v52, v51, v52, 2.0
	v_sub_f32_e32 v52, 1.0, v52
	v_sub_f32_e32 v53, 1.0, v53
	v_mul_f32_e32 v54, 0.5, v56
	v_mul_f32_e32 v55, 0.5, v57
	v_add_f32_e32 v52, 1.0, v52
	v_add_f32_e32 v53, 1.0, v53
	s_nop 0
	v_mul_f32_e32 v52, v54, v52
	v_mul_f32_e32 v53, v55, v53
	s_nop 0
	v_cvt_pk_bf16_f32 v51, v52, v53
	global_store_dwordx2 v[66:67], v[50:51], off offset:16
	v_mul_f32_e32 v50, 0x3d372713, v58
	v_mul_f32_e32 v51, 0x3d372713, v59
	v_mul_f32_e32 v50, v58, v50
	v_mul_f32_e32 v51, v59, v51
	v_fma_f32 v50, v58, v50, v58
	v_fma_f32 v51, v59, v51, v59
	v_mul_f32_e32 v50, 0x3f4c422a, v50
	v_mul_f32_e32 v51, 0x3f4c422a, v51
	v_add_f32_e32 v50, v50, v50
	v_add_f32_e32 v51, v51, v51
	v_mul_f32_e32 v50, 0x3fb8aa3b, v50
	v_mul_f32_e32 v51, 0x3fb8aa3b, v51
	v_exp_f32_e32 v50, v50
	v_exp_f32_e32 v51, v51
	s_nop 0
	v_add_f32_e32 v50, 1.0, v50
	v_add_f32_e32 v51, 1.0, v51
	s_nop 0
	v_div_scale_f32 v52, s[24:25], v51, v51, 2.0
	v_rcp_f32_e32 v53, v52
	s_nop 0
	v_fma_f32 v54, -v52, v53, 1.0
	v_fmac_f32_e32 v53, v54, v53
	v_div_scale_f32 v54, vcc, 2.0, v51, 2.0
	v_mul_f32_e32 v55, v54, v53
	v_fma_f32 v56, -v52, v55, v54
	v_fmac_f32_e32 v55, v56, v53
	v_fma_f32 v52, -v52, v55, v54
	v_div_fmas_f32 v52, v52, v53, v55
	v_div_fixup_f32 v51, v52, v51, 2.0
	v_div_scale_f32 v52, s[24:25], v50, v50, 2.0
	v_rcp_f32_e32 v53, v52
	s_nop 0
	v_fma_f32 v54, -v52, v53, 1.0
	v_fmac_f32_e32 v53, v54, v53
	v_div_scale_f32 v54, vcc, 2.0, v50, 2.0
	v_mul_f32_e32 v55, v54, v53
	v_fma_f32 v56, -v52, v55, v54
	v_fmac_f32_e32 v55, v56, v53
	v_fma_f32 v52, -v52, v55, v54
	v_div_fmas_f32 v52, v52, v53, v55
	v_div_fixup_f32 v50, v52, v50, 2.0
	v_sub_f32_e32 v50, 1.0, v50
	v_sub_f32_e32 v51, 1.0, v51
	v_mul_f32_e32 v52, 0.5, v58
	v_mul_f32_e32 v53, 0.5, v59
	v_add_f32_e32 v50, 1.0, v50
	v_add_f32_e32 v51, 1.0, v51
	s_nop 0
	v_mul_f32_e32 v50, v52, v50
	v_mul_f32_e32 v51, v53, v51
	s_nop 0
	v_cvt_pk_bf16_f32 v50, v50, v51
	v_mul_f32_e32 v51, 0x3d372713, v60
	v_mul_f32_e32 v51, v60, v51
	v_fma_f32 v51, v60, v51, v60
	v_mul_f32_e32 v51, 0x3f4c422a, v51
	v_add_f32_e32 v51, v51, v51
	v_mul_f32_e32 v51, 0x3fb8aa3b, v51
	v_exp_f32_e32 v52, v51
	v_mul_f32_e32 v51, 0x3d372713, v61
	v_mul_f32_e32 v51, v61, v51
	v_fma_f32 v51, v61, v51, v61
	v_mul_f32_e32 v51, 0x3f4c422a, v51
	v_add_f32_e32 v51, v51, v51
	v_mul_f32_e32 v51, 0x3fb8aa3b, v51
	v_exp_f32_e32 v53, v51
	s_nop 0
	v_add_f32_e32 v52, 1.0, v52
	v_add_f32_e32 v53, 1.0, v53
	s_nop 0
	v_div_scale_f32 v51, s[24:25], v53, v53, 2.0
	v_rcp_f32_e32 v54, v51
	s_nop 0
	v_fma_f32 v55, -v51, v54, 1.0
	v_fmac_f32_e32 v54, v55, v54
	v_div_scale_f32 v55, vcc, 2.0, v53, 2.0
	v_mul_f32_e32 v56, v55, v54
	v_fma_f32 v57, -v51, v56, v55
	v_fmac_f32_e32 v56, v57, v54
	v_fma_f32 v51, -v51, v56, v55
	v_div_fmas_f32 v51, v51, v54, v56
	v_div_fixup_f32 v53, v51, v53, 2.0
	v_div_scale_f32 v51, s[24:25], v52, v52, 2.0
	v_rcp_f32_e32 v54, v51
	s_nop 0
	v_fma_f32 v55, -v51, v54, 1.0
	v_fmac_f32_e32 v54, v55, v54
	v_div_scale_f32 v55, vcc, 2.0, v52, 2.0
	v_mul_f32_e32 v56, v55, v54
	v_fma_f32 v57, -v51, v56, v55
	v_fmac_f32_e32 v56, v57, v54
	v_fma_f32 v51, -v51, v56, v55
	v_div_fmas_f32 v51, v51, v54, v56
	v_div_fixup_f32 v52, v51, v52, 2.0
	v_sub_f32_e32 v52, 1.0, v52
	v_sub_f32_e32 v53, 1.0, v53
	v_mul_f32_e32 v54, 0.5, v60
	v_mul_f32_e32 v55, 0.5, v61
	v_add_f32_e32 v52, 1.0, v52
	v_add_f32_e32 v53, 1.0, v53
	s_nop 0
	v_mul_f32_e32 v52, v54, v52
	v_mul_f32_e32 v53, v55, v53
	s_nop 0
; __device__ __forceinline__ unsigned pk2(float lo, float hi) { const bfx2 b = __builtin_convertvector((f32x2){lo, hi}, bfx2); return __builtin_bit_cast(unsigned, b); }
; __device__ __forceinline__ float gelu_tanh(float x) { const float u = 0.7978845608028654f * (x + 0.044715f * x * x * x); const float th = 1.0f - 2.0f / (1.0f + __expf(2.0f * u)); return 0.5f * x * (1.0f + th); }
; __device__ __forceinline__ void cmp1_fused(const P& p, Frame& F) {
;     ...
; #pragma unroll
;         for (int mt = 0; mt < 5; ++mt) { const int rl = 32 * mt + ql; if (rl < 136) { const size_t row = (size_t)kv * CMPROWS + (rl < 128 ? 1024 + blk * 128 + rl : blk * 8 + (rl - 128));
; #pragma unroll
;                 for (int g = 0; g < 4; ++g) { u32x2 w; w.x = pk2(gelu_tanh(acc[mt][4 * g]), gelu_tanh(acc[mt][4 * g + 1])); w.y = pk2(gelu_tanh(acc[mt][4 * g + 2]), gelu_tanh(acc[mt][4 * g + 3]));
;                     *(u32x2*)(HID + row * 256 + 32 * wave + 8 * g + 4 * half) = w; } } }
	v_cvt_pk_bf16_f32 v51, v52, v53
	global_store_dwordx2 v[66:67], v[50:51], off offset:32
	v_mul_f32_e32 v50, 0x3d372713, v62
	v_mul_f32_e32 v51, 0x3d372713, v63
	v_mul_f32_e32 v50, v62, v50
	v_mul_f32_e32 v51, v63, v51
	v_fma_f32 v50, v62, v50, v62
	v_fma_f32 v51, v63, v51, v63
	v_mul_f32_e32 v50, 0x3f4c422a, v50
	v_mul_f32_e32 v51, 0x3f4c422a, v51
	v_add_f32_e32 v50, v50, v50
	v_add_f32_e32 v51, v51, v51
	v_mul_f32_e32 v50, 0x3fb8aa3b, v50
	v_mul_f32_e32 v51, 0x3fb8aa3b, v51
	v_exp_f32_e32 v50, v50
	v_exp_f32_e32 v51, v51
	s_nop 0
	v_add_f32_e32 v50, 1.0, v50
	v_add_f32_e32 v51, 1.0, v51
	s_nop 0
	v_div_scale_f32 v52, s[24:25], v51, v51, 2.0
	v_rcp_f32_e32 v53, v52
	s_nop 0
	v_fma_f32 v54, -v52, v53, 1.0
	v_fmac_f32_e32 v53, v54, v53
	v_div_scale_f32 v54, vcc, 2.0, v51, 2.0
	v_mul_f32_e32 v55, v54, v53
	v_fma_f32 v56, -v52, v55, v54
	v_fmac_f32_e32 v55, v56, v53
	v_fma_f32 v52, -v52, v55, v54
	v_div_fmas_f32 v52, v52, v53, v55
	v_div_fixup_f32 v51, v52, v51, 2.0
	v_div_scale_f32 v52, s[24:25], v50, v50, 2.0
	v_rcp_f32_e32 v53, v52
	s_nop 0
	v_fma_f32 v54, -v52, v53, 1.0
	v_fmac_f32_e32 v53, v54, v53
	v_div_scale_f32 v54, vcc, 2.0, v50, 2.0
	v_mul_f32_e32 v55, v54, v53
	v_fma_f32 v56, -v52, v55, v54
	v_fmac_f32_e32 v55, v56, v53
	v_fma_f32 v52, -v52, v55, v54
	v_div_fmas_f32 v52, v52, v53, v55
	v_div_fixup_f32 v50, v52, v50, 2.0
	v_sub_f32_e32 v50, 1.0, v50
	v_sub_f32_e32 v51, 1.0, v51
	v_mul_f32_e32 v52, 0.5, v62
	v_mul_f32_e32 v53, 0.5, v63
	v_add_f32_e32 v50, 1.0, v50
	v_add_f32_e32 v51, 1.0, v51
	s_nop 0
	v_mul_f32_e32 v50, v52, v50
	v_mul_f32_e32 v51, v53, v51
	s_nop 0
	v_cvt_pk_bf16_f32 v50, v50, v51
	v_mul_f32_e32 v51, 0x3d372713, v64
	v_mul_f32_e32 v51, v64, v51
	v_fma_f32 v51, v64, v51, v64
	v_mul_f32_e32 v51, 0x3f4c422a, v51
	v_add_f32_e32 v51, v51, v51
	v_mul_f32_e32 v51, 0x3fb8aa3b, v51
	v_exp_f32_e32 v52, v51
	v_mul_f32_e32 v51, 0x3d372713, v65
	v_mul_f32_e32 v51, v65, v51
	v_fma_f32 v51, v65, v51, v65
	v_mul_f32_e32 v51, 0x3f4c422a, v51
	v_add_f32_e32 v51, v51, v51
	v_mul_f32_e32 v51, 0x3fb8aa3b, v51
	v_exp_f32_e32 v53, v51
	s_nop 0
	v_add_f32_e32 v52, 1.0, v52
	v_add_f32_e32 v53, 1.0, v53
	s_nop 0
	v_div_scale_f32 v51, s[24:25], v53, v53, 2.0
	v_rcp_f32_e32 v54, v51
	s_nop 0
	v_fma_f32 v55, -v51, v54, 1.0
	v_fmac_f32_e32 v54, v55, v54
	v_div_scale_f32 v55, vcc, 2.0, v53, 2.0
	v_mul_f32_e32 v56, v55, v54
	v_fma_f32 v57, -v51, v56, v55
	v_fmac_f32_e32 v56, v57, v54
	v_fma_f32 v51, -v51, v56, v55
	v_div_fmas_f32 v51, v51, v54, v56
	v_div_fixup_f32 v53, v51, v53, 2.0
	v_div_scale_f32 v51, s[24:25], v52, v52, 2.0
	v_rcp_f32_e32 v54, v51
	s_nop 0
	v_fma_f32 v55, -v51, v54, 1.0
	v_fmac_f32_e32 v54, v55, v54
	v_div_scale_f32 v55, vcc, 2.0, v52, 2.0
	v_mul_f32_e32 v56, v55, v54
	v_fma_f32 v57, -v51, v56, v55
	v_fmac_f32_e32 v56, v57, v54
	v_fma_f32 v51, -v51, v56, v55
	v_div_fmas_f32 v51, v51, v54, v56
	v_div_fixup_f32 v52, v51, v52, 2.0
	v_sub_f32_e32 v52, 1.0, v52
	v_sub_f32_e32 v53, 1.0, v53
	v_mul_f32_e32 v54, 0.5, v64
	v_mul_f32_e32 v55, 0.5, v65
	v_add_f32_e32 v52, 1.0, v52
	v_add_f32_e32 v53, 1.0, v53
	s_nop 0
	v_mul_f32_e32 v52, v54, v52
	v_mul_f32_e32 v53, v55, v53
	s_nop 0
	v_cvt_pk_bf16_f32 v51, v52, v53
	v_mul_f32_e32 v52, 0x3d372713, v34
	v_mul_f32_e32 v53, 0x3d372713, v35
	v_mul_f32_e32 v52, v34, v52
	v_mul_f32_e32 v53, v35, v53
	v_fma_f32 v52, v34, v52, v34
	v_fma_f32 v53, v35, v53, v35
	v_mul_f32_e32 v52, 0x3f4c422a, v52
	v_mul_f32_e32 v53, 0x3f4c422a, v53
	v_add_f32_e32 v52, v52, v52
	v_add_f32_e32 v53, v53, v53
	v_mul_f32_e32 v52, 0x3fb8aa3b, v52
	v_mul_f32_e32 v53, 0x3fb8aa3b, v53
	v_exp_f32_e32 v52, v52
	v_exp_f32_e32 v53, v53
	v_mul_f32_e32 v34, 0.5, v34
	v_mul_f32_e32 v35, 0.5, v35
	global_store_dwordx2 v[66:67], v[50:51], off offset:48
	v_or_b32_e32 v50, 64, v180
	v_add_f32_e32 v52, 1.0, v52
	v_add_f32_e32 v53, 1.0, v53
	v_mov_b32_e32 v51, v181
	v_div_scale_f32 v54, s[24:25], v53, v53, 2.0
	v_rcp_f32_e32 v55, v54
	v_mad_i64_i32 v[50:51], s[24:25], s0, v179, v[50:51]
	v_lshlrev_b64 v[50:51], 9, v[50:51]
	v_fma_f32 v56, -v54, v55, 1.0
	v_fmac_f32_e32 v55, v56, v55
	v_div_scale_f32 v56, vcc, 2.0, v53, 2.0
	v_mul_f32_e32 v57, v56, v55
	v_fma_f32 v58, -v54, v57, v56
	v_fmac_f32_e32 v57, v58, v55
	v_fma_f32 v54, -v54, v57, v56
	v_div_fmas_f32 v54, v54, v55, v57
	v_div_fixup_f32 v53, v54, v53, 2.0
	v_div_scale_f32 v54, s[24:25], v52, v52, 2.0
	v_rcp_f32_e32 v55, v54
	v_lshl_add_u64 v[50:51], v[190:191], 0, v[50:51]
	v_or_b32_e32 v180, 0x60, v180
	v_fma_f32 v56, -v54, v55, 1.0
	v_fmac_f32_e32 v55, v56, v55
	v_div_scale_f32 v56, vcc, 2.0, v52, 2.0
	v_mul_f32_e32 v57, v56, v55
	v_fma_f32 v58, -v54, v57, v56
	v_fmac_f32_e32 v57, v58, v55
	v_fma_f32 v54, -v54, v57, v56
	v_div_fmas_f32 v54, v54, v55, v57
	v_div_fixup_f32 v52, v54, v52, 2.0
	v_sub_f32_e32 v52, 1.0, v52
	v_sub_f32_e32 v53, 1.0, v53
	s_nop 0
	v_add_f32_e32 v52, 1.0, v52
	v_add_f32_e32 v53, 1.0, v53
	s_nop 0
	v_mul_f32_e32 v34, v34, v52
	v_mul_f32_e32 v35, v35, v53
	s_nop 0
	v_cvt_pk_bf16_f32 v34, v34, v35
	v_mul_f32_e32 v35, 0x3d372713, v36
	v_mul_f32_e32 v35, v36, v35
	v_fma_f32 v35, v36, v35, v36
	v_mul_f32_e32 v35, 0x3f4c422a, v35
	v_add_f32_e32 v35, v35, v35
	v_mul_f32_e32 v35, 0x3fb8aa3b, v35
	v_exp_f32_e32 v52, v35
	v_mul_f32_e32 v35, 0x3d372713, v37
	v_mul_f32_e32 v35, v37, v35
	v_fma_f32 v35, v37, v35, v37
	v_mul_f32_e32 v35, 0x3f4c422a, v35
	v_add_f32_e32 v35, v35, v35
	v_mul_f32_e32 v35, 0x3fb8aa3b, v35
	v_exp_f32_e32 v53, v35
	v_mul_f32_e32 v36, 0.5, v36
	v_mul_f32_e32 v37, 0.5, v37
	v_add_f32_e32 v52, 1.0, v52
	v_add_f32_e32 v53, 1.0, v53
	s_nop 0
	v_div_scale_f32 v35, s[24:25], v53, v53, 2.0
	v_rcp_f32_e32 v54, v35
	s_nop 0
	v_fma_f32 v55, -v35, v54, 1.0
; __device__ __forceinline__ unsigned pk2(float lo, float hi) { const bfx2 b = __builtin_convertvector((f32x2){lo, hi}, bfx2); return __builtin_bit_cast(unsigned, b); }
; __device__ __forceinline__ float gelu_tanh(float x) { const float u = 0.7978845608028654f * (x + 0.044715f * x * x * x); const float th = 1.0f - 2.0f / (1.0f + __expf(2.0f * u)); return 0.5f * x * (1.0f + th); }
; __device__ __forceinline__ void cmp1_fused(const P& p, Frame& F) {
;     ...
; #pragma unroll
;         for (int mt = 0; mt < 5; ++mt) { const int rl = 32 * mt + ql; if (rl < 136) { const size_t row = (size_t)kv * CMPROWS + (rl < 128 ? 1024 + blk * 128 + rl : blk * 8 + (rl - 128));
; #pragma unroll
;                 for (int g = 0; g < 4; ++g) { u32x2 w; w.x = pk2(gelu_tanh(acc[mt][4 * g]), gelu_tanh(acc[mt][4 * g + 1])); w.y = pk2(gelu_tanh(acc[mt][4 * g + 2]), gelu_tanh(acc[mt][4 * g + 3]));
;                     *(u32x2*)(HID + row * 256 + 32 * wave + 8 * g + 4 * half) = w; } } }
	v_fmac_f32_e32 v54, v55, v54
	v_div_scale_f32 v55, vcc, 2.0, v53, 2.0
	v_mul_f32_e32 v56, v55, v54
	v_fma_f32 v57, -v35, v56, v55
	v_fmac_f32_e32 v56, v57, v54
	v_fma_f32 v35, -v35, v56, v55
	v_div_fmas_f32 v35, v35, v54, v56
	v_div_fixup_f32 v53, v35, v53, 2.0
	v_div_scale_f32 v35, s[24:25], v52, v52, 2.0
	v_rcp_f32_e32 v54, v35
	s_nop 0
	v_fma_f32 v55, -v35, v54, 1.0
	v_fmac_f32_e32 v54, v55, v54
	v_div_scale_f32 v55, vcc, 2.0, v52, 2.0
	v_mul_f32_e32 v56, v55, v54
	v_fma_f32 v57, -v35, v56, v55
	v_fmac_f32_e32 v56, v57, v54
	v_fma_f32 v35, -v35, v56, v55
	v_div_fmas_f32 v35, v35, v54, v56
	v_div_fixup_f32 v52, v35, v52, 2.0
	v_sub_f32_e32 v52, 1.0, v52
	v_sub_f32_e32 v53, 1.0, v53
	s_nop 0
	v_add_f32_e32 v52, 1.0, v52
	v_add_f32_e32 v53, 1.0, v53
	s_nop 0
	v_mul_f32_e32 v36, v36, v52
	v_mul_f32_e32 v37, v37, v53
	s_nop 0
	v_cvt_pk_bf16_f32 v35, v36, v37
	global_store_dwordx2 v[50:51], v[34:35], off
	v_mul_f32_e32 v34, 0x3d372713, v38
	v_mul_f32_e32 v35, 0x3d372713, v39
	v_mul_f32_e32 v34, v38, v34
	v_mul_f32_e32 v35, v39, v35
	v_fma_f32 v34, v38, v34, v38
	v_fma_f32 v35, v39, v35, v39
	v_mul_f32_e32 v34, 0x3f4c422a, v34
	v_mul_f32_e32 v35, 0x3f4c422a, v35
	v_add_f32_e32 v34, v34, v34
	v_add_f32_e32 v35, v35, v35
	v_mul_f32_e32 v34, 0x3fb8aa3b, v34
	v_mul_f32_e32 v35, 0x3fb8aa3b, v35
	v_exp_f32_e32 v34, v34
	v_exp_f32_e32 v35, v35
	s_nop 0
	v_add_f32_e32 v34, 1.0, v34
	v_add_f32_e32 v35, 1.0, v35
	s_nop 0
	v_div_scale_f32 v36, s[24:25], v35, v35, 2.0
	v_rcp_f32_e32 v37, v36
	s_nop 0
	v_fma_f32 v52, -v36, v37, 1.0
	v_fmac_f32_e32 v37, v52, v37
	v_div_scale_f32 v52, vcc, 2.0, v35, 2.0
	v_mul_f32_e32 v53, v52, v37
	v_fma_f32 v54, -v36, v53, v52
	v_fmac_f32_e32 v53, v54, v37
	v_fma_f32 v36, -v36, v53, v52
	v_div_fmas_f32 v36, v36, v37, v53
	v_div_fixup_f32 v35, v36, v35, 2.0
	v_div_scale_f32 v36, s[24:25], v34, v34, 2.0
	v_rcp_f32_e32 v37, v36
	s_nop 0
	v_fma_f32 v52, -v36, v37, 1.0
	v_fmac_f32_e32 v37, v52, v37
	v_div_scale_f32 v52, vcc, 2.0, v34, 2.0
	v_mul_f32_e32 v53, v52, v37
	v_fma_f32 v54, -v36, v53, v52
	v_fmac_f32_e32 v53, v54, v37
	v_fma_f32 v36, -v36, v53, v52
	v_div_fmas_f32 v36, v36, v37, v53
	v_div_fixup_f32 v34, v36, v34, 2.0
	v_sub_f32_e32 v34, 1.0, v34
	v_sub_f32_e32 v35, 1.0, v35
	v_mul_f32_e32 v36, 0.5, v38
	v_mul_f32_e32 v37, 0.5, v39
	v_add_f32_e32 v34, 1.0, v34
	v_add_f32_e32 v35, 1.0, v35
	s_nop 0
	v_mul_f32_e32 v34, v36, v34
	v_mul_f32_e32 v35, v37, v35
	s_nop 0
	v_cvt_pk_bf16_f32 v34, v34, v35
	v_mul_f32_e32 v35, 0x3d372713, v40
	v_mul_f32_e32 v35, v40, v35
	v_fma_f32 v35, v40, v35, v40
	v_mul_f32_e32 v35, 0x3f4c422a, v35
	v_add_f32_e32 v35, v35, v35
	v_mul_f32_e32 v35, 0x3fb8aa3b, v35
	v_exp_f32_e32 v36, v35
	v_mul_f32_e32 v35, 0x3d372713, v41
	v_mul_f32_e32 v35, v41, v35
	v_fma_f32 v35, v41, v35, v41
	v_mul_f32_e32 v35, 0x3f4c422a, v35
	v_add_f32_e32 v35, v35, v35
	v_mul_f32_e32 v35, 0x3fb8aa3b, v35
	v_exp_f32_e32 v37, v35
	s_nop 0
	v_add_f32_e32 v36, 1.0, v36
	v_add_f32_e32 v37, 1.0, v37
	s_nop 0
	v_div_scale_f32 v35, s[24:25], v37, v37, 2.0
	v_rcp_f32_e32 v38, v35
	s_nop 0
	v_fma_f32 v39, -v35, v38, 1.0
	v_fmac_f32_e32 v38, v39, v38
	v_div_scale_f32 v39, vcc, 2.0, v37, 2.0
	v_mul_f32_e32 v52, v39, v38
	v_fma_f32 v53, -v35, v52, v39
	v_fmac_f32_e32 v52, v53, v38
	v_fma_f32 v35, -v35, v52, v39
	v_div_fmas_f32 v35, v35, v38, v52
	v_div_fixup_f32 v37, v35, v37, 2.0
	v_div_scale_f32 v35, s[24:25], v36, v36, 2.0
	v_rcp_f32_e32 v38, v35
	s_nop 0
	v_fma_f32 v39, -v35, v38, 1.0
	v_fmac_f32_e32 v38, v39, v38
	v_div_scale_f32 v39, vcc, 2.0, v36, 2.0
	v_mul_f32_e32 v52, v39, v38
	v_fma_f32 v53, -v35, v52, v39
	v_fmac_f32_e32 v52, v53, v38
	v_fma_f32 v35, -v35, v52, v39
	v_div_fmas_f32 v35, v35, v38, v52
	v_div_fixup_f32 v36, v35, v36, 2.0
	v_sub_f32_e32 v36, 1.0, v36
	v_sub_f32_e32 v37, 1.0, v37
	v_mul_f32_e32 v38, 0.5, v40
	v_mul_f32_e32 v39, 0.5, v41
	v_add_f32_e32 v36, 1.0, v36
	v_add_f32_e32 v37, 1.0, v37
	s_nop 0
	v_mul_f32_e32 v36, v38, v36
	v_mul_f32_e32 v37, v39, v37
	s_nop 0
	v_cvt_pk_bf16_f32 v35, v36, v37
	global_store_dwordx2 v[50:51], v[34:35], off offset:16
	v_mul_f32_e32 v34, 0x3d372713, v42
	v_mul_f32_e32 v35, 0x3d372713, v43
	v_mul_f32_e32 v34, v42, v34
	v_mul_f32_e32 v35, v43, v35
	v_fma_f32 v34, v42, v34, v42
	v_fma_f32 v35, v43, v35, v43
	v_mul_f32_e32 v34, 0x3f4c422a, v34
	v_mul_f32_e32 v35, 0x3f4c422a, v35
	v_add_f32_e32 v34, v34, v34
	v_add_f32_e32 v35, v35, v35
	v_mul_f32_e32 v34, 0x3fb8aa3b, v34
	v_mul_f32_e32 v35, 0x3fb8aa3b, v35
	v_exp_f32_e32 v34, v34
	v_exp_f32_e32 v35, v35
	s_nop 0
	v_add_f32_e32 v34, 1.0, v34
	v_add_f32_e32 v35, 1.0, v35
	s_nop 0
	v_div_scale_f32 v36, s[24:25], v35, v35, 2.0
	v_rcp_f32_e32 v37, v36
	s_nop 0
	v_fma_f32 v38, -v36, v37, 1.0
	v_fmac_f32_e32 v37, v38, v37
	v_div_scale_f32 v38, vcc, 2.0, v35, 2.0
	v_mul_f32_e32 v39, v38, v37
	v_fma_f32 v40, -v36, v39, v38
	v_fmac_f32_e32 v39, v40, v37
	v_fma_f32 v36, -v36, v39, v38
	v_div_fmas_f32 v36, v36, v37, v39
	v_div_fixup_f32 v35, v36, v35, 2.0
	v_div_scale_f32 v36, s[24:25], v34, v34, 2.0
	v_rcp_f32_e32 v37, v36
	s_nop 0
	v_fma_f32 v38, -v36, v37, 1.0
	v_fmac_f32_e32 v37, v38, v37
	v_div_scale_f32 v38, vcc, 2.0, v34, 2.0
	v_mul_f32_e32 v39, v38, v37
	v_fma_f32 v40, -v36, v39, v38
	v_fmac_f32_e32 v39, v40, v37
	v_fma_f32 v36, -v36, v39, v38
	v_div_fmas_f32 v36, v36, v37, v39
	v_div_fixup_f32 v34, v36, v34, 2.0
	v_sub_f32_e32 v34, 1.0, v34
	v_sub_f32_e32 v35, 1.0, v35
	v_mul_f32_e32 v36, 0.5, v42
	v_mul_f32_e32 v37, 0.5, v43
	v_add_f32_e32 v34, 1.0, v34
	v_add_f32_e32 v35, 1.0, v35
	s_nop 0
	v_mul_f32_e32 v34, v36, v34
	v_mul_f32_e32 v35, v37, v35
	s_nop 0
	v_cvt_pk_bf16_f32 v34, v34, v35
	v_mul_f32_e32 v35, 0x3d372713, v44
; __device__ __forceinline__ unsigned pk2(float lo, float hi) { const bfx2 b = __builtin_convertvector((f32x2){lo, hi}, bfx2); return __builtin_bit_cast(unsigned, b); }
; __device__ __forceinline__ float gelu_tanh(float x) { const float u = 0.7978845608028654f * (x + 0.044715f * x * x * x); const float th = 1.0f - 2.0f / (1.0f + __expf(2.0f * u)); return 0.5f * x * (1.0f + th); }
; __device__ __forceinline__ void cmp1_fused(const P& p, Frame& F) {
;     ...
; #pragma unroll
;         for (int mt = 0; mt < 5; ++mt) { const int rl = 32 * mt + ql; if (rl < 136) { const size_t row = (size_t)kv * CMPROWS + (rl < 128 ? 1024 + blk * 128 + rl : blk * 8 + (rl - 128));
; #pragma unroll
;                 for (int g = 0; g < 4; ++g) { u32x2 w; w.x = pk2(gelu_tanh(acc[mt][4 * g]), gelu_tanh(acc[mt][4 * g + 1])); w.y = pk2(gelu_tanh(acc[mt][4 * g + 2]), gelu_tanh(acc[mt][4 * g + 3]));
;                     *(u32x2*)(HID + row * 256 + 32 * wave + 8 * g + 4 * half) = w; } } }
	v_mul_f32_e32 v35, v44, v35
	v_fma_f32 v35, v44, v35, v44
	v_mul_f32_e32 v35, 0x3f4c422a, v35
	v_add_f32_e32 v35, v35, v35
	v_mul_f32_e32 v35, 0x3fb8aa3b, v35
	v_exp_f32_e32 v36, v35
	v_mul_f32_e32 v35, 0x3d372713, v45
	v_mul_f32_e32 v35, v45, v35
	v_fma_f32 v35, v45, v35, v45
	v_mul_f32_e32 v35, 0x3f4c422a, v35
	v_add_f32_e32 v35, v35, v35
	v_mul_f32_e32 v35, 0x3fb8aa3b, v35
	v_exp_f32_e32 v37, v35
	s_nop 0
	v_add_f32_e32 v36, 1.0, v36
	v_add_f32_e32 v37, 1.0, v37
	s_nop 0
	v_div_scale_f32 v35, s[24:25], v37, v37, 2.0
	v_rcp_f32_e32 v38, v35
	s_nop 0
	v_fma_f32 v39, -v35, v38, 1.0
	v_fmac_f32_e32 v38, v39, v38
	v_div_scale_f32 v39, vcc, 2.0, v37, 2.0
	v_mul_f32_e32 v40, v39, v38
	v_fma_f32 v41, -v35, v40, v39
	v_fmac_f32_e32 v40, v41, v38
	v_fma_f32 v35, -v35, v40, v39
	v_div_fmas_f32 v35, v35, v38, v40
	v_div_fixup_f32 v37, v35, v37, 2.0
	v_div_scale_f32 v35, s[24:25], v36, v36, 2.0
	v_rcp_f32_e32 v38, v35
	s_nop 0
	v_fma_f32 v39, -v35, v38, 1.0
	v_fmac_f32_e32 v38, v39, v38
	v_div_scale_f32 v39, vcc, 2.0, v36, 2.0
	v_mul_f32_e32 v40, v39, v38
	v_fma_f32 v41, -v35, v40, v39
	v_fmac_f32_e32 v40, v41, v38
	v_fma_f32 v35, -v35, v40, v39
	v_div_fmas_f32 v35, v35, v38, v40
	v_div_fixup_f32 v36, v35, v36, 2.0
	v_sub_f32_e32 v36, 1.0, v36
	v_sub_f32_e32 v37, 1.0, v37
	v_mul_f32_e32 v38, 0.5, v44
	v_mul_f32_e32 v39, 0.5, v45
	v_add_f32_e32 v36, 1.0, v36
	v_add_f32_e32 v37, 1.0, v37
	s_nop 0
	v_mul_f32_e32 v36, v38, v36
	v_mul_f32_e32 v37, v39, v37
	s_nop 0
	v_cvt_pk_bf16_f32 v35, v36, v37
	global_store_dwordx2 v[50:51], v[34:35], off offset:32
	v_mul_f32_e32 v34, 0x3d372713, v46
	v_mul_f32_e32 v35, 0x3d372713, v47
	v_mul_f32_e32 v34, v46, v34
	v_mul_f32_e32 v35, v47, v35
	v_fma_f32 v34, v46, v34, v46
	v_fma_f32 v35, v47, v35, v47
	v_mul_f32_e32 v34, 0x3f4c422a, v34
	v_mul_f32_e32 v35, 0x3f4c422a, v35
	v_add_f32_e32 v34, v34, v34
	v_add_f32_e32 v35, v35, v35
	v_mul_f32_e32 v34, 0x3fb8aa3b, v34
	v_mul_f32_e32 v35, 0x3fb8aa3b, v35
	v_exp_f32_e32 v34, v34
	v_exp_f32_e32 v35, v35
	s_nop 0
	v_add_f32_e32 v34, 1.0, v34
	v_add_f32_e32 v35, 1.0, v35
	s_nop 0
	v_div_scale_f32 v36, s[24:25], v35, v35, 2.0
	v_rcp_f32_e32 v37, v36
	s_nop 0
	v_fma_f32 v38, -v36, v37, 1.0
	v_fmac_f32_e32 v37, v38, v37
	v_div_scale_f32 v38, vcc, 2.0, v35, 2.0
	v_mul_f32_e32 v39, v38, v37
	v_fma_f32 v40, -v36, v39, v38
	v_fmac_f32_e32 v39, v40, v37
	v_fma_f32 v36, -v36, v39, v38
	v_div_fmas_f32 v36, v36, v37, v39
	v_div_fixup_f32 v35, v36, v35, 2.0
	v_div_scale_f32 v36, s[24:25], v34, v34, 2.0
	v_rcp_f32_e32 v37, v36
	s_nop 0
	v_fma_f32 v38, -v36, v37, 1.0
	v_fmac_f32_e32 v37, v38, v37
	v_div_scale_f32 v38, vcc, 2.0, v34, 2.0
	v_mul_f32_e32 v39, v38, v37
	v_fma_f32 v40, -v36, v39, v38
	v_fmac_f32_e32 v39, v40, v37
	v_fma_f32 v36, -v36, v39, v38
	v_div_fmas_f32 v36, v36, v37, v39
	v_div_fixup_f32 v34, v36, v34, 2.0
	v_sub_f32_e32 v34, 1.0, v34
	v_sub_f32_e32 v35, 1.0, v35
	v_mul_f32_e32 v36, 0.5, v46
	v_mul_f32_e32 v37, 0.5, v47
	v_add_f32_e32 v34, 1.0, v34
	v_add_f32_e32 v35, 1.0, v35
	s_nop 0
	v_mul_f32_e32 v34, v36, v34
	v_mul_f32_e32 v35, v37, v35
	s_nop 0
	v_cvt_pk_bf16_f32 v34, v34, v35
	v_mul_f32_e32 v35, 0x3d372713, v48
	v_mul_f32_e32 v35, v48, v35
	v_fma_f32 v35, v48, v35, v48
	v_mul_f32_e32 v35, 0x3f4c422a, v35
	v_add_f32_e32 v35, v35, v35
	v_mul_f32_e32 v35, 0x3fb8aa3b, v35
	v_exp_f32_e32 v36, v35
	v_mul_f32_e32 v35, 0x3d372713, v49
	v_mul_f32_e32 v35, v49, v35
	v_fma_f32 v35, v49, v35, v49
	v_mul_f32_e32 v35, 0x3f4c422a, v35
	v_add_f32_e32 v35, v35, v35
	v_mul_f32_e32 v35, 0x3fb8aa3b, v35
	v_exp_f32_e32 v37, v35
	s_nop 0
	v_add_f32_e32 v36, 1.0, v36
	v_add_f32_e32 v37, 1.0, v37
	s_nop 0
	v_div_scale_f32 v35, s[24:25], v37, v37, 2.0
	v_rcp_f32_e32 v38, v35
	s_nop 0
	v_fma_f32 v39, -v35, v38, 1.0
	v_fmac_f32_e32 v38, v39, v38
	v_div_scale_f32 v39, vcc, 2.0, v37, 2.0
	v_mul_f32_e32 v40, v39, v38
	v_fma_f32 v41, -v35, v40, v39
	v_fmac_f32_e32 v40, v41, v38
	v_fma_f32 v35, -v35, v40, v39
	v_div_fmas_f32 v35, v35, v38, v40
	v_div_fixup_f32 v37, v35, v37, 2.0
	v_div_scale_f32 v35, s[24:25], v36, v36, 2.0
	v_rcp_f32_e32 v38, v35
	s_nop 0
	v_fma_f32 v39, -v35, v38, 1.0
	v_fmac_f32_e32 v38, v39, v38
	v_div_scale_f32 v39, vcc, 2.0, v36, 2.0
	v_mul_f32_e32 v40, v39, v38
	v_fma_f32 v41, -v35, v40, v39
	v_fmac_f32_e32 v40, v41, v38
	v_fma_f32 v35, -v35, v40, v39
	v_div_fmas_f32 v35, v35, v38, v40
	v_div_fixup_f32 v36, v35, v36, 2.0
	v_sub_f32_e32 v36, 1.0, v36
	v_sub_f32_e32 v37, 1.0, v37
	v_mul_f32_e32 v38, 0.5, v48
	v_mul_f32_e32 v39, 0.5, v49
	v_add_f32_e32 v36, 1.0, v36
	v_add_f32_e32 v37, 1.0, v37
	s_nop 0
	v_mul_f32_e32 v36, v38, v36
	v_mul_f32_e32 v37, v39, v37
	s_nop 0
	v_cvt_pk_bf16_f32 v35, v36, v37
	v_mul_f32_e32 v36, 0x3d372713, v18
	v_mul_f32_e32 v37, 0x3d372713, v19
	v_mul_f32_e32 v36, v18, v36
	v_mul_f32_e32 v37, v19, v37
	v_fma_f32 v36, v18, v36, v18
	v_fma_f32 v37, v19, v37, v19
	v_mul_f32_e32 v36, 0x3f4c422a, v36
	v_mul_f32_e32 v37, 0x3f4c422a, v37
	v_add_f32_e32 v36, v36, v36
	v_add_f32_e32 v37, v37, v37
	v_mul_f32_e32 v36, 0x3fb8aa3b, v36
	v_mul_f32_e32 v37, 0x3fb8aa3b, v37
	v_exp_f32_e32 v36, v36
	v_exp_f32_e32 v37, v37
	v_mul_f32_e32 v18, 0.5, v18
	v_mul_f32_e32 v19, 0.5, v19
	global_store_dwordx2 v[50:51], v[34:35], off offset:48
	v_mad_i64_i32 v[34:35], s[24:25], s0, v179, v[180:181]
	v_add_f32_e32 v36, 1.0, v36
	v_add_f32_e32 v37, 1.0, v37
	v_lshlrev_b64 v[34:35], 9, v[34:35]
	v_div_scale_f32 v38, s[24:25], v37, v37, 2.0
	v_rcp_f32_e32 v39, v38
	v_lshl_add_u64 v[34:35], v[190:191], 0, v[34:35]
	v_fma_f32 v40, -v38, v39, 1.0
	v_fmac_f32_e32 v39, v40, v39
	v_div_scale_f32 v40, vcc, 2.0, v37, 2.0
	v_mul_f32_e32 v41, v40, v39
	v_fma_f32 v42, -v38, v41, v40
; __device__ __forceinline__ unsigned pk2(float lo, float hi) { const bfx2 b = __builtin_convertvector((f32x2){lo, hi}, bfx2); return __builtin_bit_cast(unsigned, b); }
; __device__ __forceinline__ float gelu_tanh(float x) { const float u = 0.7978845608028654f * (x + 0.044715f * x * x * x); const float th = 1.0f - 2.0f / (1.0f + __expf(2.0f * u)); return 0.5f * x * (1.0f + th); }
; __device__ __forceinline__ void cmp1_fused(const P& p, Frame& F) {
;     ...
; #pragma unroll
;         for (int mt = 0; mt < 5; ++mt) { const int rl = 32 * mt + ql; if (rl < 136) { const size_t row = (size_t)kv * CMPROWS + (rl < 128 ? 1024 + blk * 128 + rl : blk * 8 + (rl - 128));
; #pragma unroll
;                 for (int g = 0; g < 4; ++g) { u32x2 w; w.x = pk2(gelu_tanh(acc[mt][4 * g]), gelu_tanh(acc[mt][4 * g + 1])); w.y = pk2(gelu_tanh(acc[mt][4 * g + 2]), gelu_tanh(acc[mt][4 * g + 3]));
;                     *(u32x2*)(HID + row * 256 + 32 * wave + 8 * g + 4 * half) = w; } } }
	v_fmac_f32_e32 v41, v42, v39
	v_fma_f32 v38, -v38, v41, v40
	v_div_fmas_f32 v38, v38, v39, v41
	v_div_fixup_f32 v37, v38, v37, 2.0
	v_div_scale_f32 v38, s[24:25], v36, v36, 2.0
	v_rcp_f32_e32 v39, v38
	s_nop 0
	v_fma_f32 v40, -v38, v39, 1.0
	v_fmac_f32_e32 v39, v40, v39
	v_div_scale_f32 v40, vcc, 2.0, v36, 2.0
	v_mul_f32_e32 v41, v40, v39
	v_fma_f32 v42, -v38, v41, v40
	v_fmac_f32_e32 v41, v42, v39
	v_fma_f32 v38, -v38, v41, v40
	v_div_fmas_f32 v38, v38, v39, v41
	v_div_fixup_f32 v36, v38, v36, 2.0
	v_sub_f32_e32 v36, 1.0, v36
	v_sub_f32_e32 v37, 1.0, v37
	s_nop 0
	v_add_f32_e32 v36, 1.0, v36
	v_add_f32_e32 v37, 1.0, v37
	s_nop 0
	v_mul_f32_e32 v18, v18, v36
	v_mul_f32_e32 v19, v19, v37
	s_nop 0
	v_cvt_pk_bf16_f32 v18, v18, v19
	v_mul_f32_e32 v19, 0x3d372713, v20
	v_mul_f32_e32 v19, v20, v19
	v_fma_f32 v19, v20, v19, v20
	v_mul_f32_e32 v19, 0x3f4c422a, v19
	v_add_f32_e32 v19, v19, v19
	v_mul_f32_e32 v19, 0x3fb8aa3b, v19
	v_exp_f32_e32 v36, v19
	v_mul_f32_e32 v19, 0x3d372713, v21
	v_mul_f32_e32 v19, v21, v19
	v_fma_f32 v19, v21, v19, v21
	v_mul_f32_e32 v19, 0x3f4c422a, v19
	v_add_f32_e32 v19, v19, v19
	v_mul_f32_e32 v19, 0x3fb8aa3b, v19
	v_exp_f32_e32 v37, v19
	v_mul_f32_e32 v20, 0.5, v20
	v_mul_f32_e32 v21, 0.5, v21
	v_add_f32_e32 v36, 1.0, v36
	v_add_f32_e32 v37, 1.0, v37
	s_nop 0
	v_div_scale_f32 v19, s[24:25], v37, v37, 2.0
	v_rcp_f32_e32 v38, v19
	s_nop 0
	v_fma_f32 v39, -v19, v38, 1.0
	v_fmac_f32_e32 v38, v39, v38
	v_div_scale_f32 v39, vcc, 2.0, v37, 2.0
	v_mul_f32_e32 v40, v39, v38
	v_fma_f32 v41, -v19, v40, v39
	v_fmac_f32_e32 v40, v41, v38
	v_fma_f32 v19, -v19, v40, v39
	v_div_fmas_f32 v19, v19, v38, v40
	v_div_fixup_f32 v37, v19, v37, 2.0
	v_div_scale_f32 v19, s[24:25], v36, v36, 2.0
	v_rcp_f32_e32 v38, v19
	s_nop 0
	v_fma_f32 v39, -v19, v38, 1.0
	v_fmac_f32_e32 v38, v39, v38
	v_div_scale_f32 v39, vcc, 2.0, v36, 2.0
	v_mul_f32_e32 v40, v39, v38
	v_fma_f32 v41, -v19, v40, v39
	v_fmac_f32_e32 v40, v41, v38
	v_fma_f32 v19, -v19, v40, v39
	v_div_fmas_f32 v19, v19, v38, v40
	v_div_fixup_f32 v36, v19, v36, 2.0
	v_sub_f32_e32 v36, 1.0, v36
	v_sub_f32_e32 v37, 1.0, v37
	s_nop 0
	v_add_f32_e32 v36, 1.0, v36
	v_add_f32_e32 v37, 1.0, v37
	s_nop 0
	v_mul_f32_e32 v20, v20, v36
	v_mul_f32_e32 v21, v21, v37
	s_nop 0
	v_cvt_pk_bf16_f32 v19, v20, v21
	global_store_dwordx2 v[34:35], v[18:19], off
	v_mul_f32_e32 v18, 0x3d372713, v22
	v_mul_f32_e32 v19, 0x3d372713, v23
	v_mul_f32_e32 v18, v22, v18
	v_mul_f32_e32 v19, v23, v19
	v_fma_f32 v18, v22, v18, v22
	v_fma_f32 v19, v23, v19, v23
	v_mul_f32_e32 v18, 0x3f4c422a, v18
	v_mul_f32_e32 v19, 0x3f4c422a, v19
	v_add_f32_e32 v18, v18, v18
	v_add_f32_e32 v19, v19, v19
	v_mul_f32_e32 v18, 0x3fb8aa3b, v18
	v_mul_f32_e32 v19, 0x3fb8aa3b, v19
	v_exp_f32_e32 v18, v18
	v_exp_f32_e32 v19, v19
	s_nop 0
	v_add_f32_e32 v18, 1.0, v18
	v_add_f32_e32 v19, 1.0, v19
	s_nop 0
	v_div_scale_f32 v20, s[24:25], v19, v19, 2.0
	v_rcp_f32_e32 v21, v20
	s_nop 0
	v_fma_f32 v36, -v20, v21, 1.0
	v_fmac_f32_e32 v21, v36, v21
	v_div_scale_f32 v36, vcc, 2.0, v19, 2.0
	v_mul_f32_e32 v37, v36, v21
	v_fma_f32 v38, -v20, v37, v36
	v_fmac_f32_e32 v37, v38, v21
	v_fma_f32 v20, -v20, v37, v36
	v_div_fmas_f32 v20, v20, v21, v37
	v_div_fixup_f32 v19, v20, v19, 2.0
	v_div_scale_f32 v20, s[24:25], v18, v18, 2.0
	v_rcp_f32_e32 v21, v20
	s_nop 0
	v_fma_f32 v36, -v20, v21, 1.0
	v_fmac_f32_e32 v21, v36, v21
	v_div_scale_f32 v36, vcc, 2.0, v18, 2.0
	v_mul_f32_e32 v37, v36, v21
	v_fma_f32 v38, -v20, v37, v36
	v_fmac_f32_e32 v37, v38, v21
	v_fma_f32 v20, -v20, v37, v36
	v_div_fmas_f32 v20, v20, v21, v37
	v_div_fixup_f32 v18, v20, v18, 2.0
	v_sub_f32_e32 v18, 1.0, v18
	v_sub_f32_e32 v19, 1.0, v19
	v_mul_f32_e32 v20, 0.5, v22
	v_mul_f32_e32 v21, 0.5, v23
	v_add_f32_e32 v18, 1.0, v18
	v_add_f32_e32 v19, 1.0, v19
	s_nop 0
	v_mul_f32_e32 v18, v20, v18
	v_mul_f32_e32 v19, v21, v19
	s_nop 0
	v_cvt_pk_bf16_f32 v18, v18, v19
	v_mul_f32_e32 v19, 0x3d372713, v24
	v_mul_f32_e32 v19, v24, v19
	v_fma_f32 v19, v24, v19, v24
	v_mul_f32_e32 v19, 0x3f4c422a, v19
	v_add_f32_e32 v19, v19, v19
	v_mul_f32_e32 v19, 0x3fb8aa3b, v19
	v_exp_f32_e32 v20, v19
	v_mul_f32_e32 v19, 0x3d372713, v25
	v_mul_f32_e32 v19, v25, v19
	v_fma_f32 v19, v25, v19, v25
	v_mul_f32_e32 v19, 0x3f4c422a, v19
	v_add_f32_e32 v19, v19, v19
	v_mul_f32_e32 v19, 0x3fb8aa3b, v19
	v_exp_f32_e32 v21, v19
	s_nop 0
	v_add_f32_e32 v20, 1.0, v20
	v_add_f32_e32 v21, 1.0, v21
	s_nop 0
	v_div_scale_f32 v19, s[24:25], v21, v21, 2.0
	v_rcp_f32_e32 v22, v19
	s_nop 0
	v_fma_f32 v23, -v19, v22, 1.0
	v_fmac_f32_e32 v22, v23, v22
	v_div_scale_f32 v23, vcc, 2.0, v21, 2.0
	v_mul_f32_e32 v36, v23, v22
	v_fma_f32 v37, -v19, v36, v23
	v_fmac_f32_e32 v36, v37, v22
	v_fma_f32 v19, -v19, v36, v23
	v_div_fmas_f32 v19, v19, v22, v36
	v_div_fixup_f32 v21, v19, v21, 2.0
	v_div_scale_f32 v19, s[24:25], v20, v20, 2.0
	v_rcp_f32_e32 v22, v19
	s_nop 0
	v_fma_f32 v23, -v19, v22, 1.0
	v_fmac_f32_e32 v22, v23, v22
	v_div_scale_f32 v23, vcc, 2.0, v20, 2.0
	v_mul_f32_e32 v36, v23, v22
	v_fma_f32 v37, -v19, v36, v23
	v_fmac_f32_e32 v36, v37, v22
	v_fma_f32 v19, -v19, v36, v23
	v_div_fmas_f32 v19, v19, v22, v36
	v_div_fixup_f32 v20, v19, v20, 2.0
	v_sub_f32_e32 v20, 1.0, v20
	v_sub_f32_e32 v21, 1.0, v21
	v_mul_f32_e32 v22, 0.5, v24
	v_mul_f32_e32 v23, 0.5, v25
	v_add_f32_e32 v20, 1.0, v20
	v_add_f32_e32 v21, 1.0, v21
	s_nop 0
	v_mul_f32_e32 v20, v22, v20
	v_mul_f32_e32 v21, v23, v21
	s_nop 0
	v_cvt_pk_bf16_f32 v19, v20, v21
	global_store_dwordx2 v[34:35], v[18:19], off offset:16
	v_mul_f32_e32 v18, 0x3d372713, v26
	v_mul_f32_e32 v19, 0x3d372713, v27
	v_mul_f32_e32 v18, v26, v18
	v_mul_f32_e32 v19, v27, v19
	v_fma_f32 v18, v26, v18, v26
; __device__ __forceinline__ unsigned pk2(float lo, float hi) { const bfx2 b = __builtin_convertvector((f32x2){lo, hi}, bfx2); return __builtin_bit_cast(unsigned, b); }
; __device__ __forceinline__ float gelu_tanh(float x) { const float u = 0.7978845608028654f * (x + 0.044715f * x * x * x); const float th = 1.0f - 2.0f / (1.0f + __expf(2.0f * u)); return 0.5f * x * (1.0f + th); }
; __device__ __forceinline__ void cmp1_fused(const P& p, Frame& F) {
;     ...
; #pragma unroll
;         for (int mt = 0; mt < 5; ++mt) { const int rl = 32 * mt + ql; if (rl < 136) { const size_t row = (size_t)kv * CMPROWS + (rl < 128 ? 1024 + blk * 128 + rl : blk * 8 + (rl - 128));
; #pragma unroll
;                 for (int g = 0; g < 4; ++g) { u32x2 w; w.x = pk2(gelu_tanh(acc[mt][4 * g]), gelu_tanh(acc[mt][4 * g + 1])); w.y = pk2(gelu_tanh(acc[mt][4 * g + 2]), gelu_tanh(acc[mt][4 * g + 3]));
;                     *(u32x2*)(HID + row * 256 + 32 * wave + 8 * g + 4 * half) = w; } } }
	v_fma_f32 v19, v27, v19, v27
	v_mul_f32_e32 v18, 0x3f4c422a, v18
	v_mul_f32_e32 v19, 0x3f4c422a, v19
	v_add_f32_e32 v18, v18, v18
	v_add_f32_e32 v19, v19, v19
	v_mul_f32_e32 v18, 0x3fb8aa3b, v18
	v_mul_f32_e32 v19, 0x3fb8aa3b, v19
	v_exp_f32_e32 v18, v18
	v_exp_f32_e32 v19, v19
	s_nop 0
	v_add_f32_e32 v18, 1.0, v18
	v_add_f32_e32 v19, 1.0, v19
	s_nop 0
	v_div_scale_f32 v20, s[24:25], v19, v19, 2.0
	v_rcp_f32_e32 v21, v20
	s_nop 0
	v_fma_f32 v22, -v20, v21, 1.0
	v_fmac_f32_e32 v21, v22, v21
	v_div_scale_f32 v22, vcc, 2.0, v19, 2.0
	v_mul_f32_e32 v23, v22, v21
	v_fma_f32 v24, -v20, v23, v22
	v_fmac_f32_e32 v23, v24, v21
	v_fma_f32 v20, -v20, v23, v22
	v_div_fmas_f32 v20, v20, v21, v23
	v_div_fixup_f32 v19, v20, v19, 2.0
	v_div_scale_f32 v20, s[24:25], v18, v18, 2.0
	v_rcp_f32_e32 v21, v20
	s_nop 0
	v_fma_f32 v22, -v20, v21, 1.0
	v_fmac_f32_e32 v21, v22, v21
	v_div_scale_f32 v22, vcc, 2.0, v18, 2.0
	v_mul_f32_e32 v23, v22, v21
	v_fma_f32 v24, -v20, v23, v22
	v_fmac_f32_e32 v23, v24, v21
	v_fma_f32 v20, -v20, v23, v22
	v_div_fmas_f32 v20, v20, v21, v23
	v_div_fixup_f32 v18, v20, v18, 2.0
	v_sub_f32_e32 v18, 1.0, v18
	v_sub_f32_e32 v19, 1.0, v19
	v_mul_f32_e32 v20, 0.5, v26
	v_mul_f32_e32 v21, 0.5, v27
	v_add_f32_e32 v18, 1.0, v18
	v_add_f32_e32 v19, 1.0, v19
	s_nop 0
	v_mul_f32_e32 v18, v20, v18
	v_mul_f32_e32 v19, v21, v19
	s_nop 0
	v_cvt_pk_bf16_f32 v18, v18, v19
	v_mul_f32_e32 v19, 0x3d372713, v28
	v_mul_f32_e32 v19, v28, v19
	v_fma_f32 v19, v28, v19, v28
	v_mul_f32_e32 v19, 0x3f4c422a, v19
	v_add_f32_e32 v19, v19, v19
	v_mul_f32_e32 v19, 0x3fb8aa3b, v19
	v_exp_f32_e32 v20, v19
	v_mul_f32_e32 v19, 0x3d372713, v29
	v_mul_f32_e32 v19, v29, v19
	v_fma_f32 v19, v29, v19, v29
	v_mul_f32_e32 v19, 0x3f4c422a, v19
	v_add_f32_e32 v19, v19, v19
	v_mul_f32_e32 v19, 0x3fb8aa3b, v19
	v_exp_f32_e32 v21, v19
	s_nop 0
	v_add_f32_e32 v20, 1.0, v20
	v_add_f32_e32 v21, 1.0, v21
	s_nop 0
	v_div_scale_f32 v19, s[24:25], v21, v21, 2.0
	v_rcp_f32_e32 v22, v19
	s_nop 0
	v_fma_f32 v23, -v19, v22, 1.0
	v_fmac_f32_e32 v22, v23, v22
	v_div_scale_f32 v23, vcc, 2.0, v21, 2.0
	v_mul_f32_e32 v24, v23, v22
	v_fma_f32 v25, -v19, v24, v23
	v_fmac_f32_e32 v24, v25, v22
	v_fma_f32 v19, -v19, v24, v23
	v_div_fmas_f32 v19, v19, v22, v24
	v_div_fixup_f32 v21, v19, v21, 2.0
	v_div_scale_f32 v19, s[24:25], v20, v20, 2.0
	v_rcp_f32_e32 v22, v19
	s_nop 0
	v_fma_f32 v23, -v19, v22, 1.0
	v_fmac_f32_e32 v22, v23, v22
	v_div_scale_f32 v23, vcc, 2.0, v20, 2.0
	v_mul_f32_e32 v24, v23, v22
	v_fma_f32 v25, -v19, v24, v23
	v_fmac_f32_e32 v24, v25, v22
	v_fma_f32 v19, -v19, v24, v23
	v_div_fmas_f32 v19, v19, v22, v24
	v_div_fixup_f32 v20, v19, v20, 2.0
	v_sub_f32_e32 v20, 1.0, v20
	v_sub_f32_e32 v21, 1.0, v21
	v_mul_f32_e32 v22, 0.5, v28
	v_mul_f32_e32 v23, 0.5, v29
	v_add_f32_e32 v20, 1.0, v20
	v_add_f32_e32 v21, 1.0, v21
	s_nop 0
	v_mul_f32_e32 v20, v22, v20
	v_mul_f32_e32 v21, v23, v21
	s_nop 0
	v_cvt_pk_bf16_f32 v19, v20, v21
	global_store_dwordx2 v[34:35], v[18:19], off offset:32
	v_mul_f32_e32 v18, 0x3d372713, v30
	v_mul_f32_e32 v19, 0x3d372713, v31
	v_mul_f32_e32 v18, v30, v18
	v_mul_f32_e32 v19, v31, v19
	v_fma_f32 v18, v30, v18, v30
	v_fma_f32 v19, v31, v19, v31
	v_mul_f32_e32 v18, 0x3f4c422a, v18
	v_mul_f32_e32 v19, 0x3f4c422a, v19
	v_add_f32_e32 v18, v18, v18
	v_add_f32_e32 v19, v19, v19
	v_mul_f32_e32 v18, 0x3fb8aa3b, v18
	v_mul_f32_e32 v19, 0x3fb8aa3b, v19
	v_exp_f32_e32 v18, v18
	v_exp_f32_e32 v19, v19
	s_nop 0
	v_add_f32_e32 v18, 1.0, v18
	v_add_f32_e32 v19, 1.0, v19
	s_nop 0
	v_div_scale_f32 v20, s[24:25], v19, v19, 2.0
	v_rcp_f32_e32 v21, v20
	s_nop 0
	v_fma_f32 v22, -v20, v21, 1.0
	v_fmac_f32_e32 v21, v22, v21
	v_div_scale_f32 v22, vcc, 2.0, v19, 2.0
	v_mul_f32_e32 v23, v22, v21
	v_fma_f32 v24, -v20, v23, v22
	v_fmac_f32_e32 v23, v24, v21
	v_fma_f32 v20, -v20, v23, v22
	v_div_fmas_f32 v20, v20, v21, v23
	v_div_fixup_f32 v19, v20, v19, 2.0
	v_div_scale_f32 v20, s[24:25], v18, v18, 2.0
	v_rcp_f32_e32 v21, v20
	s_nop 0
	v_fma_f32 v22, -v20, v21, 1.0
	v_fmac_f32_e32 v21, v22, v21
	v_div_scale_f32 v22, vcc, 2.0, v18, 2.0
	v_mul_f32_e32 v23, v22, v21
	v_fma_f32 v24, -v20, v23, v22
	v_fmac_f32_e32 v23, v24, v21
	v_fma_f32 v20, -v20, v23, v22
	v_div_fmas_f32 v20, v20, v21, v23
	v_div_fixup_f32 v18, v20, v18, 2.0
	v_sub_f32_e32 v18, 1.0, v18
	v_sub_f32_e32 v19, 1.0, v19
	v_mul_f32_e32 v20, 0.5, v30
	v_mul_f32_e32 v21, 0.5, v31
	v_add_f32_e32 v18, 1.0, v18
	v_add_f32_e32 v19, 1.0, v19
	s_nop 0
	v_mul_f32_e32 v18, v20, v18
	v_mul_f32_e32 v19, v21, v19
	s_nop 0
	v_cvt_pk_bf16_f32 v18, v18, v19
	v_mul_f32_e32 v19, 0x3d372713, v32
	v_mul_f32_e32 v19, v32, v19
	v_fma_f32 v19, v32, v19, v32
	v_mul_f32_e32 v19, 0x3f4c422a, v19
	v_add_f32_e32 v19, v19, v19
	v_mul_f32_e32 v19, 0x3fb8aa3b, v19
	v_exp_f32_e32 v20, v19
	v_mul_f32_e32 v19, 0x3d372713, v33
	v_mul_f32_e32 v19, v33, v19
	v_fma_f32 v19, v33, v19, v33
	v_mul_f32_e32 v19, 0x3f4c422a, v19
	v_add_f32_e32 v19, v19, v19
	v_mul_f32_e32 v19, 0x3fb8aa3b, v19
	v_exp_f32_e32 v21, v19
	s_nop 0
	v_add_f32_e32 v20, 1.0, v20
	v_add_f32_e32 v21, 1.0, v21
	s_nop 0
	v_div_scale_f32 v19, s[24:25], v21, v21, 2.0
	v_rcp_f32_e32 v22, v19
	s_nop 0
	v_fma_f32 v23, -v19, v22, 1.0
	v_fmac_f32_e32 v22, v23, v22
	v_div_scale_f32 v23, vcc, 2.0, v21, 2.0
	v_mul_f32_e32 v24, v23, v22
	v_fma_f32 v25, -v19, v24, v23
	v_fmac_f32_e32 v24, v25, v22
	v_fma_f32 v19, -v19, v24, v23
	v_div_fmas_f32 v19, v19, v22, v24
	v_div_fixup_f32 v21, v19, v21, 2.0
	v_div_scale_f32 v19, s[24:25], v20, v20, 2.0
	v_rcp_f32_e32 v22, v19
	s_nop 0
	v_fma_f32 v23, -v19, v22, 1.0
	v_fmac_f32_e32 v22, v23, v22
	v_div_scale_f32 v23, vcc, 2.0, v20, 2.0
	v_mul_f32_e32 v24, v23, v22
	v_fma_f32 v25, -v19, v24, v23
	v_fmac_f32_e32 v24, v25, v22
	v_fma_f32 v19, -v19, v24, v23
	v_div_fmas_f32 v19, v19, v22, v24
	v_div_fixup_f32 v20, v19, v20, 2.0
	v_sub_f32_e32 v20, 1.0, v20
	v_sub_f32_e32 v21, 1.0, v21
	v_mul_f32_e32 v22, 0.5, v32
	v_mul_f32_e32 v23, 0.5, v33
	v_add_f32_e32 v20, 1.0, v20
	v_add_f32_e32 v21, 1.0, v21
	s_nop 0
	v_mul_f32_e32 v20, v22, v20
	v_mul_f32_e32 v21, v23, v21
	s_nop 0
	v_cvt_pk_bf16_f32 v19, v20, v21
	global_store_dwordx2 v[34:35], v[18:19], off offset:48
	s_and_saveexec_b64 s[24:25], s[10:11]
	s_cbranch_execz .LBB0_1418
; __device__ __forceinline__ unsigned pk2(float lo, float hi) { const bfx2 b = __builtin_convertvector((f32x2){lo, hi}, bfx2); return __builtin_bit_cast(unsigned, b); }
; __device__ __forceinline__ float gelu_tanh(float x) { const float u = 0.7978845608028654f * (x + 0.044715f * x * x * x); const float th = 1.0f - 2.0f / (1.0f + __expf(2.0f * u)); return 0.5f * x * (1.0f + th); }
; __device__ __forceinline__ void cmp1_fused(const P& p, Frame& F) {
;     ...
; #pragma unroll
;         for (int mt = 0; mt < 5; ++mt) { const int rl = 32 * mt + ql; if (rl < 136) { const size_t row = (size_t)kv * CMPROWS + (rl < 128 ? 1024 + blk * 128 + rl : blk * 8 + (rl - 128));
; #pragma unroll
;                 for (int g = 0; g < 4; ++g) { u32x2 w; w.x = pk2(gelu_tanh(acc[mt][4 * g]), gelu_tanh(acc[mt][4 * g + 1])); w.y = pk2(gelu_tanh(acc[mt][4 * g + 2]), gelu_tanh(acc[mt][4 * g + 3]));
;                     *(u32x2*)(HID + row * 256 + 32 * wave + 8 * g + 4 * half) = w; } } }
	v_mul_f32_e32 v20, 0x3d372713, v2
	v_mul_f32_e32 v21, 0x3d372713, v3
	v_mul_f32_e32 v20, v2, v20
	v_mul_f32_e32 v21, v3, v21
	v_fma_f32 v20, v2, v20, v2
	v_fma_f32 v21, v3, v21, v3
	v_mul_f32_e32 v20, 0x3f4c422a, v20
	v_mul_f32_e32 v21, 0x3f4c422a, v21
	v_add_f32_e32 v20, v20, v20
	v_add_f32_e32 v21, v21, v21
	v_mul_f32_e32 v20, 0x3fb8aa3b, v20
	v_mul_f32_e32 v21, 0x3fb8aa3b, v21
	v_exp_f32_e32 v20, v20
	v_exp_f32_e32 v21, v21
	s_mul_hi_i32 s1, s0, 0x4400
	s_mulk_i32 s0, 0x4400
	v_lshl_add_u32 v180, s26, 3, v189
	v_add_f32_e32 v20, 1.0, v20
	v_add_f32_e32 v21, 1.0, v21
	v_lshl_add_u64 v[18:19], s[0:1], 0, v[180:181]
	v_div_scale_f32 v22, s[0:1], v21, v21, 2.0
	v_rcp_f32_e32 v23, v22
	v_mul_f32_e32 v2, 0.5, v2
	v_mul_f32_e32 v3, 0.5, v3
	v_lshlrev_b64 v[18:19], 9, v[18:19]
	v_lshl_add_u64 v[18:19], v[190:191], 0, v[18:19]
	v_fma_f32 v24, -v22, v23, 1.0
	v_fmac_f32_e32 v23, v24, v23
	v_div_scale_f32 v24, vcc, 2.0, v21, 2.0
	v_mul_f32_e32 v25, v24, v23
	v_fma_f32 v26, -v22, v25, v24
	v_fmac_f32_e32 v25, v26, v23
	v_fma_f32 v22, -v22, v25, v24
	v_div_fmas_f32 v22, v22, v23, v25
	v_div_fixup_f32 v21, v22, v21, 2.0
	v_div_scale_f32 v22, s[0:1], v20, v20, 2.0
	v_rcp_f32_e32 v23, v22
	s_nop 0
	v_fma_f32 v24, -v22, v23, 1.0
	v_fmac_f32_e32 v23, v24, v23
	v_div_scale_f32 v24, vcc, 2.0, v20, 2.0
	v_mul_f32_e32 v25, v24, v23
	v_fma_f32 v26, -v22, v25, v24
	v_fmac_f32_e32 v25, v26, v23
	v_fma_f32 v22, -v22, v25, v24
	v_div_fmas_f32 v22, v22, v23, v25
	v_div_fixup_f32 v20, v22, v20, 2.0
	v_sub_f32_e32 v20, 1.0, v20
	v_sub_f32_e32 v21, 1.0, v21
	s_nop 0
	v_add_f32_e32 v20, 1.0, v20
	v_add_f32_e32 v21, 1.0, v21
	s_nop 0
	v_mul_f32_e32 v2, v2, v20
	v_mul_f32_e32 v3, v3, v21
	s_nop 0
	v_cvt_pk_bf16_f32 v2, v2, v3
	v_mul_f32_e32 v3, 0x3d372713, v4
	v_mul_f32_e32 v3, v4, v3
	v_fma_f32 v3, v4, v3, v4
	v_mul_f32_e32 v3, 0x3f4c422a, v3
	v_add_f32_e32 v3, v3, v3
	v_mul_f32_e32 v3, 0x3fb8aa3b, v3
	v_exp_f32_e32 v20, v3
	v_mul_f32_e32 v3, 0x3d372713, v5
	v_mul_f32_e32 v3, v5, v3
	v_fma_f32 v3, v5, v3, v5
	v_mul_f32_e32 v3, 0x3f4c422a, v3
	v_add_f32_e32 v3, v3, v3
	v_mul_f32_e32 v3, 0x3fb8aa3b, v3
	v_exp_f32_e32 v21, v3
	v_mul_f32_e32 v4, 0.5, v4
	v_mul_f32_e32 v5, 0.5, v5
	v_add_f32_e32 v20, 1.0, v20
	v_add_f32_e32 v21, 1.0, v21
	s_nop 0
	v_div_scale_f32 v3, s[0:1], v21, v21, 2.0
	v_rcp_f32_e32 v22, v3
	s_nop 0
	v_fma_f32 v23, -v3, v22, 1.0
	v_fmac_f32_e32 v22, v23, v22
	v_div_scale_f32 v23, vcc, 2.0, v21, 2.0
	v_mul_f32_e32 v24, v23, v22
	v_fma_f32 v25, -v3, v24, v23
	v_fmac_f32_e32 v24, v25, v22
	v_fma_f32 v3, -v3, v24, v23
	v_div_fmas_f32 v3, v3, v22, v24
	v_div_fixup_f32 v21, v3, v21, 2.0
	v_div_scale_f32 v3, s[0:1], v20, v20, 2.0
	v_rcp_f32_e32 v22, v3
	s_nop 0
	v_fma_f32 v23, -v3, v22, 1.0
	v_fmac_f32_e32 v22, v23, v22
	v_div_scale_f32 v23, vcc, 2.0, v20, 2.0
	v_mul_f32_e32 v24, v23, v22
	v_fma_f32 v25, -v3, v24, v23
	v_fmac_f32_e32 v24, v25, v22
	v_fma_f32 v3, -v3, v24, v23
	v_div_fmas_f32 v3, v3, v22, v24
	v_div_fixup_f32 v20, v3, v20, 2.0
	v_sub_f32_e32 v20, 1.0, v20
	v_sub_f32_e32 v21, 1.0, v21
	s_nop 0
	v_add_f32_e32 v20, 1.0, v20
	v_add_f32_e32 v21, 1.0, v21
	s_nop 0
	v_mul_f32_e32 v4, v4, v20
	v_mul_f32_e32 v5, v5, v21
	s_nop 0
	v_cvt_pk_bf16_f32 v3, v4, v5
	global_store_dwordx2 v[18:19], v[2:3], off
	v_mul_f32_e32 v2, 0x3d372713, v6
	v_mul_f32_e32 v3, 0x3d372713, v7
	v_mul_f32_e32 v2, v6, v2
	v_mul_f32_e32 v3, v7, v3
	v_fma_f32 v2, v6, v2, v6
	v_fma_f32 v3, v7, v3, v7
	v_mul_f32_e32 v2, 0x3f4c422a, v2
	v_mul_f32_e32 v3, 0x3f4c422a, v3
	v_add_f32_e32 v2, v2, v2
	v_add_f32_e32 v3, v3, v3
	v_mul_f32_e32 v2, 0x3fb8aa3b, v2
	v_mul_f32_e32 v3, 0x3fb8aa3b, v3
	v_exp_f32_e32 v2, v2
	v_exp_f32_e32 v3, v3
	s_nop 0
	v_add_f32_e32 v2, 1.0, v2
	v_add_f32_e32 v3, 1.0, v3
	s_nop 0
	v_div_scale_f32 v4, s[0:1], v3, v3, 2.0
	v_rcp_f32_e32 v5, v4
	s_nop 0
	v_fma_f32 v20, -v4, v5, 1.0
	v_fmac_f32_e32 v5, v20, v5
	v_div_scale_f32 v20, vcc, 2.0, v3, 2.0
	v_mul_f32_e32 v21, v20, v5
	v_fma_f32 v22, -v4, v21, v20
	v_fmac_f32_e32 v21, v22, v5
	v_fma_f32 v4, -v4, v21, v20
	v_div_fmas_f32 v4, v4, v5, v21
	v_div_fixup_f32 v3, v4, v3, 2.0
	v_div_scale_f32 v4, s[0:1], v2, v2, 2.0
	v_rcp_f32_e32 v5, v4
	s_nop 0
	v_fma_f32 v20, -v4, v5, 1.0
	v_fmac_f32_e32 v5, v20, v5
	v_div_scale_f32 v20, vcc, 2.0, v2, 2.0
	v_mul_f32_e32 v21, v20, v5
	v_fma_f32 v22, -v4, v21, v20
	v_fmac_f32_e32 v21, v22, v5
	v_fma_f32 v4, -v4, v21, v20
	v_div_fmas_f32 v4, v4, v5, v21
	v_div_fixup_f32 v2, v4, v2, 2.0
	v_sub_f32_e32 v2, 1.0, v2
	v_sub_f32_e32 v3, 1.0, v3
	v_mul_f32_e32 v4, 0.5, v6
	v_mul_f32_e32 v5, 0.5, v7
	v_add_f32_e32 v2, 1.0, v2
	v_add_f32_e32 v3, 1.0, v3
	s_nop 0
	v_mul_f32_e32 v2, v4, v2
	v_mul_f32_e32 v3, v5, v3
	s_nop 0
	v_cvt_pk_bf16_f32 v2, v2, v3
	v_mul_f32_e32 v3, 0x3d372713, v8
	v_mul_f32_e32 v3, v8, v3
	v_fma_f32 v3, v8, v3, v8
	v_mul_f32_e32 v3, 0x3f4c422a, v3
	v_add_f32_e32 v3, v3, v3
	v_mul_f32_e32 v3, 0x3fb8aa3b, v3
	v_exp_f32_e32 v4, v3
	v_mul_f32_e32 v3, 0x3d372713, v9
	v_mul_f32_e32 v3, v9, v3
	v_fma_f32 v3, v9, v3, v9
	v_mul_f32_e32 v3, 0x3f4c422a, v3
	v_add_f32_e32 v3, v3, v3
	v_mul_f32_e32 v3, 0x3fb8aa3b, v3
	v_exp_f32_e32 v5, v3
	s_nop 0
	v_add_f32_e32 v4, 1.0, v4
	v_add_f32_e32 v5, 1.0, v5
	s_nop 0
	v_div_scale_f32 v3, s[0:1], v5, v5, 2.0
	v_rcp_f32_e32 v6, v3
	s_nop 0
	v_fma_f32 v7, -v3, v6, 1.0
	v_fmac_f32_e32 v6, v7, v6
	v_div_scale_f32 v7, vcc, 2.0, v5, 2.0
	v_mul_f32_e32 v20, v7, v6
	v_fma_f32 v21, -v3, v20, v7
	v_fmac_f32_e32 v20, v21, v6
	v_fma_f32 v3, -v3, v20, v7
	v_div_fmas_f32 v3, v3, v6, v20
	v_div_fixup_f32 v5, v3, v5, 2.0
	v_div_scale_f32 v3, s[0:1], v4, v4, 2.0
	v_rcp_f32_e32 v6, v3
	s_nop 0
	v_fma_f32 v7, -v3, v6, 1.0
	v_fmac_f32_e32 v6, v7, v6
; __device__ __forceinline__ unsigned pk2(float lo, float hi) { const bfx2 b = __builtin_convertvector((f32x2){lo, hi}, bfx2); return __builtin_bit_cast(unsigned, b); }
; __device__ __forceinline__ float gelu_tanh(float x) { const float u = 0.7978845608028654f * (x + 0.044715f * x * x * x); const float th = 1.0f - 2.0f / (1.0f + __expf(2.0f * u)); return 0.5f * x * (1.0f + th); }
; __device__ __forceinline__ void cmp1_fused(const P& p, Frame& F) {
;     ...
; #pragma unroll
;         for (int mt = 0; mt < 5; ++mt) { const int rl = 32 * mt + ql; if (rl < 136) { const size_t row = (size_t)kv * CMPROWS + (rl < 128 ? 1024 + blk * 128 + rl : blk * 8 + (rl - 128));
; #pragma unroll
;                 for (int g = 0; g < 4; ++g) { u32x2 w; w.x = pk2(gelu_tanh(acc[mt][4 * g]), gelu_tanh(acc[mt][4 * g + 1])); w.y = pk2(gelu_tanh(acc[mt][4 * g + 2]), gelu_tanh(acc[mt][4 * g + 3]));
;                     *(u32x2*)(HID + row * 256 + 32 * wave + 8 * g + 4 * half) = w; } } }
	v_div_scale_f32 v7, vcc, 2.0, v4, 2.0
	v_mul_f32_e32 v20, v7, v6
	v_fma_f32 v21, -v3, v20, v7
	v_fmac_f32_e32 v20, v21, v6
	v_fma_f32 v3, -v3, v20, v7
	v_div_fmas_f32 v3, v3, v6, v20
	v_div_fixup_f32 v4, v3, v4, 2.0
	v_sub_f32_e32 v4, 1.0, v4
	v_sub_f32_e32 v5, 1.0, v5
	v_mul_f32_e32 v6, 0.5, v8
	v_mul_f32_e32 v7, 0.5, v9
	v_add_f32_e32 v4, 1.0, v4
	v_add_f32_e32 v5, 1.0, v5
	s_nop 0
	v_mul_f32_e32 v4, v6, v4
	v_mul_f32_e32 v5, v7, v5
	s_nop 0
	v_cvt_pk_bf16_f32 v3, v4, v5
	global_store_dwordx2 v[18:19], v[2:3], off offset:16
	v_mul_f32_e32 v2, 0x3d372713, v10
	v_mul_f32_e32 v3, 0x3d372713, v11
	v_mul_f32_e32 v2, v10, v2
	v_mul_f32_e32 v3, v11, v3
	v_fma_f32 v2, v10, v2, v10
	v_fma_f32 v3, v11, v3, v11
	v_mul_f32_e32 v2, 0x3f4c422a, v2
	v_mul_f32_e32 v3, 0x3f4c422a, v3
	v_add_f32_e32 v2, v2, v2
	v_add_f32_e32 v3, v3, v3
	v_mul_f32_e32 v2, 0x3fb8aa3b, v2
	v_mul_f32_e32 v3, 0x3fb8aa3b, v3
	v_exp_f32_e32 v2, v2
	v_exp_f32_e32 v3, v3
	s_nop 0
	v_add_f32_e32 v2, 1.0, v2
	v_add_f32_e32 v3, 1.0, v3
	s_nop 0
	v_div_scale_f32 v4, s[0:1], v3, v3, 2.0
	v_rcp_f32_e32 v5, v4
	s_nop 0
	v_fma_f32 v6, -v4, v5, 1.0
	v_fmac_f32_e32 v5, v6, v5
	v_div_scale_f32 v6, vcc, 2.0, v3, 2.0
	v_mul_f32_e32 v7, v6, v5
	v_fma_f32 v8, -v4, v7, v6
	v_fmac_f32_e32 v7, v8, v5
	v_fma_f32 v4, -v4, v7, v6
	v_div_fmas_f32 v4, v4, v5, v7
	v_div_fixup_f32 v3, v4, v3, 2.0
	v_div_scale_f32 v4, s[0:1], v2, v2, 2.0
	v_rcp_f32_e32 v5, v4
	s_nop 0
	v_fma_f32 v6, -v4, v5, 1.0
	v_fmac_f32_e32 v5, v6, v5
	v_div_scale_f32 v6, vcc, 2.0, v2, 2.0
	v_mul_f32_e32 v7, v6, v5
	v_fma_f32 v8, -v4, v7, v6
	v_fmac_f32_e32 v7, v8, v5
	v_fma_f32 v4, -v4, v7, v6
	v_div_fmas_f32 v4, v4, v5, v7
	v_div_fixup_f32 v2, v4, v2, 2.0
	v_sub_f32_e32 v2, 1.0, v2
	v_sub_f32_e32 v3, 1.0, v3
	v_mul_f32_e32 v4, 0.5, v10
	v_mul_f32_e32 v5, 0.5, v11
	v_add_f32_e32 v2, 1.0, v2
	v_add_f32_e32 v3, 1.0, v3
	s_nop 0
	v_mul_f32_e32 v2, v4, v2
	v_mul_f32_e32 v3, v5, v3
	s_nop 0
	v_cvt_pk_bf16_f32 v2, v2, v3
	v_mul_f32_e32 v3, 0x3d372713, v12
	v_mul_f32_e32 v3, v12, v3
	v_fma_f32 v3, v12, v3, v12
	v_mul_f32_e32 v3, 0x3f4c422a, v3
	v_add_f32_e32 v3, v3, v3
	v_mul_f32_e32 v3, 0x3fb8aa3b, v3
	v_exp_f32_e32 v4, v3
	v_mul_f32_e32 v3, 0x3d372713, v13
	v_mul_f32_e32 v3, v13, v3
	v_fma_f32 v3, v13, v3, v13
	v_mul_f32_e32 v3, 0x3f4c422a, v3
	v_add_f32_e32 v3, v3, v3
	v_mul_f32_e32 v3, 0x3fb8aa3b, v3
	v_exp_f32_e32 v5, v3
	s_nop 0
	v_add_f32_e32 v4, 1.0, v4
	v_add_f32_e32 v5, 1.0, v5
	s_nop 0
	v_div_scale_f32 v3, s[0:1], v5, v5, 2.0
	v_rcp_f32_e32 v6, v3
	s_nop 0
	v_fma_f32 v7, -v3, v6, 1.0
	v_fmac_f32_e32 v6, v7, v6
	v_div_scale_f32 v7, vcc, 2.0, v5, 2.0
	v_mul_f32_e32 v8, v7, v6
	v_fma_f32 v9, -v3, v8, v7
	v_fmac_f32_e32 v8, v9, v6
	v_fma_f32 v3, -v3, v8, v7
	v_div_fmas_f32 v3, v3, v6, v8
	v_div_fixup_f32 v5, v3, v5, 2.0
	v_div_scale_f32 v3, s[0:1], v4, v4, 2.0
	v_rcp_f32_e32 v6, v3
	s_nop 0
	v_fma_f32 v7, -v3, v6, 1.0
	v_fmac_f32_e32 v6, v7, v6
	v_div_scale_f32 v7, vcc, 2.0, v4, 2.0
	v_mul_f32_e32 v8, v7, v6
	v_fma_f32 v9, -v3, v8, v7
	v_fmac_f32_e32 v8, v9, v6
	v_fma_f32 v3, -v3, v8, v7
	v_div_fmas_f32 v3, v3, v6, v8
	v_div_fixup_f32 v4, v3, v4, 2.0
	v_sub_f32_e32 v4, 1.0, v4
	v_sub_f32_e32 v5, 1.0, v5
	v_mul_f32_e32 v6, 0.5, v12
	v_mul_f32_e32 v7, 0.5, v13
	v_add_f32_e32 v4, 1.0, v4
	v_add_f32_e32 v5, 1.0, v5
	s_nop 0
	v_mul_f32_e32 v4, v6, v4
	v_mul_f32_e32 v5, v7, v5
	s_nop 0
	v_cvt_pk_bf16_f32 v3, v4, v5
	global_store_dwordx2 v[18:19], v[2:3], off offset:32
	v_mul_f32_e32 v2, 0x3d372713, v14
	v_mul_f32_e32 v3, 0x3d372713, v15
	v_mul_f32_e32 v2, v14, v2
	v_mul_f32_e32 v3, v15, v3
	v_fma_f32 v2, v14, v2, v14
	v_fma_f32 v3, v15, v3, v15
	v_mul_f32_e32 v2, 0x3f4c422a, v2
	v_mul_f32_e32 v3, 0x3f4c422a, v3
	v_add_f32_e32 v2, v2, v2
	v_add_f32_e32 v3, v3, v3
	v_mul_f32_e32 v2, 0x3fb8aa3b, v2
	v_mul_f32_e32 v3, 0x3fb8aa3b, v3
	v_exp_f32_e32 v2, v2
	v_exp_f32_e32 v3, v3
	s_nop 0
	v_add_f32_e32 v2, 1.0, v2
	v_add_f32_e32 v3, 1.0, v3
	s_nop 0
	v_div_scale_f32 v4, s[0:1], v3, v3, 2.0
	v_rcp_f32_e32 v5, v4
	s_nop 0
	v_fma_f32 v6, -v4, v5, 1.0
	v_fmac_f32_e32 v5, v6, v5
	v_div_scale_f32 v6, vcc, 2.0, v3, 2.0
	v_mul_f32_e32 v7, v6, v5
	v_fma_f32 v8, -v4, v7, v6
	v_fmac_f32_e32 v7, v8, v5
	v_fma_f32 v4, -v4, v7, v6
	v_div_fmas_f32 v4, v4, v5, v7
	v_div_fixup_f32 v3, v4, v3, 2.0
	v_div_scale_f32 v4, s[0:1], v2, v2, 2.0
	v_rcp_f32_e32 v5, v4
	s_nop 0
	v_fma_f32 v6, -v4, v5, 1.0
	v_fmac_f32_e32 v5, v6, v5
	v_div_scale_f32 v6, vcc, 2.0, v2, 2.0
	v_mul_f32_e32 v7, v6, v5
	v_fma_f32 v8, -v4, v7, v6
	v_fmac_f32_e32 v7, v8, v5
	v_fma_f32 v4, -v4, v7, v6
	v_div_fmas_f32 v4, v4, v5, v7
	v_div_fixup_f32 v2, v4, v2, 2.0
	v_sub_f32_e32 v2, 1.0, v2
	v_sub_f32_e32 v3, 1.0, v3
	v_mul_f32_e32 v4, 0.5, v14
	v_mul_f32_e32 v5, 0.5, v15
	v_add_f32_e32 v2, 1.0, v2
	v_add_f32_e32 v3, 1.0, v3
	s_nop 0
	v_mul_f32_e32 v2, v4, v2
	v_mul_f32_e32 v3, v5, v3
	s_nop 0
	v_cvt_pk_bf16_f32 v2, v2, v3
	v_mul_f32_e32 v3, 0x3d372713, v16
	v_mul_f32_e32 v3, v16, v3
	v_fma_f32 v3, v16, v3, v16
	v_mul_f32_e32 v3, 0x3f4c422a, v3
	v_add_f32_e32 v3, v3, v3
	v_mul_f32_e32 v3, 0x3fb8aa3b, v3
	v_exp_f32_e32 v4, v3
	v_mul_f32_e32 v3, 0x3d372713, v17
	v_mul_f32_e32 v3, v17, v3
	v_fma_f32 v3, v17, v3, v17
	v_mul_f32_e32 v3, 0x3f4c422a, v3
	v_add_f32_e32 v3, v3, v3
	v_mul_f32_e32 v3, 0x3fb8aa3b, v3
	v_exp_f32_e32 v5, v3
	s_nop 0
	v_add_f32_e32 v4, 1.0, v4
	v_add_f32_e32 v5, 1.0, v5
	s_nop 0
	v_div_scale_f32 v3, s[0:1], v5, v5, 2.0
	v_rcp_f32_e32 v6, v3
	s_nop 0
	v_fma_f32 v7, -v3, v6, 1.0
	v_fmac_f32_e32 v6, v7, v6
	v_div_scale_f32 v7, vcc, 2.0, v5, 2.0
	v_mul_f32_e32 v8, v7, v6
	v_fma_f32 v9, -v3, v8, v7
	v_fmac_f32_e32 v8, v9, v6
	v_fma_f32 v3, -v3, v8, v7
	v_div_fmas_f32 v3, v3, v6, v8
	v_div_fixup_f32 v5, v3, v5, 2.0
	v_div_scale_f32 v3, s[0:1], v4, v4, 2.0
	v_rcp_f32_e32 v6, v3
	s_nop 0
	v_fma_f32 v7, -v3, v6, 1.0
	v_fmac_f32_e32 v6, v7, v6
	v_div_scale_f32 v7, vcc, 2.0, v4, 2.0
	v_mul_f32_e32 v8, v7, v6
	v_fma_f32 v9, -v3, v8, v7
	v_fmac_f32_e32 v8, v9, v6
	v_fma_f32 v3, -v3, v8, v7
	v_div_fmas_f32 v3, v3, v6, v8
	v_div_fixup_f32 v4, v3, v4, 2.0
	v_sub_f32_e32 v4, 1.0, v4
	v_sub_f32_e32 v5, 1.0, v5
	v_mul_f32_e32 v6, 0.5, v16
	v_mul_f32_e32 v7, 0.5, v17
	v_add_f32_e32 v4, 1.0, v4
	v_add_f32_e32 v5, 1.0, v5
	s_nop 0
	v_mul_f32_e32 v4, v6, v4
	v_mul_f32_e32 v5, v7, v5
	s_nop 0
	v_cvt_pk_bf16_f32 v3, v4, v5
	global_store_dwordx2 v[18:19], v[2:3], off offset:48
	s_branch .LBB0_1418

; __device__ __forceinline__ unsigned pk2(float lo, float hi) { const bfx2 b = __builtin_convertvector((f32x2){lo, hi}, bfx2); return __builtin_bit_cast(unsigned, b); }
; __device__ __forceinline__ f32x4 sig4(const f32x4 v) { f32x4 r; r.x = sigmoidf_(v.x); r.y = sigmoidf_(v.y); r.z = sigmoidf_(v.z); r.w = sigmoidf_(v.w); return r; }
;     template <int SEG> __device__ __forceinline__ void run(const pg8::f32x4 (&acc)[2][2][4][2], const pg8::Unit& u, int wr, int wc, int fr, int fq) const {
;         const int row0 = u.pm * 256 + wr * 64 + fr, cb = (u.pn & 3) * 256 + wc * 32 + 8 * fq;
;         float* O = SEG == 0 ? DEC : (SEG == 1 ? AA : GG); const float* bias = SEG == 0 ? w0 : a0;
; #pragma unroll
;         for (int bj = 0; bj < 2; ++bj)
; #pragma unroll
;             for (int n = 0; n < 2; ++n) { const int col = cb + bj * 128 + 4 * n; f32x4 b = (f32x4){0.f, 0.f, 0.f, 0.f}; if (SEG < 2) b = *(const f32x4*)(bias + col);
; #pragma unroll
;                 for (int ai = 0; ai < 2; ++ai)
; #pragma unroll
;                     for (int m = 0; m < 4; ++m) { const int row = row0 + ai * 128 + m * 16; f32x4 v = acc[ai][bj][m][n] + b;
;                         if (SEG == 0) {
;                             const f32x4 sg = sig4(v);
; #pragma unroll
;                             for (int i = 0; i < 4; ++i) v[i] = __builtin_amdgcn_exp2f(-0.8750387749145276f * sg[i]); }
;                         else if (SEG == 1) v = sig4(v);
;                         if (SEG == 2) { u32x2 w; w.x = pk2(v.x, v.y); w.y = pk2(v.z, v.w); *(u32x2*)((bf16*)GG + (size_t)row * 1024 + col) = w; }
;                         else *(f32x4*)(O + (size_t)row * 1024 + col) = v; }
;                 asm volatile("" ::: "memory"); }
.LBB0_1469:
	v_lshl_or_b32 v180, s92, 8, v174
	v_readlane_b32 s76, v253, 48
	v_lshlrev_b64 v[136:137], 2, v[180:181]
	v_readlane_b32 s77, v253, 49
	v_ashrrev_i32_e32 v151, 31, v150
	s_mov_b64 s[38:39], 0x80000
	v_lshl_add_u64 v[134:135], s[76:77], 0, v[136:137]
	global_load_dwordx4 v[130:133], v[134:135], off
	v_lshl_add_u64 v[136:137], s[14:15], 0, v[136:137]
	v_readlane_b32 s78, v253, 50
	v_readlane_b32 s79, v253, 51
	v_readlane_b32 s80, v253, 52
	v_readlane_b32 s81, v253, 53
	v_readlane_b32 s82, v253, 54
	v_readlane_b32 s83, v253, 55
	v_readlane_b32 s84, v253, 56
	v_readlane_b32 s85, v253, 57
	v_readlane_b32 s86, v253, 58
	v_readlane_b32 s87, v253, 59
	v_readlane_b32 s88, v253, 60
	v_readlane_b32 s89, v253, 61
	v_readlane_b32 s90, v253, 62
	v_readlane_b32 s91, v253, 63
	s_waitcnt vmcnt(0)
	v_add_f32_e32 v126, v126, v130
	v_add_f32_e32 v127, v127, v131
	s_nop 0
	v_mul_f32_e32 v126, 0xbfb8aa3b, v126
	v_add_f32_e32 v128, v128, v132
	v_add_f32_e32 v129, v129, v133
	v_exp_f32_e32 v126, v126
	v_mul_f32_e32 v127, 0xbfb8aa3b, v127
	v_exp_f32_e32 v127, v127
	v_mul_f32_e32 v128, 0xbfb8aa3b, v128
	v_exp_f32_e32 v128, v128
	v_mul_f32_e32 v129, 0xbfb8aa3b, v129
	v_exp_f32_e32 v129, v129
	v_add_f32_e32 v126, 1.0, v126
	v_rcp_f32_e32 v126, v126
	v_add_f32_e32 v127, 1.0, v127
	v_add_f32_e32 v122, v122, v130
	v_add_f32_e32 v123, v123, v131
	v_rcp_f32_e32 v127, v127
	v_add_f32_e32 v128, 1.0, v128
	v_mul_f32_e32 v122, 0xbfb8aa3b, v122
	v_rcp_f32_e32 v128, v128
	v_add_f32_e32 v129, 1.0, v129
	v_add_f32_e32 v124, v124, v132
	v_add_f32_e32 v125, v125, v133
	v_exp_f32_e32 v122, v122
	v_mul_f32_e32 v123, 0xbfb8aa3b, v123
	v_rcp_f32_e32 v129, v129
	v_exp_f32_e32 v123, v123
	v_mul_f32_e32 v124, 0xbfb8aa3b, v124
	v_mul_f32_e32 v126, 0xbf60028b, v126
	v_exp_f32_e32 v124, v124
	v_mul_f32_e32 v125, 0xbfb8aa3b, v125
	v_exp_f32_e32 v152, v126
	v_mul_f32_e32 v126, 0xbf60028b, v127
	v_exp_f32_e32 v125, v125
	v_exp_f32_e32 v153, v126
	v_mul_f32_e32 v126, 0xbf60028b, v128
	v_add_f32_e32 v122, 1.0, v122
	v_exp_f32_e32 v154, v126
	v_mul_f32_e32 v126, 0xbf60028b, v129
	v_rcp_f32_e32 v122, v122
	v_add_f32_e32 v123, 1.0, v123
	v_add_f32_e32 v118, v118, v130
	v_add_f32_e32 v119, v119, v131
	v_exp_f32_e32 v155, v126
	v_rcp_f32_e32 v123, v123
	v_add_f32_e32 v124, 1.0, v124
	v_mul_f32_e32 v118, 0xbfb8aa3b, v118
	v_rcp_f32_e32 v124, v124
	v_add_f32_e32 v125, 1.0, v125
	v_add_f32_e32 v120, v120, v132
	v_add_f32_e32 v121, v121, v133
	v_exp_f32_e32 v118, v118
	v_mul_f32_e32 v119, 0xbfb8aa3b, v119
	v_lshlrev_b64 v[126:127], 12, v[150:151]
	v_rcp_f32_e32 v125, v125
	v_exp_f32_e32 v119, v119
	v_mul_f32_e32 v120, 0xbfb8aa3b, v120
	v_lshl_add_u64 v[128:129], v[136:137], 0, v[126:127]
	v_mul_f32_e32 v122, 0xbf60028b, v122
	v_exp_f32_e32 v120, v120
	v_mul_f32_e32 v121, 0xbfb8aa3b, v121
	global_store_dwordx4 v[128:129], v[152:155], off
	v_exp_f32_e32 v121, v121
	v_add_f32_e32 v118, 1.0, v118
	v_exp_f32_e32 v152, v122
	v_mul_f32_e32 v122, 0xbf60028b, v123
	v_exp_f32_e32 v153, v122
	v_mul_f32_e32 v122, 0xbf60028b, v124
	v_exp_f32_e32 v154, v122
	v_mul_f32_e32 v122, 0xbf60028b, v125
	v_rcp_f32_e32 v118, v118
	v_add_f32_e32 v119, 1.0, v119
	v_add_f32_e32 v114, v114, v130
	v_add_f32_e32 v115, v115, v131
	v_exp_f32_e32 v155, v122
	v_or_b32_e32 v122, 16, v150
	v_rcp_f32_e32 v119, v119
	v_add_f32_e32 v120, 1.0, v120
	v_mul_f32_e32 v114, 0xbfb8aa3b, v114
	v_ashrrev_i32_e32 v123, 31, v122
	v_rcp_f32_e32 v120, v120
	v_add_f32_e32 v121, 1.0, v121
	v_add_f32_e32 v116, v116, v132
	v_add_f32_e32 v117, v117, v133
	v_exp_f32_e32 v114, v114
	v_mul_f32_e32 v115, 0xbfb8aa3b, v115
	v_lshlrev_b64 v[122:123], 12, v[122:123]
	v_rcp_f32_e32 v121, v121
	v_exp_f32_e32 v115, v115
	v_mul_f32_e32 v116, 0xbfb8aa3b, v116
	v_lshl_add_u64 v[124:125], v[136:137], 0, v[122:123]
	v_mul_f32_e32 v118, 0xbf60028b, v118
	v_exp_f32_e32 v116, v116
	v_mul_f32_e32 v117, 0xbfb8aa3b, v117
	global_store_dwordx4 v[124:125], v[152:155], off
	v_exp_f32_e32 v117, v117
	v_add_f32_e32 v110, v110, v130
	v_add_f32_e32 v111, v111, v131
	v_exp_f32_e32 v152, v118
	v_mul_f32_e32 v118, 0xbf60028b, v119
	v_exp_f32_e32 v153, v118
	v_mul_f32_e32 v118, 0xbf60028b, v120
	v_add_f32_e32 v114, 1.0, v114
	v_mul_f32_e32 v110, 0xbfb8aa3b, v110
	v_exp_f32_e32 v154, v118
	v_mul_f32_e32 v118, 0xbf60028b, v121
	v_rcp_f32_e32 v114, v114
	v_add_f32_e32 v115, 1.0, v115
	v_add_f32_e32 v112, v112, v132
	v_add_f32_e32 v113, v113, v133
	v_exp_f32_e32 v110, v110
	v_mul_f32_e32 v111, 0xbfb8aa3b, v111
	v_exp_f32_e32 v155, v118
	v_or_b32_e32 v118, 32, v150
	v_rcp_f32_e32 v115, v115
	v_add_f32_e32 v116, 1.0, v116
	v_exp_f32_e32 v111, v111
	v_mul_f32_e32 v112, 0xbfb8aa3b, v112
	v_ashrrev_i32_e32 v119, 31, v118
	v_rcp_f32_e32 v116, v116
	v_add_f32_e32 v117, 1.0, v117
	v_exp_f32_e32 v112, v112
	v_mul_f32_e32 v113, 0xbfb8aa3b, v113
	v_lshlrev_b64 v[118:119], 12, v[118:119]
	v_rcp_f32_e32 v117, v117
	v_exp_f32_e32 v113, v113
	v_lshl_add_u64 v[120:121], v[136:137], 0, v[118:119]
	v_mul_f32_e32 v114, 0xbf60028b, v114
	v_add_f32_e32 v110, 1.0, v110
	global_store_dwordx4 v[120:121], v[152:155], off
	v_rcp_f32_e32 v110, v110
	v_add_f32_e32 v111, 1.0, v111
	v_exp_f32_e32 v152, v114
	v_mul_f32_e32 v114, 0xbf60028b, v115
	v_add_f32_e32 v106, v106, v130
	v_add_f32_e32 v107, v107, v131
	v_exp_f32_e32 v153, v114
	v_mul_f32_e32 v114, 0xbf60028b, v116
	v_rcp_f32_e32 v111, v111
	v_add_f32_e32 v112, 1.0, v112
	v_mul_f32_e32 v106, 0xbfb8aa3b, v106
	v_exp_f32_e32 v154, v114
	v_mul_f32_e32 v114, 0xbf60028b, v117
	v_rcp_f32_e32 v112, v112
	v_add_f32_e32 v113, 1.0, v113
	v_add_f32_e32 v108, v108, v132
	v_add_f32_e32 v109, v109, v133
	v_exp_f32_e32 v106, v106
	v_mul_f32_e32 v107, 0xbfb8aa3b, v107
; __device__ __forceinline__ unsigned pk2(float lo, float hi) { const bfx2 b = __builtin_convertvector((f32x2){lo, hi}, bfx2); return __builtin_bit_cast(unsigned, b); }
; __device__ __forceinline__ f32x4 sig4(const f32x4 v) { f32x4 r; r.x = sigmoidf_(v.x); r.y = sigmoidf_(v.y); r.z = sigmoidf_(v.z); r.w = sigmoidf_(v.w); return r; }
;     template <int SEG> __device__ __forceinline__ void run(const pg8::f32x4 (&acc)[2][2][4][2], const pg8::Unit& u, int wr, int wc, int fr, int fq) const {
;         const int row0 = u.pm * 256 + wr * 64 + fr, cb = (u.pn & 3) * 256 + wc * 32 + 8 * fq;
;         float* O = SEG == 0 ? DEC : (SEG == 1 ? AA : GG); const float* bias = SEG == 0 ? w0 : a0;
; #pragma unroll
;         for (int bj = 0; bj < 2; ++bj)
; #pragma unroll
;             for (int n = 0; n < 2; ++n) { const int col = cb + bj * 128 + 4 * n; f32x4 b = (f32x4){0.f, 0.f, 0.f, 0.f}; if (SEG < 2) b = *(const f32x4*)(bias + col);
; #pragma unroll
;                 for (int ai = 0; ai < 2; ++ai)
; #pragma unroll
;                     for (int m = 0; m < 4; ++m) { const int row = row0 + ai * 128 + m * 16; f32x4 v = acc[ai][bj][m][n] + b;
;                         if (SEG == 0) {
;                             const f32x4 sg = sig4(v);
; #pragma unroll
;                             for (int i = 0; i < 4; ++i) v[i] = __builtin_amdgcn_exp2f(-0.8750387749145276f * sg[i]); }
;                         else if (SEG == 1) v = sig4(v);
;                         if (SEG == 2) { u32x2 w; w.x = pk2(v.x, v.y); w.y = pk2(v.z, v.w); *(u32x2*)((bf16*)GG + (size_t)row * 1024 + col) = w; }
;                         else *(f32x4*)(O + (size_t)row * 1024 + col) = v; }
;                 asm volatile("" ::: "memory"); }
	v_exp_f32_e32 v155, v114
	v_or_b32_e32 v114, 48, v150
	v_rcp_f32_e32 v113, v113
	v_exp_f32_e32 v107, v107
	v_mul_f32_e32 v108, 0xbfb8aa3b, v108
	v_ashrrev_i32_e32 v115, 31, v114
	v_mul_f32_e32 v110, 0xbf60028b, v110
	v_exp_f32_e32 v108, v108
	v_mul_f32_e32 v109, 0xbfb8aa3b, v109
	v_lshlrev_b64 v[114:115], 12, v[114:115]
	v_exp_f32_e32 v150, v110
	v_mul_f32_e32 v110, 0xbf60028b, v111
	v_exp_f32_e32 v109, v109
	v_lshl_add_u64 v[116:117], v[136:137], 0, v[114:115]
	v_exp_f32_e32 v151, v110
	v_mul_f32_e32 v110, 0xbf60028b, v112
	v_add_f32_e32 v106, 1.0, v106
	global_store_dwordx4 v[116:117], v[152:155], off
	v_rcp_f32_e32 v106, v106
	v_add_f32_e32 v107, 1.0, v107
	v_exp_f32_e32 v152, v110
	v_mul_f32_e32 v110, 0xbf60028b, v113
	v_add_f32_e32 v102, v102, v130
	v_add_f32_e32 v103, v103, v131
	v_exp_f32_e32 v153, v110
	v_rcp_f32_e32 v107, v107
	v_add_f32_e32 v108, 1.0, v108
	v_mul_f32_e32 v102, 0xbfb8aa3b, v102
	v_rcp_f32_e32 v108, v108
	v_add_f32_e32 v109, 1.0, v109
	v_add_f32_e32 v104, v104, v132
	v_add_f32_e32 v105, v105, v133
	v_exp_f32_e32 v102, v102
	v_mul_f32_e32 v103, 0xbfb8aa3b, v103
	v_lshl_add_u64 v[110:111], v[126:127], 0, s[38:39]
	v_rcp_f32_e32 v109, v109
	v_exp_f32_e32 v103, v103
	v_mul_f32_e32 v104, 0xbfb8aa3b, v104
	v_lshl_add_u64 v[112:113], v[136:137], 0, v[110:111]
	v_mul_f32_e32 v106, 0xbf60028b, v106
	v_exp_f32_e32 v104, v104
	v_mul_f32_e32 v105, 0xbfb8aa3b, v105
	global_store_dwordx4 v[112:113], v[150:153], off
	v_exp_f32_e32 v105, v105
	v_add_f32_e32 v100, v100, v132
	v_add_f32_e32 v101, v101, v133
	v_exp_f32_e32 v150, v106
	v_mul_f32_e32 v106, 0xbf60028b, v107
	v_add_f32_e32 v98, v98, v130
	v_add_f32_e32 v99, v99, v131
	v_exp_f32_e32 v151, v106
	v_mul_f32_e32 v106, 0xbf60028b, v108
	v_add_f32_e32 v102, 1.0, v102
	v_mul_f32_e32 v98, 0xbfb8aa3b, v98
	v_mul_f32_e32 v99, 0xbfb8aa3b, v99
	v_mul_f32_e32 v100, 0xbfb8aa3b, v100
	v_mul_f32_e32 v101, 0xbfb8aa3b, v101
	v_exp_f32_e32 v152, v106
	v_mul_f32_e32 v106, 0xbf60028b, v109
	v_rcp_f32_e32 v102, v102
	v_add_f32_e32 v103, 1.0, v103
	v_exp_f32_e32 v98, v98
	v_exp_f32_e32 v99, v99
	v_exp_f32_e32 v100, v100
	v_exp_f32_e32 v101, v101
	v_exp_f32_e32 v153, v106
	v_rcp_f32_e32 v103, v103
	v_add_f32_e32 v104, 1.0, v104
	s_mov_b64 s[38:39], 0x90000
	v_rcp_f32_e32 v104, v104
	v_add_f32_e32 v105, 1.0, v105
	v_lshl_add_u64 v[106:107], v[126:127], 0, s[38:39]
	v_rcp_f32_e32 v105, v105
	v_lshl_add_u64 v[108:109], v[136:137], 0, v[106:107]
	v_mul_f32_e32 v102, 0xbf60028b, v102
	v_add_f32_e32 v98, 1.0, v98
	v_add_f32_e32 v99, 1.0, v99
	v_add_f32_e32 v100, 1.0, v100
	v_add_f32_e32 v101, 1.0, v101
	global_store_dwordx4 v[108:109], v[150:153], off
	v_rcp_f32_e32 v98, v98
	v_rcp_f32_e32 v99, v99
	v_exp_f32_e32 v150, v102
	v_mul_f32_e32 v102, 0xbf60028b, v103
	v_rcp_f32_e32 v100, v100
	v_rcp_f32_e32 v101, v101
	v_exp_f32_e32 v151, v102
	v_mul_f32_e32 v102, 0xbf60028b, v104
	v_exp_f32_e32 v152, v102
	v_mul_f32_e32 v102, 0xbf60028b, v105
	v_exp_f32_e32 v153, v102
	s_mov_b64 s[38:39], 0xa0000
	v_mul_f32_e32 v98, 0xbf60028b, v98
	v_mul_f32_e32 v99, 0xbf60028b, v99
	v_mul_f32_e32 v100, 0xbf60028b, v100
	v_mul_f32_e32 v101, 0xbf60028b, v101
	v_lshl_add_u64 v[102:103], v[126:127], 0, s[38:39]
	v_exp_f32_e32 v98, v98
	v_exp_f32_e32 v99, v99
	v_exp_f32_e32 v100, v100
	v_exp_f32_e32 v101, v101
	v_lshl_add_u64 v[104:105], v[136:137], 0, v[102:103]
	global_store_dwordx4 v[104:105], v[150:153], off
	v_lshl_add_u64 v[104:105], v[126:127], 0, s[20:21]
	v_lshl_add_u64 v[108:109], v[136:137], 0, v[104:105]
	global_store_dwordx4 v[108:109], v[98:101], off
	global_load_dwordx4 v[98:101], v[134:135], off offset:16
	v_or_b32_e32 v108, 4, v180
	v_mov_b32_e32 v109, v181
	s_waitcnt vmcnt(0)
	v_add_f32_e32 v94, v94, v98
	v_add_f32_e32 v95, v95, v99
	s_nop 0
	v_mul_f32_e32 v94, 0xbfb8aa3b, v94
	v_add_f32_e32 v96, v96, v100
	v_add_f32_e32 v97, v97, v101
	v_exp_f32_e32 v94, v94
	v_mul_f32_e32 v95, 0xbfb8aa3b, v95
	v_exp_f32_e32 v95, v95
	v_mul_f32_e32 v96, 0xbfb8aa3b, v96
	v_add_f32_e32 v90, v90, v98
	v_add_f32_e32 v91, v91, v99
	v_exp_f32_e32 v96, v96
	v_mul_f32_e32 v97, 0xbfb8aa3b, v97
	v_mul_f32_e32 v90, 0xbfb8aa3b, v90
	v_add_f32_e32 v86, v86, v98
	v_add_f32_e32 v87, v87, v99
	v_exp_f32_e32 v97, v97
	v_add_f32_e32 v92, v92, v100
	v_add_f32_e32 v93, v93, v101
	v_exp_f32_e32 v90, v90
	v_mul_f32_e32 v91, 0xbfb8aa3b, v91
	v_mul_f32_e32 v86, 0xbfb8aa3b, v86
	v_add_f32_e32 v82, v82, v98
	v_add_f32_e32 v83, v83, v99
	v_add_f32_e32 v94, 1.0, v94
	v_exp_f32_e32 v91, v91
	v_mul_f32_e32 v92, 0xbfb8aa3b, v92
	v_add_f32_e32 v88, v88, v100
	v_add_f32_e32 v89, v89, v101
	v_exp_f32_e32 v86, v86
	v_mul_f32_e32 v87, 0xbfb8aa3b, v87
	v_mul_f32_e32 v82, 0xbfb8aa3b, v82
	v_add_f32_e32 v78, v78, v98
	v_add_f32_e32 v79, v79, v99
	v_rcp_f32_e32 v94, v94
	v_add_f32_e32 v95, 1.0, v95
	v_exp_f32_e32 v92, v92
	v_mul_f32_e32 v93, 0xbfb8aa3b, v93
	v_exp_f32_e32 v87, v87
	v_mul_f32_e32 v88, 0xbfb8aa3b, v88
	v_add_f32_e32 v84, v84, v100
	v_add_f32_e32 v85, v85, v101
	v_exp_f32_e32 v82, v82
	v_mul_f32_e32 v83, 0xbfb8aa3b, v83
	v_mul_f32_e32 v78, 0xbfb8aa3b, v78
	v_add_f32_e32 v74, v74, v98
	v_add_f32_e32 v75, v75, v99
	v_rcp_f32_e32 v95, v95
	v_add_f32_e32 v96, 1.0, v96
	v_exp_f32_e32 v93, v93
	v_exp_f32_e32 v88, v88
	v_mul_f32_e32 v89, 0xbfb8aa3b, v89
	v_exp_f32_e32 v83, v83
	v_mul_f32_e32 v84, 0xbfb8aa3b, v84
	v_add_f32_e32 v80, v80, v100
	v_add_f32_e32 v81, v81, v101
	v_exp_f32_e32 v78, v78
	v_mul_f32_e32 v79, 0xbfb8aa3b, v79
	v_mul_f32_e32 v74, 0xbfb8aa3b, v74
	v_rcp_f32_e32 v96, v96
	v_add_f32_e32 v97, 1.0, v97
	v_add_f32_e32 v90, 1.0, v90
	v_exp_f32_e32 v89, v89
	v_exp_f32_e32 v84, v84
	v_mul_f32_e32 v85, 0xbfb8aa3b, v85
	v_exp_f32_e32 v79, v79
; __device__ __forceinline__ unsigned pk2(float lo, float hi) { const bfx2 b = __builtin_convertvector((f32x2){lo, hi}, bfx2); return __builtin_bit_cast(unsigned, b); }
; __device__ __forceinline__ f32x4 sig4(const f32x4 v) { f32x4 r; r.x = sigmoidf_(v.x); r.y = sigmoidf_(v.y); r.z = sigmoidf_(v.z); r.w = sigmoidf_(v.w); return r; }
;     template <int SEG> __device__ __forceinline__ void run(const pg8::f32x4 (&acc)[2][2][4][2], const pg8::Unit& u, int wr, int wc, int fr, int fq) const {
;         const int row0 = u.pm * 256 + wr * 64 + fr, cb = (u.pn & 3) * 256 + wc * 32 + 8 * fq;
;         float* O = SEG == 0 ? DEC : (SEG == 1 ? AA : GG); const float* bias = SEG == 0 ? w0 : a0;
; #pragma unroll
;         for (int bj = 0; bj < 2; ++bj)
; #pragma unroll
;             for (int n = 0; n < 2; ++n) { const int col = cb + bj * 128 + 4 * n; f32x4 b = (f32x4){0.f, 0.f, 0.f, 0.f}; if (SEG < 2) b = *(const f32x4*)(bias + col);
; #pragma unroll
;                 for (int ai = 0; ai < 2; ++ai)
; #pragma unroll
;                     for (int m = 0; m < 4; ++m) { const int row = row0 + ai * 128 + m * 16; f32x4 v = acc[ai][bj][m][n] + b;
;                         if (SEG == 0) {
;                             const f32x4 sg = sig4(v);
; #pragma unroll
;                             for (int i = 0; i < 4; ++i) v[i] = __builtin_amdgcn_exp2f(-0.8750387749145276f * sg[i]); }
;                         else if (SEG == 1) v = sig4(v);
;                         if (SEG == 2) { u32x2 w; w.x = pk2(v.x, v.y); w.y = pk2(v.z, v.w); *(u32x2*)((bf16*)GG + (size_t)row * 1024 + col) = w; }
;                         else *(f32x4*)(O + (size_t)row * 1024 + col) = v; }
;                 asm volatile("" ::: "memory"); }
	v_mul_f32_e32 v80, 0xbfb8aa3b, v80
	v_add_f32_e32 v76, v76, v100
	v_add_f32_e32 v77, v77, v101
	v_exp_f32_e32 v74, v74
	v_mul_f32_e32 v75, 0xbfb8aa3b, v75
	v_rcp_f32_e32 v97, v97
	v_rcp_f32_e32 v90, v90
	v_add_f32_e32 v91, 1.0, v91
	v_add_f32_e32 v86, 1.0, v86
	v_exp_f32_e32 v85, v85
	v_exp_f32_e32 v80, v80
	v_mul_f32_e32 v81, 0xbfb8aa3b, v81
	v_exp_f32_e32 v75, v75
	v_mul_f32_e32 v76, 0xbfb8aa3b, v76
	v_mul_f32_e32 v94, 0xbf60028b, v94
	v_rcp_f32_e32 v91, v91
	v_add_f32_e32 v92, 1.0, v92
	v_rcp_f32_e32 v86, v86
	v_add_f32_e32 v87, 1.0, v87
	v_add_f32_e32 v82, 1.0, v82
	v_exp_f32_e32 v81, v81
	v_exp_f32_e32 v76, v76
	v_mul_f32_e32 v77, 0xbfb8aa3b, v77
	v_exp_f32_e32 v128, v94
	v_mul_f32_e32 v94, 0xbf60028b, v95
	v_rcp_f32_e32 v92, v92
	v_add_f32_e32 v93, 1.0, v93
	v_rcp_f32_e32 v87, v87
	v_add_f32_e32 v88, 1.0, v88
	v_rcp_f32_e32 v82, v82
	v_add_f32_e32 v83, 1.0, v83
	v_add_f32_e32 v78, 1.0, v78
	v_exp_f32_e32 v77, v77
	v_add_f32_e32 v70, v70, v98
	v_add_f32_e32 v71, v71, v99
	v_exp_f32_e32 v129, v94
	v_mul_f32_e32 v94, 0xbf60028b, v96
	v_rcp_f32_e32 v93, v93
	v_rcp_f32_e32 v88, v88
	v_add_f32_e32 v89, 1.0, v89
	v_rcp_f32_e32 v83, v83
	v_add_f32_e32 v84, 1.0, v84
	v_rcp_f32_e32 v78, v78
	v_add_f32_e32 v79, 1.0, v79
	v_add_f32_e32 v74, 1.0, v74
	v_mul_f32_e32 v70, 0xbfb8aa3b, v70
	v_exp_f32_e32 v130, v94
	v_mul_f32_e32 v94, 0xbf60028b, v97
	v_mul_f32_e32 v90, 0xbf60028b, v90
	v_rcp_f32_e32 v89, v89
	v_rcp_f32_e32 v84, v84
	v_add_f32_e32 v85, 1.0, v85
	v_rcp_f32_e32 v79, v79
	v_add_f32_e32 v80, 1.0, v80
	v_rcp_f32_e32 v74, v74
	v_add_f32_e32 v75, 1.0, v75
	v_add_f32_e32 v72, v72, v100
	v_add_f32_e32 v73, v73, v101
	v_exp_f32_e32 v70, v70
	v_mul_f32_e32 v71, 0xbfb8aa3b, v71
	v_exp_f32_e32 v131, v94
	v_exp_f32_e32 v124, v90
	v_mul_f32_e32 v90, 0xbf60028b, v91
	v_mul_f32_e32 v86, 0xbf60028b, v86
	v_rcp_f32_e32 v85, v85
	v_rcp_f32_e32 v80, v80
	v_add_f32_e32 v81, 1.0, v81
	v_rcp_f32_e32 v75, v75
	v_add_f32_e32 v76, 1.0, v76
	v_exp_f32_e32 v71, v71
	v_mul_f32_e32 v72, 0xbfb8aa3b, v72
	v_exp_f32_e32 v125, v90
	v_mul_f32_e32 v90, 0xbf60028b, v92
	v_exp_f32_e32 v120, v86
	v_mul_f32_e32 v86, 0xbf60028b, v87
	v_mul_f32_e32 v82, 0xbf60028b, v82
	v_rcp_f32_e32 v81, v81
	v_rcp_f32_e32 v76, v76
	v_add_f32_e32 v77, 1.0, v77
	v_exp_f32_e32 v72, v72
	v_mul_f32_e32 v73, 0xbfb8aa3b, v73
	v_lshl_add_u64 v[94:95], s[14:15], 0, v[126:127]
	v_lshlrev_b64 v[96:97], 2, v[108:109]
	v_exp_f32_e32 v126, v90
	v_mul_f32_e32 v90, 0xbf60028b, v93
	v_exp_f32_e32 v121, v86
	v_mul_f32_e32 v86, 0xbf60028b, v88
	v_exp_f32_e32 v116, v82
	v_mul_f32_e32 v82, 0xbf60028b, v83
	v_mul_f32_e32 v78, 0xbf60028b, v78
	v_rcp_f32_e32 v77, v77
	v_exp_f32_e32 v73, v73
	v_add_f32_e32 v68, v68, v100
	v_add_f32_e32 v69, v69, v101
	v_add_f32_e32 v66, v66, v98
	v_add_f32_e32 v67, v67, v99
	v_lshl_add_u64 v[108:109], v[94:95], 0, v[96:97]
	v_exp_f32_e32 v127, v90
	v_lshl_add_u64 v[90:91], s[14:15], 0, v[122:123]
	v_exp_f32_e32 v122, v86
	v_mul_f32_e32 v86, 0xbf60028b, v89
	v_exp_f32_e32 v117, v82
	v_mul_f32_e32 v82, 0xbf60028b, v84
	v_exp_f32_e32 v112, v78
	v_mul_f32_e32 v78, 0xbf60028b, v79
	v_mul_f32_e32 v74, 0xbf60028b, v74
	v_add_f32_e32 v70, 1.0, v70
	v_mul_f32_e32 v66, 0xbfb8aa3b, v66
	v_mul_f32_e32 v67, 0xbfb8aa3b, v67
	v_mul_f32_e32 v68, 0xbfb8aa3b, v68
	v_mul_f32_e32 v69, 0xbfb8aa3b, v69
	global_store_dwordx4 v[108:109], v[128:131], off
	v_exp_f32_e32 v123, v86
	v_lshl_add_u64 v[86:87], s[14:15], 0, v[118:119]
	v_exp_f32_e32 v118, v82
	v_mul_f32_e32 v82, 0xbf60028b, v85
	v_exp_f32_e32 v113, v78
	v_mul_f32_e32 v78, 0xbf60028b, v80
	v_exp_f32_e32 v108, v74
	v_mul_f32_e32 v74, 0xbf60028b, v75
	v_rcp_f32_e32 v70, v70
	v_add_f32_e32 v71, 1.0, v71
	v_exp_f32_e32 v66, v66
	v_exp_f32_e32 v67, v67
	v_exp_f32_e32 v68, v68
	v_exp_f32_e32 v69, v69
	v_exp_f32_e32 v119, v82
	v_lshl_add_u64 v[82:83], s[14:15], 0, v[114:115]
	v_exp_f32_e32 v114, v78
	v_mul_f32_e32 v78, 0xbf60028b, v81
	v_exp_f32_e32 v109, v74
	v_mul_f32_e32 v74, 0xbf60028b, v76
	v_rcp_f32_e32 v71, v71
	v_add_f32_e32 v72, 1.0, v72
	v_exp_f32_e32 v115, v78
	v_lshl_add_u64 v[78:79], s[14:15], 0, v[110:111]
	v_exp_f32_e32 v110, v74
	v_mul_f32_e32 v74, 0xbf60028b, v77
	v_rcp_f32_e32 v72, v72
	v_add_f32_e32 v73, 1.0, v73
	v_exp_f32_e32 v111, v74
	v_rcp_f32_e32 v73, v73
	v_mul_f32_e32 v70, 0xbf60028b, v70
	v_add_f32_e32 v66, 1.0, v66
	v_add_f32_e32 v67, 1.0, v67
	v_add_f32_e32 v68, 1.0, v68
	v_add_f32_e32 v69, 1.0, v69
	v_lshl_add_u64 v[74:75], s[14:15], 0, v[106:107]
	v_exp_f32_e32 v106, v70
	v_mul_f32_e32 v70, 0xbf60028b, v71
	v_rcp_f32_e32 v66, v66
	v_rcp_f32_e32 v67, v67
	v_rcp_f32_e32 v68, v68
	v_rcp_f32_e32 v69, v69
	v_lshl_add_u64 v[76:77], v[74:75], 0, v[96:97]
	v_exp_f32_e32 v107, v70
	v_mul_f32_e32 v70, 0xbf60028b, v72
	global_store_dwordx4 v[76:77], v[108:111], off
	v_mul_f32_e32 v66, 0xbf60028b, v66
	v_mul_f32_e32 v67, 0xbf60028b, v67
	v_exp_f32_e32 v108, v70
	v_mul_f32_e32 v70, 0xbf60028b, v73
	v_exp_f32_e32 v109, v70
	v_mul_f32_e32 v68, 0xbf60028b, v68
	v_mul_f32_e32 v69, 0xbf60028b, v69
	v_lshl_add_u64 v[72:73], s[14:15], 0, v[102:103]
	v_exp_f32_e32 v66, v66
	v_exp_f32_e32 v67, v67
	v_exp_f32_e32 v68, v68
	v_exp_f32_e32 v69, v69
	v_lshl_add_u64 v[70:71], v[72:73], 0, v[96:97]
	global_store_dwordx4 v[70:71], v[106:109], off
	v_lshl_add_u64 v[70:71], s[14:15], 0, v[104:105]
	v_lshl_add_u64 v[92:93], v[90:91], 0, v[96:97]
	v_lshl_add_u64 v[88:89], v[86:87], 0, v[96:97]
	v_lshl_add_u64 v[84:85], v[82:83], 0, v[96:97]
	v_lshl_add_u64 v[80:81], v[78:79], 0, v[96:97]
	v_lshl_add_u64 v[76:77], v[70:71], 0, v[96:97]
	global_store_dwordx4 v[92:93], v[124:127], off
	global_store_dwordx4 v[88:89], v[120:123], off
	global_store_dwordx4 v[84:85], v[116:119], off
	global_store_dwordx4 v[80:81], v[112:115], off
	global_store_dwordx4 v[76:77], v[66:69], off
	global_load_dwordx4 v[66:69], v[134:135], off offset:512
	v_or_b32_e32 v76, 0x80, v180
	v_mov_b32_e32 v77, v181
	v_or_b32_e32 v180, 0x84, v180
	s_waitcnt vmcnt(0)
; __device__ __forceinline__ unsigned pk2(float lo, float hi) { const bfx2 b = __builtin_convertvector((f32x2){lo, hi}, bfx2); return __builtin_bit_cast(unsigned, b); }
; __device__ __forceinline__ f32x4 sig4(const f32x4 v) { f32x4 r; r.x = sigmoidf_(v.x); r.y = sigmoidf_(v.y); r.z = sigmoidf_(v.z); r.w = sigmoidf_(v.w); return r; }
;     template <int SEG> __device__ __forceinline__ void run(const pg8::f32x4 (&acc)[2][2][4][2], const pg8::Unit& u, int wr, int wc, int fr, int fq) const {
;         const int row0 = u.pm * 256 + wr * 64 + fr, cb = (u.pn & 3) * 256 + wc * 32 + 8 * fq;
;         float* O = SEG == 0 ? DEC : (SEG == 1 ? AA : GG); const float* bias = SEG == 0 ? w0 : a0;
; #pragma unroll
;         for (int bj = 0; bj < 2; ++bj)
; #pragma unroll
;             for (int n = 0; n < 2; ++n) { const int col = cb + bj * 128 + 4 * n; f32x4 b = (f32x4){0.f, 0.f, 0.f, 0.f}; if (SEG < 2) b = *(const f32x4*)(bias + col);
; #pragma unroll
;                 for (int ai = 0; ai < 2; ++ai)
; #pragma unroll
;                     for (int m = 0; m < 4; ++m) { const int row = row0 + ai * 128 + m * 16; f32x4 v = acc[ai][bj][m][n] + b;
;                         if (SEG == 0) {
;                             const f32x4 sg = sig4(v);
; #pragma unroll
;                             for (int i = 0; i < 4; ++i) v[i] = __builtin_amdgcn_exp2f(-0.8750387749145276f * sg[i]); }
;                         else if (SEG == 1) v = sig4(v);
;                         if (SEG == 2) { u32x2 w; w.x = pk2(v.x, v.y); w.y = pk2(v.z, v.w); *(u32x2*)((bf16*)GG + (size_t)row * 1024 + col) = w; }
;                         else *(f32x4*)(O + (size_t)row * 1024 + col) = v; }
;                 asm volatile("" ::: "memory"); }
	v_add_f32_e32 v62, v62, v66
	v_add_f32_e32 v63, v63, v67
	s_nop 0
	v_mul_f32_e32 v62, 0xbfb8aa3b, v62
	v_add_f32_e32 v64, v64, v68
	v_add_f32_e32 v65, v65, v69
	v_exp_f32_e32 v62, v62
	v_mul_f32_e32 v63, 0xbfb8aa3b, v63
	v_exp_f32_e32 v63, v63
	v_mul_f32_e32 v64, 0xbfb8aa3b, v64
	v_exp_f32_e32 v64, v64
	v_mul_f32_e32 v65, 0xbfb8aa3b, v65
	v_add_f32_e32 v60, v60, v68
	v_add_f32_e32 v61, v61, v69
	v_add_f32_e32 v58, v58, v66
	v_add_f32_e32 v59, v59, v67
	v_exp_f32_e32 v65, v65
	v_mul_f32_e32 v58, 0xbfb8aa3b, v58
	v_mul_f32_e32 v59, 0xbfb8aa3b, v59
	v_mul_f32_e32 v60, 0xbfb8aa3b, v60
	v_mul_f32_e32 v61, 0xbfb8aa3b, v61
	v_add_f32_e32 v56, v56, v68
	v_add_f32_e32 v57, v57, v69
	v_add_f32_e32 v54, v54, v66
	v_add_f32_e32 v55, v55, v67
	v_add_f32_e32 v62, 1.0, v62
	v_exp_f32_e32 v58, v58
	v_exp_f32_e32 v59, v59
	v_exp_f32_e32 v60, v60
	v_exp_f32_e32 v61, v61
	v_mul_f32_e32 v54, 0xbfb8aa3b, v54
	v_mul_f32_e32 v55, 0xbfb8aa3b, v55
	v_mul_f32_e32 v56, 0xbfb8aa3b, v56
	v_mul_f32_e32 v57, 0xbfb8aa3b, v57
	v_add_f32_e32 v52, v52, v68
	v_add_f32_e32 v53, v53, v69
	v_add_f32_e32 v50, v50, v66
	v_add_f32_e32 v51, v51, v67
	v_rcp_f32_e32 v62, v62
	v_add_f32_e32 v63, 1.0, v63
	v_exp_f32_e32 v54, v54
	v_exp_f32_e32 v55, v55
	v_exp_f32_e32 v56, v56
	v_exp_f32_e32 v57, v57
	v_mul_f32_e32 v50, 0xbfb8aa3b, v50
	v_mul_f32_e32 v51, 0xbfb8aa3b, v51
	v_mul_f32_e32 v52, 0xbfb8aa3b, v52
	v_mul_f32_e32 v53, 0xbfb8aa3b, v53
	v_add_f32_e32 v48, v48, v68
	v_add_f32_e32 v49, v49, v69
	v_add_f32_e32 v46, v46, v66
	v_add_f32_e32 v47, v47, v67
	v_rcp_f32_e32 v63, v63
	v_add_f32_e32 v64, 1.0, v64
	v_exp_f32_e32 v50, v50
	v_exp_f32_e32 v51, v51
	v_exp_f32_e32 v52, v52
	v_exp_f32_e32 v53, v53
	v_mul_f32_e32 v46, 0xbfb8aa3b, v46
	v_mul_f32_e32 v47, 0xbfb8aa3b, v47
	v_mul_f32_e32 v48, 0xbfb8aa3b, v48
	v_mul_f32_e32 v49, 0xbfb8aa3b, v49
	v_add_f32_e32 v44, v44, v68
	v_add_f32_e32 v45, v45, v69
	v_add_f32_e32 v42, v42, v66
	v_add_f32_e32 v43, v43, v67
	v_rcp_f32_e32 v64, v64
	v_add_f32_e32 v65, 1.0, v65
	v_exp_f32_e32 v46, v46
	v_exp_f32_e32 v47, v47
	v_exp_f32_e32 v48, v48
	v_exp_f32_e32 v49, v49
	v_mul_f32_e32 v42, 0xbfb8aa3b, v42
	v_mul_f32_e32 v43, 0xbfb8aa3b, v43
	v_mul_f32_e32 v44, 0xbfb8aa3b, v44
	v_mul_f32_e32 v45, 0xbfb8aa3b, v45
	v_add_f32_e32 v40, v40, v68
	v_add_f32_e32 v41, v41, v69
	v_add_f32_e32 v38, v38, v66
	v_add_f32_e32 v39, v39, v67
	v_rcp_f32_e32 v65, v65
	v_add_f32_e32 v58, 1.0, v58
	v_add_f32_e32 v59, 1.0, v59
	v_add_f32_e32 v60, 1.0, v60
	v_add_f32_e32 v61, 1.0, v61
	v_exp_f32_e32 v42, v42
	v_exp_f32_e32 v43, v43
	v_exp_f32_e32 v44, v44
	v_exp_f32_e32 v45, v45
	v_mul_f32_e32 v38, 0xbfb8aa3b, v38
	v_mul_f32_e32 v39, 0xbfb8aa3b, v39
	v_mul_f32_e32 v40, 0xbfb8aa3b, v40
	v_mul_f32_e32 v41, 0xbfb8aa3b, v41
	v_add_f32_e32 v36, v36, v68
	v_add_f32_e32 v37, v37, v69
	v_add_f32_e32 v34, v34, v66
	v_add_f32_e32 v35, v35, v67
	v_mul_f32_e32 v62, 0xbf60028b, v62
	v_rcp_f32_e32 v58, v58
	v_rcp_f32_e32 v59, v59
	v_rcp_f32_e32 v60, v60
	v_rcp_f32_e32 v61, v61
	v_add_f32_e32 v54, 1.0, v54
	v_add_f32_e32 v55, 1.0, v55
	v_add_f32_e32 v56, 1.0, v56
	v_add_f32_e32 v57, 1.0, v57
	v_exp_f32_e32 v38, v38
	v_exp_f32_e32 v39, v39
	v_exp_f32_e32 v40, v40
	v_exp_f32_e32 v41, v41
	v_mul_f32_e32 v34, 0xbfb8aa3b, v34
	v_mul_f32_e32 v35, 0xbfb8aa3b, v35
	v_mul_f32_e32 v36, 0xbfb8aa3b, v36
	v_mul_f32_e32 v37, 0xbfb8aa3b, v37
	v_exp_f32_e32 v96, v62
	v_mul_f32_e32 v62, 0xbf60028b, v63
	v_rcp_f32_e32 v54, v54
	v_rcp_f32_e32 v55, v55
	v_rcp_f32_e32 v56, v56
	v_rcp_f32_e32 v57, v57
	v_add_f32_e32 v50, 1.0, v50
	v_add_f32_e32 v51, 1.0, v51
	v_add_f32_e32 v52, 1.0, v52
	v_add_f32_e32 v53, 1.0, v53
	v_exp_f32_e32 v34, v34
	v_exp_f32_e32 v35, v35
	v_exp_f32_e32 v36, v36
	v_exp_f32_e32 v37, v37
	v_exp_f32_e32 v97, v62
	v_mul_f32_e32 v62, 0xbf60028b, v64
	v_rcp_f32_e32 v50, v50
	v_rcp_f32_e32 v51, v51
	v_rcp_f32_e32 v52, v52
	v_rcp_f32_e32 v53, v53
	v_add_f32_e32 v46, 1.0, v46
	v_add_f32_e32 v47, 1.0, v47
	v_add_f32_e32 v48, 1.0, v48
	v_add_f32_e32 v49, 1.0, v49
	v_exp_f32_e32 v98, v62
	v_mul_f32_e32 v62, 0xbf60028b, v65
	v_rcp_f32_e32 v46, v46
	v_rcp_f32_e32 v47, v47
	v_rcp_f32_e32 v48, v48
	v_rcp_f32_e32 v49, v49
	v_add_f32_e32 v42, 1.0, v42
	v_add_f32_e32 v43, 1.0, v43
	v_add_f32_e32 v44, 1.0, v44
	v_add_f32_e32 v45, 1.0, v45
	v_exp_f32_e32 v99, v62
	v_mul_f32_e32 v58, 0xbf60028b, v58
	v_mul_f32_e32 v59, 0xbf60028b, v59
	v_mul_f32_e32 v60, 0xbf60028b, v60
	v_mul_f32_e32 v61, 0xbf60028b, v61
	v_rcp_f32_e32 v42, v42
	v_rcp_f32_e32 v43, v43
	v_rcp_f32_e32 v44, v44
	v_rcp_f32_e32 v45, v45
	v_add_f32_e32 v38, 1.0, v38
	v_add_f32_e32 v39, 1.0, v39
	v_add_f32_e32 v40, 1.0, v40
	v_add_f32_e32 v41, 1.0, v41
	v_exp_f32_e32 v58, v58
	v_exp_f32_e32 v59, v59
	v_exp_f32_e32 v60, v60
	v_exp_f32_e32 v61, v61
	v_mul_f32_e32 v54, 0xbf60028b, v54
	v_mul_f32_e32 v55, 0xbf60028b, v55
	v_mul_f32_e32 v56, 0xbf60028b, v56
	v_mul_f32_e32 v57, 0xbf60028b, v57
	v_rcp_f32_e32 v38, v38
	v_rcp_f32_e32 v39, v39
	v_rcp_f32_e32 v40, v40
	v_rcp_f32_e32 v41, v41
	v_add_f32_e32 v34, 1.0, v34
	v_add_f32_e32 v35, 1.0, v35
	v_add_f32_e32 v36, 1.0, v36
	v_add_f32_e32 v37, 1.0, v37
	v_lshlrev_b64 v[62:63], 2, v[76:77]
	v_exp_f32_e32 v54, v54
	v_exp_f32_e32 v55, v55
	v_exp_f32_e32 v56, v56
	v_exp_f32_e32 v57, v57
	v_mul_f32_e32 v50, 0xbf60028b, v50
	v_mul_f32_e32 v51, 0xbf60028b, v51
	v_mul_f32_e32 v52, 0xbf60028b, v52
	v_mul_f32_e32 v53, 0xbf60028b, v53
	v_rcp_f32_e32 v34, v34
	v_rcp_f32_e32 v35, v35
	v_rcp_f32_e32 v36, v36
	v_rcp_f32_e32 v37, v37
	v_lshl_add_u64 v[64:65], v[94:95], 0, v[62:63]
	v_exp_f32_e32 v50, v50
	v_exp_f32_e32 v51, v51
	v_exp_f32_e32 v52, v52
	v_exp_f32_e32 v53, v53
	v_mul_f32_e32 v46, 0xbf60028b, v46
; __device__ __forceinline__ unsigned pk2(float lo, float hi) { const bfx2 b = __builtin_convertvector((f32x2){lo, hi}, bfx2); return __builtin_bit_cast(unsigned, b); }
; __device__ __forceinline__ f32x4 sig4(const f32x4 v) { f32x4 r; r.x = sigmoidf_(v.x); r.y = sigmoidf_(v.y); r.z = sigmoidf_(v.z); r.w = sigmoidf_(v.w); return r; }
;     template <int SEG> __device__ __forceinline__ void run(const pg8::f32x4 (&acc)[2][2][4][2], const pg8::Unit& u, int wr, int wc, int fr, int fq) const {
;         const int row0 = u.pm * 256 + wr * 64 + fr, cb = (u.pn & 3) * 256 + wc * 32 + 8 * fq;
;         float* O = SEG == 0 ? DEC : (SEG == 1 ? AA : GG); const float* bias = SEG == 0 ? w0 : a0;
; #pragma unroll
;         for (int bj = 0; bj < 2; ++bj)
; #pragma unroll
;             for (int n = 0; n < 2; ++n) { const int col = cb + bj * 128 + 4 * n; f32x4 b = (f32x4){0.f, 0.f, 0.f, 0.f}; if (SEG < 2) b = *(const f32x4*)(bias + col);
; #pragma unroll
;                 for (int ai = 0; ai < 2; ++ai)
; #pragma unroll
;                     for (int m = 0; m < 4; ++m) { const int row = row0 + ai * 128 + m * 16; f32x4 v = acc[ai][bj][m][n] + b;
;                         if (SEG == 0) {
;                             const f32x4 sg = sig4(v);
; #pragma unroll
;                             for (int i = 0; i < 4; ++i) v[i] = __builtin_amdgcn_exp2f(-0.8750387749145276f * sg[i]); }
;                         else if (SEG == 1) v = sig4(v);
;                         if (SEG == 2) { u32x2 w; w.x = pk2(v.x, v.y); w.y = pk2(v.z, v.w); *(u32x2*)((bf16*)GG + (size_t)row * 1024 + col) = w; }
;                         else *(f32x4*)(O + (size_t)row * 1024 + col) = v; }
;                 asm volatile("" ::: "memory"); }
	v_mul_f32_e32 v47, 0xbf60028b, v47
	v_mul_f32_e32 v48, 0xbf60028b, v48
	v_mul_f32_e32 v49, 0xbf60028b, v49
	global_store_dwordx4 v[64:65], v[96:99], off
	v_lshl_add_u64 v[64:65], v[90:91], 0, v[62:63]
	v_exp_f32_e32 v46, v46
	v_exp_f32_e32 v47, v47
	v_exp_f32_e32 v48, v48
	v_exp_f32_e32 v49, v49
	v_mul_f32_e32 v42, 0xbf60028b, v42
	v_mul_f32_e32 v43, 0xbf60028b, v43
	v_mul_f32_e32 v44, 0xbf60028b, v44
	v_mul_f32_e32 v45, 0xbf60028b, v45
	global_store_dwordx4 v[64:65], v[58:61], off
	v_exp_f32_e32 v42, v42
	v_exp_f32_e32 v43, v43
	v_lshl_add_u64 v[58:59], v[86:87], 0, v[62:63]
	v_exp_f32_e32 v44, v44
	v_exp_f32_e32 v45, v45
	v_mul_f32_e32 v38, 0xbf60028b, v38
	v_mul_f32_e32 v39, 0xbf60028b, v39
	v_mul_f32_e32 v40, 0xbf60028b, v40
	v_mul_f32_e32 v41, 0xbf60028b, v41
	global_store_dwordx4 v[58:59], v[54:57], off
	v_exp_f32_e32 v38, v38
	v_exp_f32_e32 v39, v39
	v_lshl_add_u64 v[54:55], v[82:83], 0, v[62:63]
	v_exp_f32_e32 v40, v40
	v_exp_f32_e32 v41, v41
	v_mul_f32_e32 v34, 0xbf60028b, v34
	v_mul_f32_e32 v35, 0xbf60028b, v35
	v_mul_f32_e32 v36, 0xbf60028b, v36
	v_mul_f32_e32 v37, 0xbf60028b, v37
	global_store_dwordx4 v[54:55], v[50:53], off
	v_exp_f32_e32 v34, v34
	v_exp_f32_e32 v35, v35
	v_lshl_add_u64 v[50:51], v[78:79], 0, v[62:63]
	v_exp_f32_e32 v36, v36
	v_exp_f32_e32 v37, v37
	global_store_dwordx4 v[50:51], v[46:49], off
	s_nop 1
	v_lshl_add_u64 v[46:47], v[74:75], 0, v[62:63]
	global_store_dwordx4 v[46:47], v[42:45], off
	s_nop 1
	v_lshl_add_u64 v[42:43], v[72:73], 0, v[62:63]
	global_store_dwordx4 v[42:43], v[38:41], off
	s_nop 1
	v_lshl_add_u64 v[38:39], v[70:71], 0, v[62:63]
	global_store_dwordx4 v[38:39], v[34:37], off
	global_load_dwordx4 v[34:37], v[134:135], off offset:528
	s_waitcnt vmcnt(0)
	v_add_f32_e32 v30, v30, v34
	v_add_f32_e32 v31, v31, v35
	s_nop 0
	v_mul_f32_e32 v30, 0xbfb8aa3b, v30
	v_add_f32_e32 v32, v32, v36
	v_add_f32_e32 v33, v33, v37
	v_exp_f32_e32 v30, v30
	v_mul_f32_e32 v31, 0xbfb8aa3b, v31
	v_exp_f32_e32 v31, v31
	v_mul_f32_e32 v32, 0xbfb8aa3b, v32
	v_exp_f32_e32 v32, v32
	v_mul_f32_e32 v33, 0xbfb8aa3b, v33
	v_add_f32_e32 v28, v28, v36
	v_add_f32_e32 v29, v29, v37
	v_add_f32_e32 v26, v26, v34
	v_add_f32_e32 v27, v27, v35
	v_exp_f32_e32 v33, v33
	v_mul_f32_e32 v26, 0xbfb8aa3b, v26
	v_mul_f32_e32 v27, 0xbfb8aa3b, v27
	v_mul_f32_e32 v28, 0xbfb8aa3b, v28
	v_mul_f32_e32 v29, 0xbfb8aa3b, v29
	v_add_f32_e32 v24, v24, v36
	v_add_f32_e32 v25, v25, v37
	v_add_f32_e32 v22, v22, v34
	v_add_f32_e32 v23, v23, v35
	v_add_f32_e32 v30, 1.0, v30
	v_exp_f32_e32 v26, v26
	v_exp_f32_e32 v27, v27
	v_exp_f32_e32 v28, v28
	v_exp_f32_e32 v29, v29
	v_mul_f32_e32 v22, 0xbfb8aa3b, v22
	v_mul_f32_e32 v23, 0xbfb8aa3b, v23
	v_mul_f32_e32 v24, 0xbfb8aa3b, v24
	v_mul_f32_e32 v25, 0xbfb8aa3b, v25
	v_add_f32_e32 v20, v20, v36
	v_add_f32_e32 v21, v21, v37
	v_add_f32_e32 v18, v18, v34
	v_add_f32_e32 v19, v19, v35
	v_rcp_f32_e32 v30, v30
	v_add_f32_e32 v31, 1.0, v31
	v_exp_f32_e32 v22, v22
	v_exp_f32_e32 v23, v23
	v_exp_f32_e32 v24, v24
	v_exp_f32_e32 v25, v25
	v_mul_f32_e32 v18, 0xbfb8aa3b, v18
	v_mul_f32_e32 v19, 0xbfb8aa3b, v19
	v_mul_f32_e32 v20, 0xbfb8aa3b, v20
	v_mul_f32_e32 v21, 0xbfb8aa3b, v21
	v_add_f32_e32 v16, v16, v36
	v_add_f32_e32 v17, v17, v37
	v_add_f32_e32 v14, v14, v34
	v_add_f32_e32 v15, v15, v35
	v_rcp_f32_e32 v31, v31
	v_add_f32_e32 v32, 1.0, v32
	v_exp_f32_e32 v18, v18
	v_exp_f32_e32 v19, v19
	v_exp_f32_e32 v20, v20
	v_exp_f32_e32 v21, v21
	v_mul_f32_e32 v14, 0xbfb8aa3b, v14
	v_mul_f32_e32 v15, 0xbfb8aa3b, v15
	v_mul_f32_e32 v16, 0xbfb8aa3b, v16
	v_mul_f32_e32 v17, 0xbfb8aa3b, v17
	v_add_f32_e32 v12, v12, v36
	v_add_f32_e32 v13, v13, v37
	v_add_f32_e32 v10, v10, v34
	v_add_f32_e32 v11, v11, v35
	v_rcp_f32_e32 v32, v32
	v_add_f32_e32 v33, 1.0, v33
	v_exp_f32_e32 v14, v14
	v_exp_f32_e32 v15, v15
	v_exp_f32_e32 v16, v16
	v_exp_f32_e32 v17, v17
	v_mul_f32_e32 v10, 0xbfb8aa3b, v10
	v_mul_f32_e32 v11, 0xbfb8aa3b, v11
	v_mul_f32_e32 v12, 0xbfb8aa3b, v12
	v_mul_f32_e32 v13, 0xbfb8aa3b, v13
	v_add_f32_e32 v8, v8, v36
	v_add_f32_e32 v9, v9, v37
	v_add_f32_e32 v6, v6, v34
	v_add_f32_e32 v7, v7, v35
	v_rcp_f32_e32 v33, v33
	v_add_f32_e32 v26, 1.0, v26
	v_add_f32_e32 v27, 1.0, v27
	v_add_f32_e32 v28, 1.0, v28
	v_add_f32_e32 v29, 1.0, v29
	v_exp_f32_e32 v10, v10
	v_exp_f32_e32 v11, v11
	v_exp_f32_e32 v12, v12
	v_exp_f32_e32 v13, v13
	v_mul_f32_e32 v6, 0xbfb8aa3b, v6
	v_mul_f32_e32 v7, 0xbfb8aa3b, v7
	v_mul_f32_e32 v8, 0xbfb8aa3b, v8
	v_mul_f32_e32 v9, 0xbfb8aa3b, v9
	v_add_f32_e32 v4, v4, v36
	v_add_f32_e32 v5, v5, v37
; __device__ __forceinline__ unsigned pk2(float lo, float hi) { const bfx2 b = __builtin_convertvector((f32x2){lo, hi}, bfx2); return __builtin_bit_cast(unsigned, b); }
; __device__ __forceinline__ f32x4 sig4(const f32x4 v) { f32x4 r; r.x = sigmoidf_(v.x); r.y = sigmoidf_(v.y); r.z = sigmoidf_(v.z); r.w = sigmoidf_(v.w); return r; }
;     template <int SEG> __device__ __forceinline__ void run(const pg8::f32x4 (&acc)[2][2][4][2], const pg8::Unit& u, int wr, int wc, int fr, int fq) const {
;         const int row0 = u.pm * 256 + wr * 64 + fr, cb = (u.pn & 3) * 256 + wc * 32 + 8 * fq;
;         float* O = SEG == 0 ? DEC : (SEG == 1 ? AA : GG); const float* bias = SEG == 0 ? w0 : a0;
; #pragma unroll
;         for (int bj = 0; bj < 2; ++bj)
; #pragma unroll
;             for (int n = 0; n < 2; ++n) { const int col = cb + bj * 128 + 4 * n; f32x4 b = (f32x4){0.f, 0.f, 0.f, 0.f}; if (SEG < 2) b = *(const f32x4*)(bias + col);
; #pragma unroll
;                 for (int ai = 0; ai < 2; ++ai)
; #pragma unroll
;                     for (int m = 0; m < 4; ++m) { const int row = row0 + ai * 128 + m * 16; f32x4 v = acc[ai][bj][m][n] + b;
;                         if (SEG == 0) {
;                             const f32x4 sg = sig4(v);
; #pragma unroll
;                             for (int i = 0; i < 4; ++i) v[i] = __builtin_amdgcn_exp2f(-0.8750387749145276f * sg[i]); }
;                         else if (SEG == 1) v = sig4(v);
;                         if (SEG == 2) { u32x2 w; w.x = pk2(v.x, v.y); w.y = pk2(v.z, v.w); *(u32x2*)((bf16*)GG + (size_t)row * 1024 + col) = w; }
;                         else *(f32x4*)(O + (size_t)row * 1024 + col) = v; }
;                 asm volatile("" ::: "memory"); }
	v_add_f32_e32 v2, v2, v34
	v_add_f32_e32 v3, v3, v35
	v_mul_f32_e32 v30, 0xbf60028b, v30
	v_rcp_f32_e32 v26, v26
	v_rcp_f32_e32 v27, v27
	v_rcp_f32_e32 v28, v28
	v_rcp_f32_e32 v29, v29
	v_add_f32_e32 v22, 1.0, v22
	v_add_f32_e32 v23, 1.0, v23
	v_add_f32_e32 v24, 1.0, v24
	v_add_f32_e32 v25, 1.0, v25
	v_exp_f32_e32 v6, v6
	v_exp_f32_e32 v7, v7
	v_exp_f32_e32 v8, v8
	v_exp_f32_e32 v9, v9
	v_mul_f32_e32 v2, 0xbfb8aa3b, v2
	v_mul_f32_e32 v3, 0xbfb8aa3b, v3
	v_mul_f32_e32 v4, 0xbfb8aa3b, v4
	v_mul_f32_e32 v5, 0xbfb8aa3b, v5
	v_exp_f32_e32 v38, v30
	v_mul_f32_e32 v30, 0xbf60028b, v31
	v_rcp_f32_e32 v22, v22
	v_rcp_f32_e32 v23, v23
	v_rcp_f32_e32 v24, v24
	v_rcp_f32_e32 v25, v25
	v_add_f32_e32 v18, 1.0, v18
	v_add_f32_e32 v19, 1.0, v19
	v_add_f32_e32 v20, 1.0, v20
	v_add_f32_e32 v21, 1.0, v21
	v_exp_f32_e32 v2, v2
	v_exp_f32_e32 v3, v3
	v_exp_f32_e32 v4, v4
	v_exp_f32_e32 v5, v5
	v_exp_f32_e32 v39, v30
	v_mul_f32_e32 v30, 0xbf60028b, v32
	v_rcp_f32_e32 v18, v18
	v_rcp_f32_e32 v19, v19
	v_rcp_f32_e32 v20, v20
	v_rcp_f32_e32 v21, v21
	v_add_f32_e32 v14, 1.0, v14
	v_add_f32_e32 v15, 1.0, v15
	v_add_f32_e32 v16, 1.0, v16
	v_add_f32_e32 v17, 1.0, v17
	v_exp_f32_e32 v40, v30
	v_mul_f32_e32 v30, 0xbf60028b, v33
	v_rcp_f32_e32 v14, v14
	v_rcp_f32_e32 v15, v15
	v_rcp_f32_e32 v16, v16
	v_rcp_f32_e32 v17, v17
	v_add_f32_e32 v10, 1.0, v10
	v_add_f32_e32 v11, 1.0, v11
	v_add_f32_e32 v12, 1.0, v12
	v_add_f32_e32 v13, 1.0, v13
	v_exp_f32_e32 v41, v30
	v_mul_f32_e32 v26, 0xbf60028b, v26
	v_mul_f32_e32 v27, 0xbf60028b, v27
	v_mul_f32_e32 v28, 0xbf60028b, v28
	v_mul_f32_e32 v29, 0xbf60028b, v29
	v_rcp_f32_e32 v10, v10
	v_rcp_f32_e32 v11, v11
	v_rcp_f32_e32 v12, v12
	v_rcp_f32_e32 v13, v13
	v_add_f32_e32 v6, 1.0, v6
	v_add_f32_e32 v7, 1.0, v7
	v_add_f32_e32 v8, 1.0, v8
	v_add_f32_e32 v9, 1.0, v9
	v_exp_f32_e32 v26, v26
	v_exp_f32_e32 v27, v27
	v_exp_f32_e32 v28, v28
	v_exp_f32_e32 v29, v29
	v_mul_f32_e32 v22, 0xbf60028b, v22
	v_mul_f32_e32 v23, 0xbf60028b, v23
	v_mul_f32_e32 v24, 0xbf60028b, v24
	v_mul_f32_e32 v25, 0xbf60028b, v25
	v_rcp_f32_e32 v6, v6
	v_rcp_f32_e32 v7, v7
	v_rcp_f32_e32 v8, v8
	v_rcp_f32_e32 v9, v9
	v_add_f32_e32 v2, 1.0, v2
	v_add_f32_e32 v3, 1.0, v3
	v_add_f32_e32 v4, 1.0, v4
	v_add_f32_e32 v5, 1.0, v5
	v_lshlrev_b64 v[30:31], 2, v[180:181]
	v_exp_f32_e32 v22, v22
	v_exp_f32_e32 v23, v23
	v_exp_f32_e32 v24, v24
	v_exp_f32_e32 v25, v25
	v_mul_f32_e32 v18, 0xbf60028b, v18
	v_mul_f32_e32 v19, 0xbf60028b, v19
	v_mul_f32_e32 v20, 0xbf60028b, v20
	v_mul_f32_e32 v21, 0xbf60028b, v21
	v_rcp_f32_e32 v2, v2
	v_rcp_f32_e32 v3, v3
	v_rcp_f32_e32 v4, v4
	v_rcp_f32_e32 v5, v5
	v_lshl_add_u64 v[32:33], v[94:95], 0, v[30:31]
	v_exp_f32_e32 v18, v18
	v_exp_f32_e32 v19, v19
	v_exp_f32_e32 v20, v20
	v_exp_f32_e32 v21, v21
	v_mul_f32_e32 v14, 0xbf60028b, v14
	v_mul_f32_e32 v15, 0xbf60028b, v15
	v_mul_f32_e32 v16, 0xbf60028b, v16
	v_mul_f32_e32 v17, 0xbf60028b, v17
	global_store_dwordx4 v[32:33], v[38:41], off
	v_lshl_add_u64 v[32:33], v[90:91], 0, v[30:31]
	v_exp_f32_e32 v14, v14
	v_exp_f32_e32 v15, v15
	v_exp_f32_e32 v16, v16
	v_exp_f32_e32 v17, v17
	v_mul_f32_e32 v10, 0xbf60028b, v10
	v_mul_f32_e32 v11, 0xbf60028b, v11
	v_mul_f32_e32 v12, 0xbf60028b, v12
	v_mul_f32_e32 v13, 0xbf60028b, v13
	global_store_dwordx4 v[32:33], v[26:29], off
	v_exp_f32_e32 v10, v10
	v_exp_f32_e32 v11, v11
	v_lshl_add_u64 v[26:27], v[86:87], 0, v[30:31]
	v_exp_f32_e32 v12, v12
	v_exp_f32_e32 v13, v13
	v_mul_f32_e32 v6, 0xbf60028b, v6
	v_mul_f32_e32 v7, 0xbf60028b, v7
	v_mul_f32_e32 v8, 0xbf60028b, v8
	v_mul_f32_e32 v9, 0xbf60028b, v9
	global_store_dwordx4 v[26:27], v[22:25], off
	v_exp_f32_e32 v6, v6
	v_exp_f32_e32 v7, v7
	v_lshl_add_u64 v[22:23], v[82:83], 0, v[30:31]
	v_exp_f32_e32 v8, v8
	v_exp_f32_e32 v9, v9
	v_mul_f32_e32 v2, 0xbf60028b, v2
	v_mul_f32_e32 v3, 0xbf60028b, v3
	v_mul_f32_e32 v4, 0xbf60028b, v4
	v_mul_f32_e32 v5, 0xbf60028b, v5
	global_store_dwordx4 v[22:23], v[18:21], off
	v_exp_f32_e32 v2, v2
	v_exp_f32_e32 v3, v3
	v_lshl_add_u64 v[18:19], v[78:79], 0, v[30:31]
	v_exp_f32_e32 v4, v4
	v_exp_f32_e32 v5, v5
	global_store_dwordx4 v[18:19], v[14:17], off
	s_nop 1
	v_lshl_add_u64 v[14:15], v[74:75], 0, v[30:31]
	global_store_dwordx4 v[14:15], v[10:13], off
	s_nop 1
	v_lshl_add_u64 v[10:11], v[72:73], 0, v[30:31]
	global_store_dwordx4 v[10:11], v[6:9], off
	s_nop 1
	v_lshl_add_u64 v[6:7], v[70:71], 0, v[30:31]
	global_store_dwordx4 v[6:7], v[2:5], off
	s_and_b64 vcc, exec, s[6:7]
	s_mov_b64 s[6:7], -1
	s_cbranch_vccnz .LBB0_1456
	s_branch .LBB0_1477

; __device__ __forceinline__ unsigned pk2(float lo, float hi) { const bfx2 b = __builtin_convertvector((f32x2){lo, hi}, bfx2); return __builtin_bit_cast(unsigned, b); }
; __device__ __forceinline__ f32x4 sig4(const f32x4 v) { f32x4 r; r.x = sigmoidf_(v.x); r.y = sigmoidf_(v.y); r.z = sigmoidf_(v.z); r.w = sigmoidf_(v.w); return r; }
;     template <int SEG> __device__ __forceinline__ void run(const pg8::f32x4 (&acc)[2][2][4][2], const pg8::Unit& u, int wr, int wc, int fr, int fq) const {
;     ...
;             for (int n = 0; n < 2; ++n) { const int col = cb + bj * 128 + 4 * n; f32x4 b = (f32x4){0.f, 0.f, 0.f, 0.f}; if (SEG < 2) b = *(const f32x4*)(bias + col);
; #pragma unroll
;                 for (int ai = 0; ai < 2; ++ai)
; #pragma unroll
;                     for (int m = 0; m < 4; ++m) { const int row = row0 + ai * 128 + m * 16; f32x4 v = acc[ai][bj][m][n] + b;
;                         if (SEG == 0) {
;                             const f32x4 sg = sig4(v);
; #pragma unroll
;                             for (int i = 0; i < 4; ++i) v[i] = __builtin_amdgcn_exp2f(-0.8750387749145276f * sg[i]); }
;                         else if (SEG == 1) v = sig4(v);
;                         if (SEG == 2) { u32x2 w; w.x = pk2(v.x, v.y); w.y = pk2(v.z, v.w); *(u32x2*)((bf16*)GG + (size_t)row * 1024 + col) = w; }
;                         else *(f32x4*)(O + (size_t)row * 1024 + col) = v; }
;                 asm volatile("" ::: "memory"); }
.LBB0_1471:
	s_lshl_b32 s54, s92, 8
	s_and_b32 s59, s54, 0x300
	s_cmp_gt_u32 s92, 7
	s_cbranch_scc0 .LBB0_1473
	v_add_f32_e32 v130, 0, v128
	v_add_f32_e32 v131, 0, v129
	v_add_f32_e32 v132, 0, v126
	v_add_f32_e32 v133, 0, v127
	v_ashrrev_i32_e32 v151, 31, v150
	v_readlane_b32 s38, v252, 3
	v_or_b32_e32 v134, s59, v174
	v_cvt_pk_bf16_f32 v132, v132, v133
	v_cvt_pk_bf16_f32 v133, v130, v131
	v_lshlrev_b64 v[130:131], 11, v[150:151]
	v_readlane_b32 s39, v252, 4
	v_lshlrev_b32_e32 v180, 1, v134
	v_add_f32_e32 v134, 0, v124
	v_add_f32_e32 v135, 0, v125
	v_lshl_add_u64 v[130:131], s[38:39], 0, v[130:131]
	v_lshl_add_u64 v[130:131], v[130:131], 0, v[180:181]
	global_store_dwordx2 v[130:131], v[132:133], off
	v_or_b32_e32 v132, 16, v150
	v_ashrrev_i32_e32 v133, 31, v132
	v_lshlrev_b64 v[132:133], 11, v[132:133]
	v_add_f32_e32 v136, 0, v122
	v_add_f32_e32 v137, 0, v123
	v_lshl_add_u64 v[132:133], s[38:39], 0, v[132:133]
	v_cvt_pk_bf16_f32 v136, v136, v137
	v_cvt_pk_bf16_f32 v137, v134, v135
	v_lshl_add_u64 v[132:133], v[132:133], 0, v[180:181]
	v_or_b32_e32 v134, 32, v150
	global_store_dwordx2 v[132:133], v[136:137], off
	v_add_f32_e32 v136, 0, v120
	v_add_f32_e32 v137, 0, v121
	v_add_f32_e32 v152, 0, v118
	v_add_f32_e32 v153, 0, v119
	v_ashrrev_i32_e32 v135, 31, v134
	v_cvt_pk_bf16_f32 v152, v152, v153
	v_cvt_pk_bf16_f32 v153, v136, v137
	v_lshlrev_b64 v[134:135], 11, v[134:135]
	v_or_b32_e32 v136, 48, v150
	v_lshl_add_u64 v[134:135], s[38:39], 0, v[134:135]
	v_ashrrev_i32_e32 v137, 31, v136
	v_lshl_add_u64 v[134:135], v[134:135], 0, v[180:181]
	v_lshlrev_b64 v[136:137], 11, v[136:137]
	global_store_dwordx2 v[134:135], v[152:153], off
	v_add_f32_e32 v152, 0, v116
	v_add_f32_e32 v153, 0, v117
	v_add_f32_e32 v154, 0, v114
	v_add_f32_e32 v155, 0, v115
	v_lshl_add_u64 v[136:137], s[38:39], 0, v[136:137]
	v_cvt_pk_bf16_f32 v154, v154, v155
	v_cvt_pk_bf16_f32 v155, v152, v153
	v_lshl_add_u64 v[136:137], v[136:137], 0, v[180:181]
	s_mov_b32 s54, 0x40000
	global_store_dwordx2 v[136:137], v[154:155], off
	v_add_f32_e32 v152, 0, v112
	v_add_f32_e32 v153, 0, v113
	v_add_f32_e32 v154, 0, v110
	v_add_f32_e32 v155, 0, v111
	v_add_co_u32_e32 v156, vcc, s54, v130
	v_cvt_pk_bf16_f32 v154, v154, v155
	v_cvt_pk_bf16_f32 v155, v152, v153
	v_addc_co_u32_e32 v157, vcc, 0, v131, vcc
	s_mov_b32 s54, 0x48000
	global_store_dwordx2 v[156:157], v[154:155], off
	v_add_f32_e32 v154, 0, v108
	v_add_f32_e32 v155, 0, v109
	v_add_f32_e32 v156, 0, v106
	v_add_f32_e32 v157, 0, v107
	v_add_co_u32_e32 v158, vcc, s54, v130
	v_cvt_pk_bf16_f32 v156, v156, v157
	v_cvt_pk_bf16_f32 v157, v154, v155
	v_addc_co_u32_e32 v159, vcc, 0, v131, vcc
	s_mov_b32 s54, 0x50000
	global_store_dwordx2 v[158:159], v[156:157], off
	v_add_f32_e32 v156, 0, v104
	v_add_f32_e32 v157, 0, v105
	v_add_f32_e32 v158, 0, v102
	v_add_f32_e32 v159, 0, v103
	v_add_co_u32_e32 v160, vcc, s54, v130
	v_cvt_pk_bf16_f32 v158, v158, v159
	v_cvt_pk_bf16_f32 v159, v156, v157
	v_addc_co_u32_e32 v161, vcc, 0, v131, vcc
	s_mov_b32 s54, 0x58000
	global_store_dwordx2 v[160:161], v[158:159], off
	v_add_f32_e32 v158, 0, v100
	v_add_f32_e32 v159, 0, v101
	v_add_f32_e32 v160, 0, v98
	v_add_f32_e32 v161, 0, v99
	v_add_co_u32_e32 v162, vcc, s54, v130
	v_cvt_pk_bf16_f32 v160, v160, v161
	v_cvt_pk_bf16_f32 v161, v158, v159
	v_addc_co_u32_e32 v163, vcc, 0, v131, vcc
	global_store_dwordx2 v[162:163], v[160:161], off
	v_add_f32_e32 v160, 0, v96
	v_add_f32_e32 v161, 0, v97
	v_add_f32_e32 v162, 0, v94
	v_add_f32_e32 v163, 0, v95
	s_mov_b64 s[60:61], 0x40000
	v_cvt_pk_bf16_f32 v162, v162, v163
	v_cvt_pk_bf16_f32 v163, v160, v161
	global_store_dwordx2 v[130:131], v[162:163], off offset:8
	v_add_f32_e32 v160, 0, v92
	v_add_f32_e32 v161, 0, v93
	v_add_f32_e32 v162, 0, v90
	v_add_f32_e32 v163, 0, v91
	v_lshl_add_u64 v[152:153], v[130:131], 0, s[60:61]
	v_cvt_pk_bf16_f32 v162, v162, v163
	v_cvt_pk_bf16_f32 v163, v160, v161
	global_store_dwordx2 v[132:133], v[162:163], off offset:8
	v_add_f32_e32 v160, 0, v88
	v_add_f32_e32 v161, 0, v89
	v_add_f32_e32 v162, 0, v86
	v_add_f32_e32 v163, 0, v87
	s_mov_b64 s[60:61], 0x48000
	v_cvt_pk_bf16_f32 v162, v162, v163
	v_cvt_pk_bf16_f32 v163, v160, v161
	global_store_dwordx2 v[134:135], v[162:163], off offset:8
	v_add_f32_e32 v160, 0, v84
	v_add_f32_e32 v161, 0, v85
	v_add_f32_e32 v162, 0, v82
	v_add_f32_e32 v163, 0, v83
	v_lshl_add_u64 v[154:155], v[130:131], 0, s[60:61]
	v_cvt_pk_bf16_f32 v162, v162, v163
	v_cvt_pk_bf16_f32 v163, v160, v161
	global_store_dwordx2 v[136:137], v[162:163], off offset:8
	v_add_f32_e32 v160, 0, v80
	v_add_f32_e32 v161, 0, v81
	v_add_f32_e32 v162, 0, v78
	v_add_f32_e32 v163, 0, v79
	s_mov_b64 s[60:61], 0x50000
	v_cvt_pk_bf16_f32 v162, v162, v163
	v_cvt_pk_bf16_f32 v163, v160, v161
	global_store_dwordx2 v[152:153], v[162:163], off offset:8
	v_add_f32_e32 v160, 0, v76
	v_add_f32_e32 v161, 0, v77
	v_add_f32_e32 v162, 0, v74
	v_add_f32_e32 v163, 0, v75
	v_lshl_add_u64 v[156:157], v[130:131], 0, s[60:61]
	v_cvt_pk_bf16_f32 v162, v162, v163
	v_cvt_pk_bf16_f32 v163, v160, v161
	global_store_dwordx2 v[154:155], v[162:163], off offset:8
	v_add_f32_e32 v160, 0, v72
	v_add_f32_e32 v161, 0, v73
	v_add_f32_e32 v162, 0, v70
	v_add_f32_e32 v163, 0, v71
	s_mov_b64 s[60:61], 0x58000
	v_cvt_pk_bf16_f32 v162, v162, v163
	v_cvt_pk_bf16_f32 v163, v160, v161
	global_store_dwordx2 v[156:157], v[162:163], off offset:8
	v_add_f32_e32 v160, 0, v68
	v_add_f32_e32 v161, 0, v69
	v_add_f32_e32 v162, 0, v66
	v_add_f32_e32 v163, 0, v67
	v_lshl_add_u64 v[158:159], v[130:131], 0, s[60:61]
	v_cvt_pk_bf16_f32 v162, v162, v163
	v_cvt_pk_bf16_f32 v163, v160, v161
	global_store_dwordx2 v[158:159], v[162:163], off offset:8
; __device__ __forceinline__ unsigned pk2(float lo, float hi) { const bfx2 b = __builtin_convertvector((f32x2){lo, hi}, bfx2); return __builtin_bit_cast(unsigned, b); }
; __device__ __forceinline__ f32x4 sig4(const f32x4 v) { f32x4 r; r.x = sigmoidf_(v.x); r.y = sigmoidf_(v.y); r.z = sigmoidf_(v.z); r.w = sigmoidf_(v.w); return r; }
;     template <int SEG> __device__ __forceinline__ void run(const pg8::f32x4 (&acc)[2][2][4][2], const pg8::Unit& u, int wr, int wc, int fr, int fq) const {
;     ...
;             for (int n = 0; n < 2; ++n) { const int col = cb + bj * 128 + 4 * n; f32x4 b = (f32x4){0.f, 0.f, 0.f, 0.f}; if (SEG < 2) b = *(const f32x4*)(bias + col);
; #pragma unroll
;                 for (int ai = 0; ai < 2; ++ai)
; #pragma unroll
;                     for (int m = 0; m < 4; ++m) { const int row = row0 + ai * 128 + m * 16; f32x4 v = acc[ai][bj][m][n] + b;
;                         if (SEG == 0) {
;                             const f32x4 sg = sig4(v);
; #pragma unroll
;                             for (int i = 0; i < 4; ++i) v[i] = __builtin_amdgcn_exp2f(-0.8750387749145276f * sg[i]); }
;                         else if (SEG == 1) v = sig4(v);
;                         if (SEG == 2) { u32x2 w; w.x = pk2(v.x, v.y); w.y = pk2(v.z, v.w); *(u32x2*)((bf16*)GG + (size_t)row * 1024 + col) = w; }
;                         else *(f32x4*)(O + (size_t)row * 1024 + col) = v; }
;                 asm volatile("" ::: "memory"); }
	v_add_f32_e32 v160, 0, v64
	v_add_f32_e32 v161, 0, v65
	v_add_f32_e32 v162, 0, v62
	v_add_f32_e32 v163, 0, v63
	s_mov_b64 s[60:61], 0
	v_cvt_pk_bf16_f32 v162, v162, v163
	v_cvt_pk_bf16_f32 v163, v160, v161
	global_store_dwordx2 v[130:131], v[162:163], off offset:256
	v_add_f32_e32 v160, 0, v60
	v_add_f32_e32 v161, 0, v61
	v_add_f32_e32 v162, 0, v58
	v_add_f32_e32 v163, 0, v59
	s_nop 0
	v_cvt_pk_bf16_f32 v162, v162, v163
	v_cvt_pk_bf16_f32 v163, v160, v161
	global_store_dwordx2 v[132:133], v[162:163], off offset:256
	v_add_f32_e32 v160, 0, v56
	v_add_f32_e32 v161, 0, v57
	v_add_f32_e32 v162, 0, v54
	v_add_f32_e32 v163, 0, v55
	s_nop 0
	v_cvt_pk_bf16_f32 v162, v162, v163
	v_cvt_pk_bf16_f32 v163, v160, v161
	global_store_dwordx2 v[134:135], v[162:163], off offset:256
	v_add_f32_e32 v160, 0, v52
	v_add_f32_e32 v161, 0, v53
	v_add_f32_e32 v162, 0, v50
	v_add_f32_e32 v163, 0, v51
	s_nop 0
	v_cvt_pk_bf16_f32 v162, v162, v163
	v_cvt_pk_bf16_f32 v163, v160, v161
	global_store_dwordx2 v[136:137], v[162:163], off offset:256
	v_add_f32_e32 v160, 0, v48
	v_add_f32_e32 v161, 0, v49
	v_add_f32_e32 v162, 0, v46
	v_add_f32_e32 v163, 0, v47
	s_nop 0
	v_cvt_pk_bf16_f32 v162, v162, v163
	v_cvt_pk_bf16_f32 v163, v160, v161
	global_store_dwordx2 v[152:153], v[162:163], off offset:256
	v_add_f32_e32 v160, 0, v44
	v_add_f32_e32 v161, 0, v45
	v_add_f32_e32 v162, 0, v42
	v_add_f32_e32 v163, 0, v43
	s_nop 0
	v_cvt_pk_bf16_f32 v162, v162, v163
	v_cvt_pk_bf16_f32 v163, v160, v161
	global_store_dwordx2 v[154:155], v[162:163], off offset:256
	v_add_f32_e32 v160, 0, v40
	v_add_f32_e32 v161, 0, v41
	v_add_f32_e32 v162, 0, v38
	v_add_f32_e32 v163, 0, v39
	s_nop 0
	v_cvt_pk_bf16_f32 v162, v162, v163
	v_cvt_pk_bf16_f32 v163, v160, v161
	global_store_dwordx2 v[156:157], v[162:163], off offset:256
	v_add_f32_e32 v160, 0, v36
	v_add_f32_e32 v161, 0, v37
	v_add_f32_e32 v162, 0, v34
	v_add_f32_e32 v163, 0, v35
	s_nop 0
	v_cvt_pk_bf16_f32 v162, v162, v163
	v_cvt_pk_bf16_f32 v163, v160, v161
	global_store_dwordx2 v[158:159], v[162:163], off offset:256
	v_add_f32_e32 v160, 0, v32
	v_add_f32_e32 v161, 0, v33
	v_add_f32_e32 v162, 0, v30
	v_add_f32_e32 v163, 0, v31
	s_nop 0
	v_cvt_pk_bf16_f32 v162, v162, v163
	v_cvt_pk_bf16_f32 v163, v160, v161
	global_store_dwordx2 v[130:131], v[162:163], off offset:264
	v_add_f32_e32 v130, 0, v28
	v_add_f32_e32 v131, 0, v29
	v_add_f32_e32 v160, 0, v26
	v_add_f32_e32 v161, 0, v27
	s_nop 0
	v_cvt_pk_bf16_f32 v160, v160, v161
	v_cvt_pk_bf16_f32 v161, v130, v131
	global_store_dwordx2 v[132:133], v[160:161], off offset:264
	v_add_f32_e32 v130, 0, v24
	v_add_f32_e32 v131, 0, v25
	v_add_f32_e32 v132, 0, v22
	v_add_f32_e32 v133, 0, v23
	s_nop 0
	v_cvt_pk_bf16_f32 v132, v132, v133
	v_cvt_pk_bf16_f32 v133, v130, v131
	global_store_dwordx2 v[134:135], v[132:133], off offset:264
	v_add_f32_e32 v130, 0, v20
	v_add_f32_e32 v131, 0, v21
	v_add_f32_e32 v132, 0, v18
	v_add_f32_e32 v133, 0, v19
	s_nop 0
	v_cvt_pk_bf16_f32 v132, v132, v133
	v_cvt_pk_bf16_f32 v133, v130, v131
	global_store_dwordx2 v[136:137], v[132:133], off offset:264
	v_add_f32_e32 v130, 0, v16
	v_add_f32_e32 v131, 0, v17
	v_add_f32_e32 v132, 0, v14
	v_add_f32_e32 v133, 0, v15
	s_nop 0
	v_cvt_pk_bf16_f32 v132, v132, v133
	v_cvt_pk_bf16_f32 v133, v130, v131
	global_store_dwordx2 v[152:153], v[132:133], off offset:264
	v_add_f32_e32 v130, 0, v12
	v_add_f32_e32 v131, 0, v13
	v_add_f32_e32 v132, 0, v10
	v_add_f32_e32 v133, 0, v11
	s_nop 0
	v_cvt_pk_bf16_f32 v132, v132, v133
	v_cvt_pk_bf16_f32 v133, v130, v131
	global_store_dwordx2 v[154:155], v[132:133], off offset:264
	v_add_f32_e32 v130, 0, v8
	v_add_f32_e32 v131, 0, v9
	v_add_f32_e32 v132, 0, v6
	v_add_f32_e32 v133, 0, v7
	s_nop 0
	v_cvt_pk_bf16_f32 v132, v132, v133
	v_cvt_pk_bf16_f32 v133, v130, v131
	global_store_dwordx2 v[156:157], v[132:133], off offset:264
	v_add_f32_e32 v130, 0, v4
	v_add_f32_e32 v131, 0, v5
	v_add_f32_e32 v132, 0, v2
	v_add_f32_e32 v133, 0, v3
	s_nop 0
	v_cvt_pk_bf16_f32 v132, v132, v133
	v_cvt_pk_bf16_f32 v133, v130, v131
	global_store_dwordx2 v[158:159], v[132:133], off offset:264
.LBB0_1473:
	s_andn2_b64 vcc, exec, s[60:61]
	s_cbranch_vccnz .LBB0_1475
	v_or_b32_e32 v130, s59, v174
	v_readlane_b32 s76, v253, 48
	v_lshlrev_b32_e32 v180, 2, v130
	v_readlane_b32 s80, v253, 52
	v_readlane_b32 s81, v253, 53
	v_readlane_b32 s38, v254, 55
	v_readlane_b32 s39, v254, 56
	v_ashrrev_i32_e32 v151, 31, v150
	v_lshlrev_b64 v[158:159], 12, v[150:151]
	v_lshl_add_u64 v[154:155], s[38:39], 0, v[180:181]
	global_load_dwordx4 v[130:133], v180, s[80:81]
	v_lshl_add_u64 v[152:153], v[154:155], 0, v[158:159]
	s_mov_b64 s[48:49], 0x80000
	v_or_b32_e32 v170, 16, v180
	v_mov_b32_e32 v171, v181
	v_readlane_b32 s77, v253, 49
	v_readlane_b32 s78, v253, 50
	v_readlane_b32 s79, v253, 51
	v_readlane_b32 s82, v253, 54
	v_readlane_b32 s83, v253, 55
	v_readlane_b32 s84, v253, 56
	v_readlane_b32 s85, v253, 57
	v_readlane_b32 s86, v253, 58
	v_readlane_b32 s87, v253, 59
	v_readlane_b32 s88, v253, 60
	v_readlane_b32 s89, v253, 61
	v_readlane_b32 s90, v253, 62
	v_readlane_b32 s91, v253, 63
	s_waitcnt vmcnt(0)
; __device__ __forceinline__ unsigned pk2(float lo, float hi) { const bfx2 b = __builtin_convertvector((f32x2){lo, hi}, bfx2); return __builtin_bit_cast(unsigned, b); }
; __device__ __forceinline__ f32x4 sig4(const f32x4 v) { f32x4 r; r.x = sigmoidf_(v.x); r.y = sigmoidf_(v.y); r.z = sigmoidf_(v.z); r.w = sigmoidf_(v.w); return r; }
;     template <int SEG> __device__ __forceinline__ void run(const pg8::f32x4 (&acc)[2][2][4][2], const pg8::Unit& u, int wr, int wc, int fr, int fq) const {
;     ...
;             for (int n = 0; n < 2; ++n) { const int col = cb + bj * 128 + 4 * n; f32x4 b = (f32x4){0.f, 0.f, 0.f, 0.f}; if (SEG < 2) b = *(const f32x4*)(bias + col);
; #pragma unroll
;                 for (int ai = 0; ai < 2; ++ai)
; #pragma unroll
;                     for (int m = 0; m < 4; ++m) { const int row = row0 + ai * 128 + m * 16; f32x4 v = acc[ai][bj][m][n] + b;
;                         if (SEG == 0) {
;                             const f32x4 sg = sig4(v);
; #pragma unroll
;                             for (int i = 0; i < 4; ++i) v[i] = __builtin_amdgcn_exp2f(-0.8750387749145276f * sg[i]); }
;                         else if (SEG == 1) v = sig4(v);
;                         if (SEG == 2) { u32x2 w; w.x = pk2(v.x, v.y); w.y = pk2(v.z, v.w); *(u32x2*)((bf16*)GG + (size_t)row * 1024 + col) = w; }
;                         else *(f32x4*)(O + (size_t)row * 1024 + col) = v; }
;                 asm volatile("" ::: "memory"); }
	v_add_f32_e32 v136, v128, v132
	v_add_f32_e32 v137, v129, v133
	v_add_f32_e32 v134, v126, v130
	v_add_f32_e32 v135, v127, v131
	v_mul_f32_e32 v136, 0xbfb8aa3b, v136
	v_mul_f32_e32 v134, 0xbfb8aa3b, v134
	v_mul_f32_e32 v135, 0xbfb8aa3b, v135
	v_mul_f32_e32 v137, 0xbfb8aa3b, v137
	v_exp_f32_e32 v134, v134
	v_exp_f32_e32 v135, v135
	v_exp_f32_e32 v136, v136
	v_exp_f32_e32 v137, v137
	v_add_f32_e32 v134, 1.0, v134
	v_add_f32_e32 v135, 1.0, v135
	v_add_f32_e32 v136, 1.0, v136
	v_add_f32_e32 v137, 1.0, v137
	v_rcp_f32_e32 v134, v134
	v_rcp_f32_e32 v135, v135
	v_rcp_f32_e32 v136, v136
	v_rcp_f32_e32 v137, v137
	global_store_dwordx4 v[152:153], v[134:137], off
	s_nop 1
	v_add_f32_e32 v136, v124, v132
	v_add_f32_e32 v137, v125, v133
	v_add_f32_e32 v134, v122, v130
	v_add_f32_e32 v135, v123, v131
	v_mul_f32_e32 v136, 0xbfb8aa3b, v136
	v_mul_f32_e32 v134, 0xbfb8aa3b, v134
	v_mul_f32_e32 v135, 0xbfb8aa3b, v135
	v_mul_f32_e32 v137, 0xbfb8aa3b, v137
	v_exp_f32_e32 v134, v134
	v_exp_f32_e32 v135, v135
	v_exp_f32_e32 v136, v136
	v_exp_f32_e32 v137, v137
	v_add_f32_e32 v134, 1.0, v134
	v_add_f32_e32 v135, 1.0, v135
	v_add_f32_e32 v136, 1.0, v136
	v_add_f32_e32 v137, 1.0, v137
	v_or_b32_e32 v152, 16, v150
	v_rcp_f32_e32 v134, v134
	v_rcp_f32_e32 v135, v135
	v_rcp_f32_e32 v136, v136
	v_rcp_f32_e32 v137, v137
	v_ashrrev_i32_e32 v153, 31, v152
	v_lshlrev_b64 v[152:153], 12, v[152:153]
	v_lshl_add_u64 v[156:157], v[154:155], 0, v[152:153]
	global_store_dwordx4 v[156:157], v[134:137], off
	v_or_b32_e32 v156, 32, v150
	v_ashrrev_i32_e32 v157, 31, v156
	v_add_f32_e32 v136, v120, v132
	v_add_f32_e32 v137, v121, v133
	v_add_f32_e32 v134, v118, v130
	v_add_f32_e32 v135, v119, v131
	v_mul_f32_e32 v136, 0xbfb8aa3b, v136
	v_mul_f32_e32 v134, 0xbfb8aa3b, v134
	v_mul_f32_e32 v135, 0xbfb8aa3b, v135
	v_mul_f32_e32 v137, 0xbfb8aa3b, v137
	v_exp_f32_e32 v134, v134
	v_exp_f32_e32 v135, v135
	v_exp_f32_e32 v136, v136
	v_exp_f32_e32 v137, v137
	v_add_f32_e32 v134, 1.0, v134
	v_add_f32_e32 v135, 1.0, v135
	v_add_f32_e32 v136, 1.0, v136
	v_add_f32_e32 v137, 1.0, v137
	v_rcp_f32_e32 v134, v134
	v_rcp_f32_e32 v135, v135
	v_rcp_f32_e32 v136, v136
	v_rcp_f32_e32 v137, v137
	v_lshlrev_b64 v[156:157], 12, v[156:157]
	v_lshl_add_u64 v[160:161], v[154:155], 0, v[156:157]
	global_store_dwordx4 v[160:161], v[134:137], off
	v_or_b32_e32 v160, 48, v150
	s_nop 0
	v_add_f32_e32 v136, v116, v132
	v_add_f32_e32 v137, v117, v133
	v_add_f32_e32 v134, v114, v130
	v_add_f32_e32 v135, v115, v131
	v_mul_f32_e32 v136, 0xbfb8aa3b, v136
	v_mul_f32_e32 v134, 0xbfb8aa3b, v134
	v_mul_f32_e32 v135, 0xbfb8aa3b, v135
	v_mul_f32_e32 v137, 0xbfb8aa3b, v137
	v_exp_f32_e32 v134, v134
	v_exp_f32_e32 v135, v135
	v_exp_f32_e32 v136, v136
	v_exp_f32_e32 v137, v137
	v_add_f32_e32 v134, 1.0, v134
	v_add_f32_e32 v135, 1.0, v135
	v_add_f32_e32 v136, 1.0, v136
	v_add_f32_e32 v137, 1.0, v137
	v_rcp_f32_e32 v134, v134
	v_rcp_f32_e32 v135, v135
	v_rcp_f32_e32 v136, v136
	v_rcp_f32_e32 v137, v137
	v_ashrrev_i32_e32 v161, 31, v160
	v_lshlrev_b64 v[164:165], 12, v[160:161]
	v_lshl_add_u64 v[160:161], v[154:155], 0, v[164:165]
	global_store_dwordx4 v[160:161], v[134:137], off
	s_nop 1
	v_add_f32_e32 v134, v112, v132
	v_add_f32_e32 v135, v113, v133
	v_add_f32_e32 v136, v110, v130
	v_add_f32_e32 v137, v111, v131
	v_mul_f32_e32 v134, 0xbfb8aa3b, v134
	v_mul_f32_e32 v136, 0xbfb8aa3b, v136
	v_exp_f32_e32 v136, v136
	v_exp_f32_e32 v134, v134
	v_add_f32_e32 v136, 1.0, v136
	v_add_f32_e32 v134, 1.0, v134
	v_rcp_f32_e32 v160, v136
	v_mul_f32_e32 v136, 0xbfb8aa3b, v137
	v_rcp_f32_e32 v162, v134
	v_mul_f32_e32 v134, 0xbfb8aa3b, v135
	v_exp_f32_e32 v136, v136
	v_exp_f32_e32 v134, v134
	v_add_f32_e32 v136, 1.0, v136
	v_add_f32_e32 v134, 1.0, v134
	v_rcp_f32_e32 v161, v136
	v_rcp_f32_e32 v163, v134
	v_lshl_add_u64 v[134:135], v[158:159], 0, s[48:49]
	v_lshl_add_u64 v[136:137], v[154:155], 0, v[134:135]
	s_mov_b64 s[48:49], 0x90000
	global_store_dwordx4 v[136:137], v[160:163], off
	v_add_f32_e32 v136, v108, v132
	v_add_f32_e32 v137, v109, v133
	s_nop 0
	v_add_f32_e32 v160, v106, v130
	v_add_f32_e32 v161, v107, v131
	v_mul_f32_e32 v136, 0xbfb8aa3b, v136
	v_mul_f32_e32 v151, 0xbfb8aa3b, v160
	v_exp_f32_e32 v151, v151
	v_exp_f32_e32 v136, v136
	v_add_f32_e32 v151, 1.0, v151
	v_add_f32_e32 v136, 1.0, v136
	v_rcp_f32_e32 v160, v151
	v_mul_f32_e32 v151, 0xbfb8aa3b, v161
	v_rcp_f32_e32 v162, v136
	v_mul_f32_e32 v136, 0xbfb8aa3b, v137
	v_exp_f32_e32 v151, v151
	v_exp_f32_e32 v136, v136
	v_add_f32_e32 v151, 1.0, v151
	v_add_f32_e32 v136, 1.0, v136
	v_rcp_f32_e32 v161, v151
	v_rcp_f32_e32 v163, v136
	v_lshl_add_u64 v[136:137], v[158:159], 0, s[48:49]
	v_lshl_add_u64 v[166:167], v[154:155], 0, v[136:137]
	s_mov_b64 s[48:49], 0xa0000
	global_store_dwordx4 v[166:167], v[160:163], off
	v_lshl_add_u64 v[168:169], v[158:159], 0, s[48:49]
	v_lshl_add_u64 v[166:167], v[154:155], 0, v[168:169]
	v_add_f32_e32 v160, v102, v130
	v_add_f32_e32 v161, v103, v131
	v_add_f32_e32 v162, v104, v132
	v_add_f32_e32 v163, v105, v133
	v_mul_f32_e32 v151, 0xbfb8aa3b, v160
	v_exp_f32_e32 v151, v151
	v_add_f32_e32 v132, v100, v132
	v_add_f32_e32 v133, v101, v133
	v_add_f32_e32 v130, v98, v130
	v_add_f32_e32 v131, v99, v131
	v_mul_f32_e32 v132, 0xbfb8aa3b, v132
	v_add_f32_e32 v151, 1.0, v151
	v_rcp_f32_e32 v160, v151
	v_mul_f32_e32 v151, 0xbfb8aa3b, v161
	v_exp_f32_e32 v151, v151
	v_mul_f32_e32 v130, 0xbfb8aa3b, v130
	v_mul_f32_e32 v131, 0xbfb8aa3b, v131
	v_mul_f32_e32 v133, 0xbfb8aa3b, v133
	v_add_f32_e32 v151, 1.0, v151
	v_rcp_f32_e32 v161, v151
	v_mul_f32_e32 v151, 0xbfb8aa3b, v162
	v_exp_f32_e32 v151, v151
	v_exp_f32_e32 v130, v130
	v_exp_f32_e32 v131, v131
	v_exp_f32_e32 v132, v132
	v_add_f32_e32 v151, 1.0, v151
	v_rcp_f32_e32 v162, v151
	v_mul_f32_e32 v151, 0xbfb8aa3b, v163
	v_exp_f32_e32 v151, v151
	v_exp_f32_e32 v133, v133
	v_add_f32_e32 v130, 1.0, v130
	v_add_f32_e32 v131, 1.0, v131
	v_add_f32_e32 v151, 1.0, v151
	v_rcp_f32_e32 v163, v151
	v_add_f32_e32 v132, 1.0, v132
	v_add_f32_e32 v133, 1.0, v133
	v_rcp_f32_e32 v130, v130
	v_rcp_f32_e32 v131, v131
	v_rcp_f32_e32 v132, v132
	v_rcp_f32_e32 v133, v133
	global_store_dwordx4 v[166:167], v[160:163], off
	v_lshl_add_u64 v[166:167], v[158:159], 0, s[20:21]
	v_lshl_add_u64 v[154:155], v[154:155], 0, v[166:167]
	global_store_dwordx4 v[154:155], v[130:133], off
	global_load_dwordx4 v[130:133], v180, s[80:81] offset:16
	v_lshl_add_u64 v[162:163], s[38:39], 0, v[158:159]
	v_lshl_add_u64 v[136:137], s[38:39], 0, v[136:137]
	s_waitcnt vmcnt(0)
; __device__ __forceinline__ unsigned pk2(float lo, float hi) { const bfx2 b = __builtin_convertvector((f32x2){lo, hi}, bfx2); return __builtin_bit_cast(unsigned, b); }
; __device__ __forceinline__ f32x4 sig4(const f32x4 v) { f32x4 r; r.x = sigmoidf_(v.x); r.y = sigmoidf_(v.y); r.z = sigmoidf_(v.z); r.w = sigmoidf_(v.w); return r; }
;     template <int SEG> __device__ __forceinline__ void run(const pg8::f32x4 (&acc)[2][2][4][2], const pg8::Unit& u, int wr, int wc, int fr, int fq) const {
;     ...
;             for (int n = 0; n < 2; ++n) { const int col = cb + bj * 128 + 4 * n; f32x4 b = (f32x4){0.f, 0.f, 0.f, 0.f}; if (SEG < 2) b = *(const f32x4*)(bias + col);
; #pragma unroll
;                 for (int ai = 0; ai < 2; ++ai)
; #pragma unroll
;                     for (int m = 0; m < 4; ++m) { const int row = row0 + ai * 128 + m * 16; f32x4 v = acc[ai][bj][m][n] + b;
;                         if (SEG == 0) {
;                             const f32x4 sg = sig4(v);
; #pragma unroll
;                             for (int i = 0; i < 4; ++i) v[i] = __builtin_amdgcn_exp2f(-0.8750387749145276f * sg[i]); }
;                         else if (SEG == 1) v = sig4(v);
;                         if (SEG == 2) { u32x2 w; w.x = pk2(v.x, v.y); w.y = pk2(v.z, v.w); *(u32x2*)((bf16*)GG + (size_t)row * 1024 + col) = w; }
;                         else *(f32x4*)(O + (size_t)row * 1024 + col) = v; }
;                 asm volatile("" ::: "memory"); }
	v_add_f32_e32 v160, v94, v130
	v_add_f32_e32 v161, v95, v131
	s_nop 0
	v_mul_f32_e32 v151, 0xbfb8aa3b, v160
	v_exp_f32_e32 v151, v151
	v_add_f32_e32 v154, v96, v132
	v_add_f32_e32 v155, v97, v133
	v_add_f32_e32 v158, v90, v130
	v_add_f32_e32 v159, v91, v131
	v_add_f32_e32 v151, 1.0, v151
	v_rcp_f32_e32 v188, v151
	v_mul_f32_e32 v151, 0xbfb8aa3b, v161
	v_exp_f32_e32 v151, v151
	v_lshl_add_u64 v[160:161], s[38:39], 0, v[156:157]
	v_lshl_add_u64 v[156:157], v[160:161], 0, v[170:171]
	v_add_f32_e32 v151, 1.0, v151
	v_rcp_f32_e32 v189, v151
	v_mul_f32_e32 v151, 0xbfb8aa3b, v154
	v_exp_f32_e32 v151, v151
	s_nop 0
	v_add_f32_e32 v151, 1.0, v151
	v_rcp_f32_e32 v190, v151
	v_mul_f32_e32 v151, 0xbfb8aa3b, v155
	v_exp_f32_e32 v151, v151
	v_lshl_add_u64 v[154:155], v[162:163], 0, v[170:171]
	v_add_f32_e32 v151, 1.0, v151
	v_rcp_f32_e32 v191, v151
	v_mul_f32_e32 v151, 0xbfb8aa3b, v158
	v_exp_f32_e32 v151, v151
	global_store_dwordx4 v[154:155], v[188:191], off
	v_add_f32_e32 v154, v92, v132
	v_add_f32_e32 v155, v93, v133
	v_add_f32_e32 v151, 1.0, v151
	v_rcp_f32_e32 v188, v151
	v_mul_f32_e32 v151, 0xbfb8aa3b, v159
	v_exp_f32_e32 v151, v151
	v_lshl_add_u64 v[158:159], s[38:39], 0, v[152:153]
	v_lshl_add_u64 v[152:153], v[158:159], 0, v[170:171]
	v_add_f32_e32 v151, 1.0, v151
	v_rcp_f32_e32 v189, v151
	v_mul_f32_e32 v151, 0xbfb8aa3b, v154
	v_exp_f32_e32 v151, v151
	s_nop 0
	v_add_f32_e32 v151, 1.0, v151
	v_rcp_f32_e32 v190, v151
	v_mul_f32_e32 v151, 0xbfb8aa3b, v155
	v_exp_f32_e32 v151, v151
	v_add_f32_e32 v154, v88, v132
	v_add_f32_e32 v155, v89, v133
	v_add_f32_e32 v151, 1.0, v151
	v_rcp_f32_e32 v191, v151
	global_store_dwordx4 v[152:153], v[188:191], off
	v_add_f32_e32 v152, v86, v130
	v_add_f32_e32 v153, v87, v131
	s_nop 0
	v_mul_f32_e32 v151, 0xbfb8aa3b, v152
	v_exp_f32_e32 v151, v151
	s_nop 0
	v_add_f32_e32 v151, 1.0, v151
	v_rcp_f32_e32 v152, v151
	v_mul_f32_e32 v151, 0xbfb8aa3b, v153
	v_exp_f32_e32 v151, v151
	s_nop 0
	v_add_f32_e32 v151, 1.0, v151
	v_rcp_f32_e32 v153, v151
	v_mul_f32_e32 v151, 0xbfb8aa3b, v154
	v_exp_f32_e32 v151, v151
	s_nop 0
	v_add_f32_e32 v151, 1.0, v151
	v_rcp_f32_e32 v154, v151
	v_mul_f32_e32 v151, 0xbfb8aa3b, v155
	v_exp_f32_e32 v151, v151
	s_nop 0
	v_add_f32_e32 v151, 1.0, v151
	v_rcp_f32_e32 v155, v151
	global_store_dwordx4 v[156:157], v[152:155], off
	s_nop 1
	v_add_f32_e32 v154, v82, v130
	v_add_f32_e32 v155, v83, v131
	v_add_f32_e32 v152, v84, v132
	v_add_f32_e32 v153, v85, v133
	v_mul_f32_e32 v151, 0xbfb8aa3b, v154
	v_exp_f32_e32 v151, v151
	v_add_f32_e32 v156, v78, v130
	v_add_f32_e32 v157, v79, v131
	v_add_f32_e32 v151, 1.0, v151
	v_rcp_f32_e32 v188, v151
	v_mul_f32_e32 v151, 0xbfb8aa3b, v155
	v_exp_f32_e32 v151, v151
	v_lshl_add_u64 v[154:155], s[38:39], 0, v[164:165]
	v_add_f32_e32 v151, 1.0, v151
	v_rcp_f32_e32 v189, v151
	v_mul_f32_e32 v151, 0xbfb8aa3b, v152
	v_exp_f32_e32 v151, v151
	s_nop 0
	v_add_f32_e32 v151, 1.0, v151
	v_rcp_f32_e32 v190, v151
	v_mul_f32_e32 v151, 0xbfb8aa3b, v153
	v_exp_f32_e32 v151, v151
	v_lshl_add_u64 v[152:153], v[154:155], 0, v[170:171]
	v_add_f32_e32 v151, 1.0, v151
	v_rcp_f32_e32 v191, v151
	v_mul_f32_e32 v151, 0xbfb8aa3b, v156
	v_exp_f32_e32 v151, v151
	global_store_dwordx4 v[152:153], v[188:191], off
	v_add_f32_e32 v152, v80, v132
	v_add_f32_e32 v153, v81, v133
	v_add_f32_e32 v151, 1.0, v151
	v_rcp_f32_e32 v188, v151
	v_mul_f32_e32 v151, 0xbfb8aa3b, v157
	v_exp_f32_e32 v151, v151
	v_lshl_add_u64 v[156:157], s[38:39], 0, v[134:135]
	v_lshl_add_u64 v[134:135], v[156:157], 0, v[170:171]
	v_add_f32_e32 v151, 1.0, v151
	v_rcp_f32_e32 v189, v151
	v_mul_f32_e32 v151, 0xbfb8aa3b, v152
	v_exp_f32_e32 v151, v151
	s_nop 0
	v_add_f32_e32 v151, 1.0, v151
	v_rcp_f32_e32 v190, v151
	v_mul_f32_e32 v151, 0xbfb8aa3b, v153
	v_exp_f32_e32 v151, v151
	v_add_f32_e32 v152, v74, v130
	v_add_f32_e32 v153, v75, v131
	v_add_f32_e32 v151, 1.0, v151
	v_rcp_f32_e32 v191, v151
	v_mul_f32_e32 v151, 0xbfb8aa3b, v152
	v_exp_f32_e32 v151, v151
	global_store_dwordx4 v[134:135], v[188:191], off
	v_add_f32_e32 v134, v76, v132
	v_add_f32_e32 v135, v77, v133
	v_add_f32_e32 v151, 1.0, v151
	v_mul_f32_e32 v134, 0xbfb8aa3b, v134
	v_exp_f32_e32 v134, v134
	v_rcp_f32_e32 v188, v151
	v_mul_f32_e32 v151, 0xbfb8aa3b, v153
	v_exp_f32_e32 v151, v151
	v_add_f32_e32 v134, 1.0, v134
	v_rcp_f32_e32 v190, v134
	v_mul_f32_e32 v134, 0xbfb8aa3b, v135
	v_exp_f32_e32 v134, v134
	v_add_f32_e32 v151, 1.0, v151
	v_rcp_f32_e32 v189, v151
	v_add_f32_e32 v152, v70, v130
	v_add_f32_e32 v153, v71, v131
	v_add_f32_e32 v134, 1.0, v134
	v_rcp_f32_e32 v191, v134
	v_lshl_add_u64 v[134:135], v[136:137], 0, v[170:171]
	v_mul_f32_e32 v151, 0xbfb8aa3b, v152
	v_exp_f32_e32 v151, v151
	global_store_dwordx4 v[134:135], v[188:191], off
	v_add_f32_e32 v134, v72, v132
	v_add_f32_e32 v135, v73, v133
	v_add_f32_e32 v132, v68, v132
	v_add_f32_e32 v133, v69, v133
	v_mul_f32_e32 v134, 0xbfb8aa3b, v134
	v_exp_f32_e32 v134, v134
	v_add_f32_e32 v151, 1.0, v151
	v_rcp_f32_e32 v188, v151
	v_mul_f32_e32 v151, 0xbfb8aa3b, v153
	v_add_f32_e32 v134, 1.0, v134
	v_rcp_f32_e32 v190, v134
	v_mul_f32_e32 v134, 0xbfb8aa3b, v135
	v_exp_f32_e32 v151, v151
	v_exp_f32_e32 v134, v134
	v_add_f32_e32 v130, v66, v130
	v_add_f32_e32 v131, v67, v131
	v_mul_f32_e32 v132, 0xbfb8aa3b, v132
	v_mul_f32_e32 v130, 0xbfb8aa3b, v130
	v_mul_f32_e32 v131, 0xbfb8aa3b, v131
	v_mul_f32_e32 v133, 0xbfb8aa3b, v133
	v_exp_f32_e32 v130, v130
	v_exp_f32_e32 v131, v131
	v_exp_f32_e32 v132, v132
	v_exp_f32_e32 v133, v133
	v_add_f32_e32 v151, 1.0, v151
	v_add_f32_e32 v134, 1.0, v134
	v_rcp_f32_e32 v189, v151
	v_rcp_f32_e32 v191, v134
	v_add_f32_e32 v130, 1.0, v130
	v_add_f32_e32 v131, 1.0, v131
	v_add_f32_e32 v132, 1.0, v132
	v_add_f32_e32 v133, 1.0, v133
	v_lshl_add_u64 v[152:153], s[38:39], 0, v[168:169]
	v_rcp_f32_e32 v130, v130
	v_rcp_f32_e32 v131, v131
	v_rcp_f32_e32 v132, v132
	v_rcp_f32_e32 v133, v133
	v_lshl_add_u64 v[134:135], v[152:153], 0, v[170:171]
	global_store_dwordx4 v[134:135], v[188:191], off
	v_lshl_add_u64 v[134:135], s[38:39], 0, v[166:167]
	v_lshl_add_u64 v[164:165], v[134:135], 0, v[170:171]
	global_store_dwordx4 v[164:165], v[130:133], off
	global_load_dwordx4 v[130:133], v180, s[80:81] offset:512
	s_waitcnt vmcnt(0)
; __device__ __forceinline__ unsigned pk2(float lo, float hi) { const bfx2 b = __builtin_convertvector((f32x2){lo, hi}, bfx2); return __builtin_bit_cast(unsigned, b); }
; __device__ __forceinline__ f32x4 sig4(const f32x4 v) { f32x4 r; r.x = sigmoidf_(v.x); r.y = sigmoidf_(v.y); r.z = sigmoidf_(v.z); r.w = sigmoidf_(v.w); return r; }
;     template <int SEG> __device__ __forceinline__ void run(const pg8::f32x4 (&acc)[2][2][4][2], const pg8::Unit& u, int wr, int wc, int fr, int fq) const {
;     ...
;             for (int n = 0; n < 2; ++n) { const int col = cb + bj * 128 + 4 * n; f32x4 b = (f32x4){0.f, 0.f, 0.f, 0.f}; if (SEG < 2) b = *(const f32x4*)(bias + col);
; #pragma unroll
;                 for (int ai = 0; ai < 2; ++ai)
; #pragma unroll
;                     for (int m = 0; m < 4; ++m) { const int row = row0 + ai * 128 + m * 16; f32x4 v = acc[ai][bj][m][n] + b;
;                         if (SEG == 0) {
;                             const f32x4 sg = sig4(v);
; #pragma unroll
;                             for (int i = 0; i < 4; ++i) v[i] = __builtin_amdgcn_exp2f(-0.8750387749145276f * sg[i]); }
;                         else if (SEG == 1) v = sig4(v);
;                         if (SEG == 2) { u32x2 w; w.x = pk2(v.x, v.y); w.y = pk2(v.z, v.w); *(u32x2*)((bf16*)GG + (size_t)row * 1024 + col) = w; }
;                         else *(f32x4*)(O + (size_t)row * 1024 + col) = v; }
;                 asm volatile("" ::: "memory"); }
	v_add_f32_e32 v166, v62, v130
	v_add_f32_e32 v167, v63, v131
	s_nop 0
	v_mul_f32_e32 v151, 0xbfb8aa3b, v166
	v_exp_f32_e32 v151, v151
	v_add_f32_e32 v164, v64, v132
	v_add_f32_e32 v165, v65, v133
	v_add_f32_e32 v151, 1.0, v151
	v_rcp_f32_e32 v166, v151
	v_mul_f32_e32 v151, 0xbfb8aa3b, v167
	v_exp_f32_e32 v151, v151
	s_nop 0
	v_add_f32_e32 v151, 1.0, v151
	v_rcp_f32_e32 v167, v151
	v_mul_f32_e32 v151, 0xbfb8aa3b, v164
	v_exp_f32_e32 v151, v151
	v_or_b32_e32 v164, 0x200, v180
	v_add_f32_e32 v151, 1.0, v151
	v_rcp_f32_e32 v168, v151
	v_mul_f32_e32 v151, 0xbfb8aa3b, v165
	v_exp_f32_e32 v151, v151
	v_mov_b32_e32 v165, v181
	v_lshl_add_u64 v[170:171], v[162:163], 0, v[164:165]
	v_add_f32_e32 v151, 1.0, v151
	v_rcp_f32_e32 v169, v151
	global_store_dwordx4 v[170:171], v[166:169], off
	s_nop 1
	v_add_f32_e32 v166, v58, v130
	v_add_f32_e32 v167, v59, v131
	v_add_f32_e32 v168, v60, v132
	v_add_f32_e32 v169, v61, v133
	v_mul_f32_e32 v151, 0xbfb8aa3b, v166
	v_exp_f32_e32 v151, v151
	v_lshl_add_u64 v[170:171], v[158:159], 0, v[164:165]
	v_add_f32_e32 v151, 1.0, v151
	v_rcp_f32_e32 v166, v151
	v_mul_f32_e32 v151, 0xbfb8aa3b, v167
	v_exp_f32_e32 v151, v151
	s_nop 0
	v_add_f32_e32 v151, 1.0, v151
	v_rcp_f32_e32 v167, v151
	v_mul_f32_e32 v151, 0xbfb8aa3b, v168
	v_exp_f32_e32 v151, v151
	s_nop 0
	v_add_f32_e32 v151, 1.0, v151
	v_rcp_f32_e32 v168, v151
	v_mul_f32_e32 v151, 0xbfb8aa3b, v169
	v_exp_f32_e32 v151, v151
	s_nop 0
	v_add_f32_e32 v151, 1.0, v151
	v_rcp_f32_e32 v169, v151
	global_store_dwordx4 v[170:171], v[166:169], off
	s_nop 1
	v_add_f32_e32 v166, v54, v130
	v_add_f32_e32 v167, v55, v131
	v_add_f32_e32 v168, v56, v132
	v_add_f32_e32 v169, v57, v133
	v_mul_f32_e32 v151, 0xbfb8aa3b, v166
	v_exp_f32_e32 v151, v151
	v_lshl_add_u64 v[170:171], v[160:161], 0, v[164:165]
	v_add_f32_e32 v151, 1.0, v151
	v_rcp_f32_e32 v166, v151
	v_mul_f32_e32 v151, 0xbfb8aa3b, v167
	v_exp_f32_e32 v151, v151
	s_nop 0
	v_add_f32_e32 v151, 1.0, v151
	v_rcp_f32_e32 v167, v151
	v_mul_f32_e32 v151, 0xbfb8aa3b, v168
	v_exp_f32_e32 v151, v151
	s_nop 0
	v_add_f32_e32 v151, 1.0, v151
	v_rcp_f32_e32 v168, v151
	v_mul_f32_e32 v151, 0xbfb8aa3b, v169
	v_exp_f32_e32 v151, v151
	s_nop 0
	v_add_f32_e32 v151, 1.0, v151
	v_rcp_f32_e32 v169, v151
	global_store_dwordx4 v[170:171], v[166:169], off
	s_nop 1
	v_add_f32_e32 v166, v50, v130
	v_add_f32_e32 v167, v51, v131
	v_add_f32_e32 v168, v52, v132
	v_add_f32_e32 v169, v53, v133
	v_mul_f32_e32 v151, 0xbfb8aa3b, v166
	v_exp_f32_e32 v151, v151
	v_lshl_add_u64 v[170:171], v[154:155], 0, v[164:165]
	v_add_f32_e32 v151, 1.0, v151
	v_rcp_f32_e32 v166, v151
	v_mul_f32_e32 v151, 0xbfb8aa3b, v167
	v_exp_f32_e32 v151, v151
	s_nop 0
	v_add_f32_e32 v151, 1.0, v151
	v_rcp_f32_e32 v167, v151
	v_mul_f32_e32 v151, 0xbfb8aa3b, v168
	v_exp_f32_e32 v151, v151
	s_nop 0
	v_add_f32_e32 v151, 1.0, v151
	v_rcp_f32_e32 v168, v151
	v_mul_f32_e32 v151, 0xbfb8aa3b, v169
	v_exp_f32_e32 v151, v151
	s_nop 0
	v_add_f32_e32 v151, 1.0, v151
	v_rcp_f32_e32 v169, v151
	global_store_dwordx4 v[170:171], v[166:169], off
	s_nop 1
	v_add_f32_e32 v166, v46, v130
	v_add_f32_e32 v167, v47, v131
	v_add_f32_e32 v168, v48, v132
	v_add_f32_e32 v169, v49, v133
	v_mul_f32_e32 v151, 0xbfb8aa3b, v166
	v_exp_f32_e32 v151, v151
	v_lshl_add_u64 v[170:171], v[156:157], 0, v[164:165]
	v_add_f32_e32 v151, 1.0, v151
	v_rcp_f32_e32 v166, v151
	v_mul_f32_e32 v151, 0xbfb8aa3b, v167
	v_exp_f32_e32 v151, v151
	s_nop 0
	v_add_f32_e32 v151, 1.0, v151
	v_rcp_f32_e32 v167, v151
	v_mul_f32_e32 v151, 0xbfb8aa3b, v168
	v_exp_f32_e32 v151, v151
	s_nop 0
	v_add_f32_e32 v151, 1.0, v151
	v_rcp_f32_e32 v168, v151
	v_mul_f32_e32 v151, 0xbfb8aa3b, v169
	v_exp_f32_e32 v151, v151
	s_nop 0
	v_add_f32_e32 v151, 1.0, v151
	v_rcp_f32_e32 v169, v151
	global_store_dwordx4 v[170:171], v[166:169], off
	s_nop 1
	v_add_f32_e32 v166, v42, v130
	v_add_f32_e32 v167, v43, v131
	v_add_f32_e32 v168, v44, v132
	v_add_f32_e32 v169, v45, v133
	v_mul_f32_e32 v151, 0xbfb8aa3b, v166
	v_exp_f32_e32 v151, v151
	v_lshl_add_u64 v[170:171], v[136:137], 0, v[164:165]
	v_add_f32_e32 v151, 1.0, v151
	v_rcp_f32_e32 v166, v151
	v_mul_f32_e32 v151, 0xbfb8aa3b, v167
	v_exp_f32_e32 v151, v151
	s_nop 0
	v_add_f32_e32 v151, 1.0, v151
	v_rcp_f32_e32 v167, v151
	v_mul_f32_e32 v151, 0xbfb8aa3b, v168
	v_exp_f32_e32 v151, v151
	s_nop 0
	v_add_f32_e32 v151, 1.0, v151
	v_rcp_f32_e32 v168, v151
	v_mul_f32_e32 v151, 0xbfb8aa3b, v169
	v_exp_f32_e32 v151, v151
	s_nop 0
	v_add_f32_e32 v151, 1.0, v151
	v_rcp_f32_e32 v169, v151
	global_store_dwordx4 v[170:171], v[166:169], off
	s_nop 1
	v_add_f32_e32 v166, v38, v130
	v_add_f32_e32 v167, v39, v131
	v_add_f32_e32 v168, v40, v132
	v_add_f32_e32 v169, v41, v133
	v_mul_f32_e32 v151, 0xbfb8aa3b, v166
	v_exp_f32_e32 v151, v151
	v_add_f32_e32 v132, v36, v132
	v_add_f32_e32 v133, v37, v133
	v_add_f32_e32 v130, v34, v130
	v_add_f32_e32 v131, v35, v131
	v_mul_f32_e32 v132, 0xbfb8aa3b, v132
	v_add_f32_e32 v151, 1.0, v151
	v_rcp_f32_e32 v166, v151
	v_mul_f32_e32 v151, 0xbfb8aa3b, v167
	v_exp_f32_e32 v151, v151
	v_mul_f32_e32 v130, 0xbfb8aa3b, v130
	v_mul_f32_e32 v131, 0xbfb8aa3b, v131
	v_mul_f32_e32 v133, 0xbfb8aa3b, v133
	v_add_f32_e32 v151, 1.0, v151
	v_rcp_f32_e32 v167, v151
	v_mul_f32_e32 v151, 0xbfb8aa3b, v168
	v_exp_f32_e32 v151, v151
	v_exp_f32_e32 v130, v130
	v_exp_f32_e32 v131, v131
	v_exp_f32_e32 v132, v132
	v_add_f32_e32 v151, 1.0, v151
	v_rcp_f32_e32 v168, v151
	v_mul_f32_e32 v151, 0xbfb8aa3b, v169
	v_exp_f32_e32 v151, v151
	v_exp_f32_e32 v133, v133
	v_add_f32_e32 v130, 1.0, v130
	v_add_f32_e32 v131, 1.0, v131
	v_add_f32_e32 v151, 1.0, v151
	v_add_f32_e32 v132, 1.0, v132
	v_add_f32_e32 v133, 1.0, v133
	v_rcp_f32_e32 v169, v151
	v_rcp_f32_e32 v130, v130
	v_rcp_f32_e32 v131, v131
	v_rcp_f32_e32 v132, v132
	v_rcp_f32_e32 v133, v133
	v_lshl_add_u64 v[170:171], v[152:153], 0, v[164:165]
	v_lshl_add_u64 v[164:165], v[134:135], 0, v[164:165]
	global_store_dwordx4 v[170:171], v[166:169], off
	global_store_dwordx4 v[164:165], v[130:133], off
	global_load_dwordx4 v[130:133], v180, s[80:81] offset:528
	v_or_b32_e32 v180, 0x210, v180
	v_lshl_add_u64 v[162:163], v[162:163], 0, v[180:181]
	v_lshl_add_u64 v[158:159], v[158:159], 0, v[180:181]
	v_lshl_add_u64 v[154:155], v[154:155], 0, v[180:181]
	v_lshl_add_u64 v[136:137], v[136:137], 0, v[180:181]
	v_lshl_add_u64 v[134:135], v[134:135], 0, v[180:181]
	s_waitcnt vmcnt(0)
; __device__ __forceinline__ unsigned pk2(float lo, float hi) { const bfx2 b = __builtin_convertvector((f32x2){lo, hi}, bfx2); return __builtin_bit_cast(unsigned, b); }
; __device__ __forceinline__ f32x4 sig4(const f32x4 v) { f32x4 r; r.x = sigmoidf_(v.x); r.y = sigmoidf_(v.y); r.z = sigmoidf_(v.z); r.w = sigmoidf_(v.w); return r; }
;     template <int SEG> __device__ __forceinline__ void run(const pg8::f32x4 (&acc)[2][2][4][2], const pg8::Unit& u, int wr, int wc, int fr, int fq) const {
;     ...
;             for (int n = 0; n < 2; ++n) { const int col = cb + bj * 128 + 4 * n; f32x4 b = (f32x4){0.f, 0.f, 0.f, 0.f}; if (SEG < 2) b = *(const f32x4*)(bias + col);
; #pragma unroll
;                 for (int ai = 0; ai < 2; ++ai)
; #pragma unroll
;                     for (int m = 0; m < 4; ++m) { const int row = row0 + ai * 128 + m * 16; f32x4 v = acc[ai][bj][m][n] + b;
;                         if (SEG == 0) {
;                             const f32x4 sg = sig4(v);
; #pragma unroll
;                             for (int i = 0; i < 4; ++i) v[i] = __builtin_amdgcn_exp2f(-0.8750387749145276f * sg[i]); }
;                         else if (SEG == 1) v = sig4(v);
;                         if (SEG == 2) { u32x2 w; w.x = pk2(v.x, v.y); w.y = pk2(v.z, v.w); *(u32x2*)((bf16*)GG + (size_t)row * 1024 + col) = w; }
;                         else *(f32x4*)(O + (size_t)row * 1024 + col) = v; }
;                 asm volatile("" ::: "memory"); }
	v_add_f32_e32 v164, v30, v130
	v_add_f32_e32 v165, v31, v131
	s_nop 0
	v_mul_f32_e32 v151, 0xbfb8aa3b, v164
	v_exp_f32_e32 v151, v151
	v_add_f32_e32 v166, v32, v132
	v_add_f32_e32 v167, v33, v133
	v_add_f32_e32 v151, 1.0, v151
	v_rcp_f32_e32 v164, v151
	v_mul_f32_e32 v151, 0xbfb8aa3b, v165
	v_exp_f32_e32 v151, v151
	s_nop 0
	v_add_f32_e32 v151, 1.0, v151
	v_rcp_f32_e32 v165, v151
	v_mul_f32_e32 v151, 0xbfb8aa3b, v166
	v_exp_f32_e32 v151, v151
	s_nop 0
	v_add_f32_e32 v151, 1.0, v151
	v_rcp_f32_e32 v166, v151
	v_mul_f32_e32 v151, 0xbfb8aa3b, v167
	v_exp_f32_e32 v151, v151
	s_nop 0
	v_add_f32_e32 v151, 1.0, v151
	v_rcp_f32_e32 v167, v151
	global_store_dwordx4 v[162:163], v[164:167], off
	v_add_f32_e32 v162, v26, v130
	v_add_f32_e32 v163, v27, v131
	s_nop 0
	v_add_f32_e32 v164, v28, v132
	v_add_f32_e32 v165, v29, v133
	v_mul_f32_e32 v151, 0xbfb8aa3b, v162
	v_exp_f32_e32 v151, v151
	s_nop 0
	v_add_f32_e32 v151, 1.0, v151
	v_rcp_f32_e32 v162, v151
	v_mul_f32_e32 v151, 0xbfb8aa3b, v163
	v_exp_f32_e32 v151, v151
	s_nop 0
	v_add_f32_e32 v151, 1.0, v151
	v_rcp_f32_e32 v163, v151
	v_mul_f32_e32 v151, 0xbfb8aa3b, v164
	v_exp_f32_e32 v151, v151
	s_nop 0
	v_add_f32_e32 v151, 1.0, v151
	v_rcp_f32_e32 v164, v151
	v_mul_f32_e32 v151, 0xbfb8aa3b, v165
	v_exp_f32_e32 v151, v151
	s_nop 0
	v_add_f32_e32 v151, 1.0, v151
	v_rcp_f32_e32 v165, v151
	global_store_dwordx4 v[158:159], v[162:165], off
	s_nop 1
	v_add_f32_e32 v162, v22, v130
	v_add_f32_e32 v163, v23, v131
	v_add_f32_e32 v158, v24, v132
	v_add_f32_e32 v159, v25, v133
	v_mul_f32_e32 v151, 0xbfb8aa3b, v162
	v_exp_f32_e32 v151, v151
	s_nop 0
	v_add_f32_e32 v151, 1.0, v151
	v_rcp_f32_e32 v162, v151
	v_mul_f32_e32 v151, 0xbfb8aa3b, v163
	v_exp_f32_e32 v151, v151
	s_nop 0
	v_add_f32_e32 v151, 1.0, v151
	v_rcp_f32_e32 v163, v151
	v_mul_f32_e32 v151, 0xbfb8aa3b, v158
	v_exp_f32_e32 v151, v151
	s_nop 0
	v_add_f32_e32 v151, 1.0, v151
	v_rcp_f32_e32 v164, v151
	v_mul_f32_e32 v151, 0xbfb8aa3b, v159
	v_exp_f32_e32 v151, v151
	v_lshl_add_u64 v[158:159], v[160:161], 0, v[180:181]
	v_add_f32_e32 v160, v20, v132
	v_add_f32_e32 v161, v21, v133
	v_add_f32_e32 v151, 1.0, v151
	v_rcp_f32_e32 v165, v151
	global_store_dwordx4 v[158:159], v[162:165], off
	v_add_f32_e32 v158, v18, v130
	v_add_f32_e32 v159, v19, v131
	s_nop 0
	v_mul_f32_e32 v151, 0xbfb8aa3b, v158
	v_exp_f32_e32 v151, v151
	s_nop 0
	v_add_f32_e32 v151, 1.0, v151
	v_rcp_f32_e32 v158, v151
	v_mul_f32_e32 v151, 0xbfb8aa3b, v159
	v_exp_f32_e32 v151, v151
	s_nop 0
	v_add_f32_e32 v151, 1.0, v151
	v_rcp_f32_e32 v159, v151
	v_mul_f32_e32 v151, 0xbfb8aa3b, v160
	v_exp_f32_e32 v151, v151
	s_nop 0
	v_add_f32_e32 v151, 1.0, v151
	v_rcp_f32_e32 v160, v151
	v_mul_f32_e32 v151, 0xbfb8aa3b, v161
	v_exp_f32_e32 v151, v151
	s_nop 0
	v_add_f32_e32 v151, 1.0, v151
	v_rcp_f32_e32 v161, v151
	global_store_dwordx4 v[154:155], v[158:161], off
	s_nop 1
	v_add_f32_e32 v158, v14, v130
	v_add_f32_e32 v159, v15, v131
	v_add_f32_e32 v154, v16, v132
	v_add_f32_e32 v155, v17, v133
	v_mul_f32_e32 v151, 0xbfb8aa3b, v158
	v_exp_f32_e32 v151, v151
	s_nop 0
	v_add_f32_e32 v151, 1.0, v151
	v_rcp_f32_e32 v158, v151
	v_mul_f32_e32 v151, 0xbfb8aa3b, v159
	v_exp_f32_e32 v151, v151
	s_nop 0
	v_add_f32_e32 v151, 1.0, v151
	v_rcp_f32_e32 v159, v151
	v_mul_f32_e32 v151, 0xbfb8aa3b, v154
	v_exp_f32_e32 v151, v151
	s_nop 0
	v_add_f32_e32 v151, 1.0, v151
	v_rcp_f32_e32 v160, v151
	v_mul_f32_e32 v151, 0xbfb8aa3b, v155
	v_exp_f32_e32 v151, v151
	v_lshl_add_u64 v[154:155], v[156:157], 0, v[180:181]
	v_add_f32_e32 v156, v12, v132
	v_add_f32_e32 v157, v13, v133
	v_add_f32_e32 v151, 1.0, v151
	v_rcp_f32_e32 v161, v151
	global_store_dwordx4 v[154:155], v[158:161], off
	v_add_f32_e32 v154, v10, v130
	v_add_f32_e32 v155, v11, v131
	s_nop 0
	v_mul_f32_e32 v151, 0xbfb8aa3b, v154
	v_exp_f32_e32 v151, v151
	s_nop 0
	v_add_f32_e32 v151, 1.0, v151
	v_rcp_f32_e32 v154, v151
	v_mul_f32_e32 v151, 0xbfb8aa3b, v155
	v_exp_f32_e32 v151, v151
	s_nop 0
	v_add_f32_e32 v151, 1.0, v151
	v_rcp_f32_e32 v155, v151
	v_mul_f32_e32 v151, 0xbfb8aa3b, v156
	v_exp_f32_e32 v151, v151
	s_nop 0
	v_add_f32_e32 v151, 1.0, v151
	v_rcp_f32_e32 v156, v151
	v_mul_f32_e32 v151, 0xbfb8aa3b, v157
	v_exp_f32_e32 v151, v151
	s_nop 0
	v_add_f32_e32 v151, 1.0, v151
	v_rcp_f32_e32 v157, v151
	global_store_dwordx4 v[136:137], v[154:157], off
	v_add_f32_e32 v136, v8, v132
	v_add_f32_e32 v137, v9, v133
	s_nop 0
	v_add_f32_e32 v154, v6, v130
	v_add_f32_e32 v155, v7, v131
	v_mul_f32_e32 v136, 0xbfb8aa3b, v136
	v_mul_f32_e32 v151, 0xbfb8aa3b, v154
	v_exp_f32_e32 v151, v151
	v_exp_f32_e32 v136, v136
	v_add_f32_e32 v132, v4, v132
	v_add_f32_e32 v133, v5, v133
	v_add_f32_e32 v130, v2, v130
	v_add_f32_e32 v131, v3, v131
	v_add_f32_e32 v151, 1.0, v151
	v_add_f32_e32 v136, 1.0, v136
	v_rcp_f32_e32 v154, v151
	v_mul_f32_e32 v151, 0xbfb8aa3b, v155
	v_rcp_f32_e32 v156, v136
	v_mul_f32_e32 v136, 0xbfb8aa3b, v137
	v_mul_f32_e32 v130, 0xbfb8aa3b, v130
	v_mul_f32_e32 v131, 0xbfb8aa3b, v131
	v_mul_f32_e32 v132, 0xbfb8aa3b, v132
	v_mul_f32_e32 v133, 0xbfb8aa3b, v133
	v_exp_f32_e32 v151, v151
	v_exp_f32_e32 v136, v136
	v_exp_f32_e32 v130, v130
	v_exp_f32_e32 v131, v131
	v_exp_f32_e32 v132, v132
	v_exp_f32_e32 v133, v133
	v_add_f32_e32 v151, 1.0, v151
	v_add_f32_e32 v136, 1.0, v136
	v_add_f32_e32 v130, 1.0, v130
	v_add_f32_e32 v131, 1.0, v131
	v_add_f32_e32 v132, 1.0, v132
	v_add_f32_e32 v133, 1.0, v133
	v_rcp_f32_e32 v155, v151
	v_rcp_f32_e32 v157, v136
	v_rcp_f32_e32 v130, v130
	v_rcp_f32_e32 v131, v131
	v_rcp_f32_e32 v132, v132
	v_rcp_f32_e32 v133, v133
	v_lshl_add_u64 v[136:137], v[152:153], 0, v[180:181]
	global_store_dwordx4 v[136:137], v[154:157], off
	global_store_dwordx4 v[134:135], v[130:133], off

; __device__ __forceinline__ unsigned pk2(float lo, float hi) { const bfx2 b = __builtin_convertvector((f32x2){lo, hi}, bfx2); return __builtin_bit_cast(unsigned, b); }
; __device__ __forceinline__ f32x4 sig4(const f32x4 v) { f32x4 r; r.x = sigmoidf_(v.x); r.y = sigmoidf_(v.y); r.z = sigmoidf_(v.z); r.w = sigmoidf_(v.w); return r; }
; template <int CW, int NB, int NS, class Epi>
; __device__ __forceinline__ void skinny_gemm(Frame& F, const bf16* A, int K, const bf16* Bt, int nchunks, const Epi& E) {
;     ...
;         if (ks == 0) {
; #pragma unroll
;             for (int i = 0; i < 2; ++i)
; #pragma unroll
;                 for (int j = 0; j < NT; ++j) {
; #pragma unroll
;                     for (int nb = 0; nb < NB; ++nb) acc[i][j][nb] += red[((i * NT + j) * NB + nb) * 256 + rg * 64 + lane];
;                     if (16 * j + 4 * lq < CW) E(32 * rg + 16 * i + lr, c0 + 16 * j + 4 * lq, acc[i][j][0], acc[i][j][NB - 1]); }
;     __device__ __forceinline__ void operator()(int r, int n, const pg8::f32x4 a, const pg8::f32x4) const {
;         const int seg = n >> 10, col = n & 1023, row = MP + r; f32x4 v = a;
;         if (seg == 0) { const f32x4 sg = sig4(v + *(const f32x4*)(w0 + col));
; #pragma unroll
;             for (int i = 0; i < 4; ++i) v[i] = __builtin_amdgcn_exp2f(-0.8750387749145276f * sg[i]);
;             *(f32x4*)(DEC + (size_t)row * 1024 + col) = v; }
;         else if (seg == 1) { *(f32x4*)(AA + (size_t)row * 1024 + col) = sig4(v + *(const f32x4*)(a0 + col)); }
;         else { u32x2 w; w.x = pk2(v.x, v.y); w.y = pk2(v.z, v.w); *(u32x2*)((bf16*)GG + (size_t)row * 1024 + col) = w; }
;     }
.LBB0_1496:
	s_andn2_b64 vcc, exec, s[24:25]
	s_waitcnt lgkmcnt(0)
	s_barrier
	s_cbranch_vccnz .LBB0_1483
	s_and_saveexec_b64 s[56:57], s[0:1]
	s_cbranch_execz .LBB0_1482
	s_waitcnt vmcnt(4)
	v_add_u32_e32 v37, s3, v80
	ds_read_b128 v[38:41], v37
	v_add_u32_e32 v34, s9, v82
	s_movk_i32 s6, 0x3ff
	v_and_b32_e32 v36, 0x3fc, v34
	v_cmp_lt_u32_e64 s[6:7], s6, v34
	v_and_b32_e32 v34, 0xfffffc00, v34
	s_movk_i32 s9, 0x400
	v_cmp_ne_u32_e32 vcc, s9, v34
	s_waitcnt lgkmcnt(0)
	v_add_f32_e32 v34, v32, v40
	v_add_f32_e32 v35, v33, v41
	v_add_f32_e32 v30, v30, v38
	v_add_f32_e32 v31, v31, v39
	s_and_saveexec_b64 s[52:53], s[6:7]
	s_xor_b64 s[60:61], exec, s[52:53]
	s_cbranch_execz .LBB0_1504
	s_and_saveexec_b64 s[52:53], vcc
	s_xor_b64 s[74:75], exec, s[52:53]
	s_cbranch_execz .LBB0_1501
	v_lshlrev_b32_e32 v180, 1, v36
	v_cvt_pk_bf16_f32 v30, v30, v31
	v_cvt_pk_bf16_f32 v31, v34, v35
	v_lshl_add_u64 v[32:33], v[68:69], 0, v[180:181]
	global_store_dwordx2 v[32:33], v[30:31], off
.LBB0_1501:
	s_andn2_saveexec_b64 s[74:75], s[74:75]
	s_cbranch_execz .LBB0_1503
	v_readlane_b32 s76, v253, 48
	v_lshlrev_b32_e32 v180, 2, v36
	v_readlane_b32 s80, v253, 52
	v_readlane_b32 s81, v253, 53
	v_readlane_b32 s82, v253, 54
	v_readlane_b32 s83, v253, 55
	v_readlane_b32 s84, v253, 56
	v_readlane_b32 s85, v253, 57
	v_readlane_b32 s86, v253, 58
	global_load_dwordx4 v[38:41], v180, s[80:81]
	v_readlane_b32 s87, v253, 59
	v_readlane_b32 s88, v253, 60
	v_readlane_b32 s89, v253, 61
	v_readlane_b32 s90, v253, 62
	v_readlane_b32 s91, v253, 63
	v_readlane_b32 s80, v254, 31
	v_readlane_b32 s84, v254, 35
	v_readlane_b32 s85, v254, 36
	v_readlane_b32 s77, v253, 49
	v_readlane_b32 s78, v253, 50
	v_readlane_b32 s79, v253, 51
	v_readlane_b32 s81, v254, 32
	v_readlane_b32 s82, v254, 33
	v_readlane_b32 s83, v254, 34
	v_readlane_b32 s86, v254, 37
	v_readlane_b32 s87, v254, 38
	v_readlane_b32 s88, v254, 39
	v_readlane_b32 s89, v254, 40
	v_readlane_b32 s90, v254, 41
	v_readlane_b32 s91, v254, 42
	v_readlane_b32 s92, v254, 43
	v_readlane_b32 s93, v254, 44
	v_readlane_b32 s94, v254, 45
	v_readlane_b32 s95, v254, 46
	s_waitcnt vmcnt(0)
	v_add_f32_e32 v32, v34, v40
	v_add_f32_e32 v33, v35, v41
	v_add_f32_e32 v30, v30, v38
	v_add_f32_e32 v31, v31, v39
	v_mul_f32_e32 v32, 0xbfb8aa3b, v32
	v_mul_f32_e32 v30, 0xbfb8aa3b, v30
	v_mul_f32_e32 v31, 0xbfb8aa3b, v31
	v_mul_f32_e32 v33, 0xbfb8aa3b, v33
	v_exp_f32_e32 v30, v30
	v_exp_f32_e32 v31, v31
	v_exp_f32_e32 v32, v32
	v_exp_f32_e32 v33, v33
	v_add_f32_e32 v30, 1.0, v30
	v_add_f32_e32 v31, 1.0, v31
	v_add_f32_e32 v32, 1.0, v32
	v_add_f32_e32 v33, 1.0, v33
	v_rcp_f32_e32 v30, v30
	v_rcp_f32_e32 v31, v31
	v_rcp_f32_e32 v32, v32
	v_rcp_f32_e32 v33, v33
	v_lshl_add_u64 v[34:35], v[70:71], 0, v[180:181]
	global_store_dwordx4 v[34:35], v[30:33], off

; __device__ __forceinline__ unsigned pk2(float lo, float hi) { const bfx2 b = __builtin_convertvector((f32x2){lo, hi}, bfx2); return __builtin_bit_cast(unsigned, b); }
; __device__ __forceinline__ f32x4 sig4(const f32x4 v) { f32x4 r; r.x = sigmoidf_(v.x); r.y = sigmoidf_(v.y); r.z = sigmoidf_(v.z); r.w = sigmoidf_(v.w); return r; }
; template <int CW, int NB, int NS, class Epi>
; __device__ __forceinline__ void skinny_gemm(Frame& F, const bf16* A, int K, const bf16* Bt, int nchunks, const Epi& E) {
;     ...
;         if (ks == 0) {
; #pragma unroll
;             for (int i = 0; i < 2; ++i)
; #pragma unroll
;                 for (int j = 0; j < NT; ++j) {
; #pragma unroll
;                     for (int nb = 0; nb < NB; ++nb) acc[i][j][nb] += red[((i * NT + j) * NB + nb) * 256 + rg * 64 + lane];
;                     if (16 * j + 4 * lq < CW) E(32 * rg + 16 * i + lr, c0 + 16 * j + 4 * lq, acc[i][j][0], acc[i][j][NB - 1]); }
;     __device__ __forceinline__ void operator()(int r, int n, const pg8::f32x4 a, const pg8::f32x4) const {
;         const int seg = n >> 10, col = n & 1023, row = MP + r; f32x4 v = a;
;         if (seg == 0) { const f32x4 sg = sig4(v + *(const f32x4*)(w0 + col));
; #pragma unroll
;             for (int i = 0; i < 4; ++i) v[i] = __builtin_amdgcn_exp2f(-0.8750387749145276f * sg[i]);
;             *(f32x4*)(DEC + (size_t)row * 1024 + col) = v; }
;         else if (seg == 1) { *(f32x4*)(AA + (size_t)row * 1024 + col) = sig4(v + *(const f32x4*)(a0 + col)); }
;         else { u32x2 w; w.x = pk2(v.x, v.y); w.y = pk2(v.z, v.w); *(u32x2*)((bf16*)GG + (size_t)row * 1024 + col) = w; }
;     }
.LBB0_1504:
	s_andn2_saveexec_b64 s[60:61], s[60:61]
	s_cbranch_execz .LBB0_1506
	v_readlane_b32 s76, v253, 48
	v_lshlrev_b32_e32 v180, 2, v36
	v_readlane_b32 s77, v253, 49
	v_readlane_b32 s80, v253, 52
	v_readlane_b32 s81, v253, 53
	v_readlane_b32 s82, v253, 54
	v_readlane_b32 s83, v253, 55
	v_readlane_b32 s84, v253, 56
	global_load_dwordx4 v[38:41], v180, s[76:77]
	v_readlane_b32 s85, v253, 57
	v_readlane_b32 s86, v253, 58
	v_readlane_b32 s87, v253, 59
	v_readlane_b32 s88, v253, 60
	v_readlane_b32 s89, v253, 61
	v_readlane_b32 s90, v253, 62
	v_readlane_b32 s91, v253, 63
	v_readlane_b32 s80, v254, 31
	v_readlane_b32 s84, v254, 35
	v_readlane_b32 s85, v254, 36
	v_readlane_b32 s78, v253, 50
	v_readlane_b32 s79, v253, 51
	v_readlane_b32 s81, v254, 32
	v_readlane_b32 s82, v254, 33
	v_readlane_b32 s83, v254, 34
	v_readlane_b32 s86, v254, 37
	v_readlane_b32 s87, v254, 38
	v_readlane_b32 s88, v254, 39
	v_readlane_b32 s89, v254, 40
	v_readlane_b32 s90, v254, 41
	v_readlane_b32 s91, v254, 42
	v_readlane_b32 s92, v254, 43
	v_readlane_b32 s93, v254, 44
	v_readlane_b32 s94, v254, 45
	v_readlane_b32 s95, v254, 46
	s_waitcnt vmcnt(0)
	v_add_f32_e32 v32, v34, v40
	v_add_f32_e32 v33, v35, v41
	v_add_f32_e32 v30, v30, v38
	v_add_f32_e32 v31, v31, v39
	v_mul_f32_e32 v32, 0xbfb8aa3b, v32
	v_mul_f32_e32 v30, 0xbfb8aa3b, v30
	v_mul_f32_e32 v31, 0xbfb8aa3b, v31
	v_mul_f32_e32 v33, 0xbfb8aa3b, v33
	v_exp_f32_e32 v30, v30
	v_exp_f32_e32 v31, v31
	v_exp_f32_e32 v32, v32
	v_exp_f32_e32 v33, v33
	v_add_f32_e32 v30, 1.0, v30
	v_add_f32_e32 v31, 1.0, v31
	v_add_f32_e32 v32, 1.0, v32
	v_add_f32_e32 v33, 1.0, v33
	v_rcp_f32_e32 v30, v30
	v_rcp_f32_e32 v31, v31
	v_rcp_f32_e32 v32, v32
	v_rcp_f32_e32 v33, v33
	v_mul_f32_e32 v30, 0xbf60028b, v30
	v_mul_f32_e32 v31, 0xbf60028b, v31
	v_mul_f32_e32 v32, 0xbf60028b, v32
	v_mul_f32_e32 v33, 0xbf60028b, v33
	v_exp_f32_e32 v30, v30
	v_exp_f32_e32 v31, v31
	v_exp_f32_e32 v32, v32
	v_exp_f32_e32 v33, v33
	v_lshl_add_u64 v[34:35], v[72:73], 0, v[180:181]
	global_store_dwordx4 v[34:35], v[30:33], off
.LBB0_1506:
	s_or_b64 exec, exec, s[60:61]
	ds_read_b128 v[30:33], v37 offset:4096
	s_waitcnt lgkmcnt(0)
	v_add_f32_e32 v26, v26, v30
	v_add_f32_e32 v27, v27, v31
	v_add_f32_e32 v30, v28, v32
	v_add_f32_e32 v31, v29, v33
	s_and_saveexec_b64 s[52:53], s[6:7]
	s_xor_b64 s[6:7], exec, s[52:53]
	s_cbranch_execz .LBB0_1512
	s_and_saveexec_b64 s[52:53], vcc
	s_xor_b64 s[60:61], exec, s[52:53]
	s_cbranch_execz .LBB0_1509
	v_lshlrev_b32_e32 v180, 1, v36
	v_cvt_pk_bf16_f32 v26, v26, v27
	v_cvt_pk_bf16_f32 v27, v30, v31
	v_lshl_add_u64 v[28:29], v[74:75], 0, v[180:181]
	global_store_dwordx2 v[28:29], v[26:27], off
.LBB0_1509:
	s_andn2_saveexec_b64 s[60:61], s[60:61]
	s_cbranch_execz .LBB0_1511
	v_readlane_b32 s76, v253, 48
	v_lshlrev_b32_e32 v180, 2, v36
	v_readlane_b32 s80, v253, 52
	v_readlane_b32 s81, v253, 53
	v_readlane_b32 s82, v253, 54
	v_readlane_b32 s83, v253, 55
	v_readlane_b32 s84, v253, 56
	v_readlane_b32 s85, v253, 57
	v_readlane_b32 s86, v253, 58
	global_load_dwordx4 v[32:35], v180, s[80:81]
	v_readlane_b32 s87, v253, 59
	v_readlane_b32 s88, v253, 60
	v_readlane_b32 s89, v253, 61
	v_readlane_b32 s90, v253, 62
	v_readlane_b32 s91, v253, 63
	v_readlane_b32 s80, v254, 31
	v_readlane_b32 s84, v254, 35
	v_readlane_b32 s85, v254, 36
	v_readlane_b32 s77, v253, 49
	v_readlane_b32 s78, v253, 50
	v_readlane_b32 s79, v253, 51
	v_readlane_b32 s81, v254, 32
	v_readlane_b32 s82, v254, 33
	v_readlane_b32 s83, v254, 34
	v_readlane_b32 s86, v254, 37
	v_readlane_b32 s87, v254, 38
	v_readlane_b32 s88, v254, 39
	v_readlane_b32 s89, v254, 40
	v_readlane_b32 s90, v254, 41
	v_readlane_b32 s91, v254, 42
	v_readlane_b32 s92, v254, 43
	v_readlane_b32 s93, v254, 44
	v_readlane_b32 s94, v254, 45
	v_readlane_b32 s95, v254, 46
	s_waitcnt vmcnt(0)
	v_add_f32_e32 v28, v30, v34
	v_add_f32_e32 v29, v31, v35
	v_add_f32_e32 v26, v26, v32
	v_add_f32_e32 v27, v27, v33
	v_mul_f32_e32 v28, 0xbfb8aa3b, v28
	v_mul_f32_e32 v26, 0xbfb8aa3b, v26
	v_mul_f32_e32 v27, 0xbfb8aa3b, v27
	v_mul_f32_e32 v29, 0xbfb8aa3b, v29
	v_exp_f32_e32 v26, v26
	v_exp_f32_e32 v27, v27
	v_exp_f32_e32 v28, v28
	v_exp_f32_e32 v29, v29
	v_add_f32_e32 v26, 1.0, v26
	v_add_f32_e32 v27, 1.0, v27
	v_add_f32_e32 v28, 1.0, v28
	v_add_f32_e32 v29, 1.0, v29
	v_rcp_f32_e32 v26, v26
	v_rcp_f32_e32 v27, v27
	v_rcp_f32_e32 v28, v28
	v_rcp_f32_e32 v29, v29
	v_lshl_add_u64 v[30:31], v[76:77], 0, v[180:181]
	global_store_dwordx4 v[30:31], v[26:29], off

; __device__ __forceinline__ unsigned pk2(float lo, float hi) { const bfx2 b = __builtin_convertvector((f32x2){lo, hi}, bfx2); return __builtin_bit_cast(unsigned, b); }
; __device__ __forceinline__ f32x4 sig4(const f32x4 v) { f32x4 r; r.x = sigmoidf_(v.x); r.y = sigmoidf_(v.y); r.z = sigmoidf_(v.z); r.w = sigmoidf_(v.w); return r; }
;     __device__ __forceinline__ void operator()(int r, int n, const pg8::f32x4 a, const pg8::f32x4) const {
;         const int seg = n >> 10, col = n & 1023, row = MP + r; f32x4 v = a;
;         if (seg == 0) { const f32x4 sg = sig4(v + *(const f32x4*)(w0 + col));
; #pragma unroll
;             for (int i = 0; i < 4; ++i) v[i] = __builtin_amdgcn_exp2f(-0.8750387749145276f * sg[i]);
;             *(f32x4*)(DEC + (size_t)row * 1024 + col) = v; }
;         else if (seg == 1) { *(f32x4*)(AA + (size_t)row * 1024 + col) = sig4(v + *(const f32x4*)(a0 + col)); }
;         else { u32x2 w; w.x = pk2(v.x, v.y); w.y = pk2(v.z, v.w); *(u32x2*)((bf16*)GG + (size_t)row * 1024 + col) = w; }
;     }
.LBB0_1512:
	s_andn2_saveexec_b64 s[6:7], s[6:7]
	s_cbranch_execz .LBB0_1482
	v_readlane_b32 s76, v253, 48
	v_lshlrev_b32_e32 v180, 2, v36
	v_readlane_b32 s77, v253, 49
	v_readlane_b32 s80, v253, 52
	v_readlane_b32 s81, v253, 53
	v_readlane_b32 s82, v253, 54
	v_readlane_b32 s83, v253, 55
	v_readlane_b32 s84, v253, 56
	global_load_dwordx4 v[32:35], v180, s[76:77]
	v_readlane_b32 s85, v253, 57
	v_readlane_b32 s86, v253, 58
	v_readlane_b32 s87, v253, 59
	v_readlane_b32 s88, v253, 60
	v_readlane_b32 s89, v253, 61
	v_readlane_b32 s90, v253, 62
	v_readlane_b32 s91, v253, 63
	v_readlane_b32 s80, v254, 31
	v_readlane_b32 s84, v254, 35
	v_readlane_b32 s85, v254, 36
	v_readlane_b32 s78, v253, 50
	v_readlane_b32 s79, v253, 51
	v_readlane_b32 s81, v254, 32
	v_readlane_b32 s82, v254, 33
	v_readlane_b32 s83, v254, 34
	v_readlane_b32 s86, v254, 37
	v_readlane_b32 s87, v254, 38
	v_readlane_b32 s88, v254, 39
	v_readlane_b32 s89, v254, 40
	v_readlane_b32 s90, v254, 41
	v_readlane_b32 s91, v254, 42
	v_readlane_b32 s92, v254, 43
	v_readlane_b32 s93, v254, 44
	v_readlane_b32 s94, v254, 45
	v_readlane_b32 s95, v254, 46
	s_waitcnt vmcnt(0)
	v_add_f32_e32 v28, v30, v34
	v_add_f32_e32 v29, v31, v35
	v_add_f32_e32 v26, v26, v32
	v_add_f32_e32 v27, v27, v33
	v_mul_f32_e32 v28, 0xbfb8aa3b, v28
	v_mul_f32_e32 v26, 0xbfb8aa3b, v26
	v_mul_f32_e32 v27, 0xbfb8aa3b, v27
	v_mul_f32_e32 v29, 0xbfb8aa3b, v29
	v_exp_f32_e32 v26, v26
	v_exp_f32_e32 v27, v27
	v_exp_f32_e32 v28, v28
	v_exp_f32_e32 v29, v29
	v_add_f32_e32 v26, 1.0, v26
	v_add_f32_e32 v27, 1.0, v27
	v_add_f32_e32 v28, 1.0, v28
	v_add_f32_e32 v29, 1.0, v29
	v_rcp_f32_e32 v26, v26
	v_rcp_f32_e32 v27, v27
	v_rcp_f32_e32 v28, v28
	v_rcp_f32_e32 v29, v29
	v_mul_f32_e32 v26, 0xbf60028b, v26
	v_mul_f32_e32 v27, 0xbf60028b, v27
	v_mul_f32_e32 v28, 0xbf60028b, v28
	v_mul_f32_e32 v29, 0xbf60028b, v29
	v_exp_f32_e32 v26, v26
	v_exp_f32_e32 v27, v27
	v_exp_f32_e32 v28, v28
	v_exp_f32_e32 v29, v29
	v_lshl_add_u64 v[30:31], v[78:79], 0, v[180:181]
	global_store_dwordx4 v[30:31], v[26:29], off
	s_branch .LBB0_1482

; __device__ __forceinline__ f32x4 bf4(const u32x2 w) { return (f32x4){bflo(w.x), bfhi(w.x), bflo(w.y), bfhi(w.y)}; }
; __device__ __forceinline__ void scan_prep(const P& p, Frame& F) {
;     ...
;     for (int it = MP * 4 + gw; it < MT * 4; it += NGW) { const int m = it >> 2, h = 4 * (it & 3) + q, c0 = h * 64 + 4 * c;
;         const bool first = m < MP ? (m & (TP - 1)) == 0 : ((m - MP) & 3) == 0;
;         f32x4 pc[3], pp[3];
; #pragma unroll
;         for (int x = 0; x < 3; ++x) { const int col = x * 1024 + c0; pc[x] = bf4(*(const u32x2*)(PRW + (size_t)m * RWP + col));
;             if (!first) pp[x] = bf4(*(const u32x2*)(PRW + (size_t)(m - 1) * RWP + col));
;             else if (m < MP) pp[x] = (f32x4){0.f, 0.f, 0.f, 0.f};
;             else pp[x] = *(const f32x4*)(p.in[I_SSH] + (size_t)((m - MP) >> 2) * RWP + col); }
;         const f32x4 a = *(const f32x4*)(AA + (size_t)m * 1024 + c0), w = *(const f32x4*)(DEC + (size_t)m * 1024 + c0);
;         f32x4 xs[3];
; #pragma unroll
;         for (int x = 0; x < 3; ++x) xs[x] = pc[x] + (pp[x] - pc[x]) * *(const f32x4*)(mu + x * 1024 + c0);
;         const f32x4 kmod = xs[1] * (1.0f + (a - 1.0f) * *(const f32x4*)(p.in[I_KA] + c0)); const f32x4 kkr = xs[1] * *(const f32x4*)(p.in[I_KK] + c0);
;         const float nrm = sqrtf(red16((kkr.x * kkr.x + kkr.y * kkr.y) + (kkr.z * kkr.z + kkr.w * kkr.w))); const f32x4 kk = kkr * (1.0f / fmaxf(nrm, 1e-12f));
;         const f32x4 rk = *(const f32x4*)(p.in[I_RK] + c0); const f32x4 t3 = xs[0] * kmod * rk; const float cb = red16((t3.x + t3.y) + (t3.z + t3.w));
.LBB0_1604:
	v_readlane_b32 s40, v253, 6
	v_readlane_b32 s52, v253, 18
	v_readlane_b32 s53, v253, 19
	v_readlane_b32 s54, v253, 20
	v_readlane_b32 s55, v253, 21
	s_mov_b64 s[28:29], s[52:53]
	s_waitcnt vmcnt(2)
	v_lshlrev_b32_e32 v36, 16, v6
	v_and_b32_e32 v37, 0xffff0000, v6
	v_lshlrev_b32_e32 v34, 16, v7
	v_and_b32_e32 v35, 0xffff0000, v7
	v_lshlrev_b32_e32 v22, 2, v10
	s_mov_b64 s[30:31], s[54:55]
	v_sub_f32_e32 v51, v15, v37
	v_sub_f32_e32 v50, v14, v36
	v_sub_f32_e32 v53, v17, v35
	v_sub_f32_e32 v52, v16, v34
	global_load_dwordx4 v[14:17], v22, s[30:31]
	v_lshl_add_u64 v[42:43], s[30:31], 0, v[22:23]
	s_movk_i32 s5, 0x2000
	v_add_co_u32_e32 v42, vcc, s5, v42
	s_lshl_b64 s[6:7], s[10:11], 12
	s_nop 0
	v_addc_co_u32_e32 v43, vcc, 0, v43, vcc
	v_readlane_b32 s8, v254, 55
	v_readlane_b32 s41, v253, 7
	v_readlane_b32 s42, v253, 8
	v_readlane_b32 s43, v253, 9
	v_readlane_b32 s44, v253, 10
	v_readlane_b32 s45, v253, 11
	v_readlane_b32 s46, v253, 12
	v_readlane_b32 s47, v253, 13
	v_readlane_b32 s48, v253, 14
	v_readlane_b32 s49, v253, 15
	v_readlane_b32 s50, v253, 16
	v_readlane_b32 s51, v253, 17
	v_readlane_b32 s9, v254, 56
	s_add_u32 s8, s8, s6
	v_readlane_b32 s36, v253, 48
	s_waitcnt vmcnt(2)
	v_lshlrev_b32_e32 v38, 16, v8
	v_and_b32_e32 v39, 0xffff0000, v8
	v_lshlrev_b32_e32 v40, 16, v9
	v_and_b32_e32 v41, 0xffff0000, v9
	s_addc_u32 s9, s9, s7
	v_readlane_b32 s48, v253, 60
	v_readlane_b32 s49, v253, 61
	global_load_dwordx4 v[10:13], v22, s[8:9]
	v_sub_f32_e32 v21, v21, v41
	v_sub_f32_e32 v20, v20, v40
	v_sub_f32_e32 v19, v19, v39
	v_sub_f32_e32 v18, v18, v38
	v_readlane_b32 s50, v253, 62
	v_readlane_b32 s51, v253, 63
	s_mov_b64 s[20:21], s[48:49]
	s_add_u32 s6, s14, s6
	s_addc_u32 s7, s15, s7
	global_load_dwordx4 v[6:9], v22, s[6:7]
	v_readlane_b32 s46, v253, 58
	v_readlane_b32 s47, v253, 59
	s_mov_b64 s[22:23], s[50:51]
	s_mov_b64 s[6:7], -1
	s_and_b64 vcc, exec, s[16:17]
	v_readlane_b32 s37, v253, 49
	v_readlane_b32 s38, v253, 50
	v_readlane_b32 s39, v253, 51
	v_readlane_b32 s40, v253, 52
	v_readlane_b32 s41, v253, 53
	v_readlane_b32 s42, v253, 54
	v_readlane_b32 s43, v253, 55
	v_readlane_b32 s44, v253, 56
	v_readlane_b32 s45, v253, 57
	global_load_dwordx4 v[54:57], v22, s[22:23]
	s_waitcnt vmcnt(3)
	v_fma_f32 v34, v52, v16, v34
	v_fma_f32 v35, v53, v17, v35
	v_fma_f32 v36, v50, v14, v36
	v_fma_f32 v37, v51, v15, v37
	global_load_dwordx4 v[14:17], v[42:43], off offset:-4096
	s_waitcnt vmcnt(0)
	v_fma_f32 v38, v18, v14, v38
	v_fma_f32 v39, v19, v15, v39
	v_fma_f32 v50, v20, v16, v40
	v_fma_f32 v51, v21, v17, v41
	global_load_dwordx4 v[18:21], v22, s[20:21]
	global_load_dwordx4 v[14:17], v[42:43], off
	v_add_f32_e32 v40, -1.0, v12
	v_add_f32_e32 v41, -1.0, v13
	v_add_f32_e32 v42, -1.0, v10
	v_add_f32_e32 v43, -1.0, v11
	s_waitcnt vmcnt(1)
	v_fma_f32 v20, v40, v20, 1.0
	v_fma_f32 v21, v41, v21, 1.0
	v_fma_f32 v18, v42, v18, 1.0
	v_fma_f32 v19, v43, v19, 1.0
	global_load_dwordx4 v[40:43], v22, s[46:47]
	v_mul_f32_e32 v18, v38, v18
	v_mul_f32_e32 v19, v39, v19
	v_mul_f32_e32 v20, v50, v20
	v_mul_f32_e32 v21, v51, v21
	v_mul_f32_e32 v58, v36, v18
	v_mul_f32_e32 v59, v37, v19
	s_waitcnt vmcnt(0)
	v_mul_f32_e32 v40, v38, v40
	v_mul_f32_e32 v41, v39, v41
	v_mul_f32_e32 v38, v50, v42
	v_mul_f32_e32 v39, v51, v43
	v_mul_f32_e32 v42, v40, v40
	v_mul_f32_e32 v43, v41, v41
	v_mul_f32_e32 v50, v38, v38
	v_mul_f32_e32 v51, v39, v39
	v_mul_f32_e32 v54, v58, v54
	v_mul_f32_e32 v55, v59, v55
	v_pk_mov_b32 v[52:53], v[42:43], v[50:51] op_sel:[1,0]
	v_mov_b32_e32 v43, v51
	v_add_f32_e32 v42, v52, v42
	v_add_f32_e32 v43, v53, v43
	v_add_f32_e32 v22, v54, v55
	v_add_f32_e32 v42, v42, v43
	s_nop 1
	v_add_f32_dpp v42, v42, v42 quad_perm:[1,0,3,2] row_mask:0xf bank_mask:0xf bound_ctrl:1
	s_nop 1
	v_add_f32_dpp v42, v42, v42 quad_perm:[2,3,0,1] row_mask:0xf bank_mask:0xf bound_ctrl:1
	s_nop 1
	v_add_f32_dpp v51, v42, v42 row_half_mirror row_mask:0xf bank_mask:0xf bound_ctrl:1
	v_mul_f32_e32 v42, v34, v20
	v_mul_f32_e32 v43, v35, v21
	s_nop 0
	v_mul_f32_e32 v42, v42, v56
	v_mul_f32_e32 v43, v43, v57
	v_mov_b32_dpp v52, v51 row_mirror row_mask:0xf bank_mask:0xf bound_ctrl:1
	v_add_f32_e32 v42, v42, v43
	v_add_f32_e32 v22, v22, v42
	s_nop 1
	v_add_f32_dpp v22, v22, v22 quad_perm:[1,0,3,2] row_mask:0xf bank_mask:0xf bound_ctrl:1
	s_nop 1
	v_add_f32_dpp v22, v22, v22 quad_perm:[2,3,0,1] row_mask:0xf bank_mask:0xf bound_ctrl:1
	s_nop 1
	v_add_f32_dpp v49, v22, v22 row_half_mirror row_mask:0xf bank_mask:0xf bound_ctrl:1
	s_nop 1
	v_mov_b32_dpp v50, v49 row_mirror row_mask:0xf bank_mask:0xf bound_ctrl:1
	s_cbranch_vccz .LBB0_1606
	s_add_i32 s5, s2, 0x7fff0000
	s_and_b32 s5, s5, 0x7ffffff0
	v_or_b32_e32 v22, s5, v48
	v_lshl_add_u64 v[42:43], v[22:23], 2, v[30:31]
	s_mov_b64 s[6:7], 0

; __device__ __forceinline__ unsigned pk2(float lo, float hi) { const bfx2 b = __builtin_convertvector((f32x2){lo, hi}, bfx2); return __builtin_bit_cast(unsigned, b); }
; __device__ __forceinline__ void scan_prep(const P& p, Frame& F) {
;     ...
;         for (int x = 0; x < 3; ++x) xs[x] = pc[x] + (pp[x] - pc[x]) * *(const f32x4*)(mu + x * 1024 + c0);
;         const f32x4 kmod = xs[1] * (1.0f + (a - 1.0f) * *(const f32x4*)(p.in[I_KA] + c0)); const f32x4 kkr = xs[1] * *(const f32x4*)(p.in[I_KK] + c0);
;         const float nrm = sqrtf(red16((kkr.x * kkr.x + kkr.y * kkr.y) + (kkr.z * kkr.z + kkr.w * kkr.w))); const f32x4 kk = kkr * (1.0f / fmaxf(nrm, 1e-12f));
;         const f32x4 rk = *(const f32x4*)(p.in[I_RK] + c0); const f32x4 t3 = xs[0] * kmod * rk; const float cb = red16((t3.x + t3.y) + (t3.z + t3.w));
;         size_t sr; if (m < MP) sr = (size_t)((m >> 11) * RWH + h) * TP + (m & (TP - 1)); else { const int x = m - MP; sr = (size_t)NSEQ_P * TP + (size_t)((x >> 2) * RWH + h) * TS + (x & 3); }
;         bf16* o = OPSB + sr * 256 + 4 * c;
;         { const f32x4 na = -(kk * a); u32x2 u; u.x = pk2(kk.x, kk.y); u.y = pk2(kk.z, kk.w); *(u32x2*)o = u; u.x = pk2(na.x, na.y); u.y = pk2(na.z, na.w); *(u32x2*)(o + 64) = u;
;           u.x = pk2(kmod.x, kmod.y); u.y = pk2(kmod.z, kmod.w); *(u32x2*)(o + 128) = u; u.x = pk2(xs[0].x, xs[0].y); u.y = pk2(xs[0].z, xs[0].w); *(u32x2*)(o + 192) = u;
;           u.x = pk2(xs[2].x, xs[2].y); u.y = pk2(xs[2].z, xs[2].w); *(u32x2*)(VVB + sr * 64 + 4 * c) = u; }
;         *(f32x4*)(WQ + sr * 64 + 4 * c) = w;
;         if (c == 0) CB[(size_t)m * 16 + h] = cb; }
.LBB0_1608:
	v_lshlrev_b32_e32 v54, 16, v32
	v_and_b32_e32 v55, 0xffff0000, v32
	v_sub_f32_e32 v3, v3, v55
	v_sub_f32_e32 v2, v2, v54
	v_fma_f32 v2, v2, v14, v54
	v_fma_f32 v3, v3, v15, v55
	v_add_f32_e32 v14, v51, v52
	s_mov_b32 s6, 0xf800000
	v_cmp_gt_f32_e32 vcc, s6, v14
	v_mul_f32_e32 v15, 0x4f800000, v14
	v_lshlrev_b32_e32 v32, 16, v33
	v_cndmask_b32_e32 v14, v14, v15, vcc
	v_sqrt_f32_e32 v15, v14
	v_and_b32_e32 v33, 0xffff0000, v33
	v_sub_f32_e32 v5, v5, v33
	v_sub_f32_e32 v4, v4, v32
	v_fma_f32 v4, v4, v16, v32
	v_fma_f32 v5, v5, v17, v33
	v_add_u32_e32 v16, -1, v15
	v_fma_f32 v17, -v16, v15, v14
	v_cmp_ge_f32_e64 s[6:7], 0, v17
	v_add_u32_e32 v17, 1, v15
	s_and_b32 s5, s5, s10
	v_cndmask_b32_e64 v16, v15, v16, s[6:7]
	v_fma_f32 v15, -v17, v15, v14
	v_cmp_lt_f32_e64 s[6:7], 0, v15
	v_or_b32_e32 v42, s5, v42
	v_xor_b32_e32 v13, 0x80000000, v13
	v_cndmask_b32_e64 v15, v16, v17, s[6:7]
	v_mul_f32_e32 v16, 0x37800000, v15
	v_cndmask_b32_e32 v15, v15, v16, vcc
	v_cmp_class_f32_e32 vcc, v14, v46
	v_xor_b32_e32 v12, 0x80000000, v12
	v_cvt_pk_bf16_f32 v2, v2, v3
	v_cndmask_b32_e32 v14, v15, v14, vcc
	v_max_f32_e32 v14, 0x2b8cbccc, v14
	v_div_scale_f32 v15, s[6:7], v14, v14, 1.0
	v_rcp_f32_e32 v16, v15
	v_cvt_pk_bf16_f32 v3, v4, v5
	v_lshlrev_b64 v[4:5], 7, v[42:43]
	v_lshl_add_u64 v[4:5], v[26:27], 0, v[4:5]
	v_fma_f32 v17, -v15, v16, 1.0
	v_fmac_f32_e32 v16, v17, v16
	v_div_scale_f32 v17, vcc, 1.0, v14, 1.0
	v_mul_f32_e32 v22, v17, v16
	v_fma_f32 v32, -v15, v22, v17
	v_fmac_f32_e32 v22, v32, v16
	v_fma_f32 v15, -v15, v22, v17
	v_div_fmas_f32 v15, v15, v16, v22
	v_div_fixup_f32 v14, v15, v14, 1.0
	v_mul_f32_e32 v16, v40, v14
	v_mul_f32_e32 v17, v41, v14
	v_mul_f32_e32 v15, v39, v14
	v_mul_f32_e32 v14, v38, v14
	v_lshlrev_b64 v[32:33], 9, v[42:43]
	v_mul_f32_e32 v12, v14, v12
	v_mul_f32_e32 v13, v15, v13
	v_mul_f32_e64 v10, v16, -v10
	v_mul_f32_e64 v11, v17, -v11
	v_lshl_add_u64 v[32:33], v[24:25], 0, v[32:33]
	v_cvt_pk_bf16_f32 v10, v10, v11
	v_cvt_pk_bf16_f32 v11, v12, v13
	global_store_dwordx2 v[32:33], v[10:11], off offset:128
	v_cvt_pk_bf16_f32 v10, v18, v19
	v_cvt_pk_bf16_f32 v11, v20, v21
	v_cvt_pk_bf16_f32 v16, v16, v17
	v_cvt_pk_bf16_f32 v17, v14, v15
	global_store_dwordx2 v[32:33], v[10:11], off offset:256
	v_cvt_pk_bf16_f32 v10, v36, v37
	v_cvt_pk_bf16_f32 v11, v34, v35
	global_store_dwordx2 v[32:33], v[16:17], off
	global_store_dwordx2 v[32:33], v[10:11], off offset:384
	global_store_dwordx2 v[4:5], v[2:3], off
	v_lshlrev_b64 v[2:3], 8, v[42:43]
	v_lshl_add_u64 v[2:3], v[28:29], 0, v[2:3]
	global_store_dwordx4 v[2:3], v[6:9], off
	s_and_saveexec_b64 s[6:7], s[0:1]
	s_cbranch_execz .LBB0_1582
	s_lshl_b64 s[8:9], s[10:11], 6
	s_add_u32 s8, s74, s8
	v_add_f32_e32 v2, v49, v50
	s_addc_u32 s9, s75, s9
	v_lshlrev_b32_e32 v3, 2, v48
	global_store_dword v3, v2, s[8:9]
	s_branch .LBB0_1582

; #define LAS __attribute__((address_space(3)))
; __device__ __forceinline__ void chunk_pre(const P& p, Frame& F, int task, int next_task, u32x4& icr, u32x4& ick, u32x4& icv, u32x4& ipr, u32x4& ipk, u32x4& ipv, f32x4& ia0, f32x4& ia1, f32x4& iw0, f32x4& iw1, int& ptag0, int& ptag1) {
;     ...
;       { const u32x4 cr = icr, ck = ick, cv = icv; u32x4 pr = ipr, pk = ipk, pv = ipv; if (first) { pr = (u32x4){0u, 0u, 0u, 0u}; pk = pr; pv = pr; }
;         const unsigned cw[3][4] = {{cr.x, cr.y, cr.z, cr.w}, {ck.x, ck.y, ck.z, ck.w}, {cv.x, cv.y, cv.z, cv.w}}, pw[3][4] = {{pr.x, pr.y, pr.z, pr.w}, {pk.x, pk.y, pk.z, pk.w}, {pv.x, pv.y, pv.z, pv.w}};
;         float mr[8], mk[8], mv[8];
;         { const f32x4 a0 = *(const LAS f32x4*)(PR), a1 = *(const LAS f32x4*)(PR + 4), b0 = *(const LAS f32x4*)(PR + 64), b1 = *(const LAS f32x4*)(PR + 68), d0 = *(const LAS f32x4*)(PR + 128), d1 = *(const LAS f32x4*)(PR + 132);
; #pragma unroll
;           for (int e = 0; e < 4; ++e) { mr[e] = a0[e]; mr[4 + e] = a1[e]; mk[e] = b0[e]; mk[4 + e] = b1[e]; mv[e] = d0[e]; mv[4 + e] = d1[e]; } }
; #pragma unroll
;         for (int e = 0; e < 8; ++e) { const int wi = e >> 1; const bool hi = e & 1;
;             const float c_r = hi ? bfhi(cw[0][wi]) : bflo(cw[0][wi]), c_k = hi ? bfhi(cw[1][wi]) : bflo(cw[1][wi]), c_v = hi ? bfhi(cw[2][wi]) : bflo(cw[2][wi]);
;             const float p_r = hi ? bfhi(pw[0][wi]) : bflo(pw[0][wi]), p_k = hi ? bfhi(pw[1][wi]) : bflo(pw[1][wi]), p_v = hi ? bfhi(pw[2][wi]) : bflo(pw[2][wi]);
;             xr[e] = c_r + (p_r - c_r) * mr[e]; xk[e] = c_k + (p_k - c_k) * mk[e]; xv[e] = c_v + (p_v - c_v) * mv[e]; }
;         { const f32x4 a0 = ia0, a1 = ia1, w0 = iw0, w1 = iw1;
; #pragma unroll
;           for (int e = 0; e < 4; ++e) { av[e] = a0[e]; av[4 + e] = a1[e]; wv[e] = w0[e]; wv[4 + e] = w1[e]; } } }
;       CKIN_LOAD(i, next_task);
;       float kmod[8], kk[8]; float n2 = 0.f, cbp = 0.f;
;       { float ka_[8], kk_[8], rk_[8];
;         { const f32x4 a0 = *(const LAS f32x4*)(PR + 192), a1 = *(const LAS f32x4*)(PR + 196), b0 = *(const LAS f32x4*)(PR + 256), b1 = *(const LAS f32x4*)(PR + 260), d0 = *(const LAS f32x4*)(PR + 320), d1 = *(const LAS f32x4*)(PR + 324);
; #pragma unroll
;           for (int e = 0; e < 4; ++e) { ka_[e] = a0[e]; ka_[4 + e] = a1[e]; kk_[e] = b0[e]; kk_[4 + e] = b1[e]; rk_[e] = d0[e]; rk_[4 + e] = d1[e]; } }
; #pragma unroll
.LBB0_1627:
	s_or_b64 exec, exec, s[20:21]
	v_cndmask_b32_e64 v35, v25, 0, s[18:19]
	v_cndmask_b32_e64 v25, v22, 0, s[18:19]
	v_cndmask_b32_e64 v104, v24, 0, s[18:19]
	v_cndmask_b32_e64 v105, v23, 0, s[18:19]
	v_lshlrev_b32_e32 v22, 16, v10
	v_and_b32_e32 v23, 0xffff0000, v10
	v_lshlrev_b32_e32 v24, 16, v25
	v_and_b32_e32 v25, 0xffff0000, v25
	v_sub_f32_e32 v24, v24, v22
	v_sub_f32_e32 v25, v25, v23
	v_lshlrev_b32_e32 v10, 16, v11
	v_fma_f32 v22, v24, v30, v22
	v_fma_f32 v23, v25, v31, v23
	v_and_b32_e32 v11, 0xffff0000, v11
	v_lshlrev_b32_e32 v24, 16, v105
	v_and_b32_e32 v25, 0xffff0000, v105
	v_sub_f32_e32 v24, v24, v10
	v_sub_f32_e32 v25, v25, v11
	v_lshlrev_b32_e32 v30, 16, v104
	v_fma_f32 v24, v24, v32, v10
	v_fma_f32 v25, v25, v33, v11
	v_lshlrev_b32_e32 v10, 16, v12
	v_and_b32_e32 v11, 0xffff0000, v12
	v_and_b32_e32 v31, 0xffff0000, v104
	v_sub_f32_e32 v30, v30, v10
	v_sub_f32_e32 v31, v31, v11
	s_ashr_i32 s7, s6, 31
	v_fma_f32 v26, v30, v26, v10
	v_fma_f32 v27, v31, v27, v11
	v_lshlrev_b32_e32 v10, 16, v13
	v_and_b32_e32 v11, 0xffff0000, v13
	v_lshlrev_b32_e32 v12, 16, v35
	v_and_b32_e32 v13, 0xffff0000, v35
	s_lshl_b64 s[6:7], s[6:7], 11
	v_sub_f32_e32 v12, v12, v10
	v_sub_f32_e32 v13, v13, v11
	s_or_b32 s6, s6, s22
	v_ashrrev_i32_e32 v35, 31, v34
	v_fma_f32 v28, v12, v28, v10
	v_fma_f32 v29, v13, v29, v11
	v_cvt_pk_bf16_f32 v10, v22, v23
	v_lshl_add_u64 v[22:23], s[6:7], 0, v[34:35]
	v_lshlrev_b32_e32 v103, 3, v130
	v_lshlrev_b64 v[22:23], 7, v[22:23]
	v_lshl_add_u64 v[22:23], s[8:9], 0, v[22:23]
	v_lshlrev_b32_e32 v114, 1, v103
	v_cvt_pk_bf16_f32 v11, v24, v25
	v_cvt_pk_bf16_f32 v12, v26, v27
	v_cvt_pk_bf16_f32 v13, v28, v29
	v_lshl_add_u64 v[22:23], v[22:23], 0, v[114:115]
	global_store_dwordx4 v[22:23], v[10:13], off
	s_waitcnt vmcnt(11)
	v_log_f32_e32 v22, v18
	v_log_f32_e32 v23, v19
	v_log_f32_e32 v26, v14
	v_log_f32_e32 v27, v15
	v_mov_b32_dpp v14, v22 row_shr:8 row_mask:0xf bank_mask:0xf bound_ctrl:1
	v_mov_b32_dpp v15, v23 row_shr:8 row_mask:0xf bank_mask:0xf bound_ctrl:1
	v_and_b32_e32 v32, 4, v34
	v_lshlrev_b32_e32 v33, 2, v130
	v_lshl_or_b32 v35, v32, 5, v33
	v_add_f32_e32 v14, v22, v14
	v_add_f32_e32 v15, v23, v15
	ds_bpermute_b32 v30, v35, v15 offset:32
	ds_bpermute_b32 v104, v35, v14 offset:32
	v_log_f32_e32 v24, v20
	v_log_f32_e32 v25, v21
	v_and_b32_e32 v31, 16, v129
	v_cmp_eq_u32_e32 vcc, 0, v31
	v_log_f32_e32 v28, v16
	v_log_f32_e32 v29, v17
	s_waitcnt lgkmcnt(1)
	v_cndmask_b32_e64 v31, v30, 0, vcc
	s_waitcnt lgkmcnt(0)
	v_cndmask_b32_e64 v30, v104, 0, vcc
	v_mov_b32_dpp v16, v24 row_shr:8 row_mask:0xf bank_mask:0xf bound_ctrl:1
	v_mov_b32_dpp v17, v25 row_shr:8 row_mask:0xf bank_mask:0xf bound_ctrl:1
	v_add_f32_e32 v14, v14, v30
	v_add_f32_e32 v15, v15, v31
	ds_bpermute_b32 v30, v33, v14 offset:96
	ds_bpermute_b32 v31, v33, v15 offset:96
	v_add_f32_e32 v16, v24, v16
	v_add_f32_e32 v17, v25, v17
	ds_bpermute_b32 v104, v35, v16 offset:32
	ds_bpermute_b32 v105, v35, v17 offset:32
	v_cmp_eq_u32_e64 s[6:7], 0, v32
	v_mov_b32_dpp v18, v26 row_shr:8 row_mask:0xf bank_mask:0xf bound_ctrl:1
	v_mov_b32_dpp v19, v27 row_shr:8 row_mask:0xf bank_mask:0xf bound_ctrl:1
	s_waitcnt lgkmcnt(2)
	v_cndmask_b32_e64 v31, v31, 0, s[6:7]
	v_cndmask_b32_e64 v30, v30, 0, s[6:7]
	v_add_f32_e32 v14, v14, v30
	v_add_f32_e32 v15, v15, v31
	s_waitcnt lgkmcnt(0)
	v_cndmask_b32_e64 v31, v105, 0, vcc
	v_cndmask_b32_e64 v30, v104, 0, vcc
	v_add_f32_e32 v16, v16, v30
	v_add_f32_e32 v17, v17, v31
	ds_bpermute_b32 v30, v33, v17 offset:96
	ds_bpermute_b32 v32, v33, v16 offset:96
	v_mov_b32_dpp v20, v28 row_shr:8 row_mask:0xf bank_mask:0xf bound_ctrl:1
	v_mov_b32_dpp v21, v29 row_shr:8 row_mask:0xf bank_mask:0xf bound_ctrl:1
	v_add_f32_e32 v18, v26, v18
	v_add_f32_e32 v19, v27, v19
	ds_bpermute_b32 v104, v35, v19 offset:32
	ds_bpermute_b32 v105, v35, v18 offset:32
	v_add_f32_e32 v20, v28, v20
	v_add_f32_e32 v21, v29, v21
	s_waitcnt lgkmcnt(3)
	v_cndmask_b32_e64 v31, v30, 0, s[6:7]
	s_waitcnt lgkmcnt(2)
	v_cndmask_b32_e64 v30, v32, 0, s[6:7]
	ds_bpermute_b32 v32, v35, v21 offset:32
	ds_bpermute_b32 v35, v35, v20 offset:32
	v_add_f32_e32 v16, v16, v30
	v_add_f32_e32 v17, v17, v31
	s_waitcnt lgkmcnt(3)
	v_cndmask_b32_e64 v31, v104, 0, vcc
	s_waitcnt lgkmcnt(2)
	v_cndmask_b32_e64 v30, v105, 0, vcc
	v_add_f32_e32 v18, v18, v30
	v_add_f32_e32 v19, v19, v31
	s_waitcnt lgkmcnt(1)
	v_cndmask_b32_e64 v31, v32, 0, vcc
	s_waitcnt lgkmcnt(0)
	v_cndmask_b32_e64 v30, v35, 0, vcc
	ds_bpermute_b32 v104, v33, v18 offset:96
	ds_bpermute_b32 v105, v33, v19 offset:96
	v_add_f32_e32 v20, v20, v30
	v_add_f32_e32 v21, v21, v31
	ds_bpermute_b32 v32, v33, v21 offset:96
	ds_bpermute_b32 v33, v33, v20 offset:96
	s_waitcnt lgkmcnt(3)
	v_cndmask_b32_e64 v30, v104, 0, s[6:7]
	s_waitcnt lgkmcnt(2)
	v_cndmask_b32_e64 v31, v105, 0, s[6:7]
	v_and_b32_e32 v92, 7, v34
	v_add_f32_e32 v18, v18, v30
	v_add_f32_e32 v19, v19, v31
	s_waitcnt lgkmcnt(1)
	v_cndmask_b32_e64 v31, v32, 0, s[6:7]
	s_waitcnt lgkmcnt(0)
	v_cndmask_b32_e64 v30, v33, 0, s[6:7]
	v_add_f32_e32 v20, v20, v30
	v_add_f32_e32 v21, v21, v31
	v_cmp_eq_u32_e32 vcc, 7, v92
	s_and_saveexec_b64 s[6:7], vcc
	s_cbranch_execz .LBB0_1629
	s_lshl_b32 s16, s56, 8
	s_add_i32 s16, s16, 0
	v_lshl_add_u32 v30, v103, 2, s16
	v_add_u32_e32 v30, 0x20100, v30
	ds_write_b128 v30, v[14:17]
	ds_write_b128 v30, v[18:21] offset:16
.LBB0_1629:
	s_or_b64 exec, exec, s[6:7]
	s_add_i32 s6, 0, 0x20100
	s_cmp_lt_i32 s56, 1
	v_lshl_add_u32 v30, v103, 2, s6
	s_waitcnt lgkmcnt(0)
	s_barrier
	s_cbranch_scc1 .LBB0_1631
	ds_read_b128 v[104:107], v30
	ds_read_b128 v[108:111], v30 offset:16
	s_waitcnt lgkmcnt(1)
	v_add_f32_e32 v14, v14, v104
	v_add_f32_e32 v15, v15, v105
	v_add_f32_e32 v16, v16, v106
	v_add_f32_e32 v17, v17, v107
	s_waitcnt lgkmcnt(0)
	v_add_f32_e32 v18, v18, v108
	v_add_f32_e32 v19, v19, v109
	v_add_f32_e32 v20, v20, v110
	v_add_f32_e32 v21, v21, v111
.LBB0_1631:
	s_cmp_lt_i32 s56, 2
	s_cbranch_scc1 .LBB0_1637
	ds_read_b128 v[104:107], v30 offset:272
	ds_read_b128 v[108:111], v30 offset:256
	s_waitcnt lgkmcnt(1)
	v_add_f32_e32 v20, v20, v106
	v_add_f32_e32 v21, v21, v107
	s_waitcnt lgkmcnt(0)
	v_add_f32_e32 v16, v16, v110
	v_add_f32_e32 v17, v17, v111
	v_add_f32_e32 v18, v18, v104
	v_add_f32_e32 v19, v19, v105
	v_add_f32_e32 v14, v14, v108
	v_add_f32_e32 v15, v15, v109
	s_cmp_lt_i32 s56, 3
	s_cbranch_scc0 .LBB0_1638

; #define LAS __attribute__((address_space(3)))
; __device__ __forceinline__ void chunk_pre(const P& p, Frame& F, int task, int next_task, u32x4& icr, u32x4& ick, u32x4& icv, u32x4& ipr, u32x4& ipk, u32x4& ipv, f32x4& ia0, f32x4& ia1, f32x4& iw0, f32x4& iw1, int& ptag0, int& ptag1) {
;     ...
; #pragma unroll
;       for (int q = 0; q < 7; ++q) if (q < wave) { const f32x4 s0 = *(const LAS f32x4*)(SEG + q * 64 + 8 * jg), s1 = *(const LAS f32x4*)(SEG + q * 64 + 8 * jg + 4);
; #pragma unroll
;           for (int e = 0; e < 4; ++e) { lx[e] += s0[e]; lx[4 + e] += s1[e]; } }
.LBB0_1634:
	ds_read_b128 v[104:107], v30 offset:784
	ds_read_b128 v[108:111], v30 offset:768
	s_waitcnt lgkmcnt(1)
	v_add_f32_e32 v20, v20, v106
	v_add_f32_e32 v21, v21, v107
	s_waitcnt lgkmcnt(0)
	v_add_f32_e32 v16, v16, v110
	v_add_f32_e32 v17, v17, v111
	v_add_f32_e32 v18, v18, v104
	v_add_f32_e32 v19, v19, v105
	v_add_f32_e32 v14, v14, v108
	v_add_f32_e32 v15, v15, v109
	s_cmp_lt_i32 s56, 5
	s_cbranch_scc0 .LBB0_1640

; #define LAS __attribute__((address_space(3)))
; __device__ __forceinline__ void chunk_pre(const P& p, Frame& F, int task, int next_task, u32x4& icr, u32x4& ick, u32x4& icv, u32x4& ipr, u32x4& ipk, u32x4& ipv, f32x4& ia0, f32x4& ia1, f32x4& iw0, f32x4& iw1, int& ptag0, int& ptag1) {
;     ...
; #pragma unroll
;       for (int q = 0; q < 7; ++q) if (q < wave) { const f32x4 s0 = *(const LAS f32x4*)(SEG + q * 64 + 8 * jg), s1 = *(const LAS f32x4*)(SEG + q * 64 + 8 * jg + 4);
; #pragma unroll
;           for (int e = 0; e < 4; ++e) { lx[e] += s0[e]; lx[4 + e] += s1[e]; } }
.LBB0_1636:
	ds_read_b128 v[104:107], v30 offset:1296
	ds_read_b128 v[108:111], v30 offset:1280
	s_waitcnt lgkmcnt(1)
	v_add_f32_e32 v20, v20, v106
	v_add_f32_e32 v21, v21, v107
	s_waitcnt lgkmcnt(0)
	v_add_f32_e32 v16, v16, v110
	v_add_f32_e32 v17, v17, v111
	v_add_f32_e32 v18, v18, v104
	v_add_f32_e32 v19, v19, v105
	v_add_f32_e32 v14, v14, v108
	v_add_f32_e32 v15, v15, v109
	s_cmp_lt_i32 s56, 7
	s_cbranch_scc0 .LBB0_1642
	s_branch .LBB0_1643

; #define LAS __attribute__((address_space(3)))
; __device__ __forceinline__ void chunk_pre(const P& p, Frame& F, int task, int next_task, u32x4& icr, u32x4& ick, u32x4& icv, u32x4& ipr, u32x4& ipk, u32x4& ipv, f32x4& ia0, f32x4& ia1, f32x4& iw0, f32x4& iw1, int& ptag0, int& ptag1) {
;     ...
; #pragma unroll
;       for (int q = 0; q < 7; ++q) if (q < wave) { const f32x4 s0 = *(const LAS f32x4*)(SEG + q * 64 + 8 * jg), s1 = *(const LAS f32x4*)(SEG + q * 64 + 8 * jg + 4);
; #pragma unroll
;           for (int e = 0; e < 4; ++e) { lx[e] += s0[e]; lx[4 + e] += s1[e]; } }
.LBB0_1638:
	ds_read_b128 v[104:107], v30 offset:528
	ds_read_b128 v[108:111], v30 offset:512
	s_waitcnt lgkmcnt(1)
	v_add_f32_e32 v20, v20, v106
	v_add_f32_e32 v21, v21, v107
	s_waitcnt lgkmcnt(0)
	v_add_f32_e32 v16, v16, v110
	v_add_f32_e32 v17, v17, v111
	v_add_f32_e32 v18, v18, v104
	v_add_f32_e32 v19, v19, v105
	v_add_f32_e32 v14, v14, v108
	v_add_f32_e32 v15, v15, v109
	s_cmp_lt_i32 s56, 4
	s_cbranch_scc0 .LBB0_1634

; #define LAS __attribute__((address_space(3)))
; __device__ __forceinline__ void chunk_pre(const P& p, Frame& F, int task, int next_task, u32x4& icr, u32x4& ick, u32x4& icv, u32x4& ipr, u32x4& ipk, u32x4& ipv, f32x4& ia0, f32x4& ia1, f32x4& iw0, f32x4& iw1, int& ptag0, int& ptag1) {
;     ...
; #pragma unroll
;       for (int q = 0; q < 7; ++q) if (q < wave) { const f32x4 s0 = *(const LAS f32x4*)(SEG + q * 64 + 8 * jg), s1 = *(const LAS f32x4*)(SEG + q * 64 + 8 * jg + 4);
; #pragma unroll
;           for (int e = 0; e < 4; ++e) { lx[e] += s0[e]; lx[4 + e] += s1[e]; } }
.LBB0_1640:
	ds_read_b128 v[104:107], v30 offset:1040
	ds_read_b128 v[108:111], v30 offset:1024
	s_waitcnt lgkmcnt(1)
	v_add_f32_e32 v20, v20, v106
	v_add_f32_e32 v21, v21, v107
	s_waitcnt lgkmcnt(0)
	v_add_f32_e32 v16, v16, v110
	v_add_f32_e32 v17, v17, v111
	v_add_f32_e32 v18, v18, v104
	v_add_f32_e32 v19, v19, v105
	v_add_f32_e32 v14, v14, v108
	v_add_f32_e32 v15, v15, v109
	s_cmp_lt_i32 s56, 6
	s_cbranch_scc0 .LBB0_1636

; #define LAS __attribute__((address_space(3)))
; __device__ __forceinline__ void chunk_pre(const P& p, Frame& F, int task, int next_task, u32x4& icr, u32x4& ick, u32x4& icv, u32x4& ipr, u32x4& ipk, u32x4& ipv, f32x4& ia0, f32x4& ia1, f32x4& iw0, f32x4& iw1, int& ptag0, int& ptag1) {
;     ...
; #pragma unroll
;       for (int q = 0; q < 7; ++q) if (q < wave) { const f32x4 s0 = *(const LAS f32x4*)(SEG + q * 64 + 8 * jg), s1 = *(const LAS f32x4*)(SEG + q * 64 + 8 * jg + 4);
; #pragma unroll
;           for (int e = 0; e < 4; ++e) { lx[e] += s0[e]; lx[4 + e] += s1[e]; } }
.LBB0_1642:
	ds_read_b128 v[104:107], v30 offset:1552
	ds_read_b128 v[30:33], v30 offset:1536
	s_waitcnt lgkmcnt(1)
	v_add_f32_e32 v20, v20, v106
	v_add_f32_e32 v21, v21, v107
	s_waitcnt lgkmcnt(0)
	v_add_f32_e32 v16, v16, v32
	v_add_f32_e32 v17, v17, v33
	v_add_f32_e32 v18, v18, v104
	v_add_f32_e32 v19, v19, v105
	v_add_f32_e32 v14, v14, v30
	v_add_f32_e32 v15, v15, v31

; #define LAS __attribute__((address_space(3)))
; __device__ __forceinline__ void chunk_pre(const P& p, Frame& F, int task, int next_task, u32x4& icr, u32x4& ick, u32x4& icv, u32x4& ipr, u32x4& ipk, u32x4& ipv, f32x4& ia0, f32x4& ia1, f32x4& iw0, f32x4& iw1, int& ptag0, int& ptag1) {
;     ...
;       const float inrm = 1.0f / fmaxf(sqrtf(red8(n2)), 1e-12f); const float cb = red8(cbp);
;       if (jg == 0) CB[(size_t)m * 16 + h] = cb;
;       { u32x4 o; o.x = pk2(xv[0], xv[1]); o.y = pk2(xv[2], xv[3]); o.z = pk2(xv[4], xv[5]); o.w = pk2(xv[6], xv[7]); *(u32x4*)(VVB + ((size_t)s * TP + 64 * c + t) * 64 + 8 * jg) = o; }
;       float lw[8], lx[8];
; #pragma unroll
;       for (int e = 0; e < 8; ++e) { lw[e] = __log2f(wv[e]); lx[e] = lw[e]; }
; #pragma unroll
;       for (int e = 0; e < 8; ++e) lx[e] += __builtin_bit_cast(float, __builtin_amdgcn_update_dpp(0, __builtin_bit_cast(int, lx[e]), 0x118, 0xF, 0xF, true));
;       { const int src2 = (jg + 8 * ((tl & 4) | 1)) << 2; const bool add2 = (tl & 2) != 0;
; #pragma unroll
;         for (int e = 0; e < 8; ++e) { const float y = __builtin_bit_cast(float, __builtin_amdgcn_ds_bpermute(src2, __builtin_bit_cast(int, lx[e]))); lx[e] += add2 ? y : 0.f; } }
;       { const int src3 = (jg + 24) << 2; const bool add3 = (tl & 4) != 0;
; #pragma unroll
;         for (int e = 0; e < 8; ++e) { const float y = __builtin_bit_cast(float, __builtin_amdgcn_ds_bpermute(src3, __builtin_bit_cast(int, lx[e]))); lx[e] += add3 ? y : 0.f; } }
;       LAS float* SEG = (LAS float*)(L + CK_GC + 256);
;       if (tl == 7) { *(LAS f32x4*)(SEG + wave * 64 + 8 * jg) = (f32x4){lx[0], lx[1], lx[2], lx[3]}; *(LAS f32x4*)(SEG + wave * 64 + 8 * jg + 4) = (f32x4){lx[4], lx[5], lx[6], lx[7]}; }
;       __syncthreads();
; #pragma unroll
;       for (int q = 0; q < 7; ++q) if (q < wave) { const f32x4 s0 = *(const LAS f32x4*)(SEG + q * 64 + 8 * jg), s1 = *(const LAS f32x4*)(SEG + q * 64 + 8 * jg + 4);
; #pragma unroll
;           for (int e = 0; e < 4; ++e) { lx[e] += s0[e]; lx[4 + e] += s1[e]; } }
;       float ka[8], bt[8], kt[8], rt[8];
; #pragma unroll
;       for (int e = 0; e < 8; ++e) { const float lt = lx[e], lp = lt - lw[e];
;           const float gt = __builtin_amdgcn_exp2f(lt), gp = __builtin_amdgcn_exp2f(lp), ig = __builtin_amdgcn_exp2f(-lt); const float kap = kk[e] * inrm;
.LBB0_1659:
	s_or_b64 exec, exec, s[6:7]
	v_add_f32_e32 v101, v101, v102
	s_mov_b32 s6, 0xf800000
	v_cmp_gt_f32_e32 vcc, s6, v101
	v_mul_f32_e32 v102, 0x4f800000, v101
	v_sub_f32_e32 v25, v17, v25
	v_cndmask_b32_e32 v101, v101, v102, vcc
	v_sqrt_f32_e32 v102, v101
	v_exp_f32_e32 v25, v25
	v_exp_f32_e64 v17, -v17
	v_mul_f32_e32 v35, v40, v35
	v_add_u32_e32 v105, -1, v102
	v_fma_f32 v107, -v105, v102, v101
	v_cmp_ge_f32_e64 s[6:7], 0, v107
	v_add_u32_e32 v107, 1, v102
	v_sub_f32_e32 v29, v21, v29
	v_cndmask_b32_e64 v105, v102, v105, s[6:7]
	v_fma_f32 v102, -v107, v102, v101
	v_cmp_lt_f32_e64 s[6:7], 0, v102
	v_sub_f32_e32 v28, v20, v28
	v_sub_f32_e32 v27, v19, v27
	v_cndmask_b32_e64 v102, v105, v107, s[6:7]
	v_mul_f32_e32 v105, 0x37800000, v102
	v_cndmask_b32_e32 v102, v102, v105, vcc
	v_cmp_class_f32_e32 vcc, v101, v127
	v_sub_f32_e32 v26, v18, v26
	v_exp_f32_e32 v29, v29
	v_cndmask_b32_e32 v101, v102, v101, vcc
	v_max_f32_e32 v101, 0x2b8cbccc, v101
	v_div_scale_f32 v102, s[6:7], v101, v101, 1.0
	v_rcp_f32_e32 v105, v102
	v_exp_f32_e32 v28, v28
	v_exp_f32_e32 v27, v27
	v_exp_f32_e32 v26, v26
	v_fma_f32 v107, -v102, v105, 1.0
	v_fmac_f32_e32 v105, v107, v105
	v_div_scale_f32 v107, vcc, 1.0, v101, 1.0
	v_mul_f32_e32 v108, v107, v105
	v_fma_f32 v109, -v102, v108, v107
	v_fmac_f32_e32 v108, v109, v105
	v_fma_f32 v102, -v102, v108, v107
	v_div_fmas_f32 v102, v102, v105, v108
	v_div_fixup_f32 v101, v102, v101, 1.0
	v_mul_f32_e32 v40, v91, v101
	v_mul_f32_e32 v5, v5, v40
	v_mul_f32_e32 v25, v40, v25
	v_mul_f32_e32 v40, v5, v17
	v_sub_f32_e32 v5, v16, v24
	v_exp_f32_e32 v5, v5
	v_exp_f32_e64 v16, -v16
	v_mul_f32_e32 v24, v49, v101
	v_mul_f32_e32 v4, v4, v24
	v_mul_f32_e32 v5, v24, v5
	v_mul_f32_e32 v24, v4, v16
	v_sub_f32_e32 v4, v15, v23
	v_exp_f32_e32 v4, v4
	v_exp_f32_e64 v15, -v15
	v_mul_f32_e32 v23, v46, v101
	v_mul_f32_e32 v3, v3, v23
	v_mul_f32_e32 v4, v23, v4
	v_mul_f32_e32 v23, v3, v15
	v_sub_f32_e32 v3, v14, v22
	v_exp_f32_e32 v3, v3
	v_exp_f32_e64 v14, -v14
	v_exp_f32_e64 v21, -v21
	v_exp_f32_e64 v20, -v20
	v_exp_f32_e64 v19, -v19
	v_exp_f32_e64 v18, -v18
	v_mul_f32_e32 v22, v43, v101
	v_mul_f32_e32 v2, v2, v22
	v_mul_f32_e32 v100, v100, v101
	v_mul_f32_e32 v98, v98, v101
	v_mul_f32_e32 v96, v96, v101
	v_mul_f32_e32 v94, v94, v101
	v_mul_f32_e32 v3, v22, v3
	v_mul_f32_e32 v22, v2, v14
	v_lshlrev_b32_e32 v2, 7, v34
	v_xor_b32_e32 v34, v92, v130
	v_mul_f32_e32 v29, v100, v29
	v_mul_f32_e32 v9, v9, v100
	v_mul_f32_e32 v28, v98, v28
	v_mul_f32_e32 v8, v8, v98
	v_mul_f32_e32 v27, v96, v27
	v_mul_f32_e32 v7, v7, v96
	v_mul_f32_e32 v26, v94, v26
	v_mul_f32_e32 v6, v6, v94
	v_lshl_or_b32 v34, v34, 4, v2
	v_mul_f32_e32 v9, v9, v21
	v_mul_f32_e32 v8, v8, v20
	v_mul_f32_e32 v7, v7, v19
	v_mul_f32_e32 v6, v6, v18
	v_cvt_pk_bf16_f32 v2, v3, v4
	v_cvt_pk_bf16_f32 v3, v5, v25
	v_cvt_pk_bf16_f32 v4, v26, v27
	v_cvt_pk_bf16_f32 v5, v28, v29
	v_add_u32_e32 v132, 0, v34
	v_mul_f32_e32 v21, v99, v21
	v_mul_f32_e32 v20, v97, v20
	v_mul_f32_e32 v19, v95, v19
	v_mul_f32_e32 v18, v93, v18
	v_mul_f32_e32 v17, v90, v17
	v_mul_f32_e32 v16, v48, v16
	v_mul_f32_e32 v15, v45, v15
	v_mul_f32_e32 v14, v42, v14
	ds_write_b128 v132, v[2:5]
	v_cvt_pk_bf16_f32 v2, v22, v23
	v_cvt_pk_bf16_f32 v3, v24, v40
	v_cvt_pk_bf16_f32 v4, v6, v7
	v_cvt_pk_bf16_f32 v5, v8, v9
	v_mul_f32_e32 v47, v47, v106
	v_mul_f32_e32 v44, v44, v104
	v_mul_f32_e32 v41, v41, v103
	v_mul_f32_e32 v33, v39, v33
	v_mul_f32_e32 v32, v38, v32
	v_mul_f32_e32 v31, v37, v31
	v_mul_f32_e32 v30, v36, v30
	ds_write_b128 v132, v[2:5] offset:8192
	v_cvt_pk_bf16_f32 v2, v14, v15
	v_cvt_pk_bf16_f32 v3, v16, v17
	v_cvt_pk_bf16_f32 v4, v18, v19
	v_cvt_pk_bf16_f32 v5, v20, v21
	ds_write_b128 v132, v[2:5] offset:16384
	v_cvt_pk_bf16_f32 v2, v30, v31
	v_cvt_pk_bf16_f32 v3, v32, v33
	v_cvt_pk_bf16_f32 v4, v35, v41
	v_cvt_pk_bf16_f32 v5, v44, v47
	v_lshrrev_b32_e32 v133, 5, v131
	ds_write_b128 v132, v[2:5] offset:24576
	v_add_u32_e32 v2, 0x1e000, v132
	s_lshr_b32 s57, s56, 1
	s_and_b32 s19, s56, 1
	ds_write_b128 v2, v[10:13]
	v_xor_b32_e32 v2, v133, v130
	s_cmp_gt_u32 s56, 3
	v_lshlrev_b32_e32 v138, 4, v2
	v_bitop3_b32 v2, v133, v130, 2 bitop3:0x36
	v_and_b32_e32 v159, 31, v129
	s_cselect_b64 s[44:45], -1, 0
	s_lshl_b32 s43, s19, 12
	v_lshlrev_b32_e32 v136, 4, v2
	v_bitop3_b32 v2, v133, v130, 4 bitop3:0x36
	v_lshlrev_b32_e32 v137, 7, v159
	s_add_i32 s58, s43, 0
	v_lshlrev_b32_e32 v135, 4, v2
	v_bitop3_b32 v2, v133, v130, 6 bitop3:0x36
	v_add_u32_e32 v153, s58, v137
	v_lshlrev_b32_e32 v134, 4, v2
	v_add_u32_e32 v142, v153, v138
	v_add_u32_e32 v141, v153, v136
	v_add_u32_e32 v140, v153, v135
	v_add_u32_e32 v139, v153, v134
	s_waitcnt lgkmcnt(0)
	s_barrier
	ds_read_b128 v[90:93], v142
	ds_read_b128 v[98:101], v141
	ds_read_b128 v[94:97], v140
	ds_read_b128 v[102:105], v139
	v_lshlrev_b32_e32 v46, 1, v159
	s_mov_b64 s[6:7], -1
	s_and_b64 vcc, exec, s[44:45]
	v_readfirstlane_b32 s16, v0
	v_readfirstlane_b32 s59, v0
	v_lshlrev_b32_e32 v156, 2, v133
	v_lshl_or_b32 v154, s19, 5, v159
	v_lshlrev_b32_e32 v155, 3, v133
	v_and_b32_e32 v157, 14, v46
	v_lshlrev_b32_e32 v158, 9, v133
	v_and_b32_e32 v160, 1, v129
	s_cbranch_vccz .LBB0_1661
; #define LAS __attribute__((address_space(3)))
; #define MFMA32(a, b, c) __builtin_amdgcn_mfma_f32_32x32x16_bf16((a), (b), (c), 0, 0, 0)
; __device__ __forceinline__ int ck_crow(int r, int half) { return (r & 3) + 8 * (r >> 2) + 4 * half; }
; __device__ __forceinline__ f32x16 ck_mm(const LAS unsigned char* A, const LAS unsigned char* BT, int mt, int nt, int ql, int half, f32x16 acc) {
;     const LAS unsigned char* ar = A + (32 * mt + ql) * 128; const LAS unsigned char* br = BT + (32 * nt + ql) * 128; const int sw = ql & 7;
;     f32x16 acc2 = ck_zero();
; #pragma unroll
;     for (int ks = 0; ks < 4; ++ks) { const int off = ((2 * ks + half) ^ sw) << 4; const bf16x8 a = *(const LAS bf16x8*)(ar + off), b = *(const LAS bf16x8*)(br + off); if (ks & 1) acc2 = MFMA32(a, b, acc2); else acc = MFMA32(a, b, acc); }
; #pragma unroll
;     for (int i = 0; i < 16; ++i) acc[i] += acc2[i];
;     return acc;
; __device__ __forceinline__ void chunk_pre(const P& p, Frame& F, int task, int next_task, u32x4& icr, u32x4& ick, u32x4& icv, u32x4& ipr, u32x4& ipk, u32x4& ipv, f32x4& ia0, f32x4& ia1, f32x4& iw0, f32x4& iw1, int& ptag0, int& ptag1) {
;     ...
;         { f32x16 a = ck_mm(SLOT(1), SLOT(0), mt, nt, ql, half, ck_zero());
; #pragma unroll
;           for (int r = 0; r < 16; ++r) { const int m = 32 * mt + ck_crow(r, half), n = 32 * nt + ql; a[r] = m < n ? -a[r] : 0.f; rtile[r] = a[r] + (m == n ? 1.0f : 0.f); }
;           ck_store_t(SLOT(8), a, mt, nt, ql, half); ck_store_n(SLOT(9), a, mt, nt, ql, half); ck_store_t(SLOT(10), rtile, mt, nt, ql, half); }
;         { f32x16 a = ck_mm(SLOT(1), SLOT(3), mt, nt, ql, half, ck_zero());
; #pragma unroll
;           for (int r = 0; r < 16; ++r) { const int m = 32 * mt + ck_crow(r, half), n = 32 * nt + ql; a[r] = m <= n ? a[r] : 0.f; }
;           ck_store_t(SLOT(12), a, mt, nt, ql, half); }
	s_and_b32 s20, s57, 1
	s_lshl_b32 s16, s20, 12
	s_add_i32 s18, s16, 0
	v_add_u32_e32 v146, s18, v137
	v_add_u32_e32 v2, v146, v138
	v_add_u32_e32 v42, v146, v135
	ds_read_b128 v[38:41], v2 offset:8192
	ds_read_b128 v[110:113], v42 offset:8192
	v_add_u32_e32 v2, v146, v136
	ds_read_b128 v[34:37], v2 offset:8192
	v_add_u32_e32 v42, v146, v134
	ds_read_b128 v[106:109], v42 offset:8192
	v_lshlrev_b32_e32 v144, 2, v133
	v_lshl_or_b32 v147, s20, 5, v144
	s_waitcnt lgkmcnt(3)
	v_mfma_f32_32x32x16_bf16 v[2:17], v[38:41], v[90:93], 0
	v_lshl_or_b32 v143, s19, 5, v159
	v_or_b32_e32 v47, 1, v147
	v_cmp_lt_u32_e32 vcc, v47, v143
	v_cmp_eq_u32_e64 s[6:7], v147, v143
	v_or_b32_e32 v152, 3, v147
	v_or_b32_e32 v161, 2, v147
	v_or_b32_e32 v163, 9, v147
	s_waitcnt lgkmcnt(1)
	v_mfma_f32_32x32x16_bf16 v[18:33], v[34:37], v[98:101], 0
	v_or_b32_e32 v165, 8, v147
	v_or_b32_e32 v170, 11, v147
	v_or_b32_e32 v175, 10, v147
	v_or_b32_e32 v180, 17, v147
	v_or_b32_e32 v193, 16, v147
	v_or_b32_e32 v198, 19, v147
	v_or_b32_e32 v199, 18, v147
	v_mfma_f32_32x32x16_bf16 v[2:17], v[110:113], v[94:97], v[2:17]
	v_or_b32_e32 v200, 25, v147
	v_or_b32_e32 v201, 24, v147
	v_or_b32_e32 v202, 27, v147
	v_or_b32_e32 v203, 26, v147
	s_lshl_b32 s20, s20, 2
	v_lshlrev_b32_e32 v145, 3, v133
	v_xor_b32_e32 v114, s20, v130
	s_waitcnt lgkmcnt(0)
	v_mfma_f32_32x32x16_bf16 v[18:33], v[106:109], v[102:105], v[18:33]
	v_lshlrev_b32_e32 v148, 4, v114
	v_lshlrev_b32_e32 v182, 9, v133
	v_and_b32_e32 v167, 14, v46
	s_lshl_b32 s59, s57, 12
	s_nop 7
	v_add_f32_e32 v2, v2, v18
	v_add_f32_e32 v3, v3, v19
	v_add_f32_e32 v4, v4, v20
	v_add_f32_e32 v5, v5, v21
	v_cndmask_b32_e64 v19, 0, -v3, vcc
	v_cmp_lt_u32_e32 vcc, v147, v143
	v_add_f32_e32 v6, v6, v22
	v_add_f32_e32 v7, v7, v23
	v_add_f32_e32 v8, v8, v24
	v_add_f32_e32 v9, v9, v25
	v_cndmask_b32_e64 v18, 0, -v2, vcc
	v_cndmask_b32_e64 v2, 0, 1.0, s[6:7]
	v_cmp_eq_u32_e64 s[6:7], v47, v143
	v_add_f32_e32 v10, v10, v26
	v_add_f32_e32 v11, v11, v27
	v_add_f32_e32 v12, v12, v28
	v_add_f32_e32 v13, v13, v29
	v_cndmask_b32_e64 v3, 0, 1.0, s[6:7]
	v_cmp_lt_u32_e64 s[6:7], v152, v143
	v_add_f32_e32 v42, v2, v18
	v_add_f32_e32 v43, v3, v19
	v_add_f32_e32 v14, v14, v30
	v_add_f32_e32 v15, v15, v31
	v_cndmask_b32_e64 v21, 0, -v5, s[6:7]
	v_cmp_lt_u32_e64 s[6:7], v161, v143
	v_add_f32_e32 v16, v16, v32
	v_add_f32_e32 v17, v17, v33
	v_cvt_pk_bf16_f32 v48, v18, v19
	v_cndmask_b32_e64 v20, 0, -v4, s[6:7]
	v_cmp_eq_u32_e64 s[6:7], v152, v143
	v_cvt_pk_bf16_f32 v49, v20, v21
	s_nop 0
	v_cndmask_b32_e64 v3, 0, 1.0, s[6:7]
	v_cmp_eq_u32_e64 s[6:7], v161, v143
	s_nop 1
	v_cndmask_b32_e64 v2, 0, 1.0, s[6:7]
	v_cmp_lt_u32_e64 s[6:7], v163, v143
	v_add_f32_e32 v44, v2, v20
	v_add_f32_e32 v45, v3, v21
	s_nop 0
	v_cndmask_b32_e64 v23, 0, -v7, s[6:7]
	v_cmp_lt_u32_e64 s[6:7], v165, v143
	s_nop 1
	v_cndmask_b32_e64 v22, 0, -v6, s[6:7]
	v_cmp_eq_u32_e64 s[6:7], v163, v143
	s_nop 1
	v_cndmask_b32_e64 v3, 0, 1.0, s[6:7]
	v_cmp_eq_u32_e64 s[6:7], v165, v143
	s_nop 1
	v_cndmask_b32_e64 v2, 0, 1.0, s[6:7]
	v_cmp_lt_u32_e64 s[6:7], v170, v143
	v_add_f32_e32 v116, v2, v22
	v_add_f32_e32 v117, v3, v23
	s_nop 0
	v_cndmask_b32_e64 v25, 0, -v9, s[6:7]
	v_cmp_lt_u32_e64 s[6:7], v175, v143
	s_nop 1
	v_cndmask_b32_e64 v24, 0, -v8, s[6:7]
	v_cmp_eq_u32_e64 s[6:7], v170, v143
	s_nop 1
	v_cndmask_b32_e64 v3, 0, 1.0, s[6:7]
	v_cmp_eq_u32_e64 s[6:7], v175, v143
	s_nop 1
	v_cndmask_b32_e64 v2, 0, 1.0, s[6:7]
	v_cmp_lt_u32_e64 s[6:7], v180, v143
	v_add_f32_e32 v118, v2, v24
	v_add_f32_e32 v119, v3, v25
	s_nop 0
	v_cndmask_b32_e64 v27, 0, -v11, s[6:7]
	v_cmp_lt_u32_e64 s[6:7], v193, v143
	s_nop 1
	v_cndmask_b32_e64 v26, 0, -v10, s[6:7]
	v_cmp_eq_u32_e64 s[6:7], v180, v143
	s_nop 1
	v_cndmask_b32_e64 v3, 0, 1.0, s[6:7]
	v_cmp_eq_u32_e64 s[6:7], v193, v143
	s_nop 1
	v_cndmask_b32_e64 v2, 0, 1.0, s[6:7]
	v_cmp_lt_u32_e64 s[6:7], v198, v143
	v_add_f32_e32 v120, v2, v26
	v_add_f32_e32 v121, v3, v27
	s_nop 0
	v_cndmask_b32_e64 v29, 0, -v13, s[6:7]
	v_cmp_lt_u32_e64 s[6:7], v199, v143
	v_cvt_pk_bf16_f32 v120, v120, v121
	s_nop 0
	v_cndmask_b32_e64 v28, 0, -v12, s[6:7]
	v_cmp_eq_u32_e64 s[6:7], v198, v143
	s_nop 1
	v_cndmask_b32_e64 v3, 0, 1.0, s[6:7]
	v_cmp_eq_u32_e64 s[6:7], v199, v143
	s_nop 1
	v_cndmask_b32_e64 v2, 0, 1.0, s[6:7]
	v_cmp_lt_u32_e64 s[6:7], v200, v143
	v_add_f32_e32 v122, v2, v28
	v_add_f32_e32 v123, v3, v29
	s_nop 0
	v_cndmask_b32_e64 v31, 0, -v15, s[6:7]
	v_cmp_lt_u32_e64 s[6:7], v201, v143
	v_cvt_pk_bf16_f32 v121, v122, v123
	s_nop 0
	v_cndmask_b32_e64 v30, 0, -v14, s[6:7]
	v_cmp_eq_u32_e64 s[6:7], v200, v143
	s_nop 1
	v_cndmask_b32_e64 v3, 0, 1.0, s[6:7]
	v_cmp_eq_u32_e64 s[6:7], v201, v143
	s_nop 1
	v_cndmask_b32_e64 v2, 0, 1.0, s[6:7]
	v_cmp_lt_u32_e64 s[6:7], v202, v143
	v_add_f32_e32 v124, v2, v30
	v_add_f32_e32 v125, v3, v31
	s_nop 0
	v_cndmask_b32_e64 v33, 0, -v17, s[6:7]
	v_cmp_lt_u32_e64 s[6:7], v203, v143
	v_cvt_pk_bf16_f32 v194, v33, s0
	s_nop 0
	v_cndmask_b32_e64 v32, 0, -v16, s[6:7]
	v_cmp_ne_u32_e64 s[6:7], v152, v143
	s_nop 1
	v_cndmask_b32_e64 v5, 1.0, 0, s[6:7]
	v_cmp_ne_u32_e64 s[6:7], v161, v143
	s_nop 1
	v_cndmask_b32_e64 v4, 1.0, 0, s[6:7]
	v_cmp_ne_u32_e64 s[6:7], v163, v143
	v_add_f32_e32 v4, v4, v20
	v_add_f32_e32 v5, v5, v21
	s_nop 0
	v_cndmask_b32_e64 v7, 1.0, 0, s[6:7]
	v_cmp_ne_u32_e64 s[6:7], v165, v143
	s_nop 1
	v_cndmask_b32_e64 v6, 1.0, 0, s[6:7]
	v_cmp_ne_u32_e64 s[6:7], v170, v143
	v_add_f32_e32 v6, v6, v22
	v_add_f32_e32 v7, v7, v23
	s_nop 0
	v_cndmask_b32_e64 v9, 1.0, 0, s[6:7]
	v_cmp_ne_u32_e64 s[6:7], v175, v143
	s_nop 1
	v_cndmask_b32_e64 v8, 1.0, 0, s[6:7]
	v_cmp_ne_u32_e64 s[6:7], v180, v143
	v_add_f32_e32 v8, v8, v24
	v_add_f32_e32 v9, v9, v25
; #define LAS __attribute__((address_space(3)))
; __device__ __forceinline__ unsigned pk2(float lo, float hi) { const bfx2 b = __builtin_convertvector((f32x2){lo, hi}, bfx2); return __builtin_bit_cast(unsigned, b); }
; __device__ __forceinline__ int ck_crow(int r, int half) { return (r & 3) + 8 * (r >> 2) + 4 * half; }
; __device__ __forceinline__ void ck_store_t(LAS unsigned char* IMG, const f32x16& v, int mt, int nt, int ql, int half) {
;     const int n = 32 * nt + ql; LAS unsigned char* row = IMG + n * 128;
; #pragma unroll
;     for (int g = 0; g < 4; ++g) { const int m0 = 32 * mt + 8 * g + 4 * half; u32x2 w; w.x = pk2(v[4 * g], v[4 * g + 1]); w.y = pk2(v[4 * g + 2], v[4 * g + 3]);
;         *(LAS u32x2*)(row + (((m0 >> 3) ^ (n & 7)) << 4) + (m0 & 4) * 2) = w; }
; }
; __device__ __forceinline__ void ck_store_n(LAS unsigned char* IMG, const f32x16& v, int mt, int nt, int ql, int half) {
;     const int n = 32 * nt + ql;
; #pragma unroll
;     for (int r = 0; r < 16; ++r) { const int m = 32 * mt + ck_crow(r, half);
;         *(LAS unsigned short*)(IMG + m * 128 + (((n >> 3) ^ (m & 7)) << 4) + (n & 7) * 2) = (unsigned short)(pk2(v[r], 0.f) & 0xffffu); }
; }
; __device__ __forceinline__ void chunk_pre(const P& p, Frame& F, int task, int next_task, u32x4& icr, u32x4& ick, u32x4& icv, u32x4& ipr, u32x4& ipk, u32x4& ipv, f32x4& ia0, f32x4& ia1, f32x4& iw0, f32x4& iw1, int& ptag0, int& ptag1) {
;     ...
;         { f32x16 a = ck_mm(SLOT(1), SLOT(0), mt, nt, ql, half, ck_zero());
; #pragma unroll
;           for (int r = 0; r < 16; ++r) { const int m = 32 * mt + ck_crow(r, half), n = 32 * nt + ql; a[r] = m < n ? -a[r] : 0.f; rtile[r] = a[r] + (m == n ? 1.0f : 0.f); }
;           ck_store_t(SLOT(8), a, mt, nt, ql, half); ck_store_n(SLOT(9), a, mt, nt, ql, half); ck_store_t(SLOT(10), rtile, mt, nt, ql, half); }
;         { f32x16 a = ck_mm(SLOT(1), SLOT(3), mt, nt, ql, half, ck_zero());
; #pragma unroll
;           for (int r = 0; r < 16; ++r) { const int m = 32 * mt + ck_crow(r, half), n = 32 * nt + ql; a[r] = m <= n ? a[r] : 0.f; }
;           ck_store_t(SLOT(12), a, mt, nt, ql, half); }
	s_nop 0
	v_cndmask_b32_e64 v11, 1.0, 0, s[6:7]
	v_cmp_ne_u32_e64 s[6:7], v193, v143
	s_nop 1
	v_cndmask_b32_e64 v10, 1.0, 0, s[6:7]
	v_cmp_ne_u32_e64 s[6:7], v198, v143
	v_add_f32_e32 v10, v10, v26
	v_add_f32_e32 v11, v11, v27
	s_nop 0
	v_cndmask_b32_e64 v13, 1.0, 0, s[6:7]
	v_cmp_ne_u32_e64 s[6:7], v199, v143
	s_nop 1
	v_cndmask_b32_e64 v12, 1.0, 0, s[6:7]
	v_cmp_ne_u32_e64 s[6:7], v200, v143
	v_add_f32_e32 v12, v12, v28
	v_add_f32_e32 v13, v13, v29
	s_nop 0
	v_cndmask_b32_e64 v15, 1.0, 0, s[6:7]
	v_cmp_ne_u32_e64 s[6:7], v201, v143
	s_nop 1
	v_cndmask_b32_e64 v14, 1.0, 0, s[6:7]
	v_cmp_ne_u32_e64 s[6:7], v202, v143
	v_add_f32_e32 v14, v14, v30
	v_add_f32_e32 v15, v15, v31
	s_nop 0
	v_cndmask_b32_e64 v17, 1.0, 0, s[6:7]
	v_cmp_ne_u32_e64 s[6:7], v203, v143
	s_nop 1
	v_cndmask_b32_e64 v16, 1.0, 0, s[6:7]
	v_cmp_ne_u32_e64 s[6:7], v147, v143
	v_add_f32_e32 v16, v16, v32
	v_add_f32_e32 v17, v17, v33
	s_nop 0
	v_cndmask_b32_e64 v2, 1.0, 0, s[6:7]
	v_cmp_ne_u32_e64 s[6:7], v47, v143
	s_nop 1
	v_cndmask_b32_e64 v3, 1.0, 0, s[6:7]
	s_add_i32 s6, s58, 0x10000
	v_add3_u32 v47, s6, v137, v145
	v_add_u32_e32 v114, v47, v148
	ds_write_b64 v114, v[48:49]
	v_bitop3_b32 v114, s20, v130, 1 bitop3:0x36
	v_lshlrev_b32_e32 v149, 4, v114
	v_cvt_pk_bf16_f32 v48, v22, v23
	v_cvt_pk_bf16_f32 v49, v24, v25
	v_add_u32_e32 v114, v47, v149
	ds_write_b64 v114, v[48:49]
	v_bitop3_b32 v114, s20, v130, 2 bitop3:0x36
	v_lshlrev_b32_e32 v150, 4, v114
	v_cvt_pk_bf16_f32 v48, v26, v27
	v_cvt_pk_bf16_f32 v49, v28, v29
	v_add_u32_e32 v114, v47, v150
	ds_write_b64 v114, v[48:49]
	v_bitop3_b32 v114, s20, v130, 3 bitop3:0x36
	v_lshlrev_b32_e32 v151, 4, v114
	v_cvt_pk_bf16_f32 v48, v30, v31
	v_cvt_pk_bf16_f32 v49, v32, v33
	v_add_u32_e32 v47, v47, v151
	ds_write_b64 v47, v[48:49]
	v_lshrrev_b32_e32 v47, 3, v143
	s_add_i32 s6, s18, 0x12000
	v_xor_b32_e32 v48, v47, v144
	v_add_u32_e32 v46, s6, v182
	v_lshlrev_b32_e32 v114, 4, v48
	v_add_f32_e32 v2, v2, v18
	v_add_f32_e32 v3, v3, v19
	v_cvt_pk_bf16_f32 v18, v18, s0
	v_add3_u32 v46, v46, v114, v167
	ds_write_b16 v46, v18
	v_or_b32_e32 v18, 1, v144
	v_lshlrev_b32_e32 v162, 7, v18
	v_bitop3_b32 v48, v47, v144, 1 bitop3:0x1e
	v_add_u32_e32 v18, s6, v162
	v_lshlrev_b32_e32 v164, 4, v48
	v_cvt_pk_bf16_f32 v19, v19, s0
	v_add3_u32 v18, v18, v164, v167
	ds_write_b16 v18, v19
	v_or_b32_e32 v18, 2, v144
	v_cvt_pk_bf16_f32 v19, v20, s0
	v_lshlrev_b32_e32 v166, 7, v18
	v_bitop3_b32 v20, v47, v144, 2 bitop3:0x1e
	v_add_u32_e32 v18, s6, v166
	v_lshlrev_b32_e32 v168, 4, v20
	v_add3_u32 v18, v18, v168, v167
	ds_write_b16 v18, v19
	v_or_b32_e32 v18, 3, v144
	v_lshlrev_b32_e32 v169, 7, v18
	v_bitop3_b32 v20, v47, v144, 3 bitop3:0x1e
	v_add_u32_e32 v18, s6, v169
	v_lshlrev_b32_e32 v171, 4, v20
	v_cvt_pk_bf16_f32 v19, v21, s0
	v_add3_u32 v18, v18, v171, v167
	ds_write_b16 v18, v19
	v_cvt_pk_bf16_f32 v18, v22, s0
	ds_write_b16 v46, v18 offset:1024
	v_or_b32_e32 v18, 9, v144
	v_lshlrev_b32_e32 v172, 7, v18
	v_bitop3_b32 v18, v18, v47, 5 bitop3:0x6c
	v_add_u32_e32 v20, s6, v172
	v_lshlrev_b32_e32 v173, 4, v18
	v_cvt_pk_bf16_f32 v19, v23, s0
	v_add3_u32 v18, v20, v173, v167
	ds_write_b16 v18, v19
	v_or_b32_e32 v18, 10, v144
	v_lshlrev_b32_e32 v174, 7, v18
	v_bitop3_b32 v18, v18, v47, 6 bitop3:0x6c
	v_add_u32_e32 v20, s6, v174
	v_lshlrev_b32_e32 v176, 4, v18
	v_cvt_pk_bf16_f32 v19, v24, s0
	v_add3_u32 v18, v20, v176, v167
	ds_write_b16 v18, v19
	v_or_b32_e32 v18, 11, v144
	v_lshlrev_b32_e32 v177, 7, v18
	v_bitop3_b32 v18, v18, v47, 7 bitop3:0x6c
	v_add_u32_e32 v20, s6, v177
	v_lshlrev_b32_e32 v178, 4, v18
	v_cvt_pk_bf16_f32 v19, v25, s0
	v_add3_u32 v18, v20, v178, v167
	ds_write_b16 v18, v19
	v_cvt_pk_bf16_f32 v18, v26, s0
	ds_write_b16 v46, v18 offset:2048
	v_or_b32_e32 v18, 17, v144
	v_lshlrev_b32_e32 v179, 7, v18
	v_bitop3_b32 v18, v18, v47, 5 bitop3:0x6c
	v_add_u32_e32 v20, s6, v179
	v_lshlrev_b32_e32 v181, 4, v18
	v_cvt_pk_bf16_f32 v19, v27, s0
	v_add3_u32 v18, v20, v181, v167
	ds_write_b16 v18, v19
	v_or_b32_e32 v18, 18, v144
	v_lshlrev_b32_e32 v183, 7, v18
	v_bitop3_b32 v18, v18, v47, 6 bitop3:0x6c
	v_add_u32_e32 v20, s6, v183
	v_lshlrev_b32_e32 v184, 4, v18
	v_cvt_pk_bf16_f32 v19, v28, s0
	v_add3_u32 v18, v20, v184, v167
	ds_write_b16 v18, v19
	v_or_b32_e32 v18, 19, v144
	v_lshlrev_b32_e32 v185, 7, v18
	v_bitop3_b32 v18, v18, v47, 7 bitop3:0x6c
	v_add_u32_e32 v20, s6, v185
	v_lshlrev_b32_e32 v186, 4, v18
	v_cvt_pk_bf16_f32 v19, v29, s0
	v_add3_u32 v18, v20, v186, v167
	ds_write_b16 v18, v19
	v_cvt_pk_bf16_f32 v18, v30, s0
	ds_write_b16 v46, v18 offset:3072
	v_or_b32_e32 v18, 25, v144
	v_lshlrev_b32_e32 v187, 7, v18
	v_bitop3_b32 v18, v18, v47, 5 bitop3:0x6c
	v_add_u32_e32 v20, s6, v187
	v_lshlrev_b32_e32 v188, 4, v18
	v_cvt_pk_bf16_f32 v19, v31, s0
	v_add3_u32 v18, v20, v188, v167
	ds_write_b16 v18, v19
	v_or_b32_e32 v18, 26, v144
	v_lshlrev_b32_e32 v189, 7, v18
	v_bitop3_b32 v18, v18, v47, 6 bitop3:0x6c
	v_add_u32_e32 v20, s6, v189
	v_lshlrev_b32_e32 v190, 4, v18
	v_cvt_pk_bf16_f32 v19, v32, s0
	v_add3_u32 v18, v20, v190, v167
	ds_write_b16 v18, v19
	v_or_b32_e32 v22, 27, v144
	ds_read_b128 v[18:21], v142 offset:24576
	v_lshlrev_b32_e32 v191, 7, v22
	v_bitop3_b32 v22, v22, v47, 7 bitop3:0x6c
	ds_read_b128 v[46:49], v141 offset:24576
	v_add_u32_e32 v23, s6, v191
	s_add_i32 s6, s58, 0x14000
	v_lshlrev_b32_e32 v192, 4, v22
	v_add3_u32 v204, s6, v137, v145
	v_add3_u32 v195, v23, v192, v167
	s_waitcnt lgkmcnt(1)
	v_mfma_f32_32x32x16_bf16 v[18:33], v[38:41], v[18:21], 0
	v_cvt_pk_bf16_f32 v38, v42, v43
	v_cvt_pk_bf16_f32 v39, v44, v45
	v_add_u32_e32 v40, v204, v148
	ds_write_b64 v40, v[38:39]
	ds_write_b16 v195, v194
	v_cvt_pk_bf16_f32 v194, v116, v117
	v_cvt_pk_bf16_f32 v195, v118, v119
	s_waitcnt lgkmcnt(2)
; #define LAS __attribute__((address_space(3)))
; #define MFMA32(a, b, c) __builtin_amdgcn_mfma_f32_32x32x16_bf16((a), (b), (c), 0, 0, 0)
; __device__ __forceinline__ int ck_crow(int r, int half) { return (r & 3) + 8 * (r >> 2) + 4 * half; }
; __device__ __forceinline__ void ck_tr(const LAS unsigned char* SRC, LAS unsigned char* DST, int mt, int nt, int ql, int half) {
;     const LAS unsigned char* ar = SRC + (32 * mt + ql) * 128; const int sw = ql & 7;
;     f32x16 acc = ck_zero();
; #pragma unroll
;     for (int d = 0; d < 2; ++d) { const int ks = 2 * nt + d, off = ((2 * ks + half) ^ sw) << 4; const bf16x8 a = *(const LAS bf16x8*)(ar + off);
;         const int e = ql - 16 * d - 8 * half; const unsigned val = (e & 1) ? 0x3F800000u : 0x00003F80u; const int w = (e >= 0 && e < 8) ? (e >> 1) : -1;
;         const u32x4 bw = (u32x4){w == 0 ? val : 0u, w == 1 ? val : 0u, w == 2 ? val : 0u, w == 3 ? val : 0u};
;         acc = MFMA32(a, __builtin_bit_cast(bf16x8, bw), acc); }
;     ck_store_t(DST, acc, mt, nt, ql, half);
; }
; __device__ __forceinline__ void chunk_pre(const P& p, Frame& F, int task, int next_task, u32x4& icr, u32x4& ick, u32x4& icv, u32x4& ipr, u32x4& ipk, u32x4& ipv, f32x4& ia0, f32x4& ia1, f32x4& iw0, f32x4& iw1, int& ptag0, int& ptag1) {
;     ...
;         { f32x16 a = ck_mm(SLOT(1), SLOT(3), mt, nt, ql, half, ck_zero());
; #pragma unroll
;           for (int r = 0; r < 16; ++r) { const int m = 32 * mt + ck_crow(r, half), n = 32 * nt + ql; a[r] = m <= n ? a[r] : 0.f; }
;           ck_store_t(SLOT(12), a, mt, nt, ql, half); }
;         ck_tr(SLOT(2), SLOT(6), mt, nt, ql, half); ck_tr(SLOT(15), SLOT(7), mt, nt, ql, half); }
	v_mfma_f32_32x32x16_bf16 v[34:49], v[34:37], v[46:49], 0
	v_add_u32_e32 v196, v204, v149
	ds_read_b128 v[116:119], v140 offset:24576
	ds_write_b64 v196, v[194:195]
	ds_read_b128 v[194:197], v139 offset:24576
	v_cmp_le_u32_e64 s[6:7], v147, v143
	s_add_i32 s18, s18, 0x1e000
	s_waitcnt lgkmcnt(2)
	v_mfma_f32_32x32x16_bf16 v[18:33], v[110:113], v[116:119], v[18:33]
	v_add_u32_e32 v110, v204, v150
	ds_write_b64 v110, v[120:121]
	v_cvt_pk_bf16_f32 v110, v124, v125
	v_cvt_pk_bf16_f32 v111, v16, v17
	v_add_u32_e32 v112, v204, v151
	ds_write_b64 v112, v[110:111]
	v_add_u32_e32 v112, v153, v145
	s_waitcnt lgkmcnt(2)
	v_mfma_f32_32x32x16_bf16 v[34:49], v[106:109], v[194:197], v[34:49]
	v_add_u32_e32 v113, v112, v148
	v_add_u32_e32 v116, v112, v149
	s_nop 9
	v_add_f32_e32 v19, v19, v35
	v_add_f32_e32 v20, v20, v36
	v_add_f32_e32 v21, v21, v37
	v_add_f32_e32 v18, v18, v34
	v_cndmask_b32_e32 v35, 0, v19, vcc
	v_cvt_pk_bf16_f32 v20, v20, v21
	v_cmp_le_u32_e32 vcc, v161, v143
	v_cndmask_b32_e64 v34, 0, v18, s[6:7]
	s_add_i32 s6, s58, 0x18000
	v_cndmask_b32_e32 v21, 0, v20, vcc
	v_lshrrev_b32_e32 v20, 16, v20
	v_cmp_le_u32_e32 vcc, v152, v143
	v_add3_u32 v36, s6, v137, v145
	v_add_f32_e32 v18, v32, v48
	v_add_f32_e32 v19, v33, v49
	v_cndmask_b32_e32 v20, 0, v20, vcc
	v_add_f32_e32 v22, v22, v38
	v_add_f32_e32 v23, v23, v39
	v_cvt_pk_bf16_f32 v32, v34, v35
	v_perm_b32 v33, v20, v21, s53
	v_add_u32_e32 v20, v36, v148
	ds_write_b64 v20, v[32:33]
	v_cvt_pk_bf16_f32 v20, v22, v23
	v_cmp_le_u32_e32 vcc, v165, v143
	v_add_f32_e32 v24, v24, v40
	v_add_f32_e32 v25, v25, v41
	v_add_f32_e32 v26, v26, v42
	v_add_f32_e32 v27, v27, v43
	v_cndmask_b32_e32 v21, 0, v20, vcc
	v_lshrrev_b32_e32 v20, 16, v20
	v_cmp_le_u32_e32 vcc, v163, v143
	v_add_f32_e32 v28, v28, v44
	v_add_f32_e32 v29, v29, v45
	v_add_f32_e32 v30, v30, v46
	v_add_f32_e32 v31, v31, v47
	v_cndmask_b32_e32 v20, 0, v20, vcc
	v_perm_b32 v20, v20, v21, s53
	v_cvt_pk_bf16_f32 v21, v24, v25
	v_cmp_le_u32_e32 vcc, v175, v143
	v_cvt_pk_bf16_f32 v18, v18, v19
	s_lshl_b32 s6, s19, 2
	v_cndmask_b32_e32 v22, 0, v21, vcc
	v_lshrrev_b32_e32 v21, 16, v21
	v_cmp_le_u32_e32 vcc, v170, v143
	v_sub_u32_e32 v23, v159, v145
	v_lshrrev_b32_e32 v24, 1, v23
	v_cndmask_b32_e32 v21, 0, v21, vcc
	v_perm_b32 v21, v21, v22, s53
	v_add_u32_e32 v22, v36, v149
	ds_write_b64 v22, v[20:21]
	v_cvt_pk_bf16_f32 v20, v26, v27
	v_cmp_le_u32_e32 vcc, v193, v143
	v_or_b32_e32 v45, 16, v145
	v_sub_u32_e32 v45, v159, v45
	v_cndmask_b32_e32 v21, 0, v20, vcc
	v_lshrrev_b32_e32 v20, 16, v20
	v_cmp_le_u32_e32 vcc, v180, v143
	v_lshrrev_b32_e32 v46, 1, v45
	v_mov_b32_e32 v152, s20
	v_cndmask_b32_e32 v20, 0, v20, vcc
	v_perm_b32 v20, v20, v21, s53
	v_cvt_pk_bf16_f32 v21, v28, v29
	v_cmp_le_u32_e32 vcc, v199, v143
	s_nop 1
	v_cndmask_b32_e32 v22, 0, v21, vcc
	v_lshrrev_b32_e32 v21, 16, v21
	v_cmp_le_u32_e32 vcc, v198, v143
	s_nop 1
	v_cndmask_b32_e32 v21, 0, v21, vcc
	v_perm_b32 v21, v21, v22, s53
	v_add_u32_e32 v22, v36, v150
	ds_write_b64 v22, v[20:21]
	v_cvt_pk_bf16_f32 v20, v30, v31
	v_cmp_le_u32_e32 vcc, v201, v143
	v_or_b32_e32 v22, s6, v133
	v_bitop3_b32 v22, v22, v130, 2 bitop3:0x36
	v_cndmask_b32_e32 v21, 0, v20, vcc
	v_lshrrev_b32_e32 v20, 16, v20
	v_cmp_le_u32_e32 vcc, v200, v143
	v_lshlrev_b32_e32 v44, 4, v22
	v_add_u32_e32 v22, v146, v44
	v_cndmask_b32_e32 v20, 0, v20, vcc
	v_cmp_le_u32_e32 vcc, v203, v143
	v_perm_b32 v20, v20, v21, s53
	ds_read_b128 v[38:41], v22 offset:16384
	v_cndmask_b32_e32 v19, 0, v18, vcc
	v_lshrrev_b32_e32 v18, 16, v18
	v_cmp_le_u32_e32 vcc, v202, v143
	s_nop 1
	v_cndmask_b32_e32 v18, 0, v18, vcc
	v_perm_b32 v21, v18, v19, s53
	v_add_u32_e32 v18, v36, v151
	ds_write_b64 v18, v[20:21]
	v_bitop3_b32 v18, s6, v130, v133 bitop3:0x36
	v_lshlrev_b32_e32 v43, 4, v18
	v_add_u32_e32 v18, v146, v43
	ds_read_b128 v[18:21], v18 offset:16384
	v_cmp_eq_u32_e32 vcc, 0, v160
	s_lshl_b32 s6, s57, 2
	s_nop 0
	v_cndmask_b32_e32 v42, 1.0, v128, vcc
	v_cmp_gt_u32_e32 vcc, 8, v23
	s_nop 1
	v_cndmask_b32_e32 v23, -1, v24, vcc
	v_cmp_eq_u32_e32 vcc, 0, v23
	s_nop 1
	v_cndmask_b32_e32 v34, 0, v42, vcc
	v_cmp_eq_u32_e32 vcc, 1, v23
	s_nop 1
	v_cndmask_b32_e32 v35, 0, v42, vcc
	v_cmp_eq_u32_e32 vcc, 2, v23
	s_nop 1
	v_cndmask_b32_e32 v36, 0, v42, vcc
	v_cmp_eq_u32_e32 vcc, 3, v23
	s_nop 1
	v_cndmask_b32_e32 v37, 0, v42, vcc
	v_cmp_gt_u32_e32 vcc, 8, v45
	s_waitcnt lgkmcnt(0)
	v_mfma_f32_32x32x16_bf16 v[18:33], v[18:21], v[34:37], 0
	v_cndmask_b32_e32 v45, -1, v46, vcc
	v_cmp_eq_u32_e32 vcc, 0, v45
	s_nop 1
	v_cndmask_b32_e32 v106, 0, v42, vcc
	v_cmp_eq_u32_e32 vcc, 1, v45
	s_nop 1
	v_cndmask_b32_e32 v107, 0, v42, vcc
	v_cmp_eq_u32_e32 vcc, 2, v45
	s_nop 1
	v_cndmask_b32_e32 v108, 0, v42, vcc
	v_cmp_eq_u32_e32 vcc, 3, v45
	s_nop 1
	v_cndmask_b32_e32 v109, 0, v42, vcc
	v_add_u32_e32 v42, s18, v137
	s_nop 0
	v_mfma_f32_32x32x16_bf16 v[18:33], v[38:41], v[106:109], v[18:33]
	v_add_u32_e32 v38, v42, v43
	ds_read_b128 v[38:41], v38
	s_nop 9
	v_cvt_pk_bf16_f32 v110, v18, v19
	v_add_u32_e32 v18, v42, v44
	v_cvt_pk_bf16_f32 v111, v20, v21
	ds_read_b128 v[18:21], v18
	s_waitcnt lgkmcnt(1)
	v_mfma_f32_32x32x16_bf16 v[34:49], v[38:41], v[34:37], 0
	v_cvt_pk_bf16_f32 v22, v22, v23
	v_cvt_pk_bf16_f32 v23, v24, v25
	v_cvt_pk_bf16_f32 v24, v26, v27
	v_cvt_pk_bf16_f32 v25, v28, v29
	v_add_u32_e32 v28, v112, v150
	v_cvt_pk_bf16_f32 v26, v30, v31
	v_cvt_pk_bf16_f32 v27, v32, v33
	s_waitcnt lgkmcnt(0)
	v_mfma_f32_32x32x16_bf16 v[34:49], v[18:21], v[106:109], v[34:49]
	v_add_u32_e32 v29, v112, v151
	s_nop 10
	v_cvt_pk_bf16_f32 v18, v34, v35
	v_cvt_pk_bf16_f32 v19, v36, v37
	ds_write2st64_b64 v113, v[110:111], v[18:19] offset0:96 offset1:112
	v_cvt_pk_bf16_f32 v18, v38, v39
	v_cvt_pk_bf16_f32 v19, v40, v41
	ds_write2st64_b64 v116, v[22:23], v[18:19] offset0:96 offset1:112
	v_cvt_pk_bf16_f32 v18, v42, v43
	v_cvt_pk_bf16_f32 v19, v44, v45
	ds_write2st64_b64 v28, v[24:25], v[18:19] offset0:96 offset1:112
	v_cvt_pk_bf16_f32 v18, v46, v47
	v_cvt_pk_bf16_f32 v19, v48, v49
	ds_write2st64_b64 v29, v[26:27], v[18:19] offset0:96 offset1:112
	v_xor_b32_e32 v18, s6, v130
	v_lshlrev_b32_e32 v124, 4, v18
	v_bitop3_b32 v18, s6, v130, 1 bitop3:0x36
	v_lshlrev_b32_e32 v125, 4, v18
	v_bitop3_b32 v18, s6, v130, 2 bitop3:0x36
	v_lshlrev_b32_e32 v146, 4, v18
	v_bitop3_b32 v18, s6, v130, 3 bitop3:0x36
	v_lshlrev_b32_e32 v147, 4, v18
	s_mov_b64 s[6:7], 0
; __device__ __forceinline__ int ck_crow(int r, int half) { return (r & 3) + 8 * (r >> 2) + 4 * half; }
; __device__ __forceinline__ void chunk_pre(const P& p, Frame& F, int task, int next_task, u32x4& icr, u32x4& ick, u32x4& icv, u32x4& ipr, u32x4& ipk, u32x4& ipv, f32x4& ia0, f32x4& ia1, f32x4& iw0, f32x4& iw1, int& ptag0, int& ptag1) {
;     ...
;     if (grp == 0) {
;         { f32x16 a = ck_mm(SLOT(2), SLOT(0), mt, nt, ql, half, ck_zero());
; #pragma unroll
;           for (int r = 0; r < 16; ++r) { const int m = 32 * mt + ck_crow(r, half), n = 32 * nt + ql; a[r] = m < n ? a[r] : 0.f; }
;           ck_store_t(SLOT(11), a, mt, nt, ql, half); }
;         { f32x16 a = ck_mm(SLOT(2), SLOT(3), mt, nt, ql, half, ck_zero());
; #pragma unroll
;           for (int r = 0; r < 16; ++r) { const int m = 32 * mt + ck_crow(r, half), n = 32 * nt + ql; a[r] = m <= n ? a[r] : 0.f; }
;           ck_store_t(SLOT(13), a, mt, nt, ql, half); }
;         ck_tr(SLOT(0), SLOT(4), mt, nt, ql, half); ck_tr(SLOT(1), SLOT(5), mt, nt, ql, half); }
.LBB0_1661:
	s_andn2_b64 vcc, exec, s[6:7]
	s_cbranch_vccnz .LBB0_1663
	s_lshl_b32 s59, s57, 12
	s_add_i32 s6, s59, 0
	v_add_u32_e32 v106, s6, v137
	v_add_u32_e32 v2, v106, v138
	v_add_u32_e32 v42, v106, v135
	ds_read_b128 v[34:37], v2 offset:16384
	ds_read_b128 v[42:45], v42 offset:16384
	v_add_u32_e32 v2, v106, v136
	ds_read_b128 v[38:41], v2 offset:16384
	v_add_u32_e32 v46, v106, v134
	ds_read_b128 v[46:49], v46 offset:16384
	s_lshl_b32 s60, s57, 2
	s_mov_b32 s16, s17
	s_waitcnt lgkmcnt(3)
	v_mfma_f32_32x32x16_bf16 v[2:17], v[34:37], v[90:93], 0
	s_mov_b32 s18, s17
	s_mov_b32 s20, s17
	s_mov_b32 s21, s17
	s_mov_b32 s22, s17
	s_mov_b32 s23, s17
	s_mov_b32 s24, s17
	s_mov_b32 s25, s17
	s_waitcnt lgkmcnt(1)
	v_mfma_f32_32x32x16_bf16 v[18:33], v[38:41], v[98:101], 0
	s_mov_b32 s26, s17
	s_mov_b32 s27, s17
	s_mov_b32 s28, s17
	s_mov_b32 s29, s17
	s_mov_b32 s30, s17
	s_mov_b32 s31, s17
	v_mov_b32_e32 v152, s60
	v_mfma_f32_32x32x16_bf16 v[2:17], v[42:45], v[94:97], v[2:17]
	v_lshl_or_b32 v94, s57, 5, v156
	v_cmp_lt_u32_e32 vcc, v94, v154
	v_or_b32_e32 v96, 2, v94
	v_or_b32_e32 v95, 3, v94
	v_or_b32_e32 v98, 8, v94
	v_or_b32_e32 v97, 9, v94
	v_or_b32_e32 v100, 10, v94
	s_waitcnt lgkmcnt(0)
	v_mfma_f32_32x32x16_bf16 v[18:33], v[46:49], v[102:105], v[18:33]
	v_or_b32_e32 v99, 11, v94
	v_or_b32_e32 v102, 16, v94
	v_or_b32_e32 v101, 17, v94
	v_or_b32_e32 v104, 18, v94
	v_or_b32_e32 v103, 19, v94
	v_or_b32_e32 v107, 24, v94
	v_or_b32_e32 v105, 25, v94
	s_nop 4
	v_add_f32_e32 v2, v2, v18
	v_cndmask_b32_e32 v18, 0, v2, vcc
	v_or_b32_e32 v2, 1, v94
	v_add_f32_e32 v3, v3, v19
	v_cmp_lt_u32_e64 s[6:7], v2, v154
	v_add_f32_e32 v4, v4, v20
	v_add_f32_e32 v5, v5, v21
	v_add_f32_e32 v6, v6, v22
	v_add_f32_e32 v7, v7, v23
	v_cndmask_b32_e64 v19, 0, v3, s[6:7]
	s_add_i32 s6, s58, 0x16000
	v_add3_u32 v110, s6, v137, v155
	v_cvt_pk_bf16_f32 v4, v4, v5
	v_cmp_lt_u32_e64 s[6:7], v96, v154
	v_add_f32_e32 v2, v12, v28
	v_add_f32_e32 v3, v13, v29
	v_cvt_pk_bf16_f32 v12, v18, v19
	v_cndmask_b32_e64 v5, 0, v4, s[6:7]
	v_lshrrev_b32_e32 v4, 16, v4
	v_cmp_lt_u32_e64 s[6:7], v95, v154
	v_add_f32_e32 v8, v8, v24
	v_add_f32_e32 v9, v9, v25
	v_add_f32_e32 v10, v10, v26
	v_add_f32_e32 v11, v11, v27
	v_cndmask_b32_e64 v4, 0, v4, s[6:7]
	v_perm_b32 v13, v4, v5, s53
	v_xor_b32_e32 v4, s60, v130
	v_lshlrev_b32_e32 v124, 4, v4
	v_add_u32_e32 v4, v110, v124
	ds_write_b64 v4, v[12:13]
	v_cvt_pk_bf16_f32 v4, v6, v7
	v_cmp_lt_u32_e64 s[6:7], v98, v154
	v_cvt_pk_bf16_f32 v2, v2, v3
	ds_read_b128 v[18:21], v141 offset:24576
	v_cndmask_b32_e64 v5, 0, v4, s[6:7]
	v_lshrrev_b32_e32 v4, 16, v4
	v_cmp_lt_u32_e64 s[6:7], v97, v154
	v_add_f32_e32 v30, v14, v30
	v_add_f32_e32 v31, v15, v31
	v_add_f32_e32 v90, v16, v32
	v_add_f32_e32 v91, v17, v33
	v_cndmask_b32_e64 v4, 0, v4, s[6:7]
	v_perm_b32 v4, v4, v5, s53
	v_cvt_pk_bf16_f32 v5, v8, v9
	v_cmp_lt_u32_e64 s[6:7], v100, v154
	v_or_b32_e32 v109, 26, v94
	v_or_b32_e32 v108, 27, v94
	v_cndmask_b32_e64 v6, 0, v5, s[6:7]
	v_lshrrev_b32_e32 v5, 16, v5
	v_cmp_lt_u32_e64 s[6:7], v99, v154
	v_mov_b32_e32 v182, v158
	v_mov_b32_e32 v167, v157
	v_cndmask_b32_e64 v5, 0, v5, s[6:7]
	v_perm_b32 v5, v5, v6, s53
	v_bitop3_b32 v6, s60, v130, 1 bitop3:0x36
	v_lshlrev_b32_e32 v125, 4, v6
	v_add_u32_e32 v6, v110, v125
	ds_write_b64 v6, v[4:5]
	v_cvt_pk_bf16_f32 v4, v10, v11
	v_cmp_lt_u32_e64 s[6:7], v102, v154
	v_bitop3_b32 v6, s60, v130, 2 bitop3:0x36
	v_lshlrev_b32_e32 v146, 4, v6
	v_cndmask_b32_e64 v5, 0, v4, s[6:7]
	v_lshrrev_b32_e32 v4, 16, v4
	v_cmp_lt_u32_e64 s[6:7], v101, v154
	v_add_u32_e32 v24, v110, v146
	v_mov_b32_e32 v144, v156
	v_cndmask_b32_e64 v4, 0, v4, s[6:7]
	v_cmp_lt_u32_e64 s[6:7], v104, v154
	v_perm_b32 v22, v4, v5, s53
	v_mov_b32_e32 v150, v146
	v_cndmask_b32_e64 v3, 0, v2, s[6:7]
	v_lshrrev_b32_e32 v2, 16, v2
	v_cmp_lt_u32_e64 s[6:7], v103, v154
	v_mov_b32_e32 v149, v125
	v_mov_b32_e32 v148, v124
	v_cndmask_b32_e64 v2, 0, v2, s[6:7]
	v_perm_b32 v23, v2, v3, s53
	ds_read_b128 v[2:5], v142 offset:24576
	ds_write_b64 v24, v[22:23]
	v_cvt_pk_bf16_f32 v22, v30, v31
	v_cmp_lt_u32_e64 s[6:7], v107, v154
	s_waitcnt lgkmcnt(1)
	v_mfma_f32_32x32x16_bf16 v[2:17], v[34:37], v[2:5], 0
	v_cndmask_b32_e64 v34, 0, v22, s[6:7]
	v_lshrrev_b32_e32 v22, 16, v22
	v_cmp_lt_u32_e64 s[6:7], v105, v154
	v_mov_b32_e32 v145, v155
	v_mov_b32_e32 v143, v154
	v_cndmask_b32_e64 v35, 0, v22, s[6:7]
	v_cmp_lt_u32_e64 s[6:7], v109, v154
	v_mfma_f32_32x32x16_bf16 v[18:33], v[38:41], v[18:21], 0
	v_cvt_pk_bf16_f32 v38, v90, v91
	v_perm_b32 v92, v35, v34, s53
	ds_read_b128 v[34:37], v140 offset:24576
	v_cndmask_b32_e64 v90, 0, v38, s[6:7]
	v_lshrrev_b32_e32 v91, 16, v38
	ds_read_b128 v[38:41], v139 offset:24576
	v_cmp_lt_u32_e64 s[6:7], v108, v154
	s_waitcnt lgkmcnt(1)
	v_mfma_f32_32x32x16_bf16 v[2:17], v[42:45], v[34:37], v[2:17]
	v_cndmask_b32_e64 v34, 0, v91, s[6:7]
	v_cmp_le_u32_e64 s[6:7], v94, v154
	v_perm_b32 v93, v34, v90, s53
	v_bitop3_b32 v34, s60, v130, 3 bitop3:0x36
	v_lshlrev_b32_e32 v147, 4, v34
	v_add_u32_e32 v34, v110, v147
	s_waitcnt lgkmcnt(0)
; #define LAS __attribute__((address_space(3)))
; #define MFMA32(a, b, c) __builtin_amdgcn_mfma_f32_32x32x16_bf16((a), (b), (c), 0, 0, 0)
; __device__ __forceinline__ int ck_crow(int r, int half) { return (r & 3) + 8 * (r >> 2) + 4 * half; }
; __device__ __forceinline__ void ck_tr(const LAS unsigned char* SRC, LAS unsigned char* DST, int mt, int nt, int ql, int half) {
;     const LAS unsigned char* ar = SRC + (32 * mt + ql) * 128; const int sw = ql & 7;
;     f32x16 acc = ck_zero();
; #pragma unroll
;     for (int d = 0; d < 2; ++d) { const int ks = 2 * nt + d, off = ((2 * ks + half) ^ sw) << 4; const bf16x8 a = *(const LAS bf16x8*)(ar + off);
;         const int e = ql - 16 * d - 8 * half; const unsigned val = (e & 1) ? 0x3F800000u : 0x00003F80u; const int w = (e >= 0 && e < 8) ? (e >> 1) : -1;
;         const u32x4 bw = (u32x4){w == 0 ? val : 0u, w == 1 ? val : 0u, w == 2 ? val : 0u, w == 3 ? val : 0u};
;         acc = MFMA32(a, __builtin_bit_cast(bf16x8, bw), acc); }
;     ck_store_t(DST, acc, mt, nt, ql, half);
; }
; __device__ __forceinline__ void chunk_pre(const P& p, Frame& F, int task, int next_task, u32x4& icr, u32x4& ick, u32x4& icv, u32x4& ipr, u32x4& ipk, u32x4& ipv, f32x4& ia0, f32x4& ia1, f32x4& iw0, f32x4& iw1, int& ptag0, int& ptag1) {
;     ...
;         { f32x16 a = ck_mm(SLOT(2), SLOT(3), mt, nt, ql, half, ck_zero());
; #pragma unroll
;           for (int r = 0; r < 16; ++r) { const int m = 32 * mt + ck_crow(r, half), n = 32 * nt + ql; a[r] = m <= n ? a[r] : 0.f; }
;           ck_store_t(SLOT(13), a, mt, nt, ql, half); }
;         ck_tr(SLOT(0), SLOT(4), mt, nt, ql, half); ck_tr(SLOT(1), SLOT(5), mt, nt, ql, half); }
	v_mfma_f32_32x32x16_bf16 v[18:33], v[46:49], v[38:41], v[18:33]
	ds_write_b64 v34, v[92:93]
	v_mov_b32_e32 v151, v147
	s_nop 9
	v_add_f32_e32 v3, v3, v19
	v_add_f32_e32 v4, v4, v20
	v_add_f32_e32 v5, v5, v21
	v_add_f32_e32 v2, v2, v18
	v_cndmask_b32_e32 v19, 0, v3, vcc
	v_cvt_pk_bf16_f32 v4, v4, v5
	v_cmp_le_u32_e32 vcc, v96, v154
	v_cndmask_b32_e64 v18, 0, v2, s[6:7]
	s_add_i32 s6, s58, 0x1a000
	v_cndmask_b32_e32 v5, 0, v4, vcc
	v_lshrrev_b32_e32 v4, 16, v4
	v_cmp_le_u32_e32 vcc, v95, v154
	v_add3_u32 v20, s6, v137, v155
	v_add_f32_e32 v2, v16, v32
	v_add_f32_e32 v3, v17, v33
	v_cndmask_b32_e32 v4, 0, v4, vcc
	v_add_f32_e32 v6, v6, v22
	v_add_f32_e32 v7, v7, v23
	v_cvt_pk_bf16_f32 v16, v18, v19
	v_perm_b32 v17, v4, v5, s53
	v_add_u32_e32 v4, v20, v124
	ds_write_b64 v4, v[16:17]
	v_cvt_pk_bf16_f32 v4, v6, v7
	v_cmp_le_u32_e32 vcc, v98, v154
	v_add_f32_e32 v8, v8, v24
	v_add_f32_e32 v9, v9, v25
	v_add_f32_e32 v10, v10, v26
	v_add_f32_e32 v11, v11, v27
	v_cndmask_b32_e32 v5, 0, v4, vcc
	v_lshrrev_b32_e32 v4, 16, v4
	v_cmp_le_u32_e32 vcc, v97, v154
	v_add_f32_e32 v12, v12, v28
	v_add_f32_e32 v13, v13, v29
	v_add_f32_e32 v14, v14, v30
	v_add_f32_e32 v15, v15, v31
	v_cndmask_b32_e32 v4, 0, v4, vcc
	v_perm_b32 v4, v4, v5, s53
	v_cvt_pk_bf16_f32 v5, v8, v9
	v_cmp_le_u32_e32 vcc, v100, v154
	v_cvt_pk_bf16_f32 v2, v2, v3
	s_lshl_b32 s6, s19, 2
	v_cndmask_b32_e32 v6, 0, v5, vcc
	v_lshrrev_b32_e32 v5, 16, v5
	v_cmp_le_u32_e32 vcc, v99, v154
	v_sub_u32_e32 v7, v159, v155
	v_lshrrev_b32_e32 v8, 1, v7
	v_cndmask_b32_e32 v5, 0, v5, vcc
	v_perm_b32 v5, v5, v6, s53
	v_add_u32_e32 v6, v20, v125
	ds_write_b64 v6, v[4:5]
	v_cvt_pk_bf16_f32 v4, v10, v11
	v_cmp_le_u32_e32 vcc, v102, v154
	v_or_b32_e32 v29, 16, v155
	v_sub_u32_e32 v29, v159, v29
	v_cndmask_b32_e32 v5, 0, v4, vcc
	v_lshrrev_b32_e32 v4, 16, v4
	v_cmp_le_u32_e32 vcc, v101, v154
	v_lshrrev_b32_e32 v30, 1, v29
	s_mov_b32 s19, s17
	v_cndmask_b32_e32 v4, 0, v4, vcc
	v_perm_b32 v4, v4, v5, s53
	v_cvt_pk_bf16_f32 v5, v12, v13
	v_cmp_le_u32_e32 vcc, v104, v154
	s_nop 1
	v_cndmask_b32_e32 v6, 0, v5, vcc
	v_lshrrev_b32_e32 v5, 16, v5
	v_cmp_le_u32_e32 vcc, v103, v154
	s_nop 1
	v_cndmask_b32_e32 v5, 0, v5, vcc
	v_perm_b32 v5, v5, v6, s53
	v_add_u32_e32 v6, v20, v146
	ds_write_b64 v6, v[4:5]
	v_cvt_pk_bf16_f32 v4, v14, v15
	v_cmp_le_u32_e32 vcc, v107, v154
	v_or_b32_e32 v6, s6, v133
	v_bitop3_b32 v6, v6, v130, 2 bitop3:0x36
	v_cndmask_b32_e32 v5, 0, v4, vcc
	v_lshrrev_b32_e32 v4, 16, v4
	v_cmp_le_u32_e32 vcc, v105, v154
	v_lshl_add_u32 v28, v6, 4, v106
	s_nop 0
	v_cndmask_b32_e32 v4, 0, v4, vcc
	v_cmp_le_u32_e32 vcc, v109, v154
	v_perm_b32 v4, v4, v5, s53
	s_nop 0
	v_cndmask_b32_e32 v3, 0, v2, vcc
	v_lshrrev_b32_e32 v2, 16, v2
	v_cmp_le_u32_e32 vcc, v108, v154
	s_nop 1
	v_cndmask_b32_e32 v2, 0, v2, vcc
	v_perm_b32 v5, v2, v3, s53
	v_add_u32_e32 v2, v20, v147
	ds_write_b64 v2, v[4:5]
	v_bitop3_b32 v2, s6, v130, v133 bitop3:0x36
	v_lshl_add_u32 v27, v2, 4, v106
	ds_read_b128 v[2:5], v27
	ds_read_b128 v[22:25], v28
	v_cmp_eq_u32_e32 vcc, 0, v160
	s_nop 1
	v_cndmask_b32_e32 v26, 1.0, v128, vcc
	v_cmp_gt_u32_e32 vcc, 8, v7
	s_nop 1
	v_cndmask_b32_e32 v7, -1, v8, vcc
	v_cmp_eq_u32_e32 vcc, 0, v7
	s_nop 1
	v_cndmask_b32_e32 v18, 0, v26, vcc
	v_cmp_eq_u32_e32 vcc, 1, v7
	s_nop 1
	v_cndmask_b32_e32 v19, 0, v26, vcc
	v_cmp_eq_u32_e32 vcc, 2, v7
	s_nop 1
	v_cndmask_b32_e32 v20, 0, v26, vcc
	v_cmp_eq_u32_e32 vcc, 3, v7
	s_nop 1
	v_cndmask_b32_e32 v21, 0, v26, vcc
	v_cmp_gt_u32_e32 vcc, 8, v29
	s_waitcnt lgkmcnt(1)
	v_mfma_f32_32x32x16_bf16 v[2:17], v[2:5], v[18:21], 0
	v_cndmask_b32_e32 v29, -1, v30, vcc
	v_cmp_eq_u32_e32 vcc, 0, v29
	s_nop 1
	v_cndmask_b32_e32 v34, 0, v26, vcc
	v_cmp_eq_u32_e32 vcc, 1, v29
	s_nop 1
	v_cndmask_b32_e32 v35, 0, v26, vcc
	v_cmp_eq_u32_e32 vcc, 2, v29
	s_nop 1
	v_cndmask_b32_e32 v36, 0, v26, vcc
	v_cmp_eq_u32_e32 vcc, 3, v29
	s_nop 1
	v_cndmask_b32_e32 v37, 0, v26, vcc
	s_waitcnt lgkmcnt(0)
	s_nop 0
	v_mfma_f32_32x32x16_bf16 v[2:17], v[22:25], v[34:37], v[2:17]
	v_add_u32_e32 v22, v153, v155
	v_add_u32_e32 v42, v22, v124
	v_add_u32_e32 v43, v22, v125
	v_add_u32_e32 v44, v22, v146
	v_add_u32_e32 v45, v22, v147
	s_nop 6
	v_cvt_pk_bf16_f32 v2, v2, v3
	v_cvt_pk_bf16_f32 v3, v4, v5
	ds_write_b64 v42, v[2:3] offset:32768
	v_cvt_pk_bf16_f32 v2, v6, v7
	v_cvt_pk_bf16_f32 v3, v8, v9
	ds_write_b64 v43, v[2:3] offset:32768
	v_cvt_pk_bf16_f32 v2, v10, v11
	v_cvt_pk_bf16_f32 v3, v12, v13
	ds_write_b64 v44, v[2:3] offset:32768
	v_cvt_pk_bf16_f32 v2, v14, v15
	v_cvt_pk_bf16_f32 v3, v16, v17
	ds_write_b64 v45, v[2:3] offset:32768
	ds_read_b128 v[2:5], v27 offset:8192
	ds_read_b128 v[38:41], v28 offset:8192
	s_waitcnt lgkmcnt(1)
	v_mfma_f32_32x32x16_bf16 v[18:33], v[2:5], v[18:21], 0
	v_mov_b64_e32 v[2:3], s[16:17]
	v_mov_b64_e32 v[4:5], s[18:19]
	v_mov_b64_e32 v[6:7], s[20:21]
	v_mov_b64_e32 v[8:9], s[22:23]
	v_mov_b64_e32 v[10:11], s[24:25]
	v_mov_b64_e32 v[12:13], s[26:27]
	v_mov_b64_e32 v[14:15], s[28:29]
	s_waitcnt lgkmcnt(0)
; __device__ __forceinline__ void chunk_pre(const P& p, Frame& F, int task, int next_task, u32x4& icr, u32x4& ick, u32x4& icv, u32x4& ipr, u32x4& ipk, u32x4& ipv, f32x4& ia0, f32x4& ia1, f32x4& iw0, f32x4& iw1, int& ptag0, int& ptag1) {
;     ...
;     for (int lev = 1; lev <= 6; ++lev) {
;         const int px = (lev & 1) ? 8 : 0, pxt = (lev & 1) ? 9 : 1, nx = (lev & 1) ? 0 : 8, nxt = (lev & 1) ? 1 : 9;
;         const int rcur = (lev & 1) ? 2 : 10, rnxt = (lev & 1) ? 10 : 2;
;         if (grp == 0) {
;             if (lev <= 5) { const f32x16 a = ck_mm(SLOT(px), SLOT(pxt), mt, nt, ql, half, ck_zero());
;                 ck_store_t(SLOT(nxt), a, mt, nt, ql, half); ck_store_n(SLOT(nx), a, mt, nt, ql, half); }
;             else aN = ck_mm(SLOT(6), SLOT(7), mt, nt, ql, half, ck_zero()); }
;         else { if (lev == 1) { f32x16 a = ck_mm(SLOT(11), SLOT(7), mt, nt, ql, half, ck_zero()); ck_store_t(SLOT(14), a, mt, nt, ql, half);
;                                aY = ck_mm(SLOT(7), SLOT(13), mt, nt, ql, half, ck_zero()); }
	v_mfma_f32_32x32x16_bf16 v[18:33], v[38:41], v[34:37], v[18:33]
	v_mov_b64_e32 v[16:17], s[30:31]
	s_mov_b32 s16, s59
	s_nop 9
	v_cvt_pk_bf16_f32 v18, v18, v19
	v_cvt_pk_bf16_f32 v19, v20, v21
	ds_write_b64 v42, v[18:19] offset:40960
	v_cvt_pk_bf16_f32 v18, v22, v23
	v_cvt_pk_bf16_f32 v19, v24, v25
	ds_write_b64 v43, v[18:19] offset:40960
	v_cvt_pk_bf16_f32 v18, v26, v27
	v_cvt_pk_bf16_f32 v19, v28, v29
	ds_write_b64 v44, v[18:19] offset:40960
	v_cvt_pk_bf16_f32 v18, v30, v31
	v_cvt_pk_bf16_f32 v19, v32, v33
	ds_write_b64 v45, v[18:19] offset:40960
	v_lshrrev_b32_e32 v18, 3, v154
	v_xor_b32_e32 v19, v18, v156
	v_lshlrev_b32_e32 v114, 4, v19
	v_or_b32_e32 v19, 1, v156
	v_lshlrev_b32_e32 v162, 7, v19
	v_bitop3_b32 v19, v18, v156, 1 bitop3:0x1e
	v_lshlrev_b32_e32 v164, 4, v19
	v_or_b32_e32 v19, 2, v156
	v_lshlrev_b32_e32 v166, 7, v19
	v_bitop3_b32 v19, v18, v156, 2 bitop3:0x1e
	v_lshlrev_b32_e32 v168, 4, v19
	v_or_b32_e32 v19, 3, v156
	v_lshlrev_b32_e32 v169, 7, v19
	v_bitop3_b32 v19, v18, v156, 3 bitop3:0x1e
	v_lshlrev_b32_e32 v171, 4, v19
	v_or_b32_e32 v19, 9, v156
	v_lshlrev_b32_e32 v172, 7, v19
	v_bitop3_b32 v19, v19, v18, 5 bitop3:0x6c
	v_lshlrev_b32_e32 v173, 4, v19
	v_or_b32_e32 v19, 10, v156
	v_lshlrev_b32_e32 v174, 7, v19
	v_bitop3_b32 v19, v19, v18, 6 bitop3:0x6c
	v_lshlrev_b32_e32 v176, 4, v19
	v_or_b32_e32 v19, 11, v156
	v_lshlrev_b32_e32 v177, 7, v19
	v_bitop3_b32 v19, v19, v18, 7 bitop3:0x6c
	v_lshlrev_b32_e32 v178, 4, v19
	v_or_b32_e32 v19, 17, v156
	v_lshlrev_b32_e32 v179, 7, v19
	v_bitop3_b32 v19, v19, v18, 5 bitop3:0x6c
	v_lshlrev_b32_e32 v181, 4, v19
	v_or_b32_e32 v19, 18, v156
	v_lshlrev_b32_e32 v183, 7, v19
	v_bitop3_b32 v19, v19, v18, 6 bitop3:0x6c
	v_lshlrev_b32_e32 v184, 4, v19
	v_or_b32_e32 v19, 19, v156
	v_lshlrev_b32_e32 v185, 7, v19
	v_bitop3_b32 v19, v19, v18, 7 bitop3:0x6c
	v_lshlrev_b32_e32 v186, 4, v19
	v_or_b32_e32 v19, 25, v156
	v_lshlrev_b32_e32 v187, 7, v19
	v_bitop3_b32 v19, v19, v18, 5 bitop3:0x6c
	v_lshlrev_b32_e32 v188, 4, v19
	v_or_b32_e32 v19, 26, v156
	v_lshlrev_b32_e32 v189, 7, v19
	v_bitop3_b32 v19, v19, v18, 6 bitop3:0x6c
	v_lshlrev_b32_e32 v190, 4, v19
	v_or_b32_e32 v19, 27, v156
	v_bitop3_b32 v18, v19, v18, 7 bitop3:0x6c
	v_lshlrev_b32_e32 v191, 7, v19
	v_lshlrev_b32_e32 v192, 4, v18
.LBB0_1663:
	s_add_i32 s16, s16, 0
	s_add_i32 s6, s16, 0x16000
	v_add_u32_e32 v18, s6, v137
	s_add_i32 s6, s58, 0x1c000
	v_add_u32_e32 v210, s16, v137
	v_add_u32_e32 v165, s6, v137
	s_mov_b64 s[6:7], -1
	s_and_b64 vcc, exec, s[44:45]
	v_add_u32_e32 v163, v210, v134
	v_add_u32_e32 v170, v210, v135
	v_add_u32_e32 v175, v210, v136
	v_add_u32_e32 v180, v210, v138
	v_add_u32_e32 v160, v18, v138
	v_add_u32_e32 v159, v18, v136
	v_add_u32_e32 v158, v18, v135
	v_add_u32_e32 v157, v18, v134
	s_waitcnt lgkmcnt(0)
	s_barrier
	s_cbranch_vccz .LBB0_1665
	ds_read_b128 v[18:21], v160
	ds_read_b128 v[22:25], v142 offset:57344
	ds_read_b128 v[34:37], v159
	ds_read_b128 v[38:41], v141 offset:57344
	ds_read_b128 v[90:93], v158
	ds_read_b128 v[94:97], v140 offset:57344
	v_add_u32_e32 v98, v165, v145
	v_add_u32_e32 v99, v98, v151
	s_waitcnt lgkmcnt(4)
	v_mfma_f32_32x32x16_bf16 v[18:33], v[18:21], v[22:25], 0
	v_add_u32_e32 v100, v98, v150
	v_add_u32_e32 v101, v98, v149
	v_add_u32_e32 v98, v98, v148
	s_add_i32 s6, s58, 0x1a000
	s_waitcnt lgkmcnt(2)
	v_mfma_f32_32x32x16_bf16 v[34:49], v[34:37], v[38:41], 0
	s_waitcnt lgkmcnt(0)
	v_mfma_f32_32x32x16_bf16 v[18:33], v[90:93], v[94:97], v[18:33]
	ds_read_b128 v[90:93], v157
	ds_read_b128 v[94:97], v139 offset:57344
	s_waitcnt lgkmcnt(0)
	v_mfma_f32_32x32x16_bf16 v[34:49], v[90:93], v[94:97], v[34:49]
	s_nop 11
	v_add_f32_e32 v20, v20, v36
	v_add_f32_e32 v21, v21, v37
	v_add_f32_e32 v18, v18, v34
	v_add_f32_e32 v19, v19, v35
	v_add_f32_e32 v24, v24, v40
	v_add_f32_e32 v25, v25, v41
	v_add_f32_e32 v22, v22, v38
	v_add_f32_e32 v23, v23, v39
	v_cvt_pk_bf16_f32 v18, v18, v19
	v_cvt_pk_bf16_f32 v19, v20, v21
	v_add_f32_e32 v28, v28, v44
	v_add_f32_e32 v29, v29, v45
	v_add_f32_e32 v26, v26, v42
	v_add_f32_e32 v27, v27, v43
	ds_write_b64 v98, v[18:19]
	v_cvt_pk_bf16_f32 v18, v22, v23
	v_cvt_pk_bf16_f32 v19, v24, v25
	v_add_f32_e32 v32, v32, v48
	v_add_f32_e32 v33, v33, v49
	v_add_f32_e32 v30, v30, v46
	v_add_f32_e32 v31, v31, v47
	ds_write_b64 v101, v[18:19]
	v_cvt_pk_bf16_f32 v18, v26, v27
	v_cvt_pk_bf16_f32 v19, v28, v29
	ds_write_b64 v100, v[18:19]
	v_cvt_pk_bf16_f32 v18, v30, v31
	v_cvt_pk_bf16_f32 v19, v32, v33
	ds_write_b64 v99, v[18:19]
	ds_read_b128 v[18:21], v180 offset:57344
	ds_read_b128 v[34:37], v175 offset:57344
	v_add_u32_e32 v98, s6, v137
	v_add_u32_e32 v22, v98, v138
	ds_read_b128 v[22:25], v22
	v_add_u32_e32 v38, v98, v136
	ds_read_b128 v[90:93], v170 offset:57344
	ds_read_b128 v[38:41], v38
	s_waitcnt lgkmcnt(2)
	v_mfma_f32_32x32x16_bf16 v[18:33], v[18:21], v[22:25], 0
	v_add_u32_e32 v94, v98, v135
	ds_read_b128 v[94:97], v94
	s_mov_b64 s[6:7], 0
	s_waitcnt lgkmcnt(0)
	v_mfma_f32_32x32x16_bf16 v[18:33], v[90:93], v[94:97], v[18:33]
	ds_read_b128 v[90:93], v163 offset:57344
	v_add_u32_e32 v94, v98, v134
	ds_read_b128 v[94:97], v94
	v_mfma_f32_32x32x16_bf16 v[34:49], v[34:37], v[38:41], 0
	s_waitcnt lgkmcnt(0)
	v_mfma_f32_32x32x16_bf16 v[34:49], v[90:93], v[94:97], v[34:49]
	s_nop 11
	v_add_f32_e32 v90, v32, v48
	v_add_f32_e32 v91, v33, v49
	v_add_f32_e32 v92, v30, v46
	v_add_f32_e32 v93, v31, v47
	v_add_f32_e32 v94, v28, v44
	v_add_f32_e32 v95, v29, v45
	v_add_f32_e32 v96, v26, v42
	v_add_f32_e32 v97, v27, v43
	v_add_f32_e32 v98, v24, v40
	v_add_f32_e32 v99, v25, v41
	v_add_f32_e32 v100, v22, v38
	v_add_f32_e32 v101, v23, v39
	v_add_f32_e32 v104, v20, v36
	v_add_f32_e32 v105, v21, v37
	v_add_f32_e32 v102, v18, v34
	v_add_f32_e32 v103, v19, v35
; __device__ __forceinline__ void chunk_pre(const P& p, Frame& F, int task, int next_task, u32x4& icr, u32x4& ick, u32x4& icv, u32x4& ipr, u32x4& ipk, u32x4& ipv, f32x4& ia0, f32x4& ia1, f32x4& iw0, f32x4& iw1, int& ptag0, int& ptag1) {
;     ...
;     for (int lev = 1; lev <= 6; ++lev) {
;         const int px = (lev & 1) ? 8 : 0, pxt = (lev & 1) ? 9 : 1, nx = (lev & 1) ? 0 : 8, nxt = (lev & 1) ? 1 : 9;
;         const int rcur = (lev & 1) ? 2 : 10, rnxt = (lev & 1) ? 10 : 2;
;         if (grp == 0) {
;             if (lev <= 5) { const f32x16 a = ck_mm(SLOT(px), SLOT(pxt), mt, nt, ql, half, ck_zero());
;                 ck_store_t(SLOT(nxt), a, mt, nt, ql, half); ck_store_n(SLOT(nx), a, mt, nt, ql, half); }
;             else aN = ck_mm(SLOT(6), SLOT(7), mt, nt, ql, half, ck_zero()); }
;         else { if (lev == 1) { f32x16 a = ck_mm(SLOT(11), SLOT(7), mt, nt, ql, half, ck_zero()); ck_store_t(SLOT(14), a, mt, nt, ql, half);
;                                aY = ck_mm(SLOT(7), SLOT(13), mt, nt, ql, half, ck_zero()); }
;           if (lev >= 2) {
;             const f32x16 a = ck_mm(SLOT(pxt), SLOT(rcur), mt, nt, ql, half, ck_zero());
; #pragma unroll
;             for (int r = 0; r < 16; ++r) rtile[r] += a[r];
;             ck_store_t(SLOT(rnxt), rtile, mt, nt, ql, half); } }
.LBB0_1665:
	s_add_i32 s20, s59, 0
	v_add_u32_e32 v211, s20, v137
	v_add_u32_e32 v161, v153, v145
	v_add_u32_e32 v18, 0x10000, v211
	v_add_u32_e32 v19, 0x12000, v153
	v_add_u32_e32 v20, s20, v182
	v_add_u32_e32 v21, s20, v162
	v_add_u32_e32 v22, s20, v166
	v_add_u32_e32 v23, s20, v169
	v_add_u32_e32 v24, s20, v172
	v_add_u32_e32 v25, s20, v174
	v_add_u32_e32 v26, s20, v177
	v_add_u32_e32 v27, s20, v179
	v_add_u32_e32 v28, s20, v183
	v_add_u32_e32 v29, s20, v185
	v_add_u32_e32 v30, s20, v187
	v_add_u32_e32 v31, s20, v189
	v_add_u32_e32 v32, s20, v191
	s_andn2_b64 vcc, exec, s[6:7]
	v_add_u32_e32 v118, v161, v124
	v_add_u32_e32 v113, v161, v125
	v_add_u32_e32 v110, v161, v146
	v_add_u32_e32 v107, v161, v147
	v_add_u32_e32 v203, v19, v138
	v_add_u32_e32 v205, v18, v138
	v_add_u32_e32 v201, v19, v136
	v_add_u32_e32 v204, v18, v136
	v_add_u32_e32 v200, v19, v135
	v_add_u32_e32 v202, v18, v135
	v_add_u32_e32 v198, v19, v134
	v_add_u32_e32 v199, v18, v134
	v_add3_u32 v106, v20, v114, v167
	v_add3_u32 v194, v21, v164, v167
	v_add3_u32 v123, v22, v168, v167
	v_add3_u32 v122, v23, v171, v167
	v_add3_u32 v121, v24, v173, v167
	v_add3_u32 v120, v25, v176, v167
	v_add3_u32 v119, v26, v178, v167
	v_add3_u32 v117, v27, v181, v167
	v_add3_u32 v116, v28, v184, v167
	v_add3_u32 v112, v29, v186, v167
	v_add3_u32 v111, v30, v188, v167
	v_add3_u32 v109, v31, v190, v167
	v_add3_u32 v108, v32, v192, v167
	s_cbranch_vccnz .LBB0_1667
	ds_read_b128 v[18:21], v205
	ds_read_b128 v[22:25], v203
	ds_read_b128 v[34:37], v204
	ds_read_b128 v[38:41], v201
	ds_read_b128 v[90:93], v202
	ds_read_b128 v[94:97], v200
	v_mov_b32_e32 v102, 0
	v_mov_b32_e32 v103, 0
	s_waitcnt lgkmcnt(4)
	v_mfma_f32_32x32x16_bf16 v[18:33], v[18:21], v[22:25], 0
	v_mov_b32_e32 v104, 0
	v_mov_b32_e32 v105, 0
	v_mov_b32_e32 v100, 0
	v_mov_b32_e32 v101, 0
	v_mov_b32_e32 v98, 0
	v_mov_b32_e32 v99, 0
	s_waitcnt lgkmcnt(2)
	v_mfma_f32_32x32x16_bf16 v[34:49], v[34:37], v[38:41], 0
	s_waitcnt lgkmcnt(0)
	v_mfma_f32_32x32x16_bf16 v[18:33], v[90:93], v[94:97], v[18:33]
	ds_read_b128 v[90:93], v199
	ds_read_b128 v[94:97], v198
	s_waitcnt lgkmcnt(0)
	v_mfma_f32_32x32x16_bf16 v[34:49], v[90:93], v[94:97], v[34:49]
	v_mov_b32_e32 v96, 0
	v_mov_b32_e32 v97, 0
	v_mov_b32_e32 v94, 0
	v_mov_b32_e32 v95, 0
	v_mov_b32_e32 v92, 0
	v_mov_b32_e32 v93, 0
	v_mov_b32_e32 v90, 0
	s_nop 4
	v_add_f32_e32 v20, v20, v36
	v_add_f32_e32 v21, v21, v37
	v_add_f32_e32 v18, v18, v34
	v_add_f32_e32 v19, v19, v35
	v_add_f32_e32 v24, v24, v40
	v_add_f32_e32 v25, v25, v41
	v_add_f32_e32 v22, v22, v38
	v_add_f32_e32 v23, v23, v39
	v_cvt_pk_bf16_f32 v34, v18, v19
	v_cvt_pk_bf16_f32 v35, v20, v21
	v_add_f32_e32 v28, v28, v44
	v_add_f32_e32 v29, v29, v45
	v_add_f32_e32 v26, v26, v42
	v_add_f32_e32 v27, v27, v43
	ds_write_b64 v118, v[34:35] offset:8192
	v_cvt_pk_bf16_f32 v34, v22, v23
	v_cvt_pk_bf16_f32 v35, v24, v25
	v_add_f32_e32 v32, v32, v48
	v_add_f32_e32 v33, v33, v49
	v_add_f32_e32 v30, v30, v46
	v_add_f32_e32 v31, v31, v47
	ds_write_b64 v113, v[34:35] offset:8192
	v_cvt_pk_bf16_f32 v34, v26, v27
	v_cvt_pk_bf16_f32 v35, v28, v29
	ds_write_b64 v110, v[34:35] offset:8192
	v_cvt_pk_bf16_f32 v34, v30, v31
	v_cvt_pk_bf16_f32 v35, v32, v33
	v_cvt_pk_bf16_f32 v18, v18, s0
	ds_write_b64 v107, v[34:35] offset:8192
	ds_write_b16 v106, v18
	v_cvt_pk_bf16_f32 v18, v19, s0
	ds_write_b16 v194, v18
	v_cvt_pk_bf16_f32 v18, v20, s0
	ds_write_b16 v123, v18
	v_cvt_pk_bf16_f32 v18, v21, s0
	ds_write_b16 v122, v18
	v_cvt_pk_bf16_f32 v18, v22, s0
	ds_write_b16 v106, v18 offset:1024
	v_cvt_pk_bf16_f32 v18, v23, s0
	ds_write_b16 v121, v18
	v_cvt_pk_bf16_f32 v18, v24, s0
	ds_write_b16 v120, v18
	v_cvt_pk_bf16_f32 v18, v25, s0
	ds_write_b16 v119, v18
	v_cvt_pk_bf16_f32 v18, v26, s0
	ds_write_b16 v106, v18 offset:2048
	v_cvt_pk_bf16_f32 v18, v27, s0
	ds_write_b16 v117, v18
	v_cvt_pk_bf16_f32 v18, v28, s0
	ds_write_b16 v116, v18
	v_cvt_pk_bf16_f32 v18, v29, s0
	ds_write_b16 v112, v18
	v_cvt_pk_bf16_f32 v18, v30, s0
	ds_write_b16 v106, v18 offset:3072
	v_cvt_pk_bf16_f32 v18, v31, s0
	ds_write_b16 v111, v18
	v_cvt_pk_bf16_f32 v18, v32, s0
	ds_write_b16 v109, v18
	v_cvt_pk_bf16_f32 v18, v33, s0
	v_mov_b32_e32 v91, 0
	ds_write_b16 v108, v18
.LBB0_1667:
	v_cndmask_b32_e64 v18, 0, 1, s[44:45]
	v_cmp_ne_u32_e64 s[6:7], 1, v18
	v_add_u32_e32 v18, 0x14000, v153
	s_mov_b64 s[18:19], -1
	s_andn2_b64 vcc, exec, s[44:45]
	v_add_u32_e32 v193, v161, v148
	v_add_u32_e32 v197, v161, v149
	v_add_u32_e32 v196, v161, v150
	v_add_u32_e32 v195, v161, v151
	v_add_u32_e32 v209, v18, v138
	v_add_u32_e32 v208, v18, v136
	v_add_u32_e32 v207, v18, v135
	v_add_u32_e32 v206, v18, v134
	s_waitcnt lgkmcnt(0)
	s_barrier
	s_cbranch_vccnz .LBB0_1669
	ds_read_b128 v[18:21], v209
	ds_read_b128 v[22:25], v180 offset:8192
	ds_read_b128 v[34:37], v208
	ds_read_b128 v[38:41], v175 offset:8192
	ds_read_b128 v[212:215], v207
	ds_read_b128 v[216:219], v170 offset:8192
	s_mov_b64 s[18:19], 0
	s_waitcnt lgkmcnt(4)
	v_mfma_f32_32x32x16_bf16 v[18:33], v[22:25], v[18:21], 0
	s_waitcnt lgkmcnt(2)
	v_mfma_f32_32x32x16_bf16 v[34:49], v[38:41], v[34:37], 0
	s_waitcnt lgkmcnt(0)
	v_mfma_f32_32x32x16_bf16 v[18:33], v[216:219], v[212:215], v[18:33]
	ds_read_b128 v[212:215], v206
	ds_read_b128 v[216:219], v163 offset:8192
	s_waitcnt lgkmcnt(0)
	v_mfma_f32_32x32x16_bf16 v[34:49], v[216:219], v[212:215], v[34:49]
	s_nop 11
	v_add_f32_e32 v20, v20, v36
	v_add_f32_e32 v21, v21, v37
	v_add_f32_e32 v18, v18, v34
	v_add_f32_e32 v19, v19, v35
	v_add_f32_e32 v22, v22, v38
	v_add_f32_e32 v23, v23, v39
	v_add_f32_e32 v24, v24, v40
	v_add_f32_e32 v25, v25, v41
	v_add_f32_e32 v20, v4, v20
	v_add_f32_e32 v21, v5, v21
	v_add_f32_e32 v18, v2, v18
	v_add_f32_e32 v19, v3, v19
	v_add_f32_e32 v26, v26, v42
	v_add_f32_e32 v27, v27, v43
	v_add_f32_e32 v28, v28, v44
	v_add_f32_e32 v29, v29, v45
	v_add_f32_e32 v24, v8, v24
	v_add_f32_e32 v25, v9, v25
	v_add_f32_e32 v22, v6, v22
	v_add_f32_e32 v23, v7, v23
	v_cvt_pk_bf16_f32 v34, v18, v19
	v_cvt_pk_bf16_f32 v35, v20, v21
	v_add_f32_e32 v30, v30, v46
	v_add_f32_e32 v31, v31, v47
	v_add_f32_e32 v32, v32, v48
	v_add_f32_e32 v33, v33, v49
	v_add_f32_e32 v28, v12, v28
	v_add_f32_e32 v29, v13, v29
	v_add_f32_e32 v26, v10, v26
	v_add_f32_e32 v27, v11, v27
	ds_write_b64 v193, v[34:35] offset:16384
	v_cvt_pk_bf16_f32 v34, v22, v23
	v_cvt_pk_bf16_f32 v35, v24, v25
	v_add_f32_e32 v32, v16, v32
	v_add_f32_e32 v33, v17, v33
	v_add_f32_e32 v30, v14, v30
	v_add_f32_e32 v31, v15, v31
	ds_write_b64 v197, v[34:35] offset:16384
	v_cvt_pk_bf16_f32 v34, v26, v27
	v_cvt_pk_bf16_f32 v35, v28, v29
	ds_write_b64 v196, v[34:35] offset:16384
	v_cvt_pk_bf16_f32 v34, v30, v31
	v_cvt_pk_bf16_f32 v35, v32, v33
	ds_write_b64 v195, v[34:35] offset:16384
; __device__ __forceinline__ void chunk_pre(const P& p, Frame& F, int task, int next_task, u32x4& icr, u32x4& ick, u32x4& icv, u32x4& ipr, u32x4& ipk, u32x4& ipv, f32x4& ia0, f32x4& ia1, f32x4& iw0, f32x4& iw1, int& ptag0, int& ptag1) {
;     ...
;     for (int lev = 1; lev <= 6; ++lev) {
;         const int px = (lev & 1) ? 8 : 0, pxt = (lev & 1) ? 9 : 1, nx = (lev & 1) ? 0 : 8, nxt = (lev & 1) ? 1 : 9;
;         const int rcur = (lev & 1) ? 2 : 10, rnxt = (lev & 1) ? 10 : 2;
;         if (grp == 0) {
;             if (lev <= 5) { const f32x16 a = ck_mm(SLOT(px), SLOT(pxt), mt, nt, ql, half, ck_zero());
;                 ck_store_t(SLOT(nxt), a, mt, nt, ql, half); ck_store_n(SLOT(nx), a, mt, nt, ql, half); }
;             else aN = ck_mm(SLOT(6), SLOT(7), mt, nt, ql, half, ck_zero()); }
;         else { if (lev == 1) { f32x16 a = ck_mm(SLOT(11), SLOT(7), mt, nt, ql, half, ck_zero()); ck_store_t(SLOT(14), a, mt, nt, ql, half);
;                                aY = ck_mm(SLOT(7), SLOT(13), mt, nt, ql, half, ck_zero()); }
;           if (lev >= 2) {
;             const f32x16 a = ck_mm(SLOT(pxt), SLOT(rcur), mt, nt, ql, half, ck_zero());
; #pragma unroll
;             for (int r = 0; r < 16; ++r) rtile[r] += a[r];
;             ck_store_t(SLOT(rnxt), rtile, mt, nt, ql, half); } }
.LBB0_1669:
	v_add_u32_e32 v34, 0x12000, v161
	s_andn2_b64 vcc, exec, s[18:19]
	v_add_u32_e32 v156, v211, v138
	v_add_u32_e32 v155, v211, v136
	v_add_u32_e32 v154, v211, v135
	v_add_u32_e32 v153, v211, v134
	v_add_u32_e32 v217, v34, v124
	v_add_u32_e32 v216, v34, v125
	v_add_u32_e32 v215, v34, v146
	v_add_u32_e32 v214, v34, v147
	s_cbranch_vccnz .LBB0_1671
	ds_read_b128 v[18:21], v142 offset:8192
	ds_read_b128 v[22:25], v156
	ds_read_b128 v[34:37], v141 offset:8192
	ds_read_b128 v[38:41], v155
	ds_read_b128 v[218:221], v140 offset:8192
	ds_read_b128 v[222:225], v154
	s_add_i32 s18, s20, 0x10000
	s_waitcnt lgkmcnt(4)
	v_mfma_f32_32x32x16_bf16 v[18:33], v[22:25], v[18:21], 0
	s_waitcnt lgkmcnt(2)
	v_mfma_f32_32x32x16_bf16 v[34:49], v[38:41], v[34:37], 0
	s_waitcnt lgkmcnt(0)
	v_mfma_f32_32x32x16_bf16 v[18:33], v[222:225], v[218:221], v[18:33]
	ds_read_b128 v[218:221], v139 offset:8192
	ds_read_b128 v[222:225], v153
	s_waitcnt lgkmcnt(0)
	v_mfma_f32_32x32x16_bf16 v[34:49], v[222:225], v[218:221], v[34:49]
	s_nop 11
	v_add_f32_e32 v20, v20, v36
	v_add_f32_e32 v21, v21, v37
	v_add_f32_e32 v18, v18, v34
	v_add_f32_e32 v19, v19, v35
	v_add_f32_e32 v24, v24, v40
	v_add_f32_e32 v25, v25, v41
	v_add_f32_e32 v22, v22, v38
	v_add_f32_e32 v23, v23, v39
	v_cvt_pk_bf16_f32 v34, v18, v19
	v_cvt_pk_bf16_f32 v35, v20, v21
	v_add_f32_e32 v28, v28, v44
	v_add_f32_e32 v29, v29, v45
	v_add_f32_e32 v26, v26, v42
	v_add_f32_e32 v27, v27, v43
	ds_write_b64 v217, v[34:35]
	v_cvt_pk_bf16_f32 v34, v22, v23
	v_cvt_pk_bf16_f32 v35, v24, v25
	v_add_f32_e32 v32, v32, v48
	v_add_f32_e32 v33, v33, v49
	v_add_f32_e32 v30, v30, v46
	v_add_f32_e32 v31, v31, v47
	ds_write_b64 v216, v[34:35]
	v_cvt_pk_bf16_f32 v34, v26, v27
	v_cvt_pk_bf16_f32 v35, v28, v29
	ds_write_b64 v215, v[34:35]
	v_cvt_pk_bf16_f32 v34, v30, v31
	v_cvt_pk_bf16_f32 v35, v32, v33
	ds_write_b64 v214, v[34:35]
	v_add_u32_e32 v34, s18, v182
	v_cvt_pk_bf16_f32 v18, v18, s0
	v_add3_u32 v34, v34, v114, v167
	ds_write_b16 v34, v18
	v_cvt_pk_bf16_f32 v18, v19, s0
	v_add_u32_e32 v19, s18, v162
	v_add3_u32 v19, v19, v164, v167
	ds_write_b16 v19, v18
	v_add_u32_e32 v19, s18, v166
	v_cvt_pk_bf16_f32 v18, v20, s0
	v_add3_u32 v19, v19, v168, v167
	ds_write_b16 v19, v18
	v_add_u32_e32 v19, s18, v169
	v_cvt_pk_bf16_f32 v18, v21, s0
	v_add3_u32 v19, v19, v171, v167
	ds_write_b16 v19, v18
	v_cvt_pk_bf16_f32 v18, v22, s0
	v_add_u32_e32 v19, s18, v172
	ds_write_b16 v34, v18 offset:1024
	v_cvt_pk_bf16_f32 v18, v23, s0
	v_add3_u32 v19, v19, v173, v167
	ds_write_b16 v19, v18
	v_add_u32_e32 v19, s18, v174
	v_cvt_pk_bf16_f32 v18, v24, s0
	v_add3_u32 v19, v19, v176, v167
	ds_write_b16 v19, v18
	v_add_u32_e32 v19, s18, v177
	v_cvt_pk_bf16_f32 v18, v25, s0
	v_add3_u32 v19, v19, v178, v167
	ds_write_b16 v19, v18
	v_cvt_pk_bf16_f32 v18, v26, s0
	v_add_u32_e32 v19, s18, v179
	ds_write_b16 v34, v18 offset:2048
	v_cvt_pk_bf16_f32 v18, v27, s0
	v_add3_u32 v19, v19, v181, v167
	ds_write_b16 v19, v18
	v_add_u32_e32 v19, s18, v183
	v_cvt_pk_bf16_f32 v18, v28, s0
	v_add3_u32 v19, v19, v184, v167
	ds_write_b16 v19, v18
	v_add_u32_e32 v19, s18, v185
	v_cvt_pk_bf16_f32 v18, v29, s0
	v_add3_u32 v19, v19, v186, v167
	ds_write_b16 v19, v18
	v_cvt_pk_bf16_f32 v18, v30, s0
	v_add_u32_e32 v19, s18, v187
	ds_write_b16 v34, v18 offset:3072
	v_cvt_pk_bf16_f32 v18, v31, s0
	v_add3_u32 v19, v19, v188, v167
	ds_write_b16 v19, v18
	v_add_u32_e32 v19, s18, v189
	v_cvt_pk_bf16_f32 v18, v32, s0
	v_add3_u32 v19, v19, v190, v167
	ds_write_b16 v19, v18
	v_add_u32_e32 v19, s18, v191
	v_cvt_pk_bf16_f32 v18, v33, s0
	v_add3_u32 v19, v19, v192, v167
	ds_write_b16 v19, v18
	v_mov_b64_e32 v[32:33], v[16:17]
	v_mov_b64_e32 v[30:31], v[14:15]
	v_mov_b64_e32 v[28:29], v[12:13]
	v_mov_b64_e32 v[26:27], v[10:11]
	v_mov_b64_e32 v[24:25], v[8:9]
	v_mov_b64_e32 v[22:23], v[6:7]
	v_mov_b64_e32 v[20:21], v[4:5]
	v_mov_b64_e32 v[18:19], v[2:3]
.LBB0_1671:
	v_add_u32_e32 v2, 0x12000, v210
	v_add_u32_e32 v3, 0x14000, v161
	s_mov_b64 s[18:19], -1
	s_and_b64 vcc, exec, s[6:7]
	v_add_u32_e32 v221, v2, v138
	v_add_u32_e32 v220, v2, v136
	v_add_u32_e32 v219, v2, v135
	v_add_u32_e32 v218, v2, v134
	v_add_u32_e32 v213, v3, v148
	v_add_u32_e32 v212, v3, v149
	v_add_u32_e32 v211, v3, v150
	v_add_u32_e32 v210, v3, v151
	s_waitcnt lgkmcnt(0)
	s_barrier
	s_cbranch_vccnz .LBB0_1673
	ds_read_b128 v[2:5], v142 offset:16384
	ds_read_b128 v[6:9], v221
	ds_read_b128 v[34:37], v141 offset:16384
	ds_read_b128 v[38:41], v220
	ds_read_b128 v[222:225], v140 offset:16384
	ds_read_b128 v[226:229], v219
	s_mov_b64 s[18:19], 0
	s_waitcnt lgkmcnt(4)
	v_mfma_f32_32x32x16_bf16 v[2:17], v[6:9], v[2:5], 0
	s_waitcnt lgkmcnt(2)
	v_mfma_f32_32x32x16_bf16 v[34:49], v[38:41], v[34:37], 0
	s_waitcnt lgkmcnt(0)
	v_mfma_f32_32x32x16_bf16 v[2:17], v[226:229], v[222:225], v[2:17]
	ds_read_b128 v[222:225], v139 offset:16384
	ds_read_b128 v[226:229], v218
	s_waitcnt lgkmcnt(0)
	v_mfma_f32_32x32x16_bf16 v[34:49], v[226:229], v[222:225], v[34:49]
	s_nop 11
	v_add_f32_e32 v4, v4, v36
	v_add_f32_e32 v5, v5, v37
	v_add_f32_e32 v2, v2, v34
	v_add_f32_e32 v3, v3, v35
	v_add_f32_e32 v6, v6, v38
	v_add_f32_e32 v7, v7, v39
	v_add_f32_e32 v8, v8, v40
	v_add_f32_e32 v9, v9, v41
	v_add_f32_e32 v4, v20, v4
	v_add_f32_e32 v5, v21, v5
	v_add_f32_e32 v2, v18, v2
	v_add_f32_e32 v3, v19, v3
	v_add_f32_e32 v10, v10, v42
	v_add_f32_e32 v11, v11, v43
	v_add_f32_e32 v12, v12, v44
	v_add_f32_e32 v13, v13, v45
	v_add_f32_e32 v8, v24, v8
	v_add_f32_e32 v9, v25, v9
	v_add_f32_e32 v6, v22, v6
	v_add_f32_e32 v7, v23, v7
	v_cvt_pk_bf16_f32 v34, v2, v3
	v_cvt_pk_bf16_f32 v35, v4, v5
	v_add_f32_e32 v14, v14, v46
	v_add_f32_e32 v15, v15, v47
	v_add_f32_e32 v16, v16, v48
	v_add_f32_e32 v17, v17, v49
	v_add_f32_e32 v12, v28, v12
	v_add_f32_e32 v13, v29, v13
	v_add_f32_e32 v10, v26, v10
	v_add_f32_e32 v11, v27, v11
	ds_write_b64 v213, v[34:35]
	v_cvt_pk_bf16_f32 v34, v6, v7
	v_cvt_pk_bf16_f32 v35, v8, v9
	v_add_f32_e32 v16, v32, v16
	v_add_f32_e32 v17, v33, v17
	v_add_f32_e32 v14, v30, v14
	v_add_f32_e32 v15, v31, v15
	ds_write_b64 v212, v[34:35]
	v_cvt_pk_bf16_f32 v34, v10, v11
	v_cvt_pk_bf16_f32 v35, v12, v13
	ds_write_b64 v211, v[34:35]
	v_cvt_pk_bf16_f32 v34, v14, v15
	v_cvt_pk_bf16_f32 v35, v16, v17
	ds_write_b64 v210, v[34:35]
; __device__ __forceinline__ void chunk_pre(const P& p, Frame& F, int task, int next_task, u32x4& icr, u32x4& ick, u32x4& icv, u32x4& ipr, u32x4& ipk, u32x4& ipv, f32x4& ia0, f32x4& ia1, f32x4& iw0, f32x4& iw1, int& ptag0, int& ptag1) {
;     ...
;     for (int lev = 1; lev <= 6; ++lev) {
;         const int px = (lev & 1) ? 8 : 0, pxt = (lev & 1) ? 9 : 1, nx = (lev & 1) ? 0 : 8, nxt = (lev & 1) ? 1 : 9;
;         const int rcur = (lev & 1) ? 2 : 10, rnxt = (lev & 1) ? 10 : 2;
;         if (grp == 0) {
;             if (lev <= 5) { const f32x16 a = ck_mm(SLOT(px), SLOT(pxt), mt, nt, ql, half, ck_zero());
;                 ck_store_t(SLOT(nxt), a, mt, nt, ql, half); ck_store_n(SLOT(nx), a, mt, nt, ql, half); }
;             else aN = ck_mm(SLOT(6), SLOT(7), mt, nt, ql, half, ck_zero()); }
;         else { if (lev == 1) { f32x16 a = ck_mm(SLOT(11), SLOT(7), mt, nt, ql, half, ck_zero()); ck_store_t(SLOT(14), a, mt, nt, ql, half);
;                                aY = ck_mm(SLOT(7), SLOT(13), mt, nt, ql, half, ck_zero()); }
;           if (lev >= 2) {
;             const f32x16 a = ck_mm(SLOT(pxt), SLOT(rcur), mt, nt, ql, half, ck_zero());
; #pragma unroll
;             for (int r = 0; r < 16; ++r) rtile[r] += a[r];
;             ck_store_t(SLOT(rnxt), rtile, mt, nt, ql, half); } }
.LBB0_1673:
	s_andn2_b64 vcc, exec, s[18:19]
	s_cbranch_vccnz .LBB0_1675
	ds_read_b128 v[2:5], v205
	ds_read_b128 v[6:9], v203
	ds_read_b128 v[34:37], v204
	ds_read_b128 v[38:41], v201
	ds_read_b128 v[222:225], v202
	ds_read_b128 v[226:229], v200
	s_waitcnt lgkmcnt(4)
	v_mfma_f32_32x32x16_bf16 v[2:17], v[2:5], v[6:9], 0
	s_waitcnt lgkmcnt(2)
	v_mfma_f32_32x32x16_bf16 v[34:49], v[34:37], v[38:41], 0
	s_waitcnt lgkmcnt(0)
	v_mfma_f32_32x32x16_bf16 v[2:17], v[222:225], v[226:229], v[2:17]
	ds_read_b128 v[222:225], v199
	ds_read_b128 v[226:229], v198
	s_waitcnt lgkmcnt(0)
	v_mfma_f32_32x32x16_bf16 v[34:49], v[222:225], v[226:229], v[34:49]
	s_nop 11
	v_add_f32_e32 v4, v4, v36
	v_add_f32_e32 v5, v5, v37
	v_add_f32_e32 v2, v2, v34
	v_add_f32_e32 v3, v3, v35
	v_add_f32_e32 v8, v8, v40
	v_add_f32_e32 v9, v9, v41
	v_add_f32_e32 v6, v6, v38
	v_add_f32_e32 v7, v7, v39
	v_cvt_pk_bf16_f32 v34, v2, v3
	v_cvt_pk_bf16_f32 v35, v4, v5
	v_add_f32_e32 v12, v12, v44
	v_add_f32_e32 v13, v13, v45
	v_add_f32_e32 v10, v10, v42
	v_add_f32_e32 v11, v11, v43
	ds_write_b64 v118, v[34:35] offset:8192
	v_cvt_pk_bf16_f32 v34, v6, v7
	v_cvt_pk_bf16_f32 v35, v8, v9
	v_add_f32_e32 v16, v16, v48
	v_add_f32_e32 v17, v17, v49
	v_add_f32_e32 v14, v14, v46
	v_add_f32_e32 v15, v15, v47
	ds_write_b64 v113, v[34:35] offset:8192
	v_cvt_pk_bf16_f32 v34, v10, v11
	v_cvt_pk_bf16_f32 v35, v12, v13
	ds_write_b64 v110, v[34:35] offset:8192
	v_cvt_pk_bf16_f32 v34, v14, v15
	v_cvt_pk_bf16_f32 v35, v16, v17
	v_cvt_pk_bf16_f32 v2, v2, s0
	ds_write_b64 v107, v[34:35] offset:8192
	ds_write_b16 v106, v2
	v_cvt_pk_bf16_f32 v2, v3, s0
	ds_write_b16 v194, v2
	v_cvt_pk_bf16_f32 v2, v4, s0
	ds_write_b16 v123, v2
	v_cvt_pk_bf16_f32 v2, v5, s0
	ds_write_b16 v122, v2
	v_cvt_pk_bf16_f32 v2, v6, s0
	ds_write_b16 v106, v2 offset:1024
	v_cvt_pk_bf16_f32 v2, v7, s0
	ds_write_b16 v121, v2
	v_cvt_pk_bf16_f32 v2, v8, s0
	ds_write_b16 v120, v2
	v_cvt_pk_bf16_f32 v2, v9, s0
	ds_write_b16 v119, v2
	v_cvt_pk_bf16_f32 v2, v10, s0
	ds_write_b16 v106, v2 offset:2048
	v_cvt_pk_bf16_f32 v2, v11, s0
	ds_write_b16 v117, v2
	v_cvt_pk_bf16_f32 v2, v12, s0
	ds_write_b16 v116, v2
	v_cvt_pk_bf16_f32 v2, v13, s0
	ds_write_b16 v112, v2
	v_cvt_pk_bf16_f32 v2, v14, s0
	ds_write_b16 v106, v2 offset:3072
	v_cvt_pk_bf16_f32 v2, v15, s0
	ds_write_b16 v111, v2
	v_cvt_pk_bf16_f32 v2, v16, s0
	ds_write_b16 v109, v2
	v_cvt_pk_bf16_f32 v2, v17, s0
	ds_write_b16 v108, v2
	v_mov_b64_e32 v[2:3], v[18:19]
	v_mov_b64_e32 v[4:5], v[20:21]
	v_mov_b64_e32 v[6:7], v[22:23]
	v_mov_b64_e32 v[8:9], v[24:25]
	v_mov_b64_e32 v[10:11], v[26:27]
	v_mov_b64_e32 v[12:13], v[28:29]
	v_mov_b64_e32 v[14:15], v[30:31]
	v_mov_b64_e32 v[16:17], v[32:33]
.LBB0_1675:
	s_and_b64 vcc, exec, s[6:7]
	s_mov_b64 s[18:19], -1
	s_waitcnt lgkmcnt(0)
	s_barrier
	s_cbranch_vccnz .LBB0_1677
	ds_read_b128 v[18:21], v209
	ds_read_b128 v[22:25], v180 offset:8192
	ds_read_b128 v[34:37], v208
	ds_read_b128 v[38:41], v175 offset:8192
	ds_read_b128 v[222:225], v207
	ds_read_b128 v[226:229], v170 offset:8192
	s_mov_b64 s[18:19], 0
	s_waitcnt lgkmcnt(4)
	v_mfma_f32_32x32x16_bf16 v[18:33], v[22:25], v[18:21], 0
	s_waitcnt lgkmcnt(2)
	v_mfma_f32_32x32x16_bf16 v[34:49], v[38:41], v[34:37], 0
	s_waitcnt lgkmcnt(0)
	v_mfma_f32_32x32x16_bf16 v[18:33], v[226:229], v[222:225], v[18:33]
	ds_read_b128 v[222:225], v206
	ds_read_b128 v[226:229], v163 offset:8192
	s_waitcnt lgkmcnt(0)
	v_mfma_f32_32x32x16_bf16 v[34:49], v[226:229], v[222:225], v[34:49]
	s_nop 11
	v_add_f32_e32 v20, v20, v36
	v_add_f32_e32 v21, v21, v37
	v_add_f32_e32 v18, v18, v34
	v_add_f32_e32 v19, v19, v35
	v_add_f32_e32 v22, v22, v38
	v_add_f32_e32 v23, v23, v39
	v_add_f32_e32 v24, v24, v40
	v_add_f32_e32 v25, v25, v41
	v_add_f32_e32 v20, v4, v20
	v_add_f32_e32 v21, v5, v21
	v_add_f32_e32 v18, v2, v18
	v_add_f32_e32 v19, v3, v19
	v_add_f32_e32 v26, v26, v42
	v_add_f32_e32 v27, v27, v43
	v_add_f32_e32 v28, v28, v44
	v_add_f32_e32 v29, v29, v45
	v_add_f32_e32 v24, v8, v24
	v_add_f32_e32 v25, v9, v25
	v_add_f32_e32 v22, v6, v22
	v_add_f32_e32 v23, v7, v23
	v_cvt_pk_bf16_f32 v34, v18, v19
	v_cvt_pk_bf16_f32 v35, v20, v21
	v_add_f32_e32 v30, v30, v46
	v_add_f32_e32 v31, v31, v47
	v_add_f32_e32 v32, v32, v48
	v_add_f32_e32 v33, v33, v49
	v_add_f32_e32 v28, v12, v28
	v_add_f32_e32 v29, v13, v29
	v_add_f32_e32 v26, v10, v26
	v_add_f32_e32 v27, v11, v27
	ds_write_b64 v193, v[34:35] offset:16384
	v_cvt_pk_bf16_f32 v34, v22, v23
	v_cvt_pk_bf16_f32 v35, v24, v25
	v_add_f32_e32 v32, v16, v32
	v_add_f32_e32 v33, v17, v33
	v_add_f32_e32 v30, v14, v30
	v_add_f32_e32 v31, v15, v31
	ds_write_b64 v197, v[34:35] offset:16384
	v_cvt_pk_bf16_f32 v34, v26, v27
	v_cvt_pk_bf16_f32 v35, v28, v29
	ds_write_b64 v196, v[34:35] offset:16384
	v_cvt_pk_bf16_f32 v34, v30, v31
	v_cvt_pk_bf16_f32 v35, v32, v33
	ds_write_b64 v195, v[34:35] offset:16384
; __device__ __forceinline__ void chunk_pre(const P& p, Frame& F, int task, int next_task, u32x4& icr, u32x4& ick, u32x4& icv, u32x4& ipr, u32x4& ipk, u32x4& ipv, f32x4& ia0, f32x4& ia1, f32x4& iw0, f32x4& iw1, int& ptag0, int& ptag1) {
;     ...
;     for (int lev = 1; lev <= 6; ++lev) {
;         const int px = (lev & 1) ? 8 : 0, pxt = (lev & 1) ? 9 : 1, nx = (lev & 1) ? 0 : 8, nxt = (lev & 1) ? 1 : 9;
;         const int rcur = (lev & 1) ? 2 : 10, rnxt = (lev & 1) ? 10 : 2;
;         if (grp == 0) {
;             if (lev <= 5) { const f32x16 a = ck_mm(SLOT(px), SLOT(pxt), mt, nt, ql, half, ck_zero());
;                 ck_store_t(SLOT(nxt), a, mt, nt, ql, half); ck_store_n(SLOT(nx), a, mt, nt, ql, half); }
;             else aN = ck_mm(SLOT(6), SLOT(7), mt, nt, ql, half, ck_zero()); }
;         else { if (lev == 1) { f32x16 a = ck_mm(SLOT(11), SLOT(7), mt, nt, ql, half, ck_zero()); ck_store_t(SLOT(14), a, mt, nt, ql, half);
;                                aY = ck_mm(SLOT(7), SLOT(13), mt, nt, ql, half, ck_zero()); }
;           if (lev >= 2) {
;             const f32x16 a = ck_mm(SLOT(pxt), SLOT(rcur), mt, nt, ql, half, ck_zero());
; #pragma unroll
;             for (int r = 0; r < 16; ++r) rtile[r] += a[r];
;             ck_store_t(SLOT(rnxt), rtile, mt, nt, ql, half); } }
.LBB0_1677:
	s_andn2_b64 vcc, exec, s[18:19]
	s_cbranch_vccnz .LBB0_1679
	ds_read_b128 v[18:21], v142 offset:8192
	ds_read_b128 v[22:25], v156
	ds_read_b128 v[34:37], v141 offset:8192
	ds_read_b128 v[38:41], v155
	ds_read_b128 v[222:225], v140 offset:8192
	ds_read_b128 v[226:229], v154
	s_add_i32 s18, s20, 0x10000
	s_waitcnt lgkmcnt(4)
	v_mfma_f32_32x32x16_bf16 v[18:33], v[22:25], v[18:21], 0
	s_waitcnt lgkmcnt(2)
	v_mfma_f32_32x32x16_bf16 v[34:49], v[38:41], v[34:37], 0
	s_waitcnt lgkmcnt(0)
	v_mfma_f32_32x32x16_bf16 v[18:33], v[226:229], v[222:225], v[18:33]
	ds_read_b128 v[222:225], v139 offset:8192
	ds_read_b128 v[226:229], v153
	s_waitcnt lgkmcnt(0)
	v_mfma_f32_32x32x16_bf16 v[34:49], v[226:229], v[222:225], v[34:49]
	s_nop 11
	v_add_f32_e32 v20, v20, v36
	v_add_f32_e32 v21, v21, v37
	v_add_f32_e32 v18, v18, v34
	v_add_f32_e32 v19, v19, v35
	v_add_f32_e32 v24, v24, v40
	v_add_f32_e32 v25, v25, v41
	v_add_f32_e32 v22, v22, v38
	v_add_f32_e32 v23, v23, v39
	v_cvt_pk_bf16_f32 v34, v18, v19
	v_cvt_pk_bf16_f32 v35, v20, v21
	v_add_f32_e32 v28, v28, v44
	v_add_f32_e32 v29, v29, v45
	v_add_f32_e32 v26, v26, v42
	v_add_f32_e32 v27, v27, v43
	ds_write_b64 v217, v[34:35]
	v_cvt_pk_bf16_f32 v34, v22, v23
	v_cvt_pk_bf16_f32 v35, v24, v25
	v_add_f32_e32 v32, v32, v48
	v_add_f32_e32 v33, v33, v49
	v_add_f32_e32 v30, v30, v46
	v_add_f32_e32 v31, v31, v47
	ds_write_b64 v216, v[34:35]
	v_cvt_pk_bf16_f32 v34, v26, v27
	v_cvt_pk_bf16_f32 v35, v28, v29
	ds_write_b64 v215, v[34:35]
	v_cvt_pk_bf16_f32 v34, v30, v31
	v_cvt_pk_bf16_f32 v35, v32, v33
	ds_write_b64 v214, v[34:35]
	v_add_u32_e32 v34, s18, v182
	v_cvt_pk_bf16_f32 v18, v18, s0
	v_add3_u32 v34, v34, v114, v167
	ds_write_b16 v34, v18
	v_cvt_pk_bf16_f32 v18, v19, s0
	v_add_u32_e32 v19, s18, v162
	v_add3_u32 v19, v19, v164, v167
	ds_write_b16 v19, v18
	v_add_u32_e32 v19, s18, v166
	v_cvt_pk_bf16_f32 v18, v20, s0
	v_add3_u32 v19, v19, v168, v167
	ds_write_b16 v19, v18
	v_add_u32_e32 v19, s18, v169
	v_cvt_pk_bf16_f32 v18, v21, s0
	v_add3_u32 v19, v19, v171, v167
	ds_write_b16 v19, v18
	v_cvt_pk_bf16_f32 v18, v22, s0
	v_add_u32_e32 v19, s18, v172
	ds_write_b16 v34, v18 offset:1024
	v_cvt_pk_bf16_f32 v18, v23, s0
	v_add3_u32 v19, v19, v173, v167
	ds_write_b16 v19, v18
	v_add_u32_e32 v19, s18, v174
	v_cvt_pk_bf16_f32 v18, v24, s0
	v_add3_u32 v19, v19, v176, v167
	ds_write_b16 v19, v18
	v_add_u32_e32 v19, s18, v177
	v_cvt_pk_bf16_f32 v18, v25, s0
	v_add3_u32 v19, v19, v178, v167
	ds_write_b16 v19, v18
	v_cvt_pk_bf16_f32 v18, v26, s0
	v_add_u32_e32 v19, s18, v179
	ds_write_b16 v34, v18 offset:2048
	v_cvt_pk_bf16_f32 v18, v27, s0
	v_add3_u32 v19, v19, v181, v167
	ds_write_b16 v19, v18
	v_add_u32_e32 v19, s18, v183
	v_cvt_pk_bf16_f32 v18, v28, s0
	v_add3_u32 v19, v19, v184, v167
	ds_write_b16 v19, v18
	v_add_u32_e32 v19, s18, v185
	v_cvt_pk_bf16_f32 v18, v29, s0
	v_add3_u32 v19, v19, v186, v167
	ds_write_b16 v19, v18
	v_cvt_pk_bf16_f32 v18, v30, s0
	v_add_u32_e32 v19, s18, v187
	ds_write_b16 v34, v18 offset:3072
	v_cvt_pk_bf16_f32 v18, v31, s0
	v_add3_u32 v19, v19, v188, v167
	ds_write_b16 v19, v18
	v_add_u32_e32 v19, s18, v189
	v_cvt_pk_bf16_f32 v18, v32, s0
	v_add3_u32 v19, v19, v190, v167
	ds_write_b16 v19, v18
	v_add_u32_e32 v19, s18, v191
	v_cvt_pk_bf16_f32 v18, v33, s0
	v_add3_u32 v19, v19, v192, v167
	ds_write_b16 v19, v18
	v_mov_b64_e32 v[32:33], v[16:17]
	v_mov_b64_e32 v[30:31], v[14:15]
	v_mov_b64_e32 v[28:29], v[12:13]
	v_mov_b64_e32 v[26:27], v[10:11]
	v_mov_b64_e32 v[24:25], v[8:9]
	v_mov_b64_e32 v[22:23], v[6:7]
	v_mov_b64_e32 v[20:21], v[4:5]
	v_mov_b64_e32 v[18:19], v[2:3]
.LBB0_1679:
	s_and_b64 vcc, exec, s[6:7]
	s_mov_b64 s[18:19], -1
	s_waitcnt lgkmcnt(0)
	s_barrier
	s_cbranch_vccnz .LBB0_1681
	ds_read_b128 v[2:5], v142 offset:16384
	ds_read_b128 v[6:9], v221
	ds_read_b128 v[34:37], v141 offset:16384
	ds_read_b128 v[38:41], v220
	ds_read_b128 v[166:169], v140 offset:16384
	ds_read_b128 v[176:179], v219
	s_mov_b64 s[18:19], 0
	s_waitcnt lgkmcnt(4)
	v_mfma_f32_32x32x16_bf16 v[2:17], v[6:9], v[2:5], 0
	s_waitcnt lgkmcnt(2)
	v_mfma_f32_32x32x16_bf16 v[34:49], v[38:41], v[34:37], 0
	s_waitcnt lgkmcnt(0)
	v_mfma_f32_32x32x16_bf16 v[2:17], v[176:179], v[166:169], v[2:17]
	ds_read_b128 v[166:169], v139 offset:16384
	ds_read_b128 v[176:179], v218
	s_waitcnt lgkmcnt(0)
	v_mfma_f32_32x32x16_bf16 v[34:49], v[176:179], v[166:169], v[34:49]
	s_nop 11
	v_add_f32_e32 v4, v4, v36
	v_add_f32_e32 v5, v5, v37
	v_add_f32_e32 v2, v2, v34
	v_add_f32_e32 v3, v3, v35
	v_add_f32_e32 v6, v6, v38
	v_add_f32_e32 v7, v7, v39
	v_add_f32_e32 v8, v8, v40
	v_add_f32_e32 v9, v9, v41
	v_add_f32_e32 v4, v20, v4
	v_add_f32_e32 v5, v21, v5
	v_add_f32_e32 v2, v18, v2
	v_add_f32_e32 v3, v19, v3
	v_add_f32_e32 v10, v10, v42
	v_add_f32_e32 v11, v11, v43
	v_add_f32_e32 v12, v12, v44
	v_add_f32_e32 v13, v13, v45
	v_add_f32_e32 v8, v24, v8
	v_add_f32_e32 v9, v25, v9
	v_add_f32_e32 v6, v22, v6
	v_add_f32_e32 v7, v23, v7
	v_cvt_pk_bf16_f32 v34, v2, v3
	v_cvt_pk_bf16_f32 v35, v4, v5
	v_add_f32_e32 v14, v14, v46
	v_add_f32_e32 v15, v15, v47
	v_add_f32_e32 v16, v16, v48
	v_add_f32_e32 v17, v17, v49
	v_add_f32_e32 v12, v28, v12
	v_add_f32_e32 v13, v29, v13
	v_add_f32_e32 v10, v26, v10
	v_add_f32_e32 v11, v27, v11
	ds_write_b64 v213, v[34:35]
	v_cvt_pk_bf16_f32 v34, v6, v7
	v_cvt_pk_bf16_f32 v35, v8, v9
	v_add_f32_e32 v16, v32, v16
	v_add_f32_e32 v17, v33, v17
	v_add_f32_e32 v14, v30, v14
	v_add_f32_e32 v15, v31, v15
	ds_write_b64 v212, v[34:35]
	v_cvt_pk_bf16_f32 v34, v10, v11
	v_cvt_pk_bf16_f32 v35, v12, v13
	ds_write_b64 v211, v[34:35]
	v_cvt_pk_bf16_f32 v34, v14, v15
	v_cvt_pk_bf16_f32 v35, v16, v17
	ds_write_b64 v210, v[34:35]
; __device__ __forceinline__ void chunk_pre(const P& p, Frame& F, int task, int next_task, u32x4& icr, u32x4& ick, u32x4& icv, u32x4& ipr, u32x4& ipk, u32x4& ipv, f32x4& ia0, f32x4& ia1, f32x4& iw0, f32x4& iw1, int& ptag0, int& ptag1) {
;     ...
;     for (int lev = 1; lev <= 6; ++lev) {
;         const int px = (lev & 1) ? 8 : 0, pxt = (lev & 1) ? 9 : 1, nx = (lev & 1) ? 0 : 8, nxt = (lev & 1) ? 1 : 9;
;         const int rcur = (lev & 1) ? 2 : 10, rnxt = (lev & 1) ? 10 : 2;
;         if (grp == 0) {
;             if (lev <= 5) { const f32x16 a = ck_mm(SLOT(px), SLOT(pxt), mt, nt, ql, half, ck_zero());
;                 ck_store_t(SLOT(nxt), a, mt, nt, ql, half); ck_store_n(SLOT(nx), a, mt, nt, ql, half); }
;             else aN = ck_mm(SLOT(6), SLOT(7), mt, nt, ql, half, ck_zero()); }
;         else { if (lev == 1) { f32x16 a = ck_mm(SLOT(11), SLOT(7), mt, nt, ql, half, ck_zero()); ck_store_t(SLOT(14), a, mt, nt, ql, half);
;                                aY = ck_mm(SLOT(7), SLOT(13), mt, nt, ql, half, ck_zero()); }
;           if (lev >= 2) {
;             const f32x16 a = ck_mm(SLOT(pxt), SLOT(rcur), mt, nt, ql, half, ck_zero());
; #pragma unroll
;             for (int r = 0; r < 16; ++r) rtile[r] += a[r];
;             ck_store_t(SLOT(rnxt), rtile, mt, nt, ql, half); } }
;         __syncthreads();
;     }
.LBB0_1681:
	s_andn2_b64 vcc, exec, s[18:19]
	s_cbranch_vccnz .LBB0_1683
	ds_read_b128 v[2:5], v205
	ds_read_b128 v[6:9], v203
	ds_read_b128 v[34:37], v204
	ds_read_b128 v[38:41], v201
	ds_read_b128 v[166:169], v202
	ds_read_b128 v[176:179], v200
	s_waitcnt lgkmcnt(4)
	v_mfma_f32_32x32x16_bf16 v[2:17], v[2:5], v[6:9], 0
	s_waitcnt lgkmcnt(2)
	v_mfma_f32_32x32x16_bf16 v[34:49], v[34:37], v[38:41], 0
	s_waitcnt lgkmcnt(0)
	v_mfma_f32_32x32x16_bf16 v[2:17], v[166:169], v[176:179], v[2:17]
	ds_read_b128 v[166:169], v199
	ds_read_b128 v[176:179], v198
	s_waitcnt lgkmcnt(0)
	v_mfma_f32_32x32x16_bf16 v[34:49], v[166:169], v[176:179], v[34:49]
	s_nop 11
	v_add_f32_e32 v4, v4, v36
	v_add_f32_e32 v5, v5, v37
	v_add_f32_e32 v2, v2, v34
	v_add_f32_e32 v3, v3, v35
	v_add_f32_e32 v8, v8, v40
	v_add_f32_e32 v9, v9, v41
	v_add_f32_e32 v6, v6, v38
	v_add_f32_e32 v7, v7, v39
	v_cvt_pk_bf16_f32 v34, v2, v3
	v_cvt_pk_bf16_f32 v35, v4, v5
	v_add_f32_e32 v12, v12, v44
	v_add_f32_e32 v13, v13, v45
	v_add_f32_e32 v10, v10, v42
	v_add_f32_e32 v11, v11, v43
	ds_write_b64 v118, v[34:35] offset:8192
	v_cvt_pk_bf16_f32 v34, v6, v7
	v_cvt_pk_bf16_f32 v35, v8, v9
	v_add_f32_e32 v16, v16, v48
	v_add_f32_e32 v17, v17, v49
	v_add_f32_e32 v14, v14, v46
	v_add_f32_e32 v15, v15, v47
	ds_write_b64 v113, v[34:35] offset:8192
	v_cvt_pk_bf16_f32 v34, v10, v11
	v_cvt_pk_bf16_f32 v35, v12, v13
	ds_write_b64 v110, v[34:35] offset:8192
	v_cvt_pk_bf16_f32 v34, v14, v15
	v_cvt_pk_bf16_f32 v35, v16, v17
	v_cvt_pk_bf16_f32 v2, v2, s0
	ds_write_b64 v107, v[34:35] offset:8192
	ds_write_b16 v106, v2
	v_cvt_pk_bf16_f32 v2, v3, s0
	ds_write_b16 v194, v2
	v_cvt_pk_bf16_f32 v2, v4, s0
	ds_write_b16 v123, v2
	v_cvt_pk_bf16_f32 v2, v5, s0
	ds_write_b16 v122, v2
	v_cvt_pk_bf16_f32 v2, v6, s0
	ds_write_b16 v106, v2 offset:1024
	v_cvt_pk_bf16_f32 v2, v7, s0
	ds_write_b16 v121, v2
	v_cvt_pk_bf16_f32 v2, v8, s0
	ds_write_b16 v120, v2
	v_cvt_pk_bf16_f32 v2, v9, s0
	ds_write_b16 v119, v2
	v_cvt_pk_bf16_f32 v2, v10, s0
	ds_write_b16 v106, v2 offset:2048
	v_cvt_pk_bf16_f32 v2, v11, s0
	ds_write_b16 v117, v2
	v_cvt_pk_bf16_f32 v2, v12, s0
	ds_write_b16 v116, v2
	v_cvt_pk_bf16_f32 v2, v13, s0
	ds_write_b16 v112, v2
	v_cvt_pk_bf16_f32 v2, v14, s0
	ds_write_b16 v106, v2 offset:3072
	v_cvt_pk_bf16_f32 v2, v15, s0
	ds_write_b16 v111, v2
	v_cvt_pk_bf16_f32 v2, v16, s0
	ds_write_b16 v109, v2
	v_cvt_pk_bf16_f32 v2, v17, s0
	ds_write_b16 v108, v2
	v_mov_b64_e32 v[2:3], v[18:19]
	v_mov_b64_e32 v[4:5], v[20:21]
	v_mov_b64_e32 v[6:7], v[22:23]
	v_mov_b64_e32 v[8:9], v[24:25]
	v_mov_b64_e32 v[10:11], v[26:27]
	v_mov_b64_e32 v[12:13], v[28:29]
	v_mov_b64_e32 v[14:15], v[30:31]
	v_mov_b64_e32 v[16:17], v[32:33]
.LBB0_1683:
	s_and_b64 vcc, exec, s[6:7]
	s_mov_b64 s[6:7], -1
	s_waitcnt lgkmcnt(0)
	s_barrier
	s_cbranch_vccnz .LBB0_1685
	ds_read_b128 v[18:21], v209
	ds_read_b128 v[22:25], v180 offset:8192
	ds_read_b128 v[34:37], v208
	ds_read_b128 v[38:41], v175 offset:8192
	ds_read_b128 v[106:109], v207
	ds_read_b128 v[110:113], v170 offset:8192
	s_mov_b64 s[6:7], 0
	s_waitcnt lgkmcnt(4)
	v_mfma_f32_32x32x16_bf16 v[18:33], v[22:25], v[18:21], 0
	s_waitcnt lgkmcnt(2)
	v_mfma_f32_32x32x16_bf16 v[34:49], v[38:41], v[34:37], 0
	s_waitcnt lgkmcnt(0)
	v_mfma_f32_32x32x16_bf16 v[18:33], v[110:113], v[106:109], v[18:33]
	ds_read_b128 v[106:109], v206
	ds_read_b128 v[110:113], v163 offset:8192
	s_waitcnt lgkmcnt(0)
	v_mfma_f32_32x32x16_bf16 v[34:49], v[110:113], v[106:109], v[34:49]
	s_nop 11
	v_add_f32_e32 v20, v20, v36
	v_add_f32_e32 v21, v21, v37
	v_add_f32_e32 v18, v18, v34
	v_add_f32_e32 v19, v19, v35
	v_add_f32_e32 v22, v22, v38
	v_add_f32_e32 v23, v23, v39
	v_add_f32_e32 v24, v24, v40
	v_add_f32_e32 v25, v25, v41
	v_add_f32_e32 v4, v4, v20
	v_add_f32_e32 v5, v5, v21
	v_add_f32_e32 v2, v2, v18
	v_add_f32_e32 v3, v3, v19
	v_add_f32_e32 v26, v26, v42
	v_add_f32_e32 v27, v27, v43
	v_add_f32_e32 v28, v28, v44
	v_add_f32_e32 v29, v29, v45
	v_add_f32_e32 v8, v8, v24
	v_add_f32_e32 v9, v9, v25
	v_add_f32_e32 v6, v6, v22
	v_add_f32_e32 v7, v7, v23
	v_cvt_pk_bf16_f32 v2, v2, v3
	v_cvt_pk_bf16_f32 v3, v4, v5
	v_add_f32_e32 v30, v30, v46
	v_add_f32_e32 v31, v31, v47
	v_add_f32_e32 v32, v32, v48
	v_add_f32_e32 v33, v33, v49
	v_add_f32_e32 v12, v12, v28
	v_add_f32_e32 v13, v13, v29
	v_add_f32_e32 v10, v10, v26
	v_add_f32_e32 v11, v11, v27
	ds_write_b64 v193, v[2:3] offset:16384
	v_cvt_pk_bf16_f32 v2, v6, v7
	v_cvt_pk_bf16_f32 v3, v8, v9
	v_add_f32_e32 v16, v16, v32
	v_add_f32_e32 v17, v17, v33
	v_add_f32_e32 v14, v14, v30
	v_add_f32_e32 v15, v15, v31
	ds_write_b64 v197, v[2:3] offset:16384
	v_cvt_pk_bf16_f32 v2, v10, v11
	v_cvt_pk_bf16_f32 v3, v12, v13
	ds_write_b64 v196, v[2:3] offset:16384
	v_cvt_pk_bf16_f32 v2, v14, v15
	v_cvt_pk_bf16_f32 v3, v16, v17
	ds_write_b64 v195, v[2:3] offset:16384
.LBB0_1685:
	v_mov_b32_e32 v106, 0
	s_andn2_b64 vcc, exec, s[6:7]
	v_mov_b32_e32 v107, 0
	v_mov_b32_e32 v122, 0
	v_mov_b32_e32 v123, 0
	v_mov_b32_e32 v120, 0
	v_mov_b32_e32 v121, 0
	v_mov_b32_e32 v118, 0
	v_mov_b32_e32 v119, 0
	v_mov_b32_e32 v116, 0
	v_mov_b32_e32 v117, 0
	v_mov_b32_e32 v112, 0
	v_mov_b32_e32 v113, 0
	v_mov_b32_e32 v110, 0
	v_mov_b32_e32 v111, 0
	v_mov_b32_e32 v108, 0
	v_mov_b32_e32 v109, 0
	s_cbranch_vccnz .LBB0_1687
	ds_read_b128 v[2:5], v142 offset:57344
	ds_read_b128 v[6:9], v156 offset:49152
	ds_read_b128 v[18:21], v141 offset:57344
	ds_read_b128 v[22:25], v155 offset:49152
	ds_read_b128 v[34:37], v140 offset:57344
	ds_read_b128 v[38:41], v154 offset:49152
	s_waitcnt lgkmcnt(4)
	v_mfma_f32_32x32x16_bf16 v[2:17], v[6:9], v[2:5], 0
	s_waitcnt lgkmcnt(2)
	v_mfma_f32_32x32x16_bf16 v[18:33], v[22:25], v[18:21], 0
	s_waitcnt lgkmcnt(0)
	v_mfma_f32_32x32x16_bf16 v[2:17], v[38:41], v[34:37], v[2:17]
	ds_read_b128 v[34:37], v139 offset:57344
	ds_read_b128 v[38:41], v153 offset:49152
	s_waitcnt lgkmcnt(0)
	v_mfma_f32_32x32x16_bf16 v[18:33], v[38:41], v[34:37], v[18:33]
	s_nop 11
	v_add_f32_e32 v108, v16, v32
	v_add_f32_e32 v109, v17, v33
	v_add_f32_e32 v110, v14, v30
	v_add_f32_e32 v111, v15, v31
	v_add_f32_e32 v112, v12, v28
	v_add_f32_e32 v113, v13, v29
	v_add_f32_e32 v116, v10, v26
	v_add_f32_e32 v117, v11, v27
	v_add_f32_e32 v118, v8, v24
	v_add_f32_e32 v119, v9, v25
	v_add_f32_e32 v120, v6, v22
	v_add_f32_e32 v121, v7, v23
	v_add_f32_e32 v122, v4, v20
	v_add_f32_e32 v123, v5, v21
	v_add_f32_e32 v106, v2, v18
	v_add_f32_e32 v107, v3, v19

; #define LAS __attribute__((address_space(3)))
; __device__ __forceinline__ unsigned pk2(float lo, float hi) { const bfx2 b = __builtin_convertvector((f32x2){lo, hi}, bfx2); return __builtin_bit_cast(unsigned, b); }
; __device__ __forceinline__ float bflo(unsigned w) { return __uint_as_float(w << 16); }
; __device__ __forceinline__ float bfhi(unsigned w) { return __uint_as_float(w & 0xffff0000u); }
; __device__ __forceinline__ void chunk_pre(const P& p, Frame& F, int task, int next_task, u32x4& icr, u32x4& ick, u32x4& icv, u32x4& ipr, u32x4& ipk, u32x4& ipv, f32x4& ia0, f32x4& ia1, f32x4& iw0, f32x4& iw1, int& ptag0, int& ptag1) {
;     ...
;     if (grp == 0) { f32x16 a = ck_mm(SLOT(2), SLOT(4), mt, nt, ql, half, ck_zero()); ck_store_t(SLOT(11), a, mt, nt, ql, half); }
;     else { f32x16 a = ck_mm(SLOT(2), SLOT(14), mt, nt, ql, half, ck_zero()); ck_store_t(SLOT(15), a, mt, nt, ql, half); }
;     ...
;     else {
;         { f32x16 a = ck_mm(SLOT(11), SLOT(12), mt, nt, ql, half, ck_zero());
;           const int n = 32 * nt + ql;
; #pragma unroll
;           for (int g = 0; g < 4; ++g) { const int m0 = 32 * mt + 8 * g + 4 * half; const u32x2 rw = *(const LAS u32x2*)(SLOT(3) + n * 128 + (((m0 >> 3) ^ (n & 7)) << 4) + (m0 & 4) * 2);
;               a[4 * g] = bflo(rw.x) - a[4 * g]; a[4 * g + 1] = bfhi(rw.x) - a[4 * g + 1]; a[4 * g + 2] = bflo(rw.y) - a[4 * g + 2]; a[4 * g + 3] = bfhi(rw.y) - a[4 * g + 3]; }
;           ck_store_t(SLOT(9), a, mt, nt, ql, half); }
;         { const f32x16 a2 = ck_mm(SLOT(15), SLOT(12), mt, nt, ql, half, ck_zero());
;           unsigned char* Yl = outp + 24576 + (mt * 2 + nt) * 2048 + lane * 16; unsigned pw[8];
; #pragma unroll
;           for (int g = 0; g < 4; ++g) { pw[2 * g] = pk2(aY[4 * g] - a2[4 * g], aY[4 * g + 1] - a2[4 * g + 1]); pw[2 * g + 1] = pk2(aY[4 * g + 2] - a2[4 * g + 2], aY[4 * g + 3] - a2[4 * g + 3]); }
;           *(u32x4*)Yl = (u32x4){pw[0], pw[1], pw[2], pw[3]}; *(u32x4*)(Yl + 1024) = (u32x4){pw[4], pw[5], pw[6], pw[7]}; } }
.LBB0_1691:
	s_add_i32 s6, s18, 0
	s_add_i32 s6, s6, s43
	s_nop 5
	v_add_f32_e32 v4, v20, v4
	v_add_f32_e32 v5, v21, v5
	v_add_f32_e32 v2, v18, v2
	v_add_f32_e32 v3, v19, v3
	v_add3_u32 v18, s6, v137, v145
	v_add_f32_e32 v8, v24, v8
	v_add_f32_e32 v9, v25, v9
	v_add_f32_e32 v6, v22, v6
	v_add_f32_e32 v7, v23, v7
	v_cvt_pk_bf16_f32 v2, v2, v3
	v_cvt_pk_bf16_f32 v3, v4, v5
	v_add_u32_e32 v4, v18, v37
	v_add_f32_e32 v12, v28, v12
	v_add_f32_e32 v13, v29, v13
	v_add_f32_e32 v10, v26, v10
	v_add_f32_e32 v11, v27, v11
	ds_write_b64 v4, v[2:3]
	v_cvt_pk_bf16_f32 v2, v6, v7
	v_cvt_pk_bf16_f32 v3, v8, v9
	v_add_u32_e32 v4, v18, v36
	v_add_f32_e32 v16, v32, v16
	v_add_f32_e32 v17, v33, v17
	v_add_f32_e32 v14, v30, v14
	v_add_f32_e32 v15, v31, v15
	ds_write_b64 v4, v[2:3]
	v_cvt_pk_bf16_f32 v2, v10, v11
	v_cvt_pk_bf16_f32 v3, v12, v13
	v_add_u32_e32 v4, v18, v35
	ds_write_b64 v4, v[2:3]
	v_cvt_pk_bf16_f32 v2, v14, v15
	v_cvt_pk_bf16_f32 v3, v16, v17
	v_add_u32_e32 v4, v18, v34
	s_mov_b64 s[6:7], -1
	s_and_b64 vcc, exec, s[44:45]
	v_lshlrev_b32_e32 v114, 4, v131
	ds_write_b64 v4, v[2:3]
	s_waitcnt lgkmcnt(0)
	s_barrier
	s_cbranch_vccz .LBB0_1693
	s_ashr_i32 s71, s70, 31
	s_lshl_b64 s[6:7], s[70:71], 15
	s_add_u32 s6, s5, s6
	s_addc_u32 s7, s33, s7
	s_add_i32 s18, s58, 0x18000
	v_add_u32_e32 v131, s18, v137
	v_add_u32_e32 v2, v131, v138
	ds_read_b128 v[34:37], v2
	ds_read_b128 v[2:5], v160
	v_add_u32_e32 v18, v131, v136
	ds_read_b128 v[38:41], v18
	ds_read_b128 v[18:21], v159
	v_add_u32_e32 v42, v131, v135
	s_waitcnt lgkmcnt(2)
	v_mfma_f32_32x32x16_bf16 v[2:17], v[2:5], v[34:37], 0
	ds_read_b128 v[42:45], v42
	ds_read_b128 v[46:49], v158
	s_add_i32 s18, s58, 0x12000
	s_add_i32 s16, s16, 0x1e000
	s_waitcnt lgkmcnt(2)
	v_mfma_f32_32x32x16_bf16 v[18:33], v[18:21], v[38:41], 0
	s_waitcnt lgkmcnt(0)
	v_mfma_f32_32x32x16_bf16 v[2:17], v[46:49], v[42:45], v[2:17]
	v_add_u32_e32 v46, v131, v134
	ds_read_b128 v[46:49], v46
	ds_read_b128 v[162:165], v157
	ds_read_b64 v[158:159], v193 offset:24576
	s_waitcnt lgkmcnt(1)
	v_mfma_f32_32x32x16_bf16 v[18:33], v[162:165], v[46:49], v[18:33]
	s_nop 11
	v_add_f32_e32 v2, v2, v18
	v_add_f32_e32 v3, v3, v19
	s_waitcnt lgkmcnt(0)
	v_lshlrev_b32_e32 v18, 16, v158
	v_and_b32_e32 v19, 0xffff0000, v158
	v_add_f32_e32 v4, v4, v20
	v_add_f32_e32 v5, v5, v21
	v_sub_f32_e32 v2, v18, v2
	v_sub_f32_e32 v3, v19, v3
	v_lshlrev_b32_e32 v18, 16, v159
	v_and_b32_e32 v19, 0xffff0000, v159
	v_sub_f32_e32 v4, v18, v4
	v_sub_f32_e32 v5, v19, v5
	v_bitop3_b32 v18, v152, v130, 1 bitop3:0x36
	v_lshl_add_u32 v18, v18, 4, v161
	ds_read_b64 v[18:19], v18 offset:24576
	v_add_f32_e32 v8, v8, v24
	v_add_f32_e32 v9, v9, v25
	v_add_f32_e32 v6, v6, v22
	v_add_f32_e32 v7, v7, v23
	v_add_f32_e32 v12, v12, v28
	v_add_f32_e32 v13, v13, v29
	v_add_f32_e32 v10, v10, v26
	v_add_f32_e32 v11, v11, v27
	s_waitcnt lgkmcnt(0)
	v_lshlrev_b32_e32 v20, 16, v18
	v_and_b32_e32 v21, 0xffff0000, v18
	v_lshlrev_b32_e32 v18, 16, v19
	v_and_b32_e32 v19, 0xffff0000, v19
	v_sub_f32_e32 v8, v18, v8
	v_sub_f32_e32 v9, v19, v9
	v_bitop3_b32 v18, v152, v130, 2 bitop3:0x36
	v_lshl_add_u32 v18, v18, 4, v161
	ds_read_b64 v[18:19], v18 offset:24576
	v_sub_f32_e32 v6, v20, v6
	v_sub_f32_e32 v7, v21, v7
	v_add_f32_e32 v16, v16, v32
	v_add_f32_e32 v17, v17, v33
	v_cvt_pk_bf16_f32 v2, v2, v3
	v_cvt_pk_bf16_f32 v3, v4, v5
	s_waitcnt lgkmcnt(0)
	v_lshlrev_b32_e32 v20, 16, v18
	v_and_b32_e32 v21, 0xffff0000, v18
	v_lshlrev_b32_e32 v18, 16, v19
	v_and_b32_e32 v19, 0xffff0000, v19
	v_sub_f32_e32 v12, v18, v12
	v_sub_f32_e32 v13, v19, v13
	v_bitop3_b32 v18, v152, v130, 3 bitop3:0x36
	v_lshl_add_u32 v18, v18, 4, v161
	ds_read_b64 v[18:19], v18 offset:24576
	v_sub_f32_e32 v10, v20, v10
	v_sub_f32_e32 v11, v21, v11
	v_add_f32_e32 v14, v14, v30
	v_add_f32_e32 v15, v15, v31
	v_add_u32_e32 v130, s16, v137
	s_lshl_b32 s16, s56, 11
	s_waitcnt lgkmcnt(0)
	v_lshlrev_b32_e32 v20, 16, v18
	v_and_b32_e32 v21, 0xffff0000, v18
	v_lshlrev_b32_e32 v18, 16, v19
	v_and_b32_e32 v19, 0xffff0000, v19
	v_sub_f32_e32 v16, v18, v16
	v_sub_f32_e32 v17, v19, v17
	v_add3_u32 v18, s18, v137, v145
	v_add_u32_e32 v4, v18, v148
	ds_write_b64 v4, v[2:3]
	v_cvt_pk_bf16_f32 v2, v6, v7
	v_cvt_pk_bf16_f32 v3, v8, v9
	v_add_u32_e32 v4, v18, v149
	v_sub_f32_e32 v14, v20, v14
	v_sub_f32_e32 v15, v21, v15
	ds_write_b64 v4, v[2:3]
	v_cvt_pk_bf16_f32 v2, v10, v11
	v_cvt_pk_bf16_f32 v3, v12, v13
	v_add_u32_e32 v4, v18, v150
	ds_write_b64 v4, v[2:3]
	v_cvt_pk_bf16_f32 v2, v14, v15
	v_cvt_pk_bf16_f32 v3, v16, v17
	v_add_u32_e32 v4, v18, v151
	ds_write_b64 v4, v[2:3]
	v_add_u32_e32 v2, v130, v138
	ds_read_b128 v[2:5], v2
	v_add_u32_e32 v18, v130, v136
	ds_read_b128 v[18:21], v18
	s_waitcnt lgkmcnt(1)
	v_mfma_f32_32x32x16_bf16 v[2:17], v[2:5], v[34:37], 0
	v_add_u32_e32 v34, v130, v135
	ds_read_b128 v[34:37], v34
	s_and_b32 s16, s16, 0x1800
	s_add_u32 s6, s6, s16
	s_addc_u32 s7, s7, 0
	s_waitcnt lgkmcnt(0)
	v_mfma_f32_32x32x16_bf16 v[2:17], v[34:37], v[42:45], v[2:17]
	v_add_u32_e32 v34, v130, v134
	ds_read_b128 v[34:37], v34
	v_mfma_f32_32x32x16_bf16 v[18:33], v[18:21], v[38:41], 0
	s_waitcnt lgkmcnt(0)
	v_mfma_f32_32x32x16_bf16 v[18:33], v[34:37], v[46:49], v[18:33]
	s_nop 11
	v_add_f32_e32 v6, v6, v22
	v_add_f32_e32 v7, v7, v23
	v_add_f32_e32 v10, v10, v26
	v_add_f32_e32 v11, v11, v27
	v_sub_f32_e32 v7, v101, v7
	v_sub_f32_e32 v6, v100, v6
	v_add_f32_e32 v4, v4, v20
	v_add_f32_e32 v5, v5, v21
	v_add_f32_e32 v8, v8, v24
	v_add_f32_e32 v9, v9, v25
	v_add_f32_e32 v2, v2, v18
	v_add_f32_e32 v3, v3, v19
	v_sub_f32_e32 v19, v96, v10
	v_cvt_pk_bf16_f32 v10, v6, v7
	v_lshl_add_u64 v[6:7], s[6:7], 0, v[114:115]
	s_mov_b64 s[6:7], 0x6000
	v_add_f32_e32 v12, v12, v28
	v_add_f32_e32 v13, v13, v29
	v_add_f32_e32 v14, v14, v30
	v_add_f32_e32 v15, v15, v31
	v_add_f32_e32 v16, v16, v32
	v_add_f32_e32 v17, v17, v33
	v_sub_f32_e32 v18, v97, v11
	v_sub_f32_e32 v11, v99, v9
	v_sub_f32_e32 v20, v98, v8
	v_sub_f32_e32 v5, v105, v5
	v_sub_f32_e32 v4, v104, v4
	v_sub_f32_e32 v3, v103, v3
	v_sub_f32_e32 v2, v102, v2
	v_lshl_add_u64 v[6:7], v[6:7], 0, s[6:7]
	s_add_u32 s6, s10, s16
	v_sub_f32_e32 v17, v91, v17
	v_sub_f32_e32 v16, v90, v16
	v_sub_f32_e32 v15, v93, v15
	v_sub_f32_e32 v14, v92, v14
	v_sub_f32_e32 v13, v95, v13
	v_sub_f32_e32 v12, v94, v12
	v_cvt_pk_bf16_f32 v8, v2, v3
	v_cvt_pk_bf16_f32 v9, v4, v5
	v_cvt_pk_bf16_f32 v11, v20, v11
	s_addc_u32 s7, s11, 0
	v_cvt_pk_bf16_f32 v2, v19, v18
	v_cvt_pk_bf16_f32 v3, v12, v13
	v_cvt_pk_bf16_f32 v4, v14, v15
	v_cvt_pk_bf16_f32 v5, v16, v17
	global_store_dwordx4 v114, v[8:11], s[6:7]
	s_mov_b64 s[6:7], 0
; __device__ __forceinline__ int ck_crow(int r, int half) { return (r & 3) + 8 * (r >> 2) + 4 * half; }
; __device__ __forceinline__ void chunk_pre(const P& p, Frame& F, int task, int next_task, u32x4& icr, u32x4& ick, u32x4& icv, u32x4& ipr, u32x4& ipk, u32x4& ipv, f32x4& ia0, f32x4& ia1, f32x4& iw0, f32x4& iw1, int& ptag0, int& ptag1) {
;     ...
;     if (grp == 0) {
;         { f32x16 a = ck_mm(SLOT(11), SLOT(5), mt, nt, ql, half, ck_zero());
;           const int n = 32 * nt + ql; const float gc = GC[n];
; #pragma unroll
;           for (int r = 0; r < 16; ++r) { const int m = 32 * mt + ck_crow(r, half); a[r] = ((m == n ? 1.0f : 0.f) - a[r]) * gc; }
;           ck_store_t(SLOT(8), a, mt, nt, ql, half); }
.LBB0_1693:
	s_andn2_b64 vcc, exec, s[6:7]
	s_cbranch_vccnz .LBB0_1612
	s_add_i32 s20, s20, 0x16000
	v_add_u32_e32 v42, s20, v137
	v_add_u32_e32 v6, v42, v138
	ds_read_b128 v[6:9], v6
	ds_read_b128 v[2:5], v142 offset:40960
	ds_read_b128 v[18:21], v141 offset:40960
	v_add_u32_e32 v38, v42, v135
	v_add_u32_e32 v22, v42, v136
	ds_read_b128 v[34:37], v140 offset:40960
	ds_read_b128 v[38:41], v38
	ds_read_b128 v[22:25], v22
	s_waitcnt lgkmcnt(4)
	v_mfma_f32_32x32x16_bf16 v[2:17], v[6:9], v[2:5], 0
	s_waitcnt lgkmcnt(1)
	v_mfma_f32_32x32x16_bf16 v[2:17], v[38:41], v[34:37], v[2:17]
	v_add_u32_e32 v38, v42, v134
	ds_read_b128 v[34:37], v139 offset:40960
	ds_read_b128 v[38:41], v38
	s_waitcnt lgkmcnt(2)
	v_mfma_f32_32x32x16_bf16 v[18:33], v[22:25], v[18:21], 0
	s_waitcnt lgkmcnt(0)
	v_mfma_f32_32x32x16_bf16 v[18:33], v[38:41], v[34:37], v[18:33]
	v_lshl_add_u32 v35, s57, 5, v144
	v_or_b32_e32 v36, 1, v35
	v_cmp_eq_u32_e32 vcc, v36, v143
	v_cmp_eq_u32_e64 s[6:7], v35, v143
	v_lshl_add_u32 v34, v143, 2, s52
	ds_read_b32 v34, v34
	s_nop 5
	v_add_f32_e32 v2, v2, v18
	v_add_f32_e32 v3, v3, v19
	v_cndmask_b32_e64 v18, 0, 1.0, s[6:7]
	v_cndmask_b32_e64 v19, 0, 1.0, vcc
	v_sub_f32_e32 v2, v18, v2
	v_sub_f32_e32 v3, v19, v3
	v_or_b32_e32 v18, 3, v35
	v_or_b32_e32 v19, 2, v35
	v_cmp_eq_u32_e32 vcc, v19, v143
	v_cmp_eq_u32_e64 s[6:7], v18, v143
	v_add_f32_e32 v4, v4, v20
	v_add_f32_e32 v5, v5, v21
	v_cndmask_b32_e64 v18, 0, 1.0, vcc
	v_cndmask_b32_e64 v19, 0, 1.0, s[6:7]
	v_sub_f32_e32 v4, v18, v4
	v_sub_f32_e32 v5, v19, v5
	v_or_b32_e32 v18, 9, v35
	v_or_b32_e32 v19, 8, v35
	v_cmp_eq_u32_e32 vcc, v19, v143
	v_cmp_eq_u32_e64 s[6:7], v18, v143
	v_add_f32_e32 v6, v6, v22
	v_add_f32_e32 v7, v7, v23
	v_cndmask_b32_e64 v18, 0, 1.0, vcc
	v_cndmask_b32_e64 v19, 0, 1.0, s[6:7]
	v_sub_f32_e32 v6, v18, v6
	v_sub_f32_e32 v7, v19, v7
	v_or_b32_e32 v18, 11, v35
	v_or_b32_e32 v19, 10, v35
	v_cmp_eq_u32_e32 vcc, v19, v143
	v_cmp_eq_u32_e64 s[6:7], v18, v143
	v_add_f32_e32 v8, v8, v24
	v_add_f32_e32 v9, v9, v25
	v_cndmask_b32_e64 v18, 0, 1.0, vcc
	v_cndmask_b32_e64 v19, 0, 1.0, s[6:7]
	v_sub_f32_e32 v8, v18, v8
	v_sub_f32_e32 v9, v19, v9
	v_or_b32_e32 v18, 17, v35
	v_or_b32_e32 v19, 16, v35
	v_cmp_eq_u32_e32 vcc, v19, v143
	v_cmp_eq_u32_e64 s[6:7], v18, v143
	v_add_f32_e32 v10, v10, v26
	v_add_f32_e32 v11, v11, v27
	v_cndmask_b32_e64 v18, 0, 1.0, vcc
	v_cndmask_b32_e64 v19, 0, 1.0, s[6:7]
	v_sub_f32_e32 v10, v18, v10
	v_sub_f32_e32 v11, v19, v11
	v_or_b32_e32 v18, 19, v35
	v_or_b32_e32 v19, 18, v35
	v_cmp_eq_u32_e32 vcc, v19, v143
	v_cmp_eq_u32_e64 s[6:7], v18, v143
	v_add_f32_e32 v12, v12, v28
	v_add_f32_e32 v13, v13, v29
	v_cndmask_b32_e64 v18, 0, 1.0, vcc
	v_cndmask_b32_e64 v19, 0, 1.0, s[6:7]
	v_sub_f32_e32 v12, v18, v12
	v_sub_f32_e32 v13, v19, v13
	v_or_b32_e32 v18, 25, v35
	v_or_b32_e32 v19, 24, v35
	v_cmp_eq_u32_e32 vcc, v19, v143
	v_cmp_eq_u32_e64 s[6:7], v18, v143
	v_add_f32_e32 v14, v14, v30
	v_add_f32_e32 v15, v15, v31
	v_cndmask_b32_e64 v18, 0, 1.0, vcc
	v_cndmask_b32_e64 v19, 0, 1.0, s[6:7]
	v_sub_f32_e32 v14, v18, v14
	v_sub_f32_e32 v15, v19, v15
	v_or_b32_e32 v18, 27, v35
	v_or_b32_e32 v19, 26, v35
	v_cmp_eq_u32_e32 vcc, v19, v143
	v_cmp_eq_u32_e64 s[6:7], v18, v143
	v_add_f32_e32 v16, v16, v32
	v_add_f32_e32 v17, v17, v33
	v_cndmask_b32_e64 v18, 0, 1.0, vcc
	v_cndmask_b32_e64 v19, 0, 1.0, s[6:7]
	s_add_i32 s6, s58, 0x10000
	s_waitcnt lgkmcnt(0)
; __device__ __forceinline__ unsigned pk2(float lo, float hi) { const bfx2 b = __builtin_convertvector((f32x2){lo, hi}, bfx2); return __builtin_bit_cast(unsigned, b); }
; __device__ __forceinline__ int ck_crow(int r, int half) { return (r & 3) + 8 * (r >> 2) + 4 * half; }
; __device__ __forceinline__ void chunk_pre(const P& p, Frame& F, int task, int next_task, u32x4& icr, u32x4& ick, u32x4& icv, u32x4& ipr, u32x4& ipk, u32x4& ipv, f32x4& ia0, f32x4& ia1, f32x4& iw0, f32x4& iw1, int& ptag0, int& ptag1) {
;     ...
;         { f32x16 a = ck_mm(SLOT(11), SLOT(5), mt, nt, ql, half, ck_zero());
;           const int n = 32 * nt + ql; const float gc = GC[n];
; #pragma unroll
;           for (int r = 0; r < 16; ++r) { const int m = 32 * mt + ck_crow(r, half); a[r] = ((m == n ? 1.0f : 0.f) - a[r]) * gc; }
;           ck_store_t(SLOT(8), a, mt, nt, ql, half); }
;         { const f32x16 a2 = ck_mm(SLOT(5), SLOT(15), mt, nt, ql, half, ck_zero());
;           unsigned char* N = outp + 16384 + (mt * 2 + nt) * 2048 + lane * 16; u32x4 w0, w1; unsigned pw[8];
; #pragma unroll
;           for (int g = 0; g < 4; ++g) { const int m0 = 32 * mt + 8 * g + 4 * half; float v[4];
; #pragma unroll
;               for (int e = 0; e < 4; ++e) v[e] = (aN[4 * g + e] - a2[4 * g + e]) * GC[m0 + e];
;               pw[2 * g] = pk2(v[0], v[1]); pw[2 * g + 1] = pk2(v[2], v[3]); }
;           w0 = (u32x4){pw[0], pw[1], pw[2], pw[3]}; w1 = (u32x4){pw[4], pw[5], pw[6], pw[7]}; *(u32x4*)N = w0; *(u32x4*)(N + 1024) = w1; } }
	v_mul_f32_e32 v2, v34, v2
	v_mul_f32_e32 v3, v34, v3
	v_mul_f32_e32 v4, v34, v4
	v_mul_f32_e32 v5, v34, v5
	v_sub_f32_e32 v16, v18, v16
	v_sub_f32_e32 v17, v19, v17
	v_add3_u32 v18, s6, v137, v145
	v_mul_f32_e32 v6, v34, v6
	v_mul_f32_e32 v7, v34, v7
	v_mul_f32_e32 v8, v34, v8
	v_mul_f32_e32 v9, v34, v9
	v_cvt_pk_bf16_f32 v2, v2, v3
	v_cvt_pk_bf16_f32 v3, v4, v5
	v_add_u32_e32 v4, v18, v124
	v_mul_f32_e32 v10, v34, v10
	v_mul_f32_e32 v11, v34, v11
	v_mul_f32_e32 v12, v34, v12
	v_mul_f32_e32 v13, v34, v13
	ds_write_b64 v4, v[2:3]
	v_cvt_pk_bf16_f32 v2, v6, v7
	v_cvt_pk_bf16_f32 v3, v8, v9
	v_add_u32_e32 v4, v18, v125
	v_mul_f32_e32 v14, v34, v14
	v_mul_f32_e32 v15, v34, v15
	v_mul_f32_e32 v16, v34, v16
	v_mul_f32_e32 v17, v34, v17
	ds_write_b64 v4, v[2:3]
	v_cvt_pk_bf16_f32 v2, v10, v11
	v_cvt_pk_bf16_f32 v3, v12, v13
	v_add_u32_e32 v4, v18, v146
	s_add_i32 s58, s58, 0x1e000
	ds_write_b64 v4, v[2:3]
	v_cvt_pk_bf16_f32 v2, v14, v15
	v_cvt_pk_bf16_f32 v3, v16, v17
	v_add_u32_e32 v4, v18, v147
	v_add_u32_e32 v42, s58, v137
	ds_write_b64 v4, v[2:3]
	v_add_u32_e32 v2, v42, v138
	ds_read_b128 v[2:5], v2
	ds_read_b128 v[6:9], v156 offset:40960
	s_waitcnt lgkmcnt(0)
	v_mfma_f32_32x32x16_bf16 v[2:17], v[6:9], v[2:5], 0
	v_add_u32_e32 v18, v42, v136
	ds_read_b128 v[18:21], v18
	ds_read_b128 v[22:25], v155 offset:40960
	v_add_u32_e32 v34, v42, v135
	ds_read_b128 v[34:37], v34
	ds_read_b128 v[38:41], v154 offset:40960
	s_lshl_b32 s7, s57, 7
	s_add_i32 s7, s52, s7
	s_lshl_b32 s6, s56, 11
	s_waitcnt lgkmcnt(2)
	v_mfma_f32_32x32x16_bf16 v[18:33], v[22:25], v[18:21], 0
	s_add_u32 s6, s10, s6
	s_waitcnt lgkmcnt(0)
	v_mfma_f32_32x32x16_bf16 v[2:17], v[38:41], v[34:37], v[2:17]
	v_add_u32_e32 v34, v42, v134
	ds_read_b128 v[34:37], v34
	ds_read_b128 v[38:41], v153 offset:40960
	s_waitcnt lgkmcnt(0)
	v_mfma_f32_32x32x16_bf16 v[18:33], v[38:41], v[34:37], v[18:33]
	v_lshl_add_u32 v34, v133, 4, s7
	s_addc_u32 s7, s11, 0
	s_nop 9
	v_add_f32_e32 v4, v4, v20
	v_add_f32_e32 v5, v5, v21
	v_add_f32_e32 v6, v6, v22
	v_add_f32_e32 v7, v7, v23
	v_add_f32_e32 v8, v8, v24
	v_add_f32_e32 v9, v9, v25
	v_add_f32_e32 v10, v10, v26
	v_add_f32_e32 v11, v11, v27
	v_add_f32_e32 v12, v12, v28
	v_add_f32_e32 v13, v13, v29
	v_add_f32_e32 v2, v2, v18
	v_add_f32_e32 v3, v3, v19
	v_sub_f32_e32 v19, v113, v13
	v_sub_f32_e32 v18, v112, v12
	v_sub_f32_e32 v21, v117, v11
	v_sub_f32_e32 v20, v116, v10
	v_sub_f32_e32 v13, v119, v9
	v_sub_f32_e32 v12, v118, v8
	v_sub_f32_e32 v23, v121, v7
	v_sub_f32_e32 v22, v120, v6
	v_sub_f32_e32 v11, v123, v5
	v_sub_f32_e32 v10, v122, v4
	v_sub_f32_e32 v25, v107, v3
	v_sub_f32_e32 v24, v106, v2
	ds_read_b128 v[2:5], v34
	ds_read_b128 v[6:9], v34 offset:32
	v_add_f32_e32 v14, v14, v30
	v_add_f32_e32 v15, v15, v31
	v_add_f32_e32 v16, v16, v32
	v_add_f32_e32 v17, v17, v33
	v_sub_f32_e32 v15, v111, v15
	s_waitcnt lgkmcnt(1)
	v_mul_f32_e32 v2, v2, v24
	v_mul_f32_e32 v3, v3, v25
	v_mul_f32_e32 v4, v10, v4
	v_mul_f32_e32 v5, v11, v5
	v_cvt_pk_bf16_f32 v10, v2, v3
	v_cvt_pk_bf16_f32 v11, v4, v5
	s_waitcnt lgkmcnt(0)
	v_mul_f32_e32 v2, v22, v6
	v_mul_f32_e32 v3, v23, v7
	v_mul_f32_e32 v4, v12, v8
	v_mul_f32_e32 v5, v13, v9
	v_cvt_pk_bf16_f32 v12, v2, v3
	v_cvt_pk_bf16_f32 v13, v4, v5
	ds_read_b128 v[2:5], v34 offset:64
	v_sub_f32_e32 v17, v109, v17
	v_sub_f32_e32 v16, v108, v16
	v_sub_f32_e32 v14, v110, v14
	v_lshl_add_u64 v[8:9], s[6:7], 0, v[114:115]
	s_waitcnt lgkmcnt(0)
	v_mul_f32_e32 v2, v20, v2
	v_mul_f32_e32 v3, v21, v3
	v_mul_f32_e32 v4, v18, v4
	v_mul_f32_e32 v5, v19, v5
	v_cvt_pk_bf16_f32 v2, v2, v3
	v_cvt_pk_bf16_f32 v3, v4, v5
	ds_read_b128 v[4:7], v34 offset:96
	s_movk_i32 s6, 0xe000
	s_mov_b32 s7, -1
	s_waitcnt lgkmcnt(0)
	v_mul_f32_e32 v4, v14, v4
	v_mul_f32_e32 v5, v15, v5
	v_mul_f32_e32 v6, v16, v6
	v_mul_f32_e32 v7, v17, v7
	v_cvt_pk_bf16_f32 v4, v4, v5
	v_cvt_pk_bf16_f32 v5, v6, v7
	v_lshl_add_u64 v[6:7], v[8:9], 0, s[6:7]
	v_add_co_u32_e32 v8, vcc, 0xffffe000, v8
	s_nop 1
	v_addc_co_u32_e32 v9, vcc, -1, v9, vcc
	global_store_dwordx4 v[8:9], v[10:13], off
	s_branch .LBB0_1612

; __device__ __forceinline__ unsigned pk2(float lo, float hi) { const bfx2 b = __builtin_convertvector((f32x2){lo, hi}, bfx2); return __builtin_bit_cast(unsigned, b); }
; __device__ __forceinline__ float bflo(unsigned w) { return __uint_as_float(w << 16); }
; __device__ __forceinline__ float bfhi(unsigned w) { return __uint_as_float(w & 0xffff0000u); }
; #define CH_LOAD(slot, cc) do { const unsigned char* src_ = base + (size_t)(cc) * CK_TASK_BYTES; pmR[slot] = *(const u32x4*)(src_ + tid * 16); pqR[slot] = *(const u32x4*)(src_ + 8192 + tid * 16); \
;         n0R[slot] = *(const u32x4*)(src_ + noff); n1R[slot] = *(const u32x4*)(src_ + noff + 1024); } while (0)
; __device__ __forceinline__ void chunk_chain(const P& p, Frame& F, int s) {
;     ...
;       for (int u = 0; u < 4; ++u) { const int c = c4 + u, cur = u & 1;
;         f32x4 ad[4];
;         { const u32x4 w0 = n0R[u], w1 = n1R[u];
;           ad[0] = (f32x4){bflo(w0.x), bfhi(w0.x), bflo(w0.y), bfhi(w0.y)}; ad[1] = (f32x4){bflo(w0.z), bfhi(w0.z), bflo(w0.w), bfhi(w0.w)};
;           ad[2] = (f32x4){bflo(w1.x), bfhi(w1.x), bflo(w1.y), bfhi(w1.y)}; ad[3] = (f32x4){bflo(w1.z), bfhi(w1.z), bflo(w1.w), bfhi(w1.w)}; }
;         if (c + 4 < 32) CH_LOAD(u, c + 4);
;         if (grp == 0) {
;             sacc = ck_mm(L + (2 + cur) * CK_SLOT, L + cur * CK_SLOT, mt, nt, ql, half, ck_zero());
; #pragma unroll
;             for (int g = 0; g < 4; ++g)
; #pragma unroll
;                 for (int e = 0; e < 4; ++e) sacc[4 * g + e] += ad[g][e];
;             ck_store_t(L + (cur ^ 1) * CK_SLOT, sacc, mt, nt, ql, half);
;         } else {
;             const f32x16 a = ck_mm(L + cur * CK_SLOT, L + (4 + cur) * CK_SLOT, mt, nt, ql, half, ck_zero());
;             bf16* yrow = YRAW + (size_t)(b * TP + 64 * c + n) * 1024 + h * 64;
; #pragma unroll
;             for (int g = 0; g < 4; ++g) { u32x2 w; w.x = pk2(a[4 * g] + ad[g][0], a[4 * g + 1] + ad[g][1]); w.y = pk2(a[4 * g + 2] + ad[g][2], a[4 * g + 3] + ad[g][3]);
;                 *(u32x2*)(yrow + 32 * mt + 8 * g + 4 * half) = w; } }
.LBB0_1757:
	v_lshlrev_b32_e32 v98, 16, v6
	v_and_b32_e32 v99, 0xffff0000, v6
	v_lshlrev_b32_e32 v100, 16, v7
	v_and_b32_e32 v101, 0xffff0000, v7
	v_lshlrev_b32_e32 v102, 16, v8
	v_and_b32_e32 v103, 0xffff0000, v8
	v_lshlrev_b32_e32 v104, 16, v9
	v_and_b32_e32 v105, 0xffff0000, v9
	v_lshlrev_b32_e32 v136, 16, v2
	v_and_b32_e32 v137, 0xffff0000, v2
	v_lshlrev_b32_e32 v138, 16, v3
	v_and_b32_e32 v139, 0xffff0000, v3
	v_lshlrev_b32_e32 v140, 16, v4
	v_and_b32_e32 v141, 0xffff0000, v4
	v_lshlrev_b32_e32 v142, 16, v5
	v_and_b32_e32 v143, 0xffff0000, v5
	s_mov_b64 s[0:1], -1
	s_and_b64 vcc, exec, s[20:21]
	v_add_u32_e32 v160, v150, v144
	v_add_u32_e32 v162, v149, v144
	v_add_u32_e32 v158, v150, v145
	v_add_u32_e32 v161, v149, v145
	v_add_u32_e32 v157, v150, v146
	v_add_u32_e32 v159, v149, v146
	v_add_u32_e32 v155, v150, v147
	v_add_u32_e32 v156, v149, v147
	s_cbranch_vccz .LBB0_1759
	ds_read_b128 v[2:5], v160 offset:32768
	ds_read_b128 v[6:9], v162
	ds_read_b128 v[18:21], v158 offset:32768
	ds_read_b128 v[22:25], v161
	ds_read_b128 v[164:167], v157 offset:32768
	ds_read_b128 v[168:171], v159
	v_ashrrev_i32_e32 v131, 31, v130
	s_mov_b64 s[0:1], 0
	s_waitcnt lgkmcnt(4)
	v_mfma_f32_32x32x16_bf16 v[2:17], v[6:9], v[2:5], 0
	s_waitcnt lgkmcnt(2)
	v_mfma_f32_32x32x16_bf16 v[18:33], v[22:25], v[18:21], 0
	s_waitcnt lgkmcnt(0)
	v_mfma_f32_32x32x16_bf16 v[2:17], v[168:171], v[164:167], v[2:17]
	ds_read_b128 v[164:167], v155 offset:32768
	ds_read_b128 v[168:171], v156
	s_waitcnt lgkmcnt(0)
	v_mfma_f32_32x32x16_bf16 v[18:33], v[168:171], v[164:167], v[18:33]
	v_lshlrev_b64 v[164:165], 11, v[130:131]
	v_lshl_add_u64 v[164:165], v[128:129], 0, v[164:165]
	s_nop 9
	v_add_f32_e32 v4, v4, v20
	v_add_f32_e32 v5, v5, v21
	v_add_f32_e32 v2, v2, v18
	v_add_f32_e32 v3, v3, v19
	v_add_f32_e32 v4, v4, v100
	v_add_f32_e32 v5, v5, v101
	v_add_f32_e32 v2, v2, v98
	v_add_f32_e32 v3, v3, v99
	v_add_f32_e32 v8, v8, v24
	v_add_f32_e32 v9, v9, v25
	v_add_f32_e32 v6, v6, v22
	v_add_f32_e32 v7, v7, v23
	v_cvt_pk_bf16_f32 v2, v2, v3
	v_cvt_pk_bf16_f32 v3, v4, v5
	global_store_dwordx2 v[164:165], v[2:3], off
	v_add_f32_e32 v2, v6, v102
	v_add_f32_e32 v3, v7, v103
	v_add_f32_e32 v4, v8, v104
	v_add_f32_e32 v5, v9, v105
	v_add_f32_e32 v12, v12, v28
	v_add_f32_e32 v13, v13, v29
	v_add_f32_e32 v10, v10, v26
	v_add_f32_e32 v11, v11, v27
	v_cvt_pk_bf16_f32 v2, v2, v3
	v_cvt_pk_bf16_f32 v3, v4, v5
	global_store_dwordx2 v[164:165], v[2:3], off offset:16
	v_add_f32_e32 v2, v10, v136
	v_add_f32_e32 v3, v11, v137
	v_add_f32_e32 v4, v12, v138
	v_add_f32_e32 v5, v13, v139
	v_add_f32_e32 v16, v16, v32
	v_add_f32_e32 v17, v17, v33
	v_add_f32_e32 v14, v14, v30
	v_add_f32_e32 v15, v15, v31
	v_cvt_pk_bf16_f32 v2, v2, v3
	v_cvt_pk_bf16_f32 v3, v4, v5
	global_store_dwordx2 v[164:165], v[2:3], off offset:32
	v_add_f32_e32 v2, v14, v140
	v_add_f32_e32 v3, v15, v141
	v_add_f32_e32 v4, v16, v142
	v_add_f32_e32 v5, v17, v143
	v_cvt_pk_bf16_f32 v2, v2, v3
	v_cvt_pk_bf16_f32 v3, v4, v5
	global_store_dwordx2 v[164:165], v[2:3], off offset:48
.LBB0_1759:
	s_andn2_b64 vcc, exec, s[0:1]
	s_cbranch_vccnz .LBB0_1761
	ds_read_b128 v[2:5], v162 offset:16384
	ds_read_b128 v[6:9], v160
	ds_read_b128 v[18:21], v161 offset:16384
	ds_read_b128 v[22:25], v158
	ds_read_b128 v[74:77], v159 offset:16384
	ds_read_b128 v[82:85], v157
	s_waitcnt lgkmcnt(4)
	v_mfma_f32_32x32x16_bf16 v[2:17], v[2:5], v[6:9], 0
	s_waitcnt lgkmcnt(2)
	v_mfma_f32_32x32x16_bf16 v[18:33], v[18:21], v[22:25], 0
	s_waitcnt lgkmcnt(0)
	v_mfma_f32_32x32x16_bf16 v[2:17], v[74:77], v[82:85], v[2:17]
	ds_read_b128 v[74:77], v156 offset:16384
	ds_read_b128 v[82:85], v155
	s_waitcnt lgkmcnt(0)
	v_mfma_f32_32x32x16_bf16 v[18:33], v[74:77], v[82:85], v[18:33]
	s_nop 11
	v_add_f32_e32 v4, v4, v20
	v_add_f32_e32 v5, v5, v21
	v_add_f32_e32 v2, v2, v18
	v_add_f32_e32 v3, v3, v19
	v_add_f32_e32 v8, v8, v24
	v_add_f32_e32 v9, v9, v25
	v_add_f32_e32 v6, v6, v22
	v_add_f32_e32 v7, v7, v23
	v_add_f32_e32 v74, v2, v98
	v_add_f32_e32 v75, v3, v99
	v_add_f32_e32 v76, v4, v100
	v_add_f32_e32 v77, v5, v101
	v_add_f32_e32 v12, v12, v28
	v_add_f32_e32 v13, v13, v29
	v_add_f32_e32 v10, v10, v26
	v_add_f32_e32 v11, v11, v27
	v_add_f32_e32 v82, v6, v102
	v_add_f32_e32 v83, v7, v103
	v_add_f32_e32 v84, v8, v104
	v_add_f32_e32 v85, v9, v105
	v_cvt_pk_bf16_f32 v2, v74, v75
	v_cvt_pk_bf16_f32 v3, v76, v77
	v_add_f32_e32 v16, v16, v32
	v_add_f32_e32 v17, v17, v33
	v_add_f32_e32 v14, v14, v30
	v_add_f32_e32 v15, v15, v31
	v_add_f32_e32 v86, v10, v136
	v_add_f32_e32 v87, v11, v137
	v_add_f32_e32 v88, v12, v138
	v_add_f32_e32 v89, v13, v139
	ds_write_b64 v151, v[2:3] offset:8192
	v_cvt_pk_bf16_f32 v2, v82, v83
	v_cvt_pk_bf16_f32 v3, v84, v85
	v_add_f32_e32 v94, v14, v140
	v_add_f32_e32 v95, v15, v141
	v_add_f32_e32 v96, v16, v142
	v_add_f32_e32 v97, v17, v143
	ds_write_b64 v152, v[2:3] offset:8192
	v_cvt_pk_bf16_f32 v2, v86, v87
	v_cvt_pk_bf16_f32 v3, v88, v89
	ds_write_b64 v153, v[2:3] offset:8192
	v_cvt_pk_bf16_f32 v2, v94, v95
	v_cvt_pk_bf16_f32 v3, v96, v97
	ds_write_b64 v154, v[2:3] offset:8192

; __device__ __forceinline__ unsigned pk2(float lo, float hi) { const bfx2 b = __builtin_convertvector((f32x2){lo, hi}, bfx2); return __builtin_bit_cast(unsigned, b); }
; __device__ __forceinline__ float bflo(unsigned w) { return __uint_as_float(w << 16); }
; __device__ __forceinline__ float bfhi(unsigned w) { return __uint_as_float(w & 0xffff0000u); }
; #define CH_LOAD(slot, cc) do { const unsigned char* src_ = base + (size_t)(cc) * CK_TASK_BYTES; pmR[slot] = *(const u32x4*)(src_ + tid * 16); pqR[slot] = *(const u32x4*)(src_ + 8192 + tid * 16); \
;         n0R[slot] = *(const u32x4*)(src_ + noff); n1R[slot] = *(const u32x4*)(src_ + noff + 1024); } while (0)
; __device__ __forceinline__ void chunk_chain(const P& p, Frame& F, int s) {
;     ...
;       for (int u = 0; u < 4; ++u) { const int c = c4 + u, cur = u & 1;
;         f32x4 ad[4];
;         { const u32x4 w0 = n0R[u], w1 = n1R[u];
;           ad[0] = (f32x4){bflo(w0.x), bfhi(w0.x), bflo(w0.y), bfhi(w0.y)}; ad[1] = (f32x4){bflo(w0.z), bfhi(w0.z), bflo(w0.w), bfhi(w0.w)};
;           ad[2] = (f32x4){bflo(w1.x), bfhi(w1.x), bflo(w1.y), bfhi(w1.y)}; ad[3] = (f32x4){bflo(w1.z), bfhi(w1.z), bflo(w1.w), bfhi(w1.w)}; }
;         if (c + 4 < 32) CH_LOAD(u, c + 4);
;         if (grp == 0) {
;             sacc = ck_mm(L + (2 + cur) * CK_SLOT, L + cur * CK_SLOT, mt, nt, ql, half, ck_zero());
; #pragma unroll
;             for (int g = 0; g < 4; ++g)
; #pragma unroll
;                 for (int e = 0; e < 4; ++e) sacc[4 * g + e] += ad[g][e];
;             ck_store_t(L + (cur ^ 1) * CK_SLOT, sacc, mt, nt, ql, half);
;         } else {
;             const f32x16 a = ck_mm(L + cur * CK_SLOT, L + (4 + cur) * CK_SLOT, mt, nt, ql, half, ck_zero());
;             bf16* yrow = YRAW + (size_t)(b * TP + 64 * c + n) * 1024 + h * 64;
; #pragma unroll
;             for (int g = 0; g < 4; ++g) { u32x2 w; w.x = pk2(a[4 * g] + ad[g][0], a[4 * g + 1] + ad[g][1]); w.y = pk2(a[4 * g + 2] + ad[g][2], a[4 * g + 3] + ad[g][3]);
;                 *(u32x2*)(yrow + 32 * mt + 8 * g + 4 * half) = w; } }
.LBB0_1763:
	v_cndmask_b32_e64 v2, 0, 1, s[20:21]
	v_lshlrev_b32_e32 v136, 16, v118
	v_and_b32_e32 v137, 0xffff0000, v118
	v_lshlrev_b32_e32 v118, 16, v119
	v_and_b32_e32 v119, 0xffff0000, v119
	v_lshlrev_b32_e32 v138, 16, v120
	v_and_b32_e32 v139, 0xffff0000, v120
	v_lshlrev_b32_e32 v120, 16, v121
	v_and_b32_e32 v121, 0xffff0000, v121
	v_lshlrev_b32_e32 v140, 16, v114
	v_and_b32_e32 v141, 0xffff0000, v114
	v_lshlrev_b32_e32 v114, 16, v115
	v_and_b32_e32 v115, 0xffff0000, v115
	v_lshlrev_b32_e32 v142, 16, v116
	v_and_b32_e32 v143, 0xffff0000, v116
	v_lshlrev_b32_e32 v116, 16, v117
	v_and_b32_e32 v117, 0xffff0000, v117
	v_cmp_ne_u32_e64 s[6:7], 1, v2
	s_andn2_b64 vcc, exec, s[20:21]
	s_mov_b64 s[24:25], -1
	s_cbranch_vccnz .LBB0_1765
	ds_read_b128 v[2:5], v160 offset:40960
	ds_read_b128 v[6:9], v162 offset:8192
	ds_read_b128 v[18:21], v158 offset:40960
	ds_read_b128 v[22:25], v161 offset:8192
	ds_read_b128 v[164:167], v157 offset:40960
	ds_read_b128 v[168:171], v159 offset:8192
	s_mov_b64 s[24:25], 0
	s_waitcnt lgkmcnt(4)
	v_mfma_f32_32x32x16_bf16 v[2:17], v[6:9], v[2:5], 0
	s_waitcnt lgkmcnt(2)
	v_mfma_f32_32x32x16_bf16 v[18:33], v[22:25], v[18:21], 0
	s_waitcnt lgkmcnt(0)
	v_mfma_f32_32x32x16_bf16 v[2:17], v[168:171], v[164:167], v[2:17]
	ds_read_b128 v[164:167], v155 offset:40960
	ds_read_b128 v[168:171], v156 offset:8192
	s_waitcnt lgkmcnt(0)
	v_mfma_f32_32x32x16_bf16 v[18:33], v[168:171], v[164:167], v[18:33]
	v_add_u32_e32 v164, 64, v130
	v_ashrrev_i32_e32 v165, 31, v164
	v_lshlrev_b64 v[164:165], 11, v[164:165]
	v_lshl_add_u64 v[164:165], v[128:129], 0, v[164:165]
	s_nop 7
	v_add_f32_e32 v4, v4, v20
	v_add_f32_e32 v5, v5, v21
	v_add_f32_e32 v2, v2, v18
	v_add_f32_e32 v3, v3, v19
	v_add_f32_e32 v4, v4, v118
	v_add_f32_e32 v5, v5, v119
	v_add_f32_e32 v2, v2, v136
	v_add_f32_e32 v3, v3, v137
	v_add_f32_e32 v8, v8, v24
	v_add_f32_e32 v9, v9, v25
	v_add_f32_e32 v6, v6, v22
	v_add_f32_e32 v7, v7, v23
	v_cvt_pk_bf16_f32 v2, v2, v3
	v_cvt_pk_bf16_f32 v3, v4, v5
	global_store_dwordx2 v[164:165], v[2:3], off
	v_add_f32_e32 v2, v6, v138
	v_add_f32_e32 v3, v7, v139
	v_add_f32_e32 v4, v8, v120
	v_add_f32_e32 v5, v9, v121
	v_add_f32_e32 v12, v12, v28
	v_add_f32_e32 v13, v13, v29
	v_add_f32_e32 v10, v10, v26
	v_add_f32_e32 v11, v11, v27
	v_cvt_pk_bf16_f32 v2, v2, v3
	v_cvt_pk_bf16_f32 v3, v4, v5
	global_store_dwordx2 v[164:165], v[2:3], off offset:16
	v_add_f32_e32 v2, v10, v140
	v_add_f32_e32 v3, v11, v141
	v_add_f32_e32 v4, v12, v114
	v_add_f32_e32 v5, v13, v115
	v_add_f32_e32 v16, v16, v32
	v_add_f32_e32 v17, v17, v33
	v_add_f32_e32 v14, v14, v30
	v_add_f32_e32 v15, v15, v31
	v_cvt_pk_bf16_f32 v2, v2, v3
	v_cvt_pk_bf16_f32 v3, v4, v5
	global_store_dwordx2 v[164:165], v[2:3], off offset:32
	v_add_f32_e32 v2, v14, v142
	v_add_f32_e32 v3, v15, v143
	v_add_f32_e32 v4, v16, v116
	v_add_f32_e32 v5, v17, v117
	v_cvt_pk_bf16_f32 v2, v2, v3
	v_cvt_pk_bf16_f32 v3, v4, v5
	global_store_dwordx2 v[164:165], v[2:3], off offset:48
.LBB0_1765:
	s_andn2_b64 vcc, exec, s[24:25]
	s_cbranch_vccnz .LBB0_1767
	ds_read_b128 v[2:5], v162 offset:24576
	ds_read_b128 v[6:9], v160 offset:8192
	ds_read_b128 v[18:21], v161 offset:24576
	ds_read_b128 v[22:25], v158 offset:8192
	ds_read_b128 v[74:77], v159 offset:24576
	ds_read_b128 v[82:85], v157 offset:8192
	s_waitcnt lgkmcnt(4)
	v_mfma_f32_32x32x16_bf16 v[2:17], v[2:5], v[6:9], 0
	s_waitcnt lgkmcnt(2)
	v_mfma_f32_32x32x16_bf16 v[18:33], v[18:21], v[22:25], 0
	s_waitcnt lgkmcnt(0)
	v_mfma_f32_32x32x16_bf16 v[2:17], v[74:77], v[82:85], v[2:17]
	ds_read_b128 v[74:77], v156 offset:24576
	ds_read_b128 v[82:85], v155 offset:8192
	s_waitcnt lgkmcnt(0)
	v_mfma_f32_32x32x16_bf16 v[18:33], v[74:77], v[82:85], v[18:33]
	s_nop 11
	v_add_f32_e32 v4, v4, v20
	v_add_f32_e32 v5, v5, v21
	v_add_f32_e32 v2, v2, v18
	v_add_f32_e32 v3, v3, v19
	v_add_f32_e32 v8, v8, v24
	v_add_f32_e32 v9, v9, v25
	v_add_f32_e32 v6, v6, v22
	v_add_f32_e32 v7, v7, v23
	v_add_f32_e32 v74, v2, v136
	v_add_f32_e32 v75, v3, v137
	v_add_f32_e32 v76, v4, v118
	v_add_f32_e32 v77, v5, v119
	v_add_f32_e32 v12, v12, v28
	v_add_f32_e32 v13, v13, v29
	v_add_f32_e32 v10, v10, v26
	v_add_f32_e32 v11, v11, v27
	v_add_f32_e32 v82, v6, v138
	v_add_f32_e32 v83, v7, v139
	v_add_f32_e32 v84, v8, v120
	v_add_f32_e32 v85, v9, v121
	v_cvt_pk_bf16_f32 v2, v74, v75
	v_cvt_pk_bf16_f32 v3, v76, v77
	v_add_f32_e32 v16, v16, v32
	v_add_f32_e32 v17, v17, v33
	v_add_f32_e32 v14, v14, v30
	v_add_f32_e32 v15, v15, v31
	v_add_f32_e32 v86, v10, v140
	v_add_f32_e32 v87, v11, v141
	v_add_f32_e32 v88, v12, v114
	v_add_f32_e32 v89, v13, v115
	ds_write_b64 v151, v[2:3]
	v_cvt_pk_bf16_f32 v2, v82, v83
	v_cvt_pk_bf16_f32 v3, v84, v85
	v_add_f32_e32 v94, v14, v142
	v_add_f32_e32 v95, v15, v143
	v_add_f32_e32 v96, v16, v116
	v_add_f32_e32 v97, v17, v117
	ds_write_b64 v152, v[2:3]
	v_cvt_pk_bf16_f32 v2, v86, v87
	v_cvt_pk_bf16_f32 v3, v88, v89
	ds_write_b64 v153, v[2:3]
	v_cvt_pk_bf16_f32 v2, v94, v95
	v_cvt_pk_bf16_f32 v3, v96, v97
	ds_write_b64 v154, v[2:3]

; __device__ __forceinline__ unsigned pk2(float lo, float hi) { const bfx2 b = __builtin_convertvector((f32x2){lo, hi}, bfx2); return __builtin_bit_cast(unsigned, b); }
; __device__ __forceinline__ float bflo(unsigned w) { return __uint_as_float(w << 16); }
; __device__ __forceinline__ float bfhi(unsigned w) { return __uint_as_float(w & 0xffff0000u); }
; #define CH_LOAD(slot, cc) do { const unsigned char* src_ = base + (size_t)(cc) * CK_TASK_BYTES; pmR[slot] = *(const u32x4*)(src_ + tid * 16); pqR[slot] = *(const u32x4*)(src_ + 8192 + tid * 16); \
;         n0R[slot] = *(const u32x4*)(src_ + noff); n1R[slot] = *(const u32x4*)(src_ + noff + 1024); } while (0)
; __device__ __forceinline__ void chunk_chain(const P& p, Frame& F, int s) {
;     ...
;       for (int u = 0; u < 4; ++u) { const int c = c4 + u, cur = u & 1;
;         f32x4 ad[4];
;         { const u32x4 w0 = n0R[u], w1 = n1R[u];
;           ad[0] = (f32x4){bflo(w0.x), bfhi(w0.x), bflo(w0.y), bfhi(w0.y)}; ad[1] = (f32x4){bflo(w0.z), bfhi(w0.z), bflo(w0.w), bfhi(w0.w)};
;           ad[2] = (f32x4){bflo(w1.x), bfhi(w1.x), bflo(w1.y), bfhi(w1.y)}; ad[3] = (f32x4){bflo(w1.z), bfhi(w1.z), bflo(w1.w), bfhi(w1.w)}; }
;         if (c + 4 < 32) CH_LOAD(u, c + 4);
;         if (grp == 0) {
;             sacc = ck_mm(L + (2 + cur) * CK_SLOT, L + cur * CK_SLOT, mt, nt, ql, half, ck_zero());
; #pragma unroll
;             for (int g = 0; g < 4; ++g)
; #pragma unroll
;                 for (int e = 0; e < 4; ++e) sacc[4 * g + e] += ad[g][e];
;             ck_store_t(L + (cur ^ 1) * CK_SLOT, sacc, mt, nt, ql, half);
;         } else {
;             const f32x16 a = ck_mm(L + cur * CK_SLOT, L + (4 + cur) * CK_SLOT, mt, nt, ql, half, ck_zero());
;             bf16* yrow = YRAW + (size_t)(b * TP + 64 * c + n) * 1024 + h * 64;
; #pragma unroll
;             for (int g = 0; g < 4; ++g) { u32x2 w; w.x = pk2(a[4 * g] + ad[g][0], a[4 * g + 1] + ad[g][1]); w.y = pk2(a[4 * g + 2] + ad[g][2], a[4 * g + 3] + ad[g][3]);
;                 *(u32x2*)(yrow + 32 * mt + 8 * g + 4 * half) = w; } }
.LBB0_1769:
	v_lshlrev_b32_e32 v136, 16, v110
	v_and_b32_e32 v137, 0xffff0000, v110
	v_lshlrev_b32_e32 v110, 16, v111
	v_and_b32_e32 v111, 0xffff0000, v111
	v_lshlrev_b32_e32 v138, 16, v112
	v_and_b32_e32 v139, 0xffff0000, v112
	v_lshlrev_b32_e32 v112, 16, v113
	v_and_b32_e32 v113, 0xffff0000, v113
	v_lshlrev_b32_e32 v140, 16, v106
	v_and_b32_e32 v141, 0xffff0000, v106
	v_lshlrev_b32_e32 v106, 16, v107
	v_and_b32_e32 v107, 0xffff0000, v107
	v_lshlrev_b32_e32 v142, 16, v108
	v_and_b32_e32 v143, 0xffff0000, v108
	v_lshlrev_b32_e32 v108, 16, v109
	v_and_b32_e32 v109, 0xffff0000, v109
	s_and_b64 vcc, exec, s[6:7]
	s_mov_b64 s[24:25], -1
	s_cbranch_vccnz .LBB0_1771
	ds_read_b128 v[2:5], v160 offset:32768
	ds_read_b128 v[6:9], v162
	ds_read_b128 v[18:21], v158 offset:32768
	ds_read_b128 v[22:25], v161
	ds_read_b128 v[164:167], v157 offset:32768
	ds_read_b128 v[168:171], v159
	s_mov_b64 s[24:25], 0
	s_waitcnt lgkmcnt(4)
	v_mfma_f32_32x32x16_bf16 v[2:17], v[6:9], v[2:5], 0
	s_waitcnt lgkmcnt(2)
	v_mfma_f32_32x32x16_bf16 v[18:33], v[22:25], v[18:21], 0
	s_waitcnt lgkmcnt(0)
	v_mfma_f32_32x32x16_bf16 v[2:17], v[168:171], v[164:167], v[2:17]
	ds_read_b128 v[164:167], v155 offset:32768
	ds_read_b128 v[168:171], v156
	s_waitcnt lgkmcnt(0)
	v_mfma_f32_32x32x16_bf16 v[18:33], v[168:171], v[164:167], v[18:33]
	v_add_u32_e32 v164, 0x80, v130
	v_ashrrev_i32_e32 v165, 31, v164
	v_lshlrev_b64 v[164:165], 11, v[164:165]
	v_lshl_add_u64 v[164:165], v[128:129], 0, v[164:165]
	s_nop 7
	v_add_f32_e32 v4, v4, v20
	v_add_f32_e32 v5, v5, v21
	v_add_f32_e32 v2, v2, v18
	v_add_f32_e32 v3, v3, v19
	v_add_f32_e32 v4, v4, v110
	v_add_f32_e32 v5, v5, v111
	v_add_f32_e32 v2, v2, v136
	v_add_f32_e32 v3, v3, v137
	v_add_f32_e32 v8, v8, v24
	v_add_f32_e32 v9, v9, v25
	v_add_f32_e32 v6, v6, v22
	v_add_f32_e32 v7, v7, v23
	v_cvt_pk_bf16_f32 v2, v2, v3
	v_cvt_pk_bf16_f32 v3, v4, v5
	global_store_dwordx2 v[164:165], v[2:3], off
	v_add_f32_e32 v2, v6, v138
	v_add_f32_e32 v3, v7, v139
	v_add_f32_e32 v4, v8, v112
	v_add_f32_e32 v5, v9, v113
	v_add_f32_e32 v12, v12, v28
	v_add_f32_e32 v13, v13, v29
	v_add_f32_e32 v10, v10, v26
	v_add_f32_e32 v11, v11, v27
	v_cvt_pk_bf16_f32 v2, v2, v3
	v_cvt_pk_bf16_f32 v3, v4, v5
	global_store_dwordx2 v[164:165], v[2:3], off offset:16
	v_add_f32_e32 v2, v10, v140
	v_add_f32_e32 v3, v11, v141
	v_add_f32_e32 v4, v12, v106
	v_add_f32_e32 v5, v13, v107
	v_add_f32_e32 v16, v16, v32
	v_add_f32_e32 v17, v17, v33
	v_add_f32_e32 v14, v14, v30
	v_add_f32_e32 v15, v15, v31
	v_cvt_pk_bf16_f32 v2, v2, v3
	v_cvt_pk_bf16_f32 v3, v4, v5
	global_store_dwordx2 v[164:165], v[2:3], off offset:32
	v_add_f32_e32 v2, v14, v142
	v_add_f32_e32 v3, v15, v143
	v_add_f32_e32 v4, v16, v108
	v_add_f32_e32 v5, v17, v109
	v_cvt_pk_bf16_f32 v2, v2, v3
	v_cvt_pk_bf16_f32 v3, v4, v5
	global_store_dwordx2 v[164:165], v[2:3], off offset:48
.LBB0_1771:
	s_andn2_b64 vcc, exec, s[24:25]
	s_cbranch_vccnz .LBB0_1773
	ds_read_b128 v[2:5], v162 offset:16384
	ds_read_b128 v[6:9], v160
	ds_read_b128 v[18:21], v161 offset:16384
	ds_read_b128 v[22:25], v158
	ds_read_b128 v[74:77], v159 offset:16384
	ds_read_b128 v[82:85], v157
	s_waitcnt lgkmcnt(4)
	v_mfma_f32_32x32x16_bf16 v[2:17], v[2:5], v[6:9], 0
	s_waitcnt lgkmcnt(2)
	v_mfma_f32_32x32x16_bf16 v[18:33], v[18:21], v[22:25], 0
	s_waitcnt lgkmcnt(0)
	v_mfma_f32_32x32x16_bf16 v[2:17], v[74:77], v[82:85], v[2:17]
	ds_read_b128 v[74:77], v156 offset:16384
	ds_read_b128 v[82:85], v155
	s_waitcnt lgkmcnt(0)
	v_mfma_f32_32x32x16_bf16 v[18:33], v[74:77], v[82:85], v[18:33]
	s_nop 11
	v_add_f32_e32 v4, v4, v20
	v_add_f32_e32 v5, v5, v21
	v_add_f32_e32 v2, v2, v18
	v_add_f32_e32 v3, v3, v19
	v_add_f32_e32 v8, v8, v24
	v_add_f32_e32 v9, v9, v25
	v_add_f32_e32 v6, v6, v22
	v_add_f32_e32 v7, v7, v23
	v_add_f32_e32 v74, v2, v136
	v_add_f32_e32 v75, v3, v137
	v_add_f32_e32 v76, v4, v110
	v_add_f32_e32 v77, v5, v111
	v_add_f32_e32 v12, v12, v28
	v_add_f32_e32 v13, v13, v29
	v_add_f32_e32 v10, v10, v26
	v_add_f32_e32 v11, v11, v27
	v_add_f32_e32 v82, v6, v138
	v_add_f32_e32 v83, v7, v139
	v_add_f32_e32 v84, v8, v112
	v_add_f32_e32 v85, v9, v113
	v_cvt_pk_bf16_f32 v2, v74, v75
	v_cvt_pk_bf16_f32 v3, v76, v77
	v_add_f32_e32 v16, v16, v32
	v_add_f32_e32 v17, v17, v33
	v_add_f32_e32 v14, v14, v30
	v_add_f32_e32 v15, v15, v31
	v_add_f32_e32 v86, v10, v140
	v_add_f32_e32 v87, v11, v141
	v_add_f32_e32 v88, v12, v106
	v_add_f32_e32 v89, v13, v107
	ds_write_b64 v151, v[2:3] offset:8192
	v_cvt_pk_bf16_f32 v2, v82, v83
	v_cvt_pk_bf16_f32 v3, v84, v85
	v_add_f32_e32 v94, v14, v142
	v_add_f32_e32 v95, v15, v143
	v_add_f32_e32 v96, v16, v108
	v_add_f32_e32 v97, v17, v109
	ds_write_b64 v152, v[2:3] offset:8192
	v_cvt_pk_bf16_f32 v2, v86, v87
	v_cvt_pk_bf16_f32 v3, v88, v89
	ds_write_b64 v153, v[2:3] offset:8192
	v_cvt_pk_bf16_f32 v2, v94, v95
	v_cvt_pk_bf16_f32 v3, v96, v97
	ds_write_b64 v154, v[2:3] offset:8192

; __device__ __forceinline__ unsigned pk2(float lo, float hi) { const bfx2 b = __builtin_convertvector((f32x2){lo, hi}, bfx2); return __builtin_bit_cast(unsigned, b); }
; __device__ __forceinline__ float bflo(unsigned w) { return __uint_as_float(w << 16); }
; __device__ __forceinline__ float bfhi(unsigned w) { return __uint_as_float(w & 0xffff0000u); }
; #define CH_LOAD(slot, cc) do { const unsigned char* src_ = base + (size_t)(cc) * CK_TASK_BYTES; pmR[slot] = *(const u32x4*)(src_ + tid * 16); pqR[slot] = *(const u32x4*)(src_ + 8192 + tid * 16); \
;         n0R[slot] = *(const u32x4*)(src_ + noff); n1R[slot] = *(const u32x4*)(src_ + noff + 1024); } while (0)
; __device__ __forceinline__ void chunk_chain(const P& p, Frame& F, int s) {
;     ...
;       for (int u = 0; u < 4; ++u) { const int c = c4 + u, cur = u & 1;
;         f32x4 ad[4];
;         { const u32x4 w0 = n0R[u], w1 = n1R[u];
;           ad[0] = (f32x4){bflo(w0.x), bfhi(w0.x), bflo(w0.y), bfhi(w0.y)}; ad[1] = (f32x4){bflo(w0.z), bfhi(w0.z), bflo(w0.w), bfhi(w0.w)};
;           ad[2] = (f32x4){bflo(w1.x), bfhi(w1.x), bflo(w1.y), bfhi(w1.y)}; ad[3] = (f32x4){bflo(w1.z), bfhi(w1.z), bflo(w1.w), bfhi(w1.w)}; }
;         if (c + 4 < 32) CH_LOAD(u, c + 4);
;         if (grp == 0) {
;             sacc = ck_mm(L + (2 + cur) * CK_SLOT, L + cur * CK_SLOT, mt, nt, ql, half, ck_zero());
; #pragma unroll
;             for (int g = 0; g < 4; ++g)
; #pragma unroll
;                 for (int e = 0; e < 4; ++e) sacc[4 * g + e] += ad[g][e];
;             ck_store_t(L + (cur ^ 1) * CK_SLOT, sacc, mt, nt, ql, half);
;         } else {
;             const f32x16 a = ck_mm(L + cur * CK_SLOT, L + (4 + cur) * CK_SLOT, mt, nt, ql, half, ck_zero());
;             bf16* yrow = YRAW + (size_t)(b * TP + 64 * c + n) * 1024 + h * 64;
; #pragma unroll
;             for (int g = 0; g < 4; ++g) { u32x2 w; w.x = pk2(a[4 * g] + ad[g][0], a[4 * g + 1] + ad[g][1]); w.y = pk2(a[4 * g + 2] + ad[g][2], a[4 * g + 3] + ad[g][3]);
;                 *(u32x2*)(yrow + 32 * mt + 8 * g + 4 * half) = w; } }
.LBB0_1775:
	v_lshlrev_b32_e32 v132, 16, v90
	v_and_b32_e32 v133, 0xffff0000, v90
	v_lshlrev_b32_e32 v90, 16, v91
	v_and_b32_e32 v91, 0xffff0000, v91
	v_lshlrev_b32_e32 v134, 16, v92
	v_and_b32_e32 v135, 0xffff0000, v92
	v_lshlrev_b32_e32 v92, 16, v93
	v_and_b32_e32 v93, 0xffff0000, v93
	v_lshlrev_b32_e32 v136, 16, v78
	v_and_b32_e32 v137, 0xffff0000, v78
	v_lshlrev_b32_e32 v78, 16, v79
	v_and_b32_e32 v79, 0xffff0000, v79
	v_lshlrev_b32_e32 v138, 16, v80
	v_and_b32_e32 v139, 0xffff0000, v80
	v_lshlrev_b32_e32 v80, 16, v81
	v_and_b32_e32 v81, 0xffff0000, v81
	s_and_b64 vcc, exec, s[6:7]
	s_mov_b64 s[0:1], -1
	s_cbranch_vccnz .LBB0_1781
	ds_read_b128 v[2:5], v160 offset:40960
	ds_read_b128 v[6:9], v162 offset:8192
	ds_read_b128 v[18:21], v158 offset:40960
	ds_read_b128 v[22:25], v161 offset:8192
	ds_read_b128 v[140:143], v157 offset:40960
	ds_read_b128 v[164:167], v159 offset:8192
	s_waitcnt lgkmcnt(4)
	v_mfma_f32_32x32x16_bf16 v[2:17], v[6:9], v[2:5], 0
	s_waitcnt lgkmcnt(2)
	v_mfma_f32_32x32x16_bf16 v[18:33], v[22:25], v[18:21], 0
	s_waitcnt lgkmcnt(0)
	v_mfma_f32_32x32x16_bf16 v[2:17], v[164:167], v[140:143], v[2:17]
	ds_read_b128 v[140:143], v155 offset:40960
	ds_read_b128 v[164:167], v156 offset:8192
	s_waitcnt lgkmcnt(0)
	v_mfma_f32_32x32x16_bf16 v[18:33], v[164:167], v[140:143], v[18:33]
	v_add_u32_e32 v140, 0xc0, v130
	v_ashrrev_i32_e32 v141, 31, v140
	v_lshlrev_b64 v[140:141], 11, v[140:141]
	v_lshl_add_u64 v[140:141], v[128:129], 0, v[140:141]
	s_nop 7
	v_add_f32_e32 v4, v4, v20
	v_add_f32_e32 v5, v5, v21
	v_add_f32_e32 v2, v2, v18
	v_add_f32_e32 v3, v3, v19
	v_add_f32_e32 v4, v4, v90
	v_add_f32_e32 v5, v5, v91
	v_add_f32_e32 v2, v2, v132
	v_add_f32_e32 v3, v3, v133
	v_add_f32_e32 v8, v8, v24
	v_add_f32_e32 v9, v9, v25
	v_add_f32_e32 v6, v6, v22
	v_add_f32_e32 v7, v7, v23
	v_cvt_pk_bf16_f32 v2, v2, v3
	v_cvt_pk_bf16_f32 v3, v4, v5
	global_store_dwordx2 v[140:141], v[2:3], off
	v_add_f32_e32 v2, v6, v134
	v_add_f32_e32 v3, v7, v135
	v_add_f32_e32 v4, v8, v92
	v_add_f32_e32 v5, v9, v93
	v_add_f32_e32 v12, v12, v28
	v_add_f32_e32 v13, v13, v29
	v_add_f32_e32 v10, v10, v26
	v_add_f32_e32 v11, v11, v27
	v_cvt_pk_bf16_f32 v2, v2, v3
	v_cvt_pk_bf16_f32 v3, v4, v5
	global_store_dwordx2 v[140:141], v[2:3], off offset:16
	v_add_f32_e32 v2, v10, v136
	v_add_f32_e32 v3, v11, v137
	v_add_f32_e32 v4, v12, v78
	v_add_f32_e32 v5, v13, v79
	v_add_f32_e32 v16, v16, v32
	v_add_f32_e32 v17, v17, v33
	v_add_f32_e32 v14, v14, v30
	v_add_f32_e32 v15, v15, v31
	v_cvt_pk_bf16_f32 v2, v2, v3
	v_cvt_pk_bf16_f32 v3, v4, v5
	global_store_dwordx2 v[140:141], v[2:3], off offset:32
	v_add_f32_e32 v2, v14, v138
	v_add_f32_e32 v3, v15, v139
	v_add_f32_e32 v4, v16, v80
	v_add_f32_e32 v5, v17, v81
	v_cvt_pk_bf16_f32 v2, v2, v3
	v_cvt_pk_bf16_f32 v3, v4, v5
	global_store_dwordx2 v[140:141], v[2:3], off offset:48
	s_cbranch_execz .LBB0_1782

; __device__ __forceinline__ unsigned pk2(float lo, float hi) { const bfx2 b = __builtin_convertvector((f32x2){lo, hi}, bfx2); return __builtin_bit_cast(unsigned, b); }
; __device__ __forceinline__ float bflo(unsigned w) { return __uint_as_float(w << 16); }
; __device__ __forceinline__ float bfhi(unsigned w) { return __uint_as_float(w & 0xffff0000u); }
; #define CH_LOAD(slot, cc) do { const unsigned char* src_ = base + (size_t)(cc) * CK_TASK_BYTES; pmR[slot] = *(const u32x4*)(src_ + tid * 16); pqR[slot] = *(const u32x4*)(src_ + 8192 + tid * 16); \
;         n0R[slot] = *(const u32x4*)(src_ + noff); n1R[slot] = *(const u32x4*)(src_ + noff + 1024); } while (0)
; __device__ __forceinline__ void chunk_chain(const P& p, Frame& F, int s) {
;     ...
;       for (int u = 0; u < 4; ++u) { const int c = c4 + u, cur = u & 1;
;         f32x4 ad[4];
;         { const u32x4 w0 = n0R[u], w1 = n1R[u];
;           ad[0] = (f32x4){bflo(w0.x), bfhi(w0.x), bflo(w0.y), bfhi(w0.y)}; ad[1] = (f32x4){bflo(w0.z), bfhi(w0.z), bflo(w0.w), bfhi(w0.w)};
;           ad[2] = (f32x4){bflo(w1.x), bfhi(w1.x), bflo(w1.y), bfhi(w1.y)}; ad[3] = (f32x4){bflo(w1.z), bfhi(w1.z), bflo(w1.w), bfhi(w1.w)}; }
;         if (c + 4 < 32) CH_LOAD(u, c + 4);
;         if (grp == 0) {
;             sacc = ck_mm(L + (2 + cur) * CK_SLOT, L + cur * CK_SLOT, mt, nt, ql, half, ck_zero());
; #pragma unroll
;             for (int g = 0; g < 4; ++g)
; #pragma unroll
;                 for (int e = 0; e < 4; ++e) sacc[4 * g + e] += ad[g][e];
;             ck_store_t(L + (cur ^ 1) * CK_SLOT, sacc, mt, nt, ql, half);
;         } else {
;             const f32x16 a = ck_mm(L + cur * CK_SLOT, L + (4 + cur) * CK_SLOT, mt, nt, ql, half, ck_zero());
;             bf16* yrow = YRAW + (size_t)(b * TP + 64 * c + n) * 1024 + h * 64;
; #pragma unroll
;             for (int g = 0; g < 4; ++g) { u32x2 w; w.x = pk2(a[4 * g] + ad[g][0], a[4 * g + 1] + ad[g][1]); w.y = pk2(a[4 * g + 2] + ad[g][2], a[4 * g + 3] + ad[g][3]);
;                 *(u32x2*)(yrow + 32 * mt + 8 * g + 4 * half) = w; } }
.LBB0_1782:
	ds_read_b128 v[2:5], v162 offset:24576
	ds_read_b128 v[6:9], v160 offset:8192
	ds_read_b128 v[18:21], v161 offset:24576
	ds_read_b128 v[22:25], v158 offset:8192
	ds_read_b128 v[74:77], v159 offset:24576
	ds_read_b128 v[82:85], v157 offset:8192
	s_waitcnt lgkmcnt(4)
	v_mfma_f32_32x32x16_bf16 v[2:17], v[2:5], v[6:9], 0
	s_waitcnt lgkmcnt(2)
	v_mfma_f32_32x32x16_bf16 v[18:33], v[18:21], v[22:25], 0
	s_waitcnt lgkmcnt(0)
	v_mfma_f32_32x32x16_bf16 v[2:17], v[74:77], v[82:85], v[2:17]
	ds_read_b128 v[74:77], v156 offset:24576
	ds_read_b128 v[82:85], v155 offset:8192
	s_waitcnt lgkmcnt(0)
	v_mfma_f32_32x32x16_bf16 v[18:33], v[74:77], v[82:85], v[18:33]
	s_nop 11
	v_add_f32_e32 v4, v4, v20
	v_add_f32_e32 v5, v5, v21
	v_add_f32_e32 v2, v2, v18
	v_add_f32_e32 v3, v3, v19
	v_add_f32_e32 v8, v8, v24
	v_add_f32_e32 v9, v9, v25
	v_add_f32_e32 v6, v6, v22
	v_add_f32_e32 v7, v7, v23
	v_add_f32_e32 v74, v2, v132
	v_add_f32_e32 v75, v3, v133
	v_add_f32_e32 v76, v4, v90
	v_add_f32_e32 v77, v5, v91
	v_add_f32_e32 v12, v12, v28
	v_add_f32_e32 v13, v13, v29
	v_add_f32_e32 v10, v10, v26
	v_add_f32_e32 v11, v11, v27
	v_add_f32_e32 v82, v6, v134
	v_add_f32_e32 v83, v7, v135
	v_add_f32_e32 v84, v8, v92
	v_add_f32_e32 v85, v9, v93
	v_cvt_pk_bf16_f32 v2, v74, v75
	v_cvt_pk_bf16_f32 v3, v76, v77
	v_add_f32_e32 v16, v16, v32
	v_add_f32_e32 v17, v17, v33
	v_add_f32_e32 v14, v14, v30
	v_add_f32_e32 v15, v15, v31
	v_add_f32_e32 v86, v10, v136
	v_add_f32_e32 v87, v11, v137
	v_add_f32_e32 v88, v12, v78
	v_add_f32_e32 v89, v13, v79
	ds_write_b64 v151, v[2:3]
	v_cvt_pk_bf16_f32 v2, v82, v83
	v_cvt_pk_bf16_f32 v3, v84, v85
	v_add_f32_e32 v94, v14, v138
	v_add_f32_e32 v95, v15, v139
	v_add_f32_e32 v96, v16, v80
	v_add_f32_e32 v97, v17, v81
	ds_write_b64 v152, v[2:3]
	v_cvt_pk_bf16_f32 v2, v86, v87
	v_cvt_pk_bf16_f32 v3, v88, v89
	ds_write_b64 v153, v[2:3]
	v_cvt_pk_bf16_f32 v2, v94, v95
	v_cvt_pk_bf16_f32 v3, v96, v97
	ds_write_b64 v154, v[2:3]
	s_cmp_gt_u32 s17, 30
	s_cbranch_scc0 .LBB0_1778
	s_branch .LBB0_1779

; #define LAS __attribute__((address_space(3)))
; #define SCAN_FETCH(srow) do { const char* so_ = (const char*)(OPSB + (srow) * 256); pb0 = *(const u32x4*)(so_ + (size_t)tid * 32); pb1 = *(const u32x4*)(so_ + (size_t)tid * 32 + 16); \
;         pw = *(const f32x4*)((const char*)(WQ + (srow) * 64) + (size_t)tid * 16); pv = *(const u32x2*)((const char*)(VVB + (srow) * 64) + (size_t)tid * 8); } while (0)
; __device__ __forceinline__ void scan_half(const P& p, Frame& F, size_t sr0, int T, const float* S0, float* Sout, int m0, int h, int hf) {
;     ...
;     SCAN_FETCH(sr0);
;     __syncthreads();
;     SCAN_PUT(0);
;     __syncthreads();
;     for (int k = 0; k < nch; ++k) {
;         const int buf = k & 1, t0 = k * 32, ns = (T - t0) < 32 ? (T - t0) : 32;
;         if (k + 1 < nch) SCAN_FETCH(sr0 + t0 + 32);
;         const LAS float* opl = (const LAS float*)(F.lds + S_OPL + buf * 40960) + c * 4;
;         const LAS float* vl = (const LAS float*)(F.lds + S_VL + buf * 8192) + row;
;         LAS float* yl = (LAS float*)(F.lds + S_YL + buf * 4096) + rowl;
.LBB0_1793:
	s_lshl_b64 s[20:21], s[18:19], 2
	s_add_u32 s20, s20, 0x40000
	s_addc_u32 s21, s21, 0
	s_lshl_b64 s[26:27], s[20:21], 9
	v_lshl_add_u64 v[2:3], v[44:45], 0, s[26:27]
	s_lshl_b64 s[26:27], s[20:21], 7
	global_load_dwordx4 v[6:9], v[2:3], off
	global_load_dwordx4 v[10:13], v[2:3], off offset:16
	v_lshl_add_u64 v[2:3], v[48:49], 0, s[26:27]
	global_load_dwordx2 v[30:31], v[2:3], off
	s_lshl_b64 s[20:21], s[20:21], 8
	v_lshl_add_u64 v[2:3], v[46:47], 0, s[20:21]
	global_load_dwordx4 v[18:21], v[2:3], off
	v_lshl_add_u32 v2, v4, 2, 0
	v_add_u32_e32 v51, 0x14000, v2
	s_barrier
	s_waitcnt vmcnt(3)
	v_lshlrev_b32_e32 v2, 16, v6
	v_and_b32_e32 v3, 0xffff0000, v6
	v_lshlrev_b32_e32 v4, 16, v7
	v_and_b32_e32 v5, 0xffff0000, v7
	v_lshlrev_b32_e32 v6, 16, v8
	v_and_b32_e32 v7, 0xffff0000, v8
	v_lshlrev_b32_e32 v8, 16, v9
	v_and_b32_e32 v9, 0xffff0000, v9
	s_waitcnt vmcnt(2)
	v_lshlrev_b32_e32 v24, 16, v10
	v_and_b32_e32 v25, 0xffff0000, v10
	v_lshlrev_b32_e32 v26, 16, v11
	v_and_b32_e32 v27, 0xffff0000, v11
	v_lshlrev_b32_e32 v10, 16, v12
	v_and_b32_e32 v11, 0xffff0000, v12
	v_lshlrev_b32_e32 v12, 16, v13
	v_and_b32_e32 v13, 0xffff0000, v13
	s_waitcnt vmcnt(1)
	v_lshlrev_b32_e32 v28, 16, v30
	v_and_b32_e32 v29, 0xffff0000, v30
	v_lshlrev_b32_e32 v30, 16, v31
	v_and_b32_e32 v31, 0xffff0000, v31
	ds_write_b128 v63, v[2:5]
	ds_write_b128 v63, v[6:9] offset:16
	ds_write_b128 v63, v[24:27] offset:32
	ds_write_b128 v63, v[10:13] offset:48
	s_waitcnt vmcnt(0)
	ds_write_b128 v64, v[18:21] offset:256
	ds_write_b128 v65, v[28:31]
	s_waitcnt lgkmcnt(0)
	s_barrier
	ds_read_b128 v[24:27], v68
	ds_read_b128 v[28:31], v68 offset:256
	ds_read_b128 v[38:41], v68 offset:512
	ds_read_b128 v[56:59], v68 offset:768
	ds_read2st64_b32 v[54:55], v51 offset1:1
	ds_read_b128 v[70:73], v68 offset:1024
	ds_read_b128 v[34:37], v68 offset:1280
	ds_read_b128 v[6:9], v68 offset:1536
	ds_read_b128 v[18:21], v68 offset:1792
	ds_read_b128 v[10:13], v68 offset:2048
	ds_read_b128 v[2:5], v68 offset:2304
	s_waitcnt lgkmcnt(10)
	v_mul_f32_e32 v26, v22, v26
	v_mul_f32_e32 v27, v23, v27
	s_nop 0
	v_fma_f32 v16, v16, v24, v26
	v_fma_f32 v17, v17, v25, v27
	s_nop 0
	v_add_f32_e32 v16, v16, v17
	s_nop 1
	v_add_f32_dpp v16, v16, v16 quad_perm:[1,0,3,2] row_mask:0xf bank_mask:0xf bound_ctrl:1
	s_nop 1
	v_add_f32_dpp v16, v16, v16 quad_perm:[2,3,0,1] row_mask:0xf bank_mask:0xf bound_ctrl:1
	s_nop 1
	v_add_f32_dpp v16, v16, v16 row_half_mirror row_mask:0xf bank_mask:0xf bound_ctrl:1
	s_nop 1
	v_add_f32_dpp v16, v16, v16 row_mirror row_mask:0xf bank_mask:0xf bound_ctrl:1
	s_waitcnt lgkmcnt(8)
	v_mul_f32_e32 v24, v38, v16
	v_mul_f32_e32 v25, v39, v16
	v_mul_f32_e32 v17, v41, v16
	v_mul_f32_e32 v16, v40, v16
	s_waitcnt lgkmcnt(6)
	v_fma_f32 v24, v56, v54, v24
	v_fma_f32 v25, v57, v54, v25
	v_fma_f32 v16, v58, v54, v16
	v_fma_f32 v17, v59, v54, v17
	v_fma_f32 v58, v14, v28, v24
	v_fma_f32 v59, v15, v29, v25
	v_fma_f32 v56, v22, v30, v16
	v_fma_f32 v57, v23, v31, v17
	s_waitcnt lgkmcnt(5)
	v_mul_f32_e32 v14, v70, v58
	v_mul_f32_e32 v15, v71, v59
	s_nop 0
	v_fma_f32 v14, v72, v56, v14
	v_fma_f32 v15, v73, v57, v15
	s_nop 0
	v_add_f32_e32 v14, v14, v15
	s_nop 1
	v_add_f32_dpp v14, v14, v14 quad_perm:[1,0,3,2] row_mask:0xf bank_mask:0xf bound_ctrl:1
	s_nop 1
	v_add_f32_dpp v14, v14, v14 quad_perm:[2,3,0,1] row_mask:0xf bank_mask:0xf bound_ctrl:1
	s_nop 1
	v_add_f32_dpp v14, v14, v14 row_half_mirror row_mask:0xf bank_mask:0xf bound_ctrl:1
	s_nop 1
	v_mov_b32_dpp v15, v14 row_mirror row_mask:0xf bank_mask:0xf bound_ctrl:1
	s_and_saveexec_b64 s[20:21], s[0:1]
	v_add_f32_e32 v14, v14, v15
	ds_write_b32 v67, v14
	s_or_b64 exec, exec, s[20:21]
	s_waitcnt lgkmcnt(4)
	v_mul_f32_e32 v34, v34, v58
	v_mul_f32_e32 v35, v35, v59
	ds_read_b128 v[22:25], v68 offset:2816
	ds_read_b128 v[30:33], v68 offset:3072
	ds_read_b128 v[26:29], v68 offset:3328
	ds_read_b128 v[14:17], v68 offset:3584
	ds_read_b128 v[38:41], v68 offset:2560
	ds_read_b32 v54, v51 offset:512
	v_fma_f32 v34, v36, v56, v34
	v_fma_f32 v35, v37, v57, v35
	v_mov_b32_e32 v36, v55
	v_add_f32_e32 v34, v34, v35
	s_nop 1
	v_add_f32_dpp v34, v34, v34 quad_perm:[1,0,3,2] row_mask:0xf bank_mask:0xf bound_ctrl:1
	s_nop 1
	v_add_f32_dpp v34, v34, v34 quad_perm:[2,3,0,1] row_mask:0xf bank_mask:0xf bound_ctrl:1
	s_nop 1
	v_add_f32_dpp v34, v34, v34 row_half_mirror row_mask:0xf bank_mask:0xf bound_ctrl:1
	s_nop 1
	v_add_f32_dpp v34, v34, v34 row_mirror row_mask:0xf bank_mask:0xf bound_ctrl:1
	s_waitcnt lgkmcnt(8)
	v_mul_f32_e32 v18, v18, v34
	v_mul_f32_e32 v19, v19, v34
	s_waitcnt lgkmcnt(7)
	v_fma_f32 v10, v10, v36, v18
	v_fma_f32 v11, v11, v36, v19
	s_nop 0
	v_fma_f32 v58, v6, v58, v10
	v_fma_f32 v59, v7, v59, v11
	v_mul_f32_e32 v6, v20, v34
	v_mul_f32_e32 v7, v21, v34
	s_waitcnt lgkmcnt(6)
; #define LAS __attribute__((address_space(3)))
; __device__ __forceinline__ unsigned pk2(float lo, float hi) { const bfx2 b = __builtin_convertvector((f32x2){lo, hi}, bfx2); return __builtin_bit_cast(unsigned, b); }
; __device__ __forceinline__ void scan_half(const P& p, Frame& F, size_t sr0, int T, const float* S0, float* Sout, int m0, int h, int hf) {
;     ...
;         { const int tt = tid >> 4, rl = (tid & 15) * 2;
;           if (tt < ns) { const LAS float* ys = (const LAS float*)(F.lds + S_YL + buf * 4096) + tt * 32 + rl;
;               *(unsigned*)(YRAW + (size_t)(m0 + t0 + tt) * 1024 + h * 64 + 32 * hf + rl) = pk2(ys[0], ys[1]); } }
	v_mul_f32_e32 v2, v2, v58
	v_mul_f32_e32 v3, v3, v59
	v_fma_f32 v6, v12, v36, v6
	v_fma_f32 v7, v13, v36, v7
	s_nop 0
	v_fma_f32 v60, v8, v56, v6
	v_fma_f32 v61, v9, v57, v7
	s_nop 0
	v_fma_f32 v2, v4, v60, v2
	v_fma_f32 v3, v5, v61, v3
	s_nop 0
	v_add_f32_e32 v2, v2, v3
	s_nop 1
	v_add_f32_dpp v2, v2, v2 quad_perm:[1,0,3,2] row_mask:0xf bank_mask:0xf bound_ctrl:1
	s_nop 1
	v_add_f32_dpp v2, v2, v2 quad_perm:[2,3,0,1] row_mask:0xf bank_mask:0xf bound_ctrl:1
	s_nop 1
	v_add_f32_dpp v2, v2, v2 row_half_mirror row_mask:0xf bank_mask:0xf bound_ctrl:1
	s_nop 1
	v_mov_b32_dpp v3, v2 row_mirror row_mask:0xf bank_mask:0xf bound_ctrl:1
	s_and_saveexec_b64 s[20:21], s[0:1]
	v_add_f32_e32 v2, v2, v3
	ds_write_b32 v67, v2 offset:128
	s_or_b64 exec, exec, s[20:21]
	s_waitcnt lgkmcnt(1)
	v_mul_f32_e32 v38, v38, v58
	v_mul_f32_e32 v39, v39, v59
	ds_read_b128 v[2:5], v68 offset:4096
	ds_read_b128 v[18:21], v68 offset:4352
	ds_read_b128 v[10:13], v68 offset:4608
	ds_read_b128 v[6:9], v68 offset:4864
	ds_read_b128 v[34:37], v68 offset:3840
	ds_read_b32 v56, v51 offset:768
	v_fma_f32 v38, v40, v60, v38
	v_fma_f32 v39, v41, v61, v39
	s_nop 0
	v_add_f32_e32 v38, v38, v39
	s_nop 1
	v_add_f32_dpp v38, v38, v38 quad_perm:[1,0,3,2] row_mask:0xf bank_mask:0xf bound_ctrl:1
	s_nop 1
	v_add_f32_dpp v38, v38, v38 quad_perm:[2,3,0,1] row_mask:0xf bank_mask:0xf bound_ctrl:1
	s_nop 1
	v_add_f32_dpp v38, v38, v38 row_half_mirror row_mask:0xf bank_mask:0xf bound_ctrl:1
	s_nop 1
	v_add_f32_dpp v38, v38, v38 row_mirror row_mask:0xf bank_mask:0xf bound_ctrl:1
	v_mul_f32_e32 v30, v30, v38
	v_mul_f32_e32 v31, v31, v38
	s_waitcnt lgkmcnt(6)
	v_fma_f32 v26, v26, v54, v30
	v_fma_f32 v27, v27, v54, v31
	s_nop 0
	v_fma_f32 v26, v22, v58, v26
	v_fma_f32 v27, v23, v59, v27
	v_mul_f32_e32 v22, v32, v38
	v_mul_f32_e32 v23, v33, v38
	v_mul_f32_e32 v14, v14, v26
	v_mul_f32_e32 v15, v15, v27
	v_fma_f32 v22, v28, v54, v22
	v_fma_f32 v23, v29, v54, v23
	s_nop 0
	v_fma_f32 v22, v24, v60, v22
	v_fma_f32 v23, v25, v61, v23
	s_nop 0
	v_fma_f32 v14, v16, v22, v14
	v_fma_f32 v15, v17, v23, v15
	s_nop 0
	v_add_f32_e32 v14, v14, v15
	s_nop 1
	v_add_f32_dpp v14, v14, v14 quad_perm:[1,0,3,2] row_mask:0xf bank_mask:0xf bound_ctrl:1
	s_nop 1
	v_add_f32_dpp v14, v14, v14 quad_perm:[2,3,0,1] row_mask:0xf bank_mask:0xf bound_ctrl:1
	s_nop 1
	v_add_f32_dpp v14, v14, v14 row_half_mirror row_mask:0xf bank_mask:0xf bound_ctrl:1
	s_nop 1
	v_mov_b32_dpp v15, v14 row_mirror row_mask:0xf bank_mask:0xf bound_ctrl:1
	s_and_saveexec_b64 s[20:21], s[0:1]
	v_add_f32_e32 v14, v14, v15
	ds_write_b32 v67, v14 offset:256
	s_or_b64 exec, exec, s[20:21]
	s_waitcnt lgkmcnt(1)
	v_mul_f32_e32 v14, v34, v26
	v_mul_f32_e32 v15, v35, v27
	s_nop 0
	v_fma_f32 v14, v36, v22, v14
	v_fma_f32 v15, v37, v23, v15
	s_nop 0
	v_add_f32_e32 v14, v14, v15
	s_nop 1
	v_add_f32_dpp v14, v14, v14 quad_perm:[1,0,3,2] row_mask:0xf bank_mask:0xf bound_ctrl:1
	s_nop 1
	v_add_f32_dpp v14, v14, v14 quad_perm:[2,3,0,1] row_mask:0xf bank_mask:0xf bound_ctrl:1
	s_nop 1
	v_add_f32_dpp v14, v14, v14 row_half_mirror row_mask:0xf bank_mask:0xf bound_ctrl:1
	s_nop 1
	v_add_f32_dpp v14, v14, v14 row_mirror row_mask:0xf bank_mask:0xf bound_ctrl:1
	v_mul_f32_e32 v16, v18, v14
	v_mul_f32_e32 v17, v19, v14
	s_waitcnt lgkmcnt(0)
	v_fma_f32 v10, v10, v56, v16
	v_fma_f32 v11, v11, v56, v17
	s_nop 0
	v_fma_f32 v2, v2, v26, v10
	v_fma_f32 v3, v3, v27, v11
	v_mul_f32_e32 v10, v20, v14
	v_mul_f32_e32 v11, v21, v14
	v_mul_f32_e32 v6, v6, v2
	v_mul_f32_e32 v7, v7, v3
	v_fma_f32 v10, v12, v56, v10
	v_fma_f32 v11, v13, v56, v11
	s_nop 0
	v_fma_f32 v4, v4, v22, v10
	v_fma_f32 v5, v5, v23, v11
	s_nop 0
	v_fma_f32 v6, v8, v4, v6
	v_fma_f32 v7, v9, v5, v7
	s_nop 0
	v_add_f32_e32 v6, v6, v7
	s_nop 1
	v_add_f32_dpp v6, v6, v6 quad_perm:[1,0,3,2] row_mask:0xf bank_mask:0xf bound_ctrl:1
	s_nop 1
	v_add_f32_dpp v6, v6, v6 quad_perm:[2,3,0,1] row_mask:0xf bank_mask:0xf bound_ctrl:1
	s_nop 1
	v_add_f32_dpp v6, v6, v6 row_half_mirror row_mask:0xf bank_mask:0xf bound_ctrl:1
	s_nop 1
	v_mov_b32_dpp v7, v6 row_mirror row_mask:0xf bank_mask:0xf bound_ctrl:1
	s_and_saveexec_b64 s[20:21], s[0:1]
	v_add_f32_e32 v6, v6, v7
	ds_write_b32 v67, v6 offset:384
	s_or_b64 exec, exec, s[20:21]
	s_waitcnt lgkmcnt(0)
	s_barrier
	s_and_saveexec_b64 s[20:21], s[6:7]
	s_cbranch_execz .LBB0_1787
	s_ashr_i32 s14, s24, 3
	s_and_b32 s14, s14, -4
	v_add_u32_e32 v6, s14, v66
	v_ashrrev_i32_e32 v7, 31, v6
	ds_read_b64 v[8:9], v69
	v_lshlrev_b64 v[6:7], 11, v[6:7]
	s_lshl_b32 s14, s18, 7
	v_lshl_add_u64 v[6:7], s[16:17], 0, v[6:7]
	s_and_b32 s14, s14, 0x780
	v_lshl_add_u64 v[6:7], v[6:7], 0, s[14:15]
	s_lshl_b32 s14, s25, 1
	v_lshl_add_u64 v[6:7], v[6:7], 0, s[14:15]
	v_mov_b32_e32 v51, v43
	v_lshl_add_u64 v[6:7], v[6:7], 0, v[50:51]
	s_waitcnt lgkmcnt(0)
	v_cvt_pk_bf16_f32 v8, v8, v9
	global_store_dword v[6:7], v8, off
	s_branch .LBB0_1787

; #define LAS __attribute__((address_space(3)))
; #define SCAN_FETCH(srow) do { const char* so_ = (const char*)(OPSB + (srow) * 256); pb0 = *(const u32x4*)(so_ + (size_t)tid * 32); pb1 = *(const u32x4*)(so_ + (size_t)tid * 32 + 16); \
;         pw = *(const f32x4*)((const char*)(WQ + (srow) * 64) + (size_t)tid * 16); pv = *(const u32x2*)((const char*)(VVB + (srow) * 64) + (size_t)tid * 8); } while (0)
; __device__ __forceinline__ void scan_half(const P& p, Frame& F, size_t sr0, int T, const float* S0, float* Sout, int m0, int h, int hf) {
;     ...
;     SCAN_FETCH(sr0);
;     __syncthreads();
;     SCAN_PUT(0);
;     __syncthreads();
;     for (int k = 0; k < nch; ++k) {
;         const int buf = k & 1, t0 = k * 32, ns = (T - t0) < 32 ? (T - t0) : 32;
;         if (k + 1 < nch) SCAN_FETCH(sr0 + t0 + 32);
;         const LAS float* opl = (const LAS float*)(F.lds + S_OPL + buf * 40960) + c * 4;
;         const LAS float* vl = (const LAS float*)(F.lds + S_VL + buf * 8192) + row;
;         LAS float* yl = (LAS float*)(F.lds + S_YL + buf * 4096) + rowl;
.LBB0_1814:
	s_lshl_b64 s[16:17], s[10:11], 2
	s_add_u32 s16, s16, 0x40000
	s_addc_u32 s17, s17, 0
	s_lshl_b64 s[24:25], s[16:17], 9
	v_lshl_add_u64 v[2:3], v[44:45], 0, s[24:25]
	s_lshl_b64 s[24:25], s[16:17], 7
	global_load_dwordx4 v[6:9], v[2:3], off
	global_load_dwordx4 v[10:13], v[2:3], off offset:16
	v_lshl_add_u64 v[2:3], v[48:49], 0, s[24:25]
	global_load_dwordx2 v[30:31], v[2:3], off
	s_lshl_b64 s[16:17], s[16:17], 8
	v_lshl_add_u64 v[2:3], v[46:47], 0, s[16:17]
	global_load_dwordx4 v[18:21], v[2:3], off
	v_lshl_add_u32 v2, v4, 2, 0
	v_add_u32_e32 v51, 0x14000, v2
	s_barrier
	s_waitcnt vmcnt(3)
	v_lshlrev_b32_e32 v2, 16, v6
	v_and_b32_e32 v3, 0xffff0000, v6
	v_lshlrev_b32_e32 v4, 16, v7
	v_and_b32_e32 v5, 0xffff0000, v7
	v_lshlrev_b32_e32 v6, 16, v8
	v_and_b32_e32 v7, 0xffff0000, v8
	v_lshlrev_b32_e32 v8, 16, v9
	v_and_b32_e32 v9, 0xffff0000, v9
	s_waitcnt vmcnt(2)
	v_lshlrev_b32_e32 v24, 16, v10
	v_and_b32_e32 v25, 0xffff0000, v10
	v_lshlrev_b32_e32 v26, 16, v11
	v_and_b32_e32 v27, 0xffff0000, v11
	v_lshlrev_b32_e32 v10, 16, v12
	v_and_b32_e32 v11, 0xffff0000, v12
	v_lshlrev_b32_e32 v12, 16, v13
	v_and_b32_e32 v13, 0xffff0000, v13
	s_waitcnt vmcnt(1)
	v_lshlrev_b32_e32 v28, 16, v30
	v_and_b32_e32 v29, 0xffff0000, v30
	v_lshlrev_b32_e32 v30, 16, v31
	v_and_b32_e32 v31, 0xffff0000, v31
	ds_write_b128 v62, v[2:5]
	ds_write_b128 v62, v[6:9] offset:16
	ds_write_b128 v62, v[24:27] offset:32
	ds_write_b128 v62, v[10:13] offset:48
	s_waitcnt vmcnt(0)
	ds_write_b128 v63, v[18:21] offset:256
	ds_write_b128 v64, v[28:31]
	s_waitcnt lgkmcnt(0)
	s_barrier
	ds_read_b128 v[24:27], v67
	ds_read_b128 v[28:31], v67 offset:256
	ds_read_b128 v[38:41], v67 offset:512
	ds_read_b128 v[56:59], v67 offset:768
	ds_read2st64_b32 v[54:55], v51 offset1:1
	ds_read_b128 v[70:73], v67 offset:1024
	ds_read_b128 v[34:37], v67 offset:1280
	ds_read_b128 v[6:9], v67 offset:1536
	ds_read_b128 v[18:21], v67 offset:1792
	ds_read_b128 v[10:13], v67 offset:2048
	ds_read_b128 v[2:5], v67 offset:2304
	s_waitcnt lgkmcnt(10)
	v_mul_f32_e32 v26, v22, v26
	v_mul_f32_e32 v27, v23, v27
	s_nop 0
	v_fma_f32 v16, v16, v24, v26
	v_fma_f32 v17, v17, v25, v27
	s_nop 0
	v_add_f32_e32 v16, v16, v17
	s_nop 1
	v_add_f32_dpp v16, v16, v16 quad_perm:[1,0,3,2] row_mask:0xf bank_mask:0xf bound_ctrl:1
	s_nop 1
	v_add_f32_dpp v16, v16, v16 quad_perm:[2,3,0,1] row_mask:0xf bank_mask:0xf bound_ctrl:1
	s_nop 1
	v_add_f32_dpp v16, v16, v16 row_half_mirror row_mask:0xf bank_mask:0xf bound_ctrl:1
	s_nop 1
	v_add_f32_dpp v16, v16, v16 row_mirror row_mask:0xf bank_mask:0xf bound_ctrl:1
	s_waitcnt lgkmcnt(8)
	v_mul_f32_e32 v24, v38, v16
	v_mul_f32_e32 v25, v39, v16
	v_mul_f32_e32 v17, v41, v16
	v_mul_f32_e32 v16, v40, v16
	s_waitcnt lgkmcnt(6)
	v_fma_f32 v24, v56, v54, v24
	v_fma_f32 v25, v57, v54, v25
	v_fma_f32 v16, v58, v54, v16
	v_fma_f32 v17, v59, v54, v17
	v_fma_f32 v58, v14, v28, v24
	v_fma_f32 v59, v15, v29, v25
	v_fma_f32 v56, v22, v30, v16
	v_fma_f32 v57, v23, v31, v17
	s_waitcnt lgkmcnt(5)
	v_mul_f32_e32 v14, v70, v58
	v_mul_f32_e32 v15, v71, v59
	s_nop 0
	v_fma_f32 v14, v72, v56, v14
	v_fma_f32 v15, v73, v57, v15
	s_nop 0
	v_add_f32_e32 v14, v14, v15
	s_nop 1
	v_add_f32_dpp v14, v14, v14 quad_perm:[1,0,3,2] row_mask:0xf bank_mask:0xf bound_ctrl:1
	s_nop 1
	v_add_f32_dpp v14, v14, v14 quad_perm:[2,3,0,1] row_mask:0xf bank_mask:0xf bound_ctrl:1
	s_nop 1
	v_add_f32_dpp v14, v14, v14 row_half_mirror row_mask:0xf bank_mask:0xf bound_ctrl:1
	s_nop 1
	v_mov_b32_dpp v15, v14 row_mirror row_mask:0xf bank_mask:0xf bound_ctrl:1
	s_and_saveexec_b64 s[16:17], s[0:1]
	v_add_f32_e32 v14, v14, v15
	ds_write_b32 v66, v14
	s_or_b64 exec, exec, s[16:17]
	s_waitcnt lgkmcnt(4)
	v_mul_f32_e32 v34, v34, v58
	v_mul_f32_e32 v35, v35, v59
	ds_read_b128 v[22:25], v67 offset:2816
	ds_read_b128 v[30:33], v67 offset:3072
	ds_read_b128 v[26:29], v67 offset:3328
	ds_read_b128 v[14:17], v67 offset:3584
	ds_read_b128 v[38:41], v67 offset:2560
	ds_read_b32 v54, v51 offset:512
	v_fma_f32 v34, v36, v56, v34
	v_fma_f32 v35, v37, v57, v35
	v_mov_b32_e32 v36, v55
	v_add_f32_e32 v34, v34, v35
	s_nop 1
	v_add_f32_dpp v34, v34, v34 quad_perm:[1,0,3,2] row_mask:0xf bank_mask:0xf bound_ctrl:1
	s_nop 1
	v_add_f32_dpp v34, v34, v34 quad_perm:[2,3,0,1] row_mask:0xf bank_mask:0xf bound_ctrl:1
	s_nop 1
	v_add_f32_dpp v34, v34, v34 row_half_mirror row_mask:0xf bank_mask:0xf bound_ctrl:1
	s_nop 1
	v_add_f32_dpp v34, v34, v34 row_mirror row_mask:0xf bank_mask:0xf bound_ctrl:1
	s_waitcnt lgkmcnt(8)
	v_mul_f32_e32 v18, v18, v34
	v_mul_f32_e32 v19, v19, v34
	s_waitcnt lgkmcnt(7)
	v_fma_f32 v10, v10, v36, v18
	v_fma_f32 v11, v11, v36, v19
	s_nop 0
	v_fma_f32 v58, v6, v58, v10
	v_fma_f32 v59, v7, v59, v11
	v_mul_f32_e32 v6, v20, v34
	v_mul_f32_e32 v7, v21, v34
	s_waitcnt lgkmcnt(6)
; #define LAS __attribute__((address_space(3)))
; __device__ __forceinline__ unsigned pk2(float lo, float hi) { const bfx2 b = __builtin_convertvector((f32x2){lo, hi}, bfx2); return __builtin_bit_cast(unsigned, b); }
; #define SCAN_LOAD(o, v, tt) do { const LAS f32x4* o4_ = (const LAS f32x4*)(opl + (tt) * 320); _Pragma("unroll") for (int q_ = 0; q_ < 5; ++q_) o[q_] = o4_[16 * q_]; v = vl[(tt) * 64]; } while (0)
; __device__ __forceinline__ void scan_half(const P& p, Frame& F, size_t sr0, int T, const float* S0, float* Sout, int m0, int h, int hf) {
;     ...
;         { f32x4 oa[5], ob[5]; float va, vb;
;           SCAN_LOAD(oa, va, 0);
;           int tt = 0;
;           for (; tt + 1 < ns; tt += 2) {
;               SCAN_LOAD(ob, vb, tt + 1);
;               SCAN_STEP(oa, va, tt);
;               if (tt + 2 < ns) SCAN_LOAD(oa, va, tt + 2);
;               SCAN_STEP(ob, vb, tt + 1);
;           }
;           if (tt < ns) SCAN_STEP(oa, va, tt);
;         }
;     ...
;         __syncthreads();
;         { const int tt = tid >> 4, rl = (tid & 15) * 2;
;           if (tt < ns) { const LAS float* ys = (const LAS float*)(F.lds + S_YL + buf * 4096) + tt * 32 + rl;
;               *(unsigned*)(YRAW + (size_t)(m0 + t0 + tt) * 1024 + h * 64 + 32 * hf + rl) = pk2(ys[0], ys[1]); } }
	v_mul_f32_e32 v2, v2, v58
	v_mul_f32_e32 v3, v3, v59
	v_fma_f32 v6, v12, v36, v6
	v_fma_f32 v7, v13, v36, v7
	s_nop 0
	v_fma_f32 v60, v8, v56, v6
	v_fma_f32 v61, v9, v57, v7
	s_nop 0
	v_fma_f32 v2, v4, v60, v2
	v_fma_f32 v3, v5, v61, v3
	s_nop 0
	v_add_f32_e32 v2, v2, v3
	s_nop 1
	v_add_f32_dpp v2, v2, v2 quad_perm:[1,0,3,2] row_mask:0xf bank_mask:0xf bound_ctrl:1
	s_nop 1
	v_add_f32_dpp v2, v2, v2 quad_perm:[2,3,0,1] row_mask:0xf bank_mask:0xf bound_ctrl:1
	s_nop 1
	v_add_f32_dpp v2, v2, v2 row_half_mirror row_mask:0xf bank_mask:0xf bound_ctrl:1
	s_nop 1
	v_mov_b32_dpp v3, v2 row_mirror row_mask:0xf bank_mask:0xf bound_ctrl:1
	s_and_saveexec_b64 s[16:17], s[0:1]
	v_add_f32_e32 v2, v2, v3
	ds_write_b32 v66, v2 offset:128
	s_or_b64 exec, exec, s[16:17]
	s_waitcnt lgkmcnt(1)
	v_mul_f32_e32 v38, v38, v58
	v_mul_f32_e32 v39, v39, v59
	ds_read_b128 v[2:5], v67 offset:4096
	ds_read_b128 v[18:21], v67 offset:4352
	ds_read_b128 v[10:13], v67 offset:4608
	ds_read_b128 v[6:9], v67 offset:4864
	ds_read_b128 v[34:37], v67 offset:3840
	ds_read_b32 v56, v51 offset:768
	v_fma_f32 v38, v40, v60, v38
	v_fma_f32 v39, v41, v61, v39
	s_nop 0
	v_add_f32_e32 v38, v38, v39
	s_nop 1
	v_add_f32_dpp v38, v38, v38 quad_perm:[1,0,3,2] row_mask:0xf bank_mask:0xf bound_ctrl:1
	s_nop 1
	v_add_f32_dpp v38, v38, v38 quad_perm:[2,3,0,1] row_mask:0xf bank_mask:0xf bound_ctrl:1
	s_nop 1
	v_add_f32_dpp v38, v38, v38 row_half_mirror row_mask:0xf bank_mask:0xf bound_ctrl:1
	s_nop 1
	v_add_f32_dpp v38, v38, v38 row_mirror row_mask:0xf bank_mask:0xf bound_ctrl:1
	v_mul_f32_e32 v30, v30, v38
	v_mul_f32_e32 v31, v31, v38
	s_waitcnt lgkmcnt(6)
	v_fma_f32 v26, v26, v54, v30
	v_fma_f32 v27, v27, v54, v31
	s_nop 0
	v_fma_f32 v26, v22, v58, v26
	v_fma_f32 v27, v23, v59, v27
	v_mul_f32_e32 v22, v32, v38
	v_mul_f32_e32 v23, v33, v38
	v_mul_f32_e32 v14, v14, v26
	v_mul_f32_e32 v15, v15, v27
	v_fma_f32 v22, v28, v54, v22
	v_fma_f32 v23, v29, v54, v23
	s_nop 0
	v_fma_f32 v22, v24, v60, v22
	v_fma_f32 v23, v25, v61, v23
	s_nop 0
	v_fma_f32 v14, v16, v22, v14
	v_fma_f32 v15, v17, v23, v15
	s_nop 0
	v_add_f32_e32 v14, v14, v15
	s_nop 1
	v_add_f32_dpp v14, v14, v14 quad_perm:[1,0,3,2] row_mask:0xf bank_mask:0xf bound_ctrl:1
	s_nop 1
	v_add_f32_dpp v14, v14, v14 quad_perm:[2,3,0,1] row_mask:0xf bank_mask:0xf bound_ctrl:1
	s_nop 1
	v_add_f32_dpp v14, v14, v14 row_half_mirror row_mask:0xf bank_mask:0xf bound_ctrl:1
	s_nop 1
	v_mov_b32_dpp v15, v14 row_mirror row_mask:0xf bank_mask:0xf bound_ctrl:1
	s_and_saveexec_b64 s[16:17], s[0:1]
	v_add_f32_e32 v14, v14, v15
	ds_write_b32 v66, v14 offset:256
	s_or_b64 exec, exec, s[16:17]
	s_waitcnt lgkmcnt(1)
	v_mul_f32_e32 v14, v34, v26
	v_mul_f32_e32 v15, v35, v27
	s_nop 0
	v_fma_f32 v14, v36, v22, v14
	v_fma_f32 v15, v37, v23, v15
	s_nop 0
	v_add_f32_e32 v14, v14, v15
	s_nop 1
	v_add_f32_dpp v14, v14, v14 quad_perm:[1,0,3,2] row_mask:0xf bank_mask:0xf bound_ctrl:1
	s_nop 1
	v_add_f32_dpp v14, v14, v14 quad_perm:[2,3,0,1] row_mask:0xf bank_mask:0xf bound_ctrl:1
	s_nop 1
	v_add_f32_dpp v14, v14, v14 row_half_mirror row_mask:0xf bank_mask:0xf bound_ctrl:1
	s_nop 1
	v_add_f32_dpp v14, v14, v14 row_mirror row_mask:0xf bank_mask:0xf bound_ctrl:1
	v_mul_f32_e32 v16, v18, v14
	v_mul_f32_e32 v17, v19, v14
	s_waitcnt lgkmcnt(0)
	v_fma_f32 v10, v10, v56, v16
	v_fma_f32 v11, v11, v56, v17
	s_nop 0
	v_fma_f32 v2, v2, v26, v10
	v_fma_f32 v3, v3, v27, v11
	v_mul_f32_e32 v10, v20, v14
	v_mul_f32_e32 v11, v21, v14
	v_mul_f32_e32 v6, v6, v2
	v_mul_f32_e32 v7, v7, v3
	v_fma_f32 v10, v12, v56, v10
	v_fma_f32 v11, v13, v56, v11
	s_nop 0
	v_fma_f32 v4, v4, v22, v10
	v_fma_f32 v5, v5, v23, v11
	s_nop 0
	v_fma_f32 v6, v8, v4, v6
	v_fma_f32 v7, v9, v5, v7
	s_nop 0
	v_add_f32_e32 v6, v6, v7
	s_nop 1
	v_add_f32_dpp v6, v6, v6 quad_perm:[1,0,3,2] row_mask:0xf bank_mask:0xf bound_ctrl:1
	s_nop 1
	v_add_f32_dpp v6, v6, v6 quad_perm:[2,3,0,1] row_mask:0xf bank_mask:0xf bound_ctrl:1
	s_nop 1
	v_add_f32_dpp v6, v6, v6 row_half_mirror row_mask:0xf bank_mask:0xf bound_ctrl:1
	s_nop 1
	v_mov_b32_dpp v7, v6 row_mirror row_mask:0xf bank_mask:0xf bound_ctrl:1
	s_and_saveexec_b64 s[16:17], s[0:1]
	v_add_f32_e32 v6, v6, v7
	ds_write_b32 v66, v6 offset:384
	s_or_b64 exec, exec, s[16:17]
	s_waitcnt lgkmcnt(0)
	s_barrier
	s_and_saveexec_b64 s[16:17], s[6:7]
	s_cbranch_execz .LBB0_1808
	s_lshr_b32 s23, s4, 3
	s_and_b32 s23, s23, 0x1ffffffc
	v_add_u32_e32 v6, s23, v65
	v_ashrrev_i32_e32 v7, 31, v6
	ds_read_b64 v[8:9], v68
	v_lshlrev_b64 v[6:7], 11, v[6:7]
	s_lshl_b32 s23, s10, 7
	v_lshl_add_u64 v[6:7], s[14:15], 0, v[6:7]
	s_and_b32 s24, s23, 0x780
	s_mov_b32 s25, s11
	v_lshl_add_u64 v[6:7], v[6:7], 0, s[24:25]
	s_lshl_b32 s22, s22, 1
	s_mov_b32 s23, s11
	v_lshl_add_u64 v[6:7], v[6:7], 0, s[22:23]
	v_mov_b32_e32 v51, v43
	v_lshl_add_u64 v[6:7], v[6:7], 0, v[50:51]
	s_waitcnt lgkmcnt(0)
	v_cvt_pk_bf16_f32 v8, v8, v9
	global_store_dword v[6:7], v8, off
	s_branch .LBB0_1808

; #define LAS __attribute__((address_space(3)))
; __device__ __forceinline__ unsigned pk2(float lo, float hi) { const bfx2 b = __builtin_convertvector((f32x2){lo, hi}, bfx2); return __builtin_bit_cast(unsigned, b); }
; __device__ __forceinline__ f32x16 ck_mm(const LAS unsigned char* A, const LAS unsigned char* BT, int mt, int nt, int ql, int half, f32x16 acc) {
;     const LAS unsigned char* ar = A + (32 * mt + ql) * 128; const LAS unsigned char* br = BT + (32 * nt + ql) * 128; const int sw = ql & 7;
;     f32x16 acc2 = ck_zero();
; #pragma unroll
;     for (int ks = 0; ks < 4; ++ks) { const int off = ((2 * ks + half) ^ sw) << 4; const bf16x8 a = *(const LAS bf16x8*)(ar + off), b = *(const LAS bf16x8*)(br + off); if (ks & 1) acc2 = MFMA32(a, b, acc2); else acc = MFMA32(a, b, acc); }
; #pragma unroll
;     for (int i = 0; i < 16; ++i) acc[i] += acc2[i];
;     return acc;
; __device__ __forceinline__ void chunk_chain(const P& p, Frame& F, int s) {
;     ...
;         { const u32x4 w0 = n0R[u], w1 = n1R[u];
;           ad[0] = (f32x4){bflo(w0.x), bfhi(w0.x), bflo(w0.y), bfhi(w0.y)}; ad[1] = (f32x4){bflo(w0.z), bfhi(w0.z), bflo(w0.w), bfhi(w0.w)};
;           ad[2] = (f32x4){bflo(w1.x), bfhi(w1.x), bflo(w1.y), bfhi(w1.y)}; ad[3] = (f32x4){bflo(w1.z), bfhi(w1.z), bflo(w1.w), bfhi(w1.w)}; }
;         if (c + 4 < 32) CH_LOAD(u, c + 4);
;         if (grp == 0) {
;             sacc = ck_mm(L + (2 + cur) * CK_SLOT, L + cur * CK_SLOT, mt, nt, ql, half, ck_zero());
; #pragma unroll
;             for (int g = 0; g < 4; ++g)
; #pragma unroll
;                 for (int e = 0; e < 4; ++e) sacc[4 * g + e] += ad[g][e];
;             ck_store_t(L + (cur ^ 1) * CK_SLOT, sacc, mt, nt, ql, half);
;         } else {
;             const f32x16 a = ck_mm(L + cur * CK_SLOT, L + (4 + cur) * CK_SLOT, mt, nt, ql, half, ck_zero());
;             bf16* yrow = YRAW + (size_t)(b * TP + 64 * c + n) * 1024 + h * 64;
; #pragma unroll
;             for (int g = 0; g < 4; ++g) { u32x2 w; w.x = pk2(a[4 * g] + ad[g][0], a[4 * g + 1] + ad[g][1]); w.y = pk2(a[4 * g + 2] + ad[g][2], a[4 * g + 3] + ad[g][3]);
;                 *(u32x2*)(yrow + 32 * mt + 8 * g + 4 * half) = w; } }
;         if (c + 1 < 32) { *(LAS u32x4*)(L + (2 + (cur ^ 1)) * CK_SLOT + ioff) = pmR[(u + 1) & 3]; *(LAS u32x4*)(L + (4 + (cur ^ 1)) * CK_SLOT + ioff) = pqR[(u + 1) & 3]; }
.LBB0_1832:
	v_lshlrev_b32_e32 v106, 16, v6
	v_and_b32_e32 v107, 0xffff0000, v6
	v_lshlrev_b32_e32 v108, 16, v7
	v_and_b32_e32 v109, 0xffff0000, v7
	v_lshlrev_b32_e32 v110, 16, v8
	v_and_b32_e32 v111, 0xffff0000, v8
	v_lshlrev_b32_e32 v112, 16, v9
	v_and_b32_e32 v113, 0xffff0000, v9
	v_lshlrev_b32_e32 v132, 16, v2
	v_and_b32_e32 v133, 0xffff0000, v2
	v_lshlrev_b32_e32 v134, 16, v3
	v_and_b32_e32 v135, 0xffff0000, v3
	v_lshlrev_b32_e32 v136, 16, v4
	v_and_b32_e32 v137, 0xffff0000, v4
	v_lshlrev_b32_e32 v138, 16, v5
	v_and_b32_e32 v139, 0xffff0000, v5
	s_mov_b64 s[0:1], -1
	s_and_b64 vcc, exec, s[8:9]
	s_cbranch_vccz .LBB0_1834
	v_add_u32_e32 v2, v145, v140
	v_add_u32_e32 v6, v144, v140
	ds_read_b128 v[2:5], v2 offset:32768
	ds_read_b128 v[6:9], v6
	v_add_u32_e32 v131, v145, v142
	ds_read_b128 v[152:155], v131 offset:32768
	v_add_u32_e32 v131, v144, v142
	ds_read_b128 v[156:159], v131
	v_add_u32_e32 v18, v145, v141
	v_add_u32_e32 v22, v144, v141
	s_waitcnt lgkmcnt(2)
	v_mfma_f32_32x32x16_bf16 v[2:17], v[6:9], v[2:5], 0
	ds_read_b128 v[18:21], v18 offset:32768
	ds_read_b128 v[22:25], v22
	v_add_u32_e32 v131, v145, v143
	s_mov_b64 s[0:1], 0
	s_waitcnt lgkmcnt(2)
	v_mfma_f32_32x32x16_bf16 v[2:17], v[156:159], v[152:155], v[2:17]
	ds_read_b128 v[152:155], v131 offset:32768
	v_add_u32_e32 v131, v144, v143
	ds_read_b128 v[156:159], v131
	v_ashrrev_i32_e32 v131, 31, v130
	s_waitcnt lgkmcnt(2)
	v_mfma_f32_32x32x16_bf16 v[18:33], v[22:25], v[18:21], 0
	s_waitcnt lgkmcnt(0)
	v_mfma_f32_32x32x16_bf16 v[18:33], v[156:159], v[152:155], v[18:33]
	v_lshlrev_b64 v[152:153], 11, v[130:131]
	v_lshl_add_u64 v[152:153], v[128:129], 0, v[152:153]
	s_nop 9
	v_add_f32_e32 v4, v4, v20
	v_add_f32_e32 v5, v5, v21
	v_add_f32_e32 v2, v2, v18
	v_add_f32_e32 v3, v3, v19
	v_add_f32_e32 v4, v4, v108
	v_add_f32_e32 v5, v5, v109
	v_add_f32_e32 v2, v2, v106
	v_add_f32_e32 v3, v3, v107
	v_add_f32_e32 v8, v8, v24
	v_add_f32_e32 v9, v9, v25
	v_add_f32_e32 v6, v6, v22
	v_add_f32_e32 v7, v7, v23
	v_cvt_pk_bf16_f32 v2, v2, v3
	v_cvt_pk_bf16_f32 v3, v4, v5
	global_store_dwordx2 v[152:153], v[2:3], off
	v_add_f32_e32 v2, v6, v110
	v_add_f32_e32 v3, v7, v111
	v_add_f32_e32 v4, v8, v112
	v_add_f32_e32 v5, v9, v113
	v_add_f32_e32 v12, v12, v28
	v_add_f32_e32 v13, v13, v29
	v_add_f32_e32 v10, v10, v26
	v_add_f32_e32 v11, v11, v27
	v_cvt_pk_bf16_f32 v2, v2, v3
	v_cvt_pk_bf16_f32 v3, v4, v5
	global_store_dwordx2 v[152:153], v[2:3], off offset:16
	v_add_f32_e32 v2, v10, v132
	v_add_f32_e32 v3, v11, v133
	v_add_f32_e32 v4, v12, v134
	v_add_f32_e32 v5, v13, v135
	v_add_f32_e32 v16, v16, v32
	v_add_f32_e32 v17, v17, v33
	v_add_f32_e32 v14, v14, v30
	v_add_f32_e32 v15, v15, v31
	v_cvt_pk_bf16_f32 v2, v2, v3
	v_cvt_pk_bf16_f32 v3, v4, v5
	global_store_dwordx2 v[152:153], v[2:3], off offset:32
	v_add_f32_e32 v2, v14, v136
	v_add_f32_e32 v3, v15, v137
	v_add_f32_e32 v4, v16, v138
	v_add_f32_e32 v5, v17, v139
	v_cvt_pk_bf16_f32 v2, v2, v3
	v_cvt_pk_bf16_f32 v3, v4, v5
	global_store_dwordx2 v[152:153], v[2:3], off offset:48
.LBB0_1834:
	s_andn2_b64 vcc, exec, s[0:1]
	s_cbranch_vccnz .LBB0_1836
	v_add_u32_e32 v2, v144, v140
	ds_read_b128 v[2:5], v2 offset:16384
	v_add_u32_e32 v6, v145, v140
	ds_read_b128 v[6:9], v6
	v_add_u32_e32 v82, v144, v142
	v_add_u32_e32 v18, v144, v141
	ds_read_b128 v[82:85], v82 offset:16384
	ds_read_b128 v[18:21], v18 offset:16384
	v_add_u32_e32 v86, v145, v142
	v_add_u32_e32 v22, v145, v141
	s_waitcnt lgkmcnt(2)
	v_mfma_f32_32x32x16_bf16 v[2:17], v[2:5], v[6:9], 0
	ds_read_b128 v[86:89], v86
	ds_read_b128 v[22:25], v22
	v_add_u32_e32 v90, v144, v143
	s_waitcnt lgkmcnt(1)
	v_mfma_f32_32x32x16_bf16 v[2:17], v[82:85], v[86:89], v[2:17]
	ds_read_b128 v[82:85], v90 offset:16384
	v_add_u32_e32 v86, v145, v143
	ds_read_b128 v[86:89], v86
	s_waitcnt lgkmcnt(2)
	v_mfma_f32_32x32x16_bf16 v[18:33], v[18:21], v[22:25], 0
	s_waitcnt lgkmcnt(0)
	v_mfma_f32_32x32x16_bf16 v[18:33], v[82:85], v[86:89], v[18:33]
	s_nop 11
	v_add_f32_e32 v4, v4, v20
	v_add_f32_e32 v5, v5, v21
	v_add_f32_e32 v2, v2, v18
	v_add_f32_e32 v3, v3, v19
	v_add_f32_e32 v8, v8, v24
	v_add_f32_e32 v9, v9, v25
	v_add_f32_e32 v6, v6, v22
	v_add_f32_e32 v7, v7, v23
	v_add_f32_e32 v82, v2, v106
	v_add_f32_e32 v83, v3, v107
	v_add_f32_e32 v84, v4, v108
	v_add_f32_e32 v85, v5, v109
	v_add_f32_e32 v12, v12, v28
	v_add_f32_e32 v13, v13, v29
	v_add_f32_e32 v10, v10, v26
	v_add_f32_e32 v11, v11, v27
	v_add_f32_e32 v86, v6, v110
	v_add_f32_e32 v87, v7, v111
	v_add_f32_e32 v88, v8, v112
	v_add_f32_e32 v89, v9, v113
	v_cvt_pk_bf16_f32 v2, v82, v83
	v_cvt_pk_bf16_f32 v3, v84, v85
	v_add_u32_e32 v4, v146, v147
	v_add_f32_e32 v16, v16, v32
	v_add_f32_e32 v17, v17, v33
	v_add_f32_e32 v14, v14, v30
	v_add_f32_e32 v15, v15, v31
	v_add_f32_e32 v90, v10, v132
	v_add_f32_e32 v91, v11, v133
	v_add_f32_e32 v92, v12, v134
	v_add_f32_e32 v93, v13, v135
	ds_write_b64 v4, v[2:3] offset:8192
	v_cvt_pk_bf16_f32 v2, v86, v87
	v_cvt_pk_bf16_f32 v3, v88, v89
	v_add_u32_e32 v4, v146, v148
	v_add_f32_e32 v94, v14, v136
	v_add_f32_e32 v95, v15, v137
	v_add_f32_e32 v96, v16, v138
	v_add_f32_e32 v97, v17, v139
	ds_write_b64 v4, v[2:3] offset:8192
	v_cvt_pk_bf16_f32 v2, v90, v91
	v_cvt_pk_bf16_f32 v3, v92, v93
	v_add_u32_e32 v4, v146, v149
	ds_write_b64 v4, v[2:3] offset:8192
	v_cvt_pk_bf16_f32 v2, v94, v95
	v_cvt_pk_bf16_f32 v3, v96, v97
	v_add_u32_e32 v4, v146, v150
	ds_write_b64 v4, v[2:3] offset:8192

; #define LAS __attribute__((address_space(3)))
; __device__ __forceinline__ unsigned pk2(float lo, float hi) { const bfx2 b = __builtin_convertvector((f32x2){lo, hi}, bfx2); return __builtin_bit_cast(unsigned, b); }
; __device__ __forceinline__ f32x16 ck_mm(const LAS unsigned char* A, const LAS unsigned char* BT, int mt, int nt, int ql, int half, f32x16 acc) {
;     const LAS unsigned char* ar = A + (32 * mt + ql) * 128; const LAS unsigned char* br = BT + (32 * nt + ql) * 128; const int sw = ql & 7;
;     f32x16 acc2 = ck_zero();
; #pragma unroll
;     for (int ks = 0; ks < 4; ++ks) { const int off = ((2 * ks + half) ^ sw) << 4; const bf16x8 a = *(const LAS bf16x8*)(ar + off), b = *(const LAS bf16x8*)(br + off); if (ks & 1) acc2 = MFMA32(a, b, acc2); else acc = MFMA32(a, b, acc); }
; #pragma unroll
;     for (int i = 0; i < 16; ++i) acc[i] += acc2[i];
;     return acc;
; __device__ __forceinline__ void chunk_chain(const P& p, Frame& F, int s) {
;     ...
;         { const u32x4 w0 = n0R[u], w1 = n1R[u];
;           ad[0] = (f32x4){bflo(w0.x), bfhi(w0.x), bflo(w0.y), bfhi(w0.y)}; ad[1] = (f32x4){bflo(w0.z), bfhi(w0.z), bflo(w0.w), bfhi(w0.w)};
;           ad[2] = (f32x4){bflo(w1.x), bfhi(w1.x), bflo(w1.y), bfhi(w1.y)}; ad[3] = (f32x4){bflo(w1.z), bfhi(w1.z), bflo(w1.w), bfhi(w1.w)}; }
;         if (c + 4 < 32) CH_LOAD(u, c + 4);
;         if (grp == 0) {
;             sacc = ck_mm(L + (2 + cur) * CK_SLOT, L + cur * CK_SLOT, mt, nt, ql, half, ck_zero());
; #pragma unroll
;             for (int g = 0; g < 4; ++g)
; #pragma unroll
;                 for (int e = 0; e < 4; ++e) sacc[4 * g + e] += ad[g][e];
;             ck_store_t(L + (cur ^ 1) * CK_SLOT, sacc, mt, nt, ql, half);
;         } else {
;             const f32x16 a = ck_mm(L + cur * CK_SLOT, L + (4 + cur) * CK_SLOT, mt, nt, ql, half, ck_zero());
;             bf16* yrow = YRAW + (size_t)(b * TP + 64 * c + n) * 1024 + h * 64;
; #pragma unroll
;             for (int g = 0; g < 4; ++g) { u32x2 w; w.x = pk2(a[4 * g] + ad[g][0], a[4 * g + 1] + ad[g][1]); w.y = pk2(a[4 * g + 2] + ad[g][2], a[4 * g + 3] + ad[g][3]);
;                 *(u32x2*)(yrow + 32 * mt + 8 * g + 4 * half) = w; } }
;         if (c + 1 < 32) { *(LAS u32x4*)(L + (2 + (cur ^ 1)) * CK_SLOT + ioff) = pmR[(u + 1) & 3]; *(LAS u32x4*)(L + (4 + (cur ^ 1)) * CK_SLOT + ioff) = pqR[(u + 1) & 3]; }
.LBB0_1838:
	v_cndmask_b32_e64 v2, 0, 1, s[8:9]
	v_lshlrev_b32_e32 v132, 16, v118
	v_and_b32_e32 v133, 0xffff0000, v118
	v_lshlrev_b32_e32 v118, 16, v119
	v_and_b32_e32 v119, 0xffff0000, v119
	v_lshlrev_b32_e32 v134, 16, v120
	v_and_b32_e32 v135, 0xffff0000, v120
	v_lshlrev_b32_e32 v120, 16, v121
	v_and_b32_e32 v121, 0xffff0000, v121
	v_lshlrev_b32_e32 v136, 16, v114
	v_and_b32_e32 v137, 0xffff0000, v114
	v_lshlrev_b32_e32 v114, 16, v115
	v_and_b32_e32 v115, 0xffff0000, v115
	v_lshlrev_b32_e32 v138, 16, v116
	v_and_b32_e32 v139, 0xffff0000, v116
	v_lshlrev_b32_e32 v116, 16, v117
	v_and_b32_e32 v117, 0xffff0000, v117
	v_cmp_ne_u32_e64 s[6:7], 1, v2
	s_andn2_b64 vcc, exec, s[8:9]
	s_mov_b64 s[16:17], -1
	s_cbranch_vccnz .LBB0_1840
	v_add_u32_e32 v2, v145, v140
	v_add_u32_e32 v6, v144, v140
	ds_read_b128 v[2:5], v2 offset:40960
	ds_read_b128 v[6:9], v6 offset:8192
	v_add_u32_e32 v131, v145, v142
	ds_read_b128 v[152:155], v131 offset:40960
	v_add_u32_e32 v131, v144, v142
	ds_read_b128 v[156:159], v131 offset:8192
	v_add_u32_e32 v18, v145, v141
	v_add_u32_e32 v22, v144, v141
	s_waitcnt lgkmcnt(2)
	v_mfma_f32_32x32x16_bf16 v[2:17], v[6:9], v[2:5], 0
	ds_read_b128 v[18:21], v18 offset:40960
	ds_read_b128 v[22:25], v22 offset:8192
	v_add_u32_e32 v131, v145, v143
	s_mov_b64 s[16:17], 0
	s_waitcnt lgkmcnt(2)
	v_mfma_f32_32x32x16_bf16 v[2:17], v[156:159], v[152:155], v[2:17]
	ds_read_b128 v[152:155], v131 offset:40960
	v_add_u32_e32 v131, v144, v143
	ds_read_b128 v[156:159], v131 offset:8192
	s_waitcnt lgkmcnt(2)
	v_mfma_f32_32x32x16_bf16 v[18:33], v[22:25], v[18:21], 0
	s_waitcnt lgkmcnt(0)
	v_mfma_f32_32x32x16_bf16 v[18:33], v[156:159], v[152:155], v[18:33]
	v_add_u32_e32 v152, 64, v130
	v_ashrrev_i32_e32 v153, 31, v152
	v_lshlrev_b64 v[152:153], 11, v[152:153]
	v_lshl_add_u64 v[152:153], v[128:129], 0, v[152:153]
	s_nop 7
	v_add_f32_e32 v4, v4, v20
	v_add_f32_e32 v5, v5, v21
	v_add_f32_e32 v2, v2, v18
	v_add_f32_e32 v3, v3, v19
	v_add_f32_e32 v4, v4, v118
	v_add_f32_e32 v5, v5, v119
	v_add_f32_e32 v2, v2, v132
	v_add_f32_e32 v3, v3, v133
	v_add_f32_e32 v8, v8, v24
	v_add_f32_e32 v9, v9, v25
	v_add_f32_e32 v6, v6, v22
	v_add_f32_e32 v7, v7, v23
	v_cvt_pk_bf16_f32 v2, v2, v3
	v_cvt_pk_bf16_f32 v3, v4, v5
	global_store_dwordx2 v[152:153], v[2:3], off
	v_add_f32_e32 v2, v6, v134
	v_add_f32_e32 v3, v7, v135
	v_add_f32_e32 v4, v8, v120
	v_add_f32_e32 v5, v9, v121
	v_add_f32_e32 v12, v12, v28
	v_add_f32_e32 v13, v13, v29
	v_add_f32_e32 v10, v10, v26
	v_add_f32_e32 v11, v11, v27
	v_cvt_pk_bf16_f32 v2, v2, v3
	v_cvt_pk_bf16_f32 v3, v4, v5
	global_store_dwordx2 v[152:153], v[2:3], off offset:16
	v_add_f32_e32 v2, v10, v136
	v_add_f32_e32 v3, v11, v137
	v_add_f32_e32 v4, v12, v114
	v_add_f32_e32 v5, v13, v115
	v_add_f32_e32 v16, v16, v32
	v_add_f32_e32 v17, v17, v33
	v_add_f32_e32 v14, v14, v30
	v_add_f32_e32 v15, v15, v31
	v_cvt_pk_bf16_f32 v2, v2, v3
	v_cvt_pk_bf16_f32 v3, v4, v5
	global_store_dwordx2 v[152:153], v[2:3], off offset:32
	v_add_f32_e32 v2, v14, v138
	v_add_f32_e32 v3, v15, v139
	v_add_f32_e32 v4, v16, v116
	v_add_f32_e32 v5, v17, v117
	v_cvt_pk_bf16_f32 v2, v2, v3
	v_cvt_pk_bf16_f32 v3, v4, v5
	global_store_dwordx2 v[152:153], v[2:3], off offset:48
.LBB0_1840:
	s_andn2_b64 vcc, exec, s[16:17]
	s_cbranch_vccnz .LBB0_1842
	v_add_u32_e32 v2, v144, v140
	ds_read_b128 v[2:5], v2 offset:24576
	v_add_u32_e32 v6, v145, v140
	ds_read_b128 v[6:9], v6 offset:8192
	v_add_u32_e32 v82, v144, v142
	v_add_u32_e32 v18, v144, v141
	ds_read_b128 v[82:85], v82 offset:24576
	ds_read_b128 v[18:21], v18 offset:24576
	v_add_u32_e32 v86, v145, v142
	v_add_u32_e32 v22, v145, v141
	s_waitcnt lgkmcnt(2)
	v_mfma_f32_32x32x16_bf16 v[2:17], v[2:5], v[6:9], 0
	ds_read_b128 v[86:89], v86 offset:8192
	ds_read_b128 v[22:25], v22 offset:8192
	v_add_u32_e32 v90, v144, v143
	s_waitcnt lgkmcnt(1)
	v_mfma_f32_32x32x16_bf16 v[2:17], v[82:85], v[86:89], v[2:17]
	ds_read_b128 v[82:85], v90 offset:24576
	v_add_u32_e32 v86, v145, v143
	ds_read_b128 v[86:89], v86 offset:8192
	s_waitcnt lgkmcnt(2)
	v_mfma_f32_32x32x16_bf16 v[18:33], v[18:21], v[22:25], 0
	s_waitcnt lgkmcnt(0)
	v_mfma_f32_32x32x16_bf16 v[18:33], v[82:85], v[86:89], v[18:33]
	s_nop 11
	v_add_f32_e32 v4, v4, v20
	v_add_f32_e32 v5, v5, v21
	v_add_f32_e32 v2, v2, v18
	v_add_f32_e32 v3, v3, v19
	v_add_f32_e32 v8, v8, v24
	v_add_f32_e32 v9, v9, v25
	v_add_f32_e32 v6, v6, v22
	v_add_f32_e32 v7, v7, v23
	v_add_f32_e32 v82, v2, v132
	v_add_f32_e32 v83, v3, v133
	v_add_f32_e32 v84, v4, v118
	v_add_f32_e32 v85, v5, v119
	v_add_f32_e32 v12, v12, v28
	v_add_f32_e32 v13, v13, v29
	v_add_f32_e32 v10, v10, v26
	v_add_f32_e32 v11, v11, v27
	v_add_f32_e32 v86, v6, v134
	v_add_f32_e32 v87, v7, v135
	v_add_f32_e32 v88, v8, v120
	v_add_f32_e32 v89, v9, v121
	v_cvt_pk_bf16_f32 v2, v82, v83
	v_cvt_pk_bf16_f32 v3, v84, v85
	v_add_u32_e32 v4, v146, v147
	v_add_f32_e32 v16, v16, v32
	v_add_f32_e32 v17, v17, v33
	v_add_f32_e32 v14, v14, v30
	v_add_f32_e32 v15, v15, v31
	v_add_f32_e32 v90, v10, v136
	v_add_f32_e32 v91, v11, v137
	v_add_f32_e32 v92, v12, v114
	v_add_f32_e32 v93, v13, v115
	ds_write_b64 v4, v[2:3]
	v_cvt_pk_bf16_f32 v2, v86, v87
	v_cvt_pk_bf16_f32 v3, v88, v89
	v_add_u32_e32 v4, v146, v148
	v_add_f32_e32 v94, v14, v138
	v_add_f32_e32 v95, v15, v139
	v_add_f32_e32 v96, v16, v116
	v_add_f32_e32 v97, v17, v117
	ds_write_b64 v4, v[2:3]
	v_cvt_pk_bf16_f32 v2, v90, v91
	v_cvt_pk_bf16_f32 v3, v92, v93
	v_add_u32_e32 v4, v146, v149
	ds_write_b64 v4, v[2:3]
	v_cvt_pk_bf16_f32 v2, v94, v95
	v_cvt_pk_bf16_f32 v3, v96, v97
	v_add_u32_e32 v4, v146, v150
	ds_write_b64 v4, v[2:3]

; #define LAS __attribute__((address_space(3)))
; __device__ __forceinline__ unsigned pk2(float lo, float hi) { const bfx2 b = __builtin_convertvector((f32x2){lo, hi}, bfx2); return __builtin_bit_cast(unsigned, b); }
; __device__ __forceinline__ f32x16 ck_mm(const LAS unsigned char* A, const LAS unsigned char* BT, int mt, int nt, int ql, int half, f32x16 acc) {
;     const LAS unsigned char* ar = A + (32 * mt + ql) * 128; const LAS unsigned char* br = BT + (32 * nt + ql) * 128; const int sw = ql & 7;
;     f32x16 acc2 = ck_zero();
; #pragma unroll
;     for (int ks = 0; ks < 4; ++ks) { const int off = ((2 * ks + half) ^ sw) << 4; const bf16x8 a = *(const LAS bf16x8*)(ar + off), b = *(const LAS bf16x8*)(br + off); if (ks & 1) acc2 = MFMA32(a, b, acc2); else acc = MFMA32(a, b, acc); }
; #pragma unroll
;     for (int i = 0; i < 16; ++i) acc[i] += acc2[i];
;     return acc;
; __device__ __forceinline__ void chunk_chain(const P& p, Frame& F, int s) {
;     ...
;         { const u32x4 w0 = n0R[u], w1 = n1R[u];
;           ad[0] = (f32x4){bflo(w0.x), bfhi(w0.x), bflo(w0.y), bfhi(w0.y)}; ad[1] = (f32x4){bflo(w0.z), bfhi(w0.z), bflo(w0.w), bfhi(w0.w)};
;           ad[2] = (f32x4){bflo(w1.x), bfhi(w1.x), bflo(w1.y), bfhi(w1.y)}; ad[3] = (f32x4){bflo(w1.z), bfhi(w1.z), bflo(w1.w), bfhi(w1.w)}; }
;         if (c + 4 < 32) CH_LOAD(u, c + 4);
;         if (grp == 0) {
;             sacc = ck_mm(L + (2 + cur) * CK_SLOT, L + cur * CK_SLOT, mt, nt, ql, half, ck_zero());
; #pragma unroll
;             for (int g = 0; g < 4; ++g)
; #pragma unroll
;                 for (int e = 0; e < 4; ++e) sacc[4 * g + e] += ad[g][e];
;             ck_store_t(L + (cur ^ 1) * CK_SLOT, sacc, mt, nt, ql, half);
;         } else {
;             const f32x16 a = ck_mm(L + cur * CK_SLOT, L + (4 + cur) * CK_SLOT, mt, nt, ql, half, ck_zero());
;             bf16* yrow = YRAW + (size_t)(b * TP + 64 * c + n) * 1024 + h * 64;
; #pragma unroll
;             for (int g = 0; g < 4; ++g) { u32x2 w; w.x = pk2(a[4 * g] + ad[g][0], a[4 * g + 1] + ad[g][1]); w.y = pk2(a[4 * g + 2] + ad[g][2], a[4 * g + 3] + ad[g][3]);
;                 *(u32x2*)(yrow + 32 * mt + 8 * g + 4 * half) = w; } }
;         if (c + 1 < 32) { *(LAS u32x4*)(L + (2 + (cur ^ 1)) * CK_SLOT + ioff) = pmR[(u + 1) & 3]; *(LAS u32x4*)(L + (4 + (cur ^ 1)) * CK_SLOT + ioff) = pqR[(u + 1) & 3]; }
.LBB0_1844:
	v_lshlrev_b32_e32 v132, 16, v102
	v_and_b32_e32 v133, 0xffff0000, v102
	v_lshlrev_b32_e32 v102, 16, v103
	v_and_b32_e32 v103, 0xffff0000, v103
	v_lshlrev_b32_e32 v134, 16, v104
	v_and_b32_e32 v135, 0xffff0000, v104
	v_lshlrev_b32_e32 v104, 16, v105
	v_and_b32_e32 v105, 0xffff0000, v105
	v_lshlrev_b32_e32 v136, 16, v98
	v_and_b32_e32 v137, 0xffff0000, v98
	v_lshlrev_b32_e32 v98, 16, v99
	v_and_b32_e32 v99, 0xffff0000, v99
	v_lshlrev_b32_e32 v138, 16, v100
	v_and_b32_e32 v139, 0xffff0000, v100
	v_lshlrev_b32_e32 v100, 16, v101
	v_and_b32_e32 v101, 0xffff0000, v101
	s_and_b64 vcc, exec, s[6:7]
	s_mov_b64 s[16:17], -1
	s_cbranch_vccnz .LBB0_1846
	v_add_u32_e32 v2, v145, v140
	v_add_u32_e32 v6, v144, v140
	ds_read_b128 v[2:5], v2 offset:32768
	ds_read_b128 v[6:9], v6
	v_add_u32_e32 v131, v145, v142
	ds_read_b128 v[152:155], v131 offset:32768
	v_add_u32_e32 v131, v144, v142
	ds_read_b128 v[156:159], v131
	v_add_u32_e32 v18, v145, v141
	v_add_u32_e32 v22, v144, v141
	s_waitcnt lgkmcnt(2)
	v_mfma_f32_32x32x16_bf16 v[2:17], v[6:9], v[2:5], 0
	ds_read_b128 v[18:21], v18 offset:32768
	ds_read_b128 v[22:25], v22
	v_add_u32_e32 v131, v145, v143
	s_mov_b64 s[16:17], 0
	s_waitcnt lgkmcnt(2)
	v_mfma_f32_32x32x16_bf16 v[2:17], v[156:159], v[152:155], v[2:17]
	ds_read_b128 v[152:155], v131 offset:32768
	v_add_u32_e32 v131, v144, v143
	ds_read_b128 v[156:159], v131
	s_waitcnt lgkmcnt(2)
	v_mfma_f32_32x32x16_bf16 v[18:33], v[22:25], v[18:21], 0
	s_waitcnt lgkmcnt(0)
	v_mfma_f32_32x32x16_bf16 v[18:33], v[156:159], v[152:155], v[18:33]
	v_add_u32_e32 v152, 0x80, v130
	v_ashrrev_i32_e32 v153, 31, v152
	v_lshlrev_b64 v[152:153], 11, v[152:153]
	v_lshl_add_u64 v[152:153], v[128:129], 0, v[152:153]
	s_nop 7
	v_add_f32_e32 v4, v4, v20
	v_add_f32_e32 v5, v5, v21
	v_add_f32_e32 v2, v2, v18
	v_add_f32_e32 v3, v3, v19
	v_add_f32_e32 v4, v4, v102
	v_add_f32_e32 v5, v5, v103
	v_add_f32_e32 v2, v2, v132
	v_add_f32_e32 v3, v3, v133
	v_add_f32_e32 v8, v8, v24
	v_add_f32_e32 v9, v9, v25
	v_add_f32_e32 v6, v6, v22
	v_add_f32_e32 v7, v7, v23
	v_cvt_pk_bf16_f32 v2, v2, v3
	v_cvt_pk_bf16_f32 v3, v4, v5
	global_store_dwordx2 v[152:153], v[2:3], off
	v_add_f32_e32 v2, v6, v134
	v_add_f32_e32 v3, v7, v135
	v_add_f32_e32 v4, v8, v104
	v_add_f32_e32 v5, v9, v105
	v_add_f32_e32 v12, v12, v28
	v_add_f32_e32 v13, v13, v29
	v_add_f32_e32 v10, v10, v26
	v_add_f32_e32 v11, v11, v27
	v_cvt_pk_bf16_f32 v2, v2, v3
	v_cvt_pk_bf16_f32 v3, v4, v5
	global_store_dwordx2 v[152:153], v[2:3], off offset:16
	v_add_f32_e32 v2, v10, v136
	v_add_f32_e32 v3, v11, v137
	v_add_f32_e32 v4, v12, v98
	v_add_f32_e32 v5, v13, v99
	v_add_f32_e32 v16, v16, v32
	v_add_f32_e32 v17, v17, v33
	v_add_f32_e32 v14, v14, v30
	v_add_f32_e32 v15, v15, v31
	v_cvt_pk_bf16_f32 v2, v2, v3
	v_cvt_pk_bf16_f32 v3, v4, v5
	global_store_dwordx2 v[152:153], v[2:3], off offset:32
	v_add_f32_e32 v2, v14, v138
	v_add_f32_e32 v3, v15, v139
	v_add_f32_e32 v4, v16, v100
	v_add_f32_e32 v5, v17, v101
	v_cvt_pk_bf16_f32 v2, v2, v3
	v_cvt_pk_bf16_f32 v3, v4, v5
	global_store_dwordx2 v[152:153], v[2:3], off offset:48
.LBB0_1846:
	s_andn2_b64 vcc, exec, s[16:17]
	s_cbranch_vccnz .LBB0_1848
	v_add_u32_e32 v2, v144, v140
	ds_read_b128 v[2:5], v2 offset:16384
	v_add_u32_e32 v6, v145, v140
	ds_read_b128 v[6:9], v6
	v_add_u32_e32 v82, v144, v142
	v_add_u32_e32 v18, v144, v141
	ds_read_b128 v[82:85], v82 offset:16384
	ds_read_b128 v[18:21], v18 offset:16384
	v_add_u32_e32 v86, v145, v142
	v_add_u32_e32 v22, v145, v141
	s_waitcnt lgkmcnt(2)
	v_mfma_f32_32x32x16_bf16 v[2:17], v[2:5], v[6:9], 0
	ds_read_b128 v[86:89], v86
	ds_read_b128 v[22:25], v22
	v_add_u32_e32 v90, v144, v143
	s_waitcnt lgkmcnt(1)
	v_mfma_f32_32x32x16_bf16 v[2:17], v[82:85], v[86:89], v[2:17]
	ds_read_b128 v[82:85], v90 offset:16384
	v_add_u32_e32 v86, v145, v143
	ds_read_b128 v[86:89], v86
	s_waitcnt lgkmcnt(2)
	v_mfma_f32_32x32x16_bf16 v[18:33], v[18:21], v[22:25], 0
	s_waitcnt lgkmcnt(0)
	v_mfma_f32_32x32x16_bf16 v[18:33], v[82:85], v[86:89], v[18:33]
	s_nop 11
	v_add_f32_e32 v4, v4, v20
	v_add_f32_e32 v5, v5, v21
	v_add_f32_e32 v2, v2, v18
	v_add_f32_e32 v3, v3, v19
	v_add_f32_e32 v8, v8, v24
	v_add_f32_e32 v9, v9, v25
	v_add_f32_e32 v6, v6, v22
	v_add_f32_e32 v7, v7, v23
	v_add_f32_e32 v82, v2, v132
	v_add_f32_e32 v83, v3, v133
	v_add_f32_e32 v84, v4, v102
	v_add_f32_e32 v85, v5, v103
	v_add_f32_e32 v12, v12, v28
	v_add_f32_e32 v13, v13, v29
	v_add_f32_e32 v10, v10, v26
	v_add_f32_e32 v11, v11, v27
	v_add_f32_e32 v86, v6, v134
	v_add_f32_e32 v87, v7, v135
	v_add_f32_e32 v88, v8, v104
	v_add_f32_e32 v89, v9, v105
	v_cvt_pk_bf16_f32 v2, v82, v83
	v_cvt_pk_bf16_f32 v3, v84, v85
	v_add_u32_e32 v4, v146, v147
	v_add_f32_e32 v16, v16, v32
	v_add_f32_e32 v17, v17, v33
	v_add_f32_e32 v14, v14, v30
	v_add_f32_e32 v15, v15, v31
	v_add_f32_e32 v90, v10, v136
	v_add_f32_e32 v91, v11, v137
	v_add_f32_e32 v92, v12, v98
	v_add_f32_e32 v93, v13, v99
	ds_write_b64 v4, v[2:3] offset:8192
	v_cvt_pk_bf16_f32 v2, v86, v87
	v_cvt_pk_bf16_f32 v3, v88, v89
	v_add_u32_e32 v4, v146, v148
	v_add_f32_e32 v94, v14, v138
	v_add_f32_e32 v95, v15, v139
	v_add_f32_e32 v96, v16, v100
	v_add_f32_e32 v97, v17, v101
	ds_write_b64 v4, v[2:3] offset:8192
	v_cvt_pk_bf16_f32 v2, v90, v91
	v_cvt_pk_bf16_f32 v3, v92, v93
	v_add_u32_e32 v4, v146, v149
	ds_write_b64 v4, v[2:3] offset:8192
	v_cvt_pk_bf16_f32 v2, v94, v95
	v_cvt_pk_bf16_f32 v3, v96, v97
	v_add_u32_e32 v4, v146, v150
	ds_write_b64 v4, v[2:3] offset:8192

; #define LAS __attribute__((address_space(3)))
; __device__ __forceinline__ unsigned pk2(float lo, float hi) { const bfx2 b = __builtin_convertvector((f32x2){lo, hi}, bfx2); return __builtin_bit_cast(unsigned, b); }
; __device__ __forceinline__ f32x16 ck_mm(const LAS unsigned char* A, const LAS unsigned char* BT, int mt, int nt, int ql, int half, f32x16 acc) {
;     const LAS unsigned char* ar = A + (32 * mt + ql) * 128; const LAS unsigned char* br = BT + (32 * nt + ql) * 128; const int sw = ql & 7;
;     f32x16 acc2 = ck_zero();
; #pragma unroll
;     for (int ks = 0; ks < 4; ++ks) { const int off = ((2 * ks + half) ^ sw) << 4; const bf16x8 a = *(const LAS bf16x8*)(ar + off), b = *(const LAS bf16x8*)(br + off); if (ks & 1) acc2 = MFMA32(a, b, acc2); else acc = MFMA32(a, b, acc); }
; #pragma unroll
;     for (int i = 0; i < 16; ++i) acc[i] += acc2[i];
;     return acc;
; __device__ __forceinline__ void chunk_chain(const P& p, Frame& F, int s) {
;     ...
;         { const u32x4 w0 = n0R[u], w1 = n1R[u];
;           ad[0] = (f32x4){bflo(w0.x), bfhi(w0.x), bflo(w0.y), bfhi(w0.y)}; ad[1] = (f32x4){bflo(w0.z), bfhi(w0.z), bflo(w0.w), bfhi(w0.w)};
;           ad[2] = (f32x4){bflo(w1.x), bfhi(w1.x), bflo(w1.y), bfhi(w1.y)}; ad[3] = (f32x4){bflo(w1.z), bfhi(w1.z), bflo(w1.w), bfhi(w1.w)}; }
;         if (c + 4 < 32) CH_LOAD(u, c + 4);
;         if (grp == 0) {
;             sacc = ck_mm(L + (2 + cur) * CK_SLOT, L + cur * CK_SLOT, mt, nt, ql, half, ck_zero());
; #pragma unroll
;             for (int g = 0; g < 4; ++g)
; #pragma unroll
;                 for (int e = 0; e < 4; ++e) sacc[4 * g + e] += ad[g][e];
;             ck_store_t(L + (cur ^ 1) * CK_SLOT, sacc, mt, nt, ql, half);
;         } else {
;             const f32x16 a = ck_mm(L + cur * CK_SLOT, L + (4 + cur) * CK_SLOT, mt, nt, ql, half, ck_zero());
;             bf16* yrow = YRAW + (size_t)(b * TP + 64 * c + n) * 1024 + h * 64;
; #pragma unroll
;             for (int g = 0; g < 4; ++g) { u32x2 w; w.x = pk2(a[4 * g] + ad[g][0], a[4 * g + 1] + ad[g][1]); w.y = pk2(a[4 * g + 2] + ad[g][2], a[4 * g + 3] + ad[g][3]);
;                 *(u32x2*)(yrow + 32 * mt + 8 * g + 4 * half) = w; } }
;         if (c + 1 < 32) { *(LAS u32x4*)(L + (2 + (cur ^ 1)) * CK_SLOT + ioff) = pmR[(u + 1) & 3]; *(LAS u32x4*)(L + (4 + (cur ^ 1)) * CK_SLOT + ioff) = pqR[(u + 1) & 3]; }
.LBB0_1850:
	v_lshlrev_b32_e32 v132, 16, v78
	v_and_b32_e32 v133, 0xffff0000, v78
	v_lshlrev_b32_e32 v78, 16, v79
	v_and_b32_e32 v79, 0xffff0000, v79
	v_lshlrev_b32_e32 v134, 16, v80
	v_and_b32_e32 v135, 0xffff0000, v80
	v_lshlrev_b32_e32 v80, 16, v81
	v_and_b32_e32 v81, 0xffff0000, v81
	v_lshlrev_b32_e32 v136, 16, v74
	v_and_b32_e32 v137, 0xffff0000, v74
	v_lshlrev_b32_e32 v74, 16, v75
	v_and_b32_e32 v75, 0xffff0000, v75
	v_lshlrev_b32_e32 v138, 16, v76
	v_and_b32_e32 v139, 0xffff0000, v76
	v_lshlrev_b32_e32 v76, 16, v77
	v_and_b32_e32 v77, 0xffff0000, v77
	s_and_b64 vcc, exec, s[6:7]
	s_mov_b64 s[0:1], -1
	s_cbranch_vccnz .LBB0_1856
	v_add_u32_e32 v2, v145, v140
	v_add_u32_e32 v6, v144, v140
	ds_read_b128 v[2:5], v2 offset:40960
	ds_read_b128 v[6:9], v6 offset:8192
	v_add_u32_e32 v131, v145, v142
	ds_read_b128 v[152:155], v131 offset:40960
	v_add_u32_e32 v131, v144, v142
	ds_read_b128 v[156:159], v131 offset:8192
	v_add_u32_e32 v18, v145, v141
	v_add_u32_e32 v22, v144, v141
	s_waitcnt lgkmcnt(2)
	v_mfma_f32_32x32x16_bf16 v[2:17], v[6:9], v[2:5], 0
	ds_read_b128 v[18:21], v18 offset:40960
	ds_read_b128 v[22:25], v22 offset:8192
	v_add_u32_e32 v131, v145, v143
	s_waitcnt lgkmcnt(2)
	v_mfma_f32_32x32x16_bf16 v[2:17], v[156:159], v[152:155], v[2:17]
	ds_read_b128 v[152:155], v131 offset:40960
	v_add_u32_e32 v131, v144, v143
	ds_read_b128 v[156:159], v131 offset:8192
	s_waitcnt lgkmcnt(2)
	v_mfma_f32_32x32x16_bf16 v[18:33], v[22:25], v[18:21], 0
	s_waitcnt lgkmcnt(0)
	v_mfma_f32_32x32x16_bf16 v[18:33], v[156:159], v[152:155], v[18:33]
	v_add_u32_e32 v152, 0xc0, v130
	v_ashrrev_i32_e32 v153, 31, v152
	v_lshlrev_b64 v[152:153], 11, v[152:153]
	v_lshl_add_u64 v[152:153], v[128:129], 0, v[152:153]
	s_nop 7
	v_add_f32_e32 v4, v4, v20
	v_add_f32_e32 v5, v5, v21
	v_add_f32_e32 v2, v2, v18
	v_add_f32_e32 v3, v3, v19
	v_add_f32_e32 v4, v4, v78
	v_add_f32_e32 v5, v5, v79
	v_add_f32_e32 v2, v2, v132
	v_add_f32_e32 v3, v3, v133
	v_add_f32_e32 v8, v8, v24
	v_add_f32_e32 v9, v9, v25
	v_add_f32_e32 v6, v6, v22
	v_add_f32_e32 v7, v7, v23
	v_cvt_pk_bf16_f32 v2, v2, v3
	v_cvt_pk_bf16_f32 v3, v4, v5
	global_store_dwordx2 v[152:153], v[2:3], off
	v_add_f32_e32 v2, v6, v134
	v_add_f32_e32 v3, v7, v135
	v_add_f32_e32 v4, v8, v80
	v_add_f32_e32 v5, v9, v81
	v_add_f32_e32 v12, v12, v28
	v_add_f32_e32 v13, v13, v29
	v_add_f32_e32 v10, v10, v26
	v_add_f32_e32 v11, v11, v27
	v_cvt_pk_bf16_f32 v2, v2, v3
	v_cvt_pk_bf16_f32 v3, v4, v5
	global_store_dwordx2 v[152:153], v[2:3], off offset:16
	v_add_f32_e32 v2, v10, v136
	v_add_f32_e32 v3, v11, v137
	v_add_f32_e32 v4, v12, v74
	v_add_f32_e32 v5, v13, v75
	v_add_f32_e32 v16, v16, v32
	v_add_f32_e32 v17, v17, v33
	v_add_f32_e32 v14, v14, v30
	v_add_f32_e32 v15, v15, v31
	v_cvt_pk_bf16_f32 v2, v2, v3
	v_cvt_pk_bf16_f32 v3, v4, v5
	global_store_dwordx2 v[152:153], v[2:3], off offset:32
	v_add_f32_e32 v2, v14, v138
	v_add_f32_e32 v3, v15, v139
	v_add_f32_e32 v4, v16, v76
	v_add_f32_e32 v5, v17, v77
	v_cvt_pk_bf16_f32 v2, v2, v3
	v_cvt_pk_bf16_f32 v3, v4, v5
	global_store_dwordx2 v[152:153], v[2:3], off offset:48
	s_cbranch_execz .LBB0_1857

; #define LAS __attribute__((address_space(3)))
; __device__ __forceinline__ unsigned pk2(float lo, float hi) { const bfx2 b = __builtin_convertvector((f32x2){lo, hi}, bfx2); return __builtin_bit_cast(unsigned, b); }
; __device__ __forceinline__ void chunk_chain(const P& p, Frame& F, int s) {
;     ...
;         if (grp == 0) {
;             sacc = ck_mm(L + (2 + cur) * CK_SLOT, L + cur * CK_SLOT, mt, nt, ql, half, ck_zero());
; #pragma unroll
;             for (int g = 0; g < 4; ++g)
; #pragma unroll
;                 for (int e = 0; e < 4; ++e) sacc[4 * g + e] += ad[g][e];
;             ck_store_t(L + (cur ^ 1) * CK_SLOT, sacc, mt, nt, ql, half);
;         } else {
;             const f32x16 a = ck_mm(L + cur * CK_SLOT, L + (4 + cur) * CK_SLOT, mt, nt, ql, half, ck_zero());
;             bf16* yrow = YRAW + (size_t)(b * TP + 64 * c + n) * 1024 + h * 64;
; #pragma unroll
;             for (int g = 0; g < 4; ++g) { u32x2 w; w.x = pk2(a[4 * g] + ad[g][0], a[4 * g + 1] + ad[g][1]); w.y = pk2(a[4 * g + 2] + ad[g][2], a[4 * g + 3] + ad[g][3]);
;                 *(u32x2*)(yrow + 32 * mt + 8 * g + 4 * half) = w; } }
;         if (c + 1 < 32) { *(LAS u32x4*)(L + (2 + (cur ^ 1)) * CK_SLOT + ioff) = pmR[(u + 1) & 3]; *(LAS u32x4*)(L + (4 + (cur ^ 1)) * CK_SLOT + ioff) = pqR[(u + 1) & 3]; }
;         __syncthreads();
;       }
;     }
.LBB0_1857:
	v_add_u32_e32 v2, v144, v140
	ds_read_b128 v[2:5], v2 offset:24576
	v_add_u32_e32 v6, v145, v140
	ds_read_b128 v[6:9], v6 offset:8192
	v_add_u32_e32 v82, v144, v142
	v_add_u32_e32 v18, v144, v141
	ds_read_b128 v[82:85], v82 offset:24576
	ds_read_b128 v[18:21], v18 offset:24576
	v_add_u32_e32 v86, v145, v142
	v_add_u32_e32 v22, v145, v141
	s_waitcnt lgkmcnt(2)
	v_mfma_f32_32x32x16_bf16 v[2:17], v[2:5], v[6:9], 0
	ds_read_b128 v[86:89], v86 offset:8192
	ds_read_b128 v[22:25], v22 offset:8192
	v_add_u32_e32 v90, v144, v143
	s_waitcnt lgkmcnt(1)
	v_mfma_f32_32x32x16_bf16 v[2:17], v[82:85], v[86:89], v[2:17]
	ds_read_b128 v[82:85], v90 offset:24576
	v_add_u32_e32 v86, v145, v143
	ds_read_b128 v[86:89], v86 offset:8192
	s_waitcnt lgkmcnt(2)
	v_mfma_f32_32x32x16_bf16 v[18:33], v[18:21], v[22:25], 0
	s_waitcnt lgkmcnt(0)
	v_mfma_f32_32x32x16_bf16 v[18:33], v[82:85], v[86:89], v[18:33]
	s_nop 11
	v_add_f32_e32 v4, v4, v20
	v_add_f32_e32 v5, v5, v21
	v_add_f32_e32 v2, v2, v18
	v_add_f32_e32 v3, v3, v19
	v_add_f32_e32 v8, v8, v24
	v_add_f32_e32 v9, v9, v25
	v_add_f32_e32 v6, v6, v22
	v_add_f32_e32 v7, v7, v23
	v_add_f32_e32 v82, v2, v132
	v_add_f32_e32 v83, v3, v133
	v_add_f32_e32 v84, v4, v78
	v_add_f32_e32 v85, v5, v79
	v_add_f32_e32 v12, v12, v28
	v_add_f32_e32 v13, v13, v29
	v_add_f32_e32 v10, v10, v26
	v_add_f32_e32 v11, v11, v27
	v_add_f32_e32 v86, v6, v134
	v_add_f32_e32 v87, v7, v135
	v_add_f32_e32 v88, v8, v80
	v_add_f32_e32 v89, v9, v81
	v_cvt_pk_bf16_f32 v2, v82, v83
	v_cvt_pk_bf16_f32 v3, v84, v85
	v_add_u32_e32 v4, v146, v147
	v_add_f32_e32 v16, v16, v32
	v_add_f32_e32 v17, v17, v33
	v_add_f32_e32 v14, v14, v30
	v_add_f32_e32 v15, v15, v31
	v_add_f32_e32 v90, v10, v136
	v_add_f32_e32 v91, v11, v137
	v_add_f32_e32 v92, v12, v74
	v_add_f32_e32 v93, v13, v75
	ds_write_b64 v4, v[2:3]
	v_cvt_pk_bf16_f32 v2, v86, v87
	v_cvt_pk_bf16_f32 v3, v88, v89
	v_add_u32_e32 v4, v146, v148
	v_add_f32_e32 v94, v14, v138
	v_add_f32_e32 v95, v15, v139
	v_add_f32_e32 v96, v16, v76
	v_add_f32_e32 v97, v17, v77
	ds_write_b64 v4, v[2:3]
	v_cvt_pk_bf16_f32 v2, v90, v91
	v_cvt_pk_bf16_f32 v3, v92, v93
	v_add_u32_e32 v4, v146, v149
	ds_write_b64 v4, v[2:3]
	v_cvt_pk_bf16_f32 v2, v94, v95
	v_cvt_pk_bf16_f32 v3, v96, v97
	v_add_u32_e32 v4, v146, v150
	ds_write_b64 v4, v[2:3]
	s_cmp_gt_u32 s18, 30
	s_cbranch_scc0 .LBB0_1853
	s_branch .LBB0_1854

; __device__ __forceinline__ unsigned pk2(float lo, float hi) { const bfx2 b = __builtin_convertvector((f32x2){lo, hi}, bfx2); return __builtin_bit_cast(unsigned, b); }
; #define PKP(var) unsigned char* var; { int l_ = threadIdx.x; asm volatile("" : "+v"(l_)); var = ws + WS_PARK + (size_t)(item8 + (l_ >> 6)) * 8192 + (l_ & 63) * 16; }
; __device__ __forceinline__ void attn_item(const P& p, Frame& F, const bool is_s, const int b, const int g, const int c) {
;     ...
;         if (ph == 1) { const float lt = l + __shfl_xor(l, 32); invl = lt > 0.f ? 1.0f / lt : 0.f; const float sc = NGt[(size_t)mrow * 32 + 0 * 8 + h] * invl;
;             if (qvalid) {
;                 PKP(PK);
; #pragma unroll
;                 for (int dt = 0; dt < 4; ++dt)
; #pragma unroll
;                     for (int hf = 0; hf < 2; ++hf) { u32x4 w; w.x = pk2(ot[dt][8 * hf + 0] * sc, ot[dt][8 * hf + 1] * sc); w.y = pk2(ot[dt][8 * hf + 2] * sc, ot[dt][8 * hf + 3] * sc);
;                         w.z = pk2(ot[dt][8 * hf + 4] * sc, ot[dt][8 * hf + 5] * sc); w.w = pk2(ot[dt][8 * hf + 6] * sc, ot[dt][8 * hf + 7] * sc); *(u32x4*)(PK + (2 * dt + hf) * 1024) = w; } } }
.LBB0_1954:
	v_and_b32_e32 v2, 64, v221
	v_xor_b32_e32 v1, 32, v221
	v_add_u32_e32 v2, 64, v2
	v_cmp_lt_i32_e32 vcc, v1, v2
	s_nop 1
	v_cndmask_b32_e32 v1, v221, v1, vcc
	v_lshlrev_b32_e32 v1, 2, v1
	ds_bpermute_b32 v1, v1, v240
	s_waitcnt lgkmcnt(0)
	v_add_f32_e32 v1, v240, v1
	v_div_scale_f32 v2, s[0:1], v1, v1, 1.0
	v_rcp_f32_e32 v4, v2
	v_div_scale_f32 v5, vcc, 1.0, v1, 1.0
	v_fma_f32 v6, -v2, v4, 1.0
	v_fmac_f32_e32 v4, v6, v4
	v_mul_f32_e32 v6, v5, v4
	v_fma_f32 v7, -v2, v6, v5
	v_fmac_f32_e32 v6, v7, v4
	v_fma_f32 v2, -v2, v6, v5
	v_div_fmas_f32 v2, v2, v4, v6
	v_div_fixup_f32 v2, v2, v1, 1.0
	v_cmp_lt_f32_e32 vcc, 0, v1
	s_nop 1
	v_cndmask_b32_e32 v204, 0, v2, vcc
	s_and_saveexec_b64 s[0:1], s[22:23]
	s_cbranch_execz .LBB0_1956
	global_load_dword v1, v[202:203], off
	v_readlane_b32 s2, v252, 13
	v_readlane_b32 s6, v254, 49
	v_readlane_b32 s7, v254, 50
	s_waitcnt vmcnt(0)
	v_mul_f32_e32 v4, v1, v204
	v_mov_b32_e32 v1, v0
	v_mul_f32_e32 v8, v66, v4
	v_mul_f32_e32 v9, v67, v4
	v_ashrrev_i32_e32 v2, 6, v1
	v_add_u32_e32 v6, s2, v2
	v_ashrrev_i32_e32 v7, 31, v6
	v_lshlrev_b64 v[6:7], 13, v[6:7]
	v_lshlrev_b32_e32 v1, 4, v1
	v_mul_f32_e32 v10, v68, v4
	v_mul_f32_e32 v11, v69, v4
	v_lshl_add_u64 v[6:7], s[6:7], 0, v[6:7]
	v_and_b32_e32 v2, 0x3f0, v1
	v_cvt_pk_bf16_f32 v8, v8, v9
	v_cvt_pk_bf16_f32 v9, v10, v11
	v_mul_f32_e32 v10, v70, v4
	v_mul_f32_e32 v11, v71, v4
	v_mul_f32_e32 v12, v72, v4
	v_mul_f32_e32 v13, v73, v4
	v_lshl_add_u64 v[6:7], v[6:7], 0, v[2:3]
	v_cvt_pk_bf16_f32 v10, v10, v11
	v_cvt_pk_bf16_f32 v11, v12, v13
	global_store_dwordx4 v[6:7], v[8:11], off
	v_mul_f32_e32 v12, v80, v4
	v_mul_f32_e32 v13, v81, v4
	s_movk_i32 s2, 0x1000
	v_mul_f32_e32 v8, v74, v4
	v_mul_f32_e32 v9, v75, v4
	v_mul_f32_e32 v10, v76, v4
	v_mul_f32_e32 v11, v77, v4
	v_cvt_pk_bf16_f32 v8, v8, v9
	v_cvt_pk_bf16_f32 v9, v10, v11
	v_mul_f32_e32 v10, v78, v4
	v_mul_f32_e32 v11, v79, v4
	s_nop 0
	v_cvt_pk_bf16_f32 v10, v10, v11
	v_cvt_pk_bf16_f32 v11, v12, v13
	global_store_dwordx4 v[6:7], v[8:11], off offset:1024
	v_mul_f32_e32 v12, v56, v4
	v_mul_f32_e32 v13, v57, v4
	s_nop 0
	v_mul_f32_e32 v8, v50, v4
	v_mul_f32_e32 v9, v51, v4
	v_mul_f32_e32 v10, v52, v4
	v_mul_f32_e32 v11, v53, v4
	v_cvt_pk_bf16_f32 v8, v8, v9
	v_cvt_pk_bf16_f32 v9, v10, v11
	v_mul_f32_e32 v10, v54, v4
	v_mul_f32_e32 v11, v55, v4
	s_nop 0
	v_cvt_pk_bf16_f32 v10, v10, v11
	v_cvt_pk_bf16_f32 v11, v12, v13
	global_store_dwordx4 v[6:7], v[8:11], off offset:2048
	v_mul_f32_e32 v12, v64, v4
	v_mul_f32_e32 v13, v65, v4
	s_nop 0
	v_mul_f32_e32 v8, v58, v4
	v_mul_f32_e32 v9, v59, v4
	v_mul_f32_e32 v10, v60, v4
	v_mul_f32_e32 v11, v61, v4
	v_cvt_pk_bf16_f32 v8, v8, v9
	v_cvt_pk_bf16_f32 v9, v10, v11
	v_mul_f32_e32 v10, v62, v4
	v_mul_f32_e32 v11, v63, v4
	s_nop 0
	v_cvt_pk_bf16_f32 v10, v10, v11
	v_cvt_pk_bf16_f32 v11, v12, v13
	global_store_dwordx4 v[6:7], v[8:11], off offset:3072
	v_mul_f32_e32 v12, v40, v4
	v_mul_f32_e32 v13, v41, v4
	v_add_co_u32_e32 v6, vcc, s2, v6
	v_mul_f32_e32 v8, v34, v4
	v_mul_f32_e32 v9, v35, v4
	v_mul_f32_e32 v10, v36, v4
	v_mul_f32_e32 v11, v37, v4
	v_cvt_pk_bf16_f32 v8, v8, v9
	v_cvt_pk_bf16_f32 v9, v10, v11
	v_mul_f32_e32 v10, v38, v4
	v_mul_f32_e32 v11, v39, v4
	v_addc_co_u32_e32 v7, vcc, 0, v7, vcc
	v_cvt_pk_bf16_f32 v10, v10, v11
	v_cvt_pk_bf16_f32 v11, v12, v13
	global_store_dwordx4 v[6:7], v[8:11], off
	v_mul_f32_e32 v12, v48, v4
	v_mul_f32_e32 v13, v49, v4
	s_nop 0
	v_mul_f32_e32 v8, v42, v4
	v_mul_f32_e32 v9, v43, v4
	v_mul_f32_e32 v10, v44, v4
	v_mul_f32_e32 v11, v45, v4
	v_cvt_pk_bf16_f32 v8, v8, v9
	v_cvt_pk_bf16_f32 v9, v10, v11
	v_mul_f32_e32 v10, v46, v4
	v_mul_f32_e32 v11, v47, v4
	s_nop 0
	v_cvt_pk_bf16_f32 v10, v10, v11
	v_cvt_pk_bf16_f32 v11, v12, v13
	global_store_dwordx4 v[6:7], v[8:11], off offset:1024
	v_mul_f32_e32 v12, v24, v4
	v_mul_f32_e32 v13, v25, v4
	s_nop 0
	v_mul_f32_e32 v8, v18, v4
	v_mul_f32_e32 v9, v19, v4
	v_mul_f32_e32 v10, v20, v4
	v_mul_f32_e32 v11, v21, v4
	v_cvt_pk_bf16_f32 v8, v8, v9
	v_cvt_pk_bf16_f32 v9, v10, v11
	v_mul_f32_e32 v10, v22, v4
	v_mul_f32_e32 v11, v23, v4
	s_nop 0
	v_cvt_pk_bf16_f32 v10, v10, v11
	v_cvt_pk_bf16_f32 v11, v12, v13
	global_store_dwordx4 v[6:7], v[8:11], off offset:2048
	s_nop 1
	v_mul_f32_e32 v8, v26, v4
	v_mul_f32_e32 v9, v27, v4
	v_mul_f32_e32 v10, v28, v4
	v_mul_f32_e32 v11, v29, v4
	v_cvt_pk_bf16_f32 v8, v8, v9
	v_cvt_pk_bf16_f32 v9, v10, v11
	v_mul_f32_e32 v10, v30, v4
	v_mul_f32_e32 v11, v31, v4
	v_mul_f32_e32 v5, v33, v4
	v_mul_f32_e32 v4, v32, v4
	v_cvt_pk_bf16_f32 v10, v10, v11
	v_cvt_pk_bf16_f32 v11, v4, v5
	global_store_dwordx4 v[6:7], v[8:11], off offset:3072

; __device__ __forceinline__ void attn_item(const P& p, Frame& F, const bool is_s, const int b, const int g, const int c) {
;     ...
;                 { const int q = tid2 >> 3, jg = tid2 & 7; const int tq = 64 * c + q;
; #pragma unroll
;                   for (int jj = 0; jj < 4; ++jj) { const int j = jg * 4 + jj; float v = ((IMP[(0 * 64 + q) * 33 + j] + IMP[(1 * 64 + q) * 33 + j]) + IMP[(2 * 64 + q) * 33 + j]) + IMP[(3 * 64 + q) * 33 + j];
;                       if (j == 0 || j == c || j == c - 1) v += 1e4f; if (j * 64 > tq) v = NEGB; IMP[q * 33 + j] = v; } }
;                 __syncthreads();
;                 { const int q = tid2 >> 3, jg = tid2 & 7; unsigned bits = 0u;
;                   for (int jj = 0; jj < 4; ++jj) { const int j = jg * 4 + jj; const float vj = IMP[q * 33 + j]; int rank = 0;
; #pragma nounroll
;                       for (int i = 0; i < 32; ++i) { const float vi = IMP[q * 33 + i]; rank += (vi > vj || (vi == vj && i < j)) ? 1 : 0; }
;                       if (rank < 16) bits |= 1u << j; }
.LBB0_1957:
	s_cmp_eq_u32 s5, 2
	s_cselect_b64 s[46:47], -1, 0
	s_cmp_lg_u32 s5, 2
	s_cselect_b64 s[42:43], -1, 0
	s_and_b64 vcc, exec, s[42:43]
	s_cbranch_vccnz .LBB0_2003
	v_mov_b32_e32 v9, v226
	s_mov_b64 s[0:1], -1
	s_and_b64 vcc, exec, s[56:57]
	s_waitcnt lgkmcnt(0)
	s_barrier
	s_cbranch_vccz .LBB0_1970
	v_ashrrev_i32_e32 v10, 3, v9
	v_readlane_b32 s0, v252, 44
	v_lshlrev_b32_e32 v1, 2, v9
	s_mov_b32 s14, s91
	v_add_u32_e32 v15, s0, v10
	s_movk_i32 s0, 0x84
	v_mul_lo_u32 v2, v10, s0
	v_readlane_b32 s0, v252, 14
	s_mov_b32 s15, s87
	s_mov_b32 s16, s90
	v_add_u32_e32 v11, s0, v2
	v_and_b32_e32 v2, 28, v1
	v_lshl_add_u32 v14, v2, 2, v11
	v_add_u32_e32 v16, 0x6300, v14
	v_add_u32_e32 v1, 0x2100, v14
	v_add_u32_e32 v8, 0x4200, v14
	ds_read2_b32 v[4:5], v14 offset1:1
	ds_read2_b32 v[6:7], v1 offset1:1
	ds_read2_b32 v[12:13], v8 offset1:1
	ds_read2_b32 v[16:17], v16 offset1:1
	v_cmp_eq_u32_e32 vcc, 0, v2
	v_cmp_eq_u32_e64 s[0:1], s14, v2
	s_waitcnt lgkmcnt(2)
	v_add_f32_e32 v4, v4, v6
	v_add_f32_e32 v5, v5, v7
	v_or_b32_e32 v1, 1, v2
	s_waitcnt lgkmcnt(1)
	v_add_f32_e32 v4, v4, v12
	v_add_f32_e32 v5, v5, v13
	s_or_b64 s[6:7], vcc, s[0:1]
	s_waitcnt lgkmcnt(0)
	v_add_f32_e32 v4, v4, v16
	v_add_f32_e32 v5, v5, v17
	v_cmp_eq_u32_e32 vcc, s14, v1
	v_cmp_eq_u32_e64 s[0:1], s15, v2
	v_cmp_eq_u32_e64 s[10:11], s16, v1
	s_mov_b32 s2, 0x461c4000
	v_add_f32_e32 v6, s2, v4
	v_add_f32_e32 v7, s2, v5
	s_or_b64 s[0:1], s[6:7], s[0:1]
	s_or_b64 vcc, vcc, s[10:11]
	v_lshlrev_b32_e32 v1, 6, v1
	v_cndmask_b32_e64 v4, v4, v6, s[0:1]
	v_cndmask_b32_e32 v5, v5, v7, vcc
	v_lshlrev_b32_e32 v6, 6, v2
	v_cmp_le_i32_e32 vcc, v1, v15
	s_mov_b32 s6, 1
	s_mov_b32 s7, 0
	v_cndmask_b32_e32 v1, v222, v5, vcc
	v_cmp_le_i32_e32 vcc, v6, v15
	s_nop 1
	v_cndmask_b32_e32 v4, v222, v4, vcc
	ds_write2_b32 v14, v4, v1 offset1:1
	v_or_b32_e32 v4, 2, v2
	v_lshl_add_u32 v8, v4, 2, v11
	s_waitcnt vmcnt(0)
	v_add_u32_e32 v98, 0x6300, v8
	v_add_u32_e32 v1, 0x2100, v8
	v_add_u32_e32 v5, 0x4200, v8
	ds_read2_b32 v[6:7], v8 offset1:1
	ds_read2_b32 v[12:13], v1 offset1:1
	ds_read2_b32 v[16:17], v5 offset1:1
	ds_read2_b32 v[98:99], v98 offset1:1
	v_or_b32_e32 v1, 3, v2
	v_cmp_eq_u32_e32 vcc, s14, v4
	s_waitcnt lgkmcnt(2)
	v_add_f32_e32 v6, v6, v12
	v_add_f32_e32 v7, v7, v13
	v_cmp_eq_u32_e64 s[10:11], s15, v4
	s_waitcnt lgkmcnt(1)
	v_add_f32_e32 v6, v6, v16
	v_add_f32_e32 v7, v7, v17
	v_cmp_eq_u32_e64 s[0:1], s89, v1
	s_waitcnt lgkmcnt(0)
	v_add_f32_e32 v6, v6, v98
	v_add_f32_e32 v7, v7, v99
	v_cmp_eq_u32_e64 s[14:15], s16, v1
	v_add_f32_e32 v12, s2, v6
	v_add_f32_e32 v13, s2, v7
	s_or_b64 vcc, vcc, s[10:11]
	v_cndmask_b32_e32 v5, v6, v12, vcc
	s_or_b64 vcc, s[0:1], s[14:15]
	v_lshlrev_b32_e32 v12, 6, v1
	v_cndmask_b32_e32 v6, v7, v13, vcc
	v_lshlrev_b32_e32 v7, 6, v4
	v_cmp_le_i32_e32 vcc, v12, v15
	s_mov_b32 s2, 0
	v_mov_b32_e32 v12, 0
	v_cndmask_b32_e32 v6, v222, v6, vcc
	v_cmp_le_i32_e32 vcc, v7, v15
	v_mov_b32_e32 v13, 0
	s_nop 0
	v_cndmask_b32_e32 v5, v222, v5, vcc
	ds_write2_b32 v8, v5, v6 offset1:1
	s_waitcnt lgkmcnt(0)
	s_barrier
	ds_read_b32 v6, v14
	ds_read2_b32 v[18:19], v11 offset0:0 offset1:1
	ds_read2_b32 v[20:21], v11 offset0:2 offset1:3
	ds_read2_b32 v[22:23], v11 offset0:4 offset1:5
	ds_read2_b32 v[24:25], v11 offset0:6 offset1:7
	ds_read2_b32 v[26:27], v11 offset0:8 offset1:9
	ds_read2_b32 v[28:29], v11 offset0:10 offset1:11
	ds_read2_b32 v[30:31], v11 offset0:12 offset1:13
	ds_read2_b32 v[32:33], v11 offset0:14 offset1:15
	s_waitcnt lgkmcnt(4)
	ds_read2_b32 v[34:35], v11 offset0:16 offset1:17
	ds_read2_b32 v[36:37], v11 offset0:18 offset1:19
	ds_read2_b32 v[38:39], v11 offset0:20 offset1:21
	ds_read2_b32 v[40:41], v11 offset0:22 offset1:23
	ds_read2_b32 v[42:43], v11 offset0:24 offset1:25
	ds_read2_b32 v[44:45], v11 offset0:26 offset1:27
	ds_read2_b32 v[46:47], v11 offset0:28 offset1:29
	ds_read2_b32 v[48:49], v11 offset0:30 offset1:31
	v_mov_b32_e32 v5, v2
	s_waitcnt lgkmcnt(0)
	v_mov_b32_e32 v7, v6
	v_cmp_lt_u32_e32 vcc, 0, v2
	v_cmp_lt_u32_e64 s[0:1], 1, v5
	v_cmp_eq_f32_e64 s[16:17], v18, v6
	v_cmp_eq_f32_e64 s[18:19], v19, v7
	v_cmp_gt_f32_e64 s[10:11], v19, v7
	v_cmp_gt_f32_e64 s[14:15], v18, v6
	s_and_b64 s[0:1], s[18:19], s[0:1]
	s_and_b64 s[16:17], s[16:17], vcc
	s_or_b64 vcc, s[14:15], s[16:17]
	s_or_b64 s[0:1], s[10:11], s[0:1]
	v_addc_co_u32_e64 v13, s[0:1], 0, v13, s[0:1]
	v_addc_co_u32_e32 v12, vcc, 0, v12, vcc
	v_cmp_lt_u32_e32 vcc, 2, v2
	v_cmp_lt_u32_e64 s[0:1], 3, v5
	v_cmp_eq_f32_e64 s[16:17], v20, v6
	v_cmp_eq_f32_e64 s[18:19], v21, v7
	v_cmp_gt_f32_e64 s[10:11], v21, v7
	v_cmp_gt_f32_e64 s[14:15], v20, v6
	s_and_b64 s[0:1], s[18:19], s[0:1]
	s_and_b64 s[16:17], s[16:17], vcc
	s_or_b64 vcc, s[14:15], s[16:17]
	s_or_b64 s[0:1], s[10:11], s[0:1]
	v_addc_co_u32_e64 v13, s[0:1], 0, v13, s[0:1]
	v_addc_co_u32_e32 v12, vcc, 0, v12, vcc
	v_cmp_lt_u32_e32 vcc, 4, v2
	v_cmp_lt_u32_e64 s[0:1], 5, v5
	v_cmp_eq_f32_e64 s[16:17], v22, v6
	v_cmp_eq_f32_e64 s[18:19], v23, v7
	v_cmp_gt_f32_e64 s[10:11], v23, v7
	v_cmp_gt_f32_e64 s[14:15], v22, v6
	s_and_b64 s[0:1], s[18:19], s[0:1]
	s_and_b64 s[16:17], s[16:17], vcc
	s_or_b64 vcc, s[14:15], s[16:17]
	s_or_b64 s[0:1], s[10:11], s[0:1]
	v_addc_co_u32_e64 v13, s[0:1], 0, v13, s[0:1]
	v_addc_co_u32_e32 v12, vcc, 0, v12, vcc
	v_cmp_lt_u32_e32 vcc, 6, v2
	v_cmp_lt_u32_e64 s[0:1], 7, v5
	v_cmp_eq_f32_e64 s[16:17], v24, v6
	v_cmp_eq_f32_e64 s[18:19], v25, v7
	v_cmp_gt_f32_e64 s[10:11], v25, v7
	v_cmp_gt_f32_e64 s[14:15], v24, v6
	s_and_b64 s[0:1], s[18:19], s[0:1]
	s_and_b64 s[16:17], s[16:17], vcc
	s_or_b64 vcc, s[14:15], s[16:17]
	s_or_b64 s[0:1], s[10:11], s[0:1]
	v_addc_co_u32_e64 v13, s[0:1], 0, v13, s[0:1]
; __device__ __forceinline__ void attn_item(const P& p, Frame& F, const bool is_s, const int b, const int g, const int c) {
;     ...
;                 { const int q = tid2 >> 3, jg = tid2 & 7; unsigned bits = 0u;
;                   for (int jj = 0; jj < 4; ++jj) { const int j = jg * 4 + jj; const float vj = IMP[q * 33 + j]; int rank = 0;
; #pragma nounroll
;                       for (int i = 0; i < 32; ++i) { const float vi = IMP[q * 33 + i]; rank += (vi > vj || (vi == vj && i < j)) ? 1 : 0; }
;                       if (rank < 16) bits |= 1u << j; }
	v_addc_co_u32_e32 v12, vcc, 0, v12, vcc
	v_cmp_lt_u32_e32 vcc, 8, v2
	v_cmp_lt_u32_e64 s[0:1], 9, v5
	v_cmp_eq_f32_e64 s[16:17], v26, v6
	v_cmp_eq_f32_e64 s[18:19], v27, v7
	v_cmp_gt_f32_e64 s[10:11], v27, v7
	v_cmp_gt_f32_e64 s[14:15], v26, v6
	s_and_b64 s[0:1], s[18:19], s[0:1]
	s_and_b64 s[16:17], s[16:17], vcc
	s_or_b64 vcc, s[14:15], s[16:17]
	s_or_b64 s[0:1], s[10:11], s[0:1]
	v_addc_co_u32_e64 v13, s[0:1], 0, v13, s[0:1]
	v_addc_co_u32_e32 v12, vcc, 0, v12, vcc
	v_cmp_lt_u32_e32 vcc, 10, v2
	v_cmp_lt_u32_e64 s[0:1], 11, v5
	v_cmp_eq_f32_e64 s[16:17], v28, v6
	v_cmp_eq_f32_e64 s[18:19], v29, v7
	v_cmp_gt_f32_e64 s[10:11], v29, v7
	v_cmp_gt_f32_e64 s[14:15], v28, v6
	s_and_b64 s[0:1], s[18:19], s[0:1]
	s_and_b64 s[16:17], s[16:17], vcc
	s_or_b64 vcc, s[14:15], s[16:17]
	s_or_b64 s[0:1], s[10:11], s[0:1]
	v_addc_co_u32_e64 v13, s[0:1], 0, v13, s[0:1]
	v_addc_co_u32_e32 v12, vcc, 0, v12, vcc
	v_cmp_lt_u32_e32 vcc, 12, v2
	v_cmp_lt_u32_e64 s[0:1], 13, v5
	v_cmp_eq_f32_e64 s[16:17], v30, v6
	v_cmp_eq_f32_e64 s[18:19], v31, v7
	v_cmp_gt_f32_e64 s[10:11], v31, v7
	v_cmp_gt_f32_e64 s[14:15], v30, v6
	s_and_b64 s[0:1], s[18:19], s[0:1]
	s_and_b64 s[16:17], s[16:17], vcc
	s_or_b64 vcc, s[14:15], s[16:17]
	s_or_b64 s[0:1], s[10:11], s[0:1]
	v_addc_co_u32_e64 v13, s[0:1], 0, v13, s[0:1]
	v_addc_co_u32_e32 v12, vcc, 0, v12, vcc
	v_cmp_lt_u32_e32 vcc, 14, v2
	v_cmp_lt_u32_e64 s[0:1], 15, v5
	v_cmp_eq_f32_e64 s[16:17], v32, v6
	v_cmp_eq_f32_e64 s[18:19], v33, v7
	v_cmp_gt_f32_e64 s[10:11], v33, v7
	v_cmp_gt_f32_e64 s[14:15], v32, v6
	s_and_b64 s[0:1], s[18:19], s[0:1]
	s_and_b64 s[16:17], s[16:17], vcc
	s_or_b64 vcc, s[14:15], s[16:17]
	s_or_b64 s[0:1], s[10:11], s[0:1]
	v_addc_co_u32_e64 v13, s[0:1], 0, v13, s[0:1]
	v_addc_co_u32_e32 v12, vcc, 0, v12, vcc
	v_cmp_lt_u32_e32 vcc, 16, v2
	v_cmp_lt_u32_e64 s[0:1], 17, v5
	v_cmp_eq_f32_e64 s[16:17], v34, v6
	v_cmp_eq_f32_e64 s[18:19], v35, v7
	v_cmp_gt_f32_e64 s[10:11], v35, v7
	v_cmp_gt_f32_e64 s[14:15], v34, v6
	s_and_b64 s[0:1], s[18:19], s[0:1]
	s_and_b64 s[16:17], s[16:17], vcc
	s_or_b64 vcc, s[14:15], s[16:17]
	s_or_b64 s[0:1], s[10:11], s[0:1]
	v_addc_co_u32_e64 v13, s[0:1], 0, v13, s[0:1]
	v_addc_co_u32_e32 v12, vcc, 0, v12, vcc
	v_cmp_lt_u32_e32 vcc, 18, v2
	v_cmp_lt_u32_e64 s[0:1], 19, v5
	v_cmp_eq_f32_e64 s[16:17], v36, v6
	v_cmp_eq_f32_e64 s[18:19], v37, v7
	v_cmp_gt_f32_e64 s[10:11], v37, v7
	v_cmp_gt_f32_e64 s[14:15], v36, v6
	s_and_b64 s[0:1], s[18:19], s[0:1]
	s_and_b64 s[16:17], s[16:17], vcc
	s_or_b64 vcc, s[14:15], s[16:17]
	s_or_b64 s[0:1], s[10:11], s[0:1]
	v_addc_co_u32_e64 v13, s[0:1], 0, v13, s[0:1]
	v_addc_co_u32_e32 v12, vcc, 0, v12, vcc
	v_cmp_lt_u32_e32 vcc, 20, v2
	v_cmp_lt_u32_e64 s[0:1], 21, v5
	v_cmp_eq_f32_e64 s[16:17], v38, v6
	v_cmp_eq_f32_e64 s[18:19], v39, v7
	v_cmp_gt_f32_e64 s[10:11], v39, v7
	v_cmp_gt_f32_e64 s[14:15], v38, v6
	s_and_b64 s[0:1], s[18:19], s[0:1]
	s_and_b64 s[16:17], s[16:17], vcc
	s_or_b64 vcc, s[14:15], s[16:17]
	s_or_b64 s[0:1], s[10:11], s[0:1]
	v_addc_co_u32_e64 v13, s[0:1], 0, v13, s[0:1]
	v_addc_co_u32_e32 v12, vcc, 0, v12, vcc
	v_cmp_lt_u32_e32 vcc, 22, v2
	v_cmp_lt_u32_e64 s[0:1], 23, v5
	v_cmp_eq_f32_e64 s[16:17], v40, v6
	v_cmp_eq_f32_e64 s[18:19], v41, v7
	v_cmp_gt_f32_e64 s[10:11], v41, v7
	v_cmp_gt_f32_e64 s[14:15], v40, v6
	s_and_b64 s[0:1], s[18:19], s[0:1]
	s_and_b64 s[16:17], s[16:17], vcc
	s_or_b64 vcc, s[14:15], s[16:17]
	s_or_b64 s[0:1], s[10:11], s[0:1]
	v_addc_co_u32_e64 v13, s[0:1], 0, v13, s[0:1]
	v_addc_co_u32_e32 v12, vcc, 0, v12, vcc
	v_cmp_lt_u32_e32 vcc, 24, v2
	v_cmp_lt_u32_e64 s[0:1], 25, v5
	v_cmp_eq_f32_e64 s[16:17], v42, v6
	v_cmp_eq_f32_e64 s[18:19], v43, v7
	v_cmp_gt_f32_e64 s[10:11], v43, v7
	v_cmp_gt_f32_e64 s[14:15], v42, v6
	s_and_b64 s[0:1], s[18:19], s[0:1]
	s_and_b64 s[16:17], s[16:17], vcc
	s_or_b64 vcc, s[14:15], s[16:17]
	s_or_b64 s[0:1], s[10:11], s[0:1]
	v_addc_co_u32_e64 v13, s[0:1], 0, v13, s[0:1]
	v_addc_co_u32_e32 v12, vcc, 0, v12, vcc
	v_cmp_lt_u32_e32 vcc, 26, v2
	v_cmp_lt_u32_e64 s[0:1], 27, v5
	v_cmp_eq_f32_e64 s[16:17], v44, v6
	v_cmp_eq_f32_e64 s[18:19], v45, v7
	v_cmp_gt_f32_e64 s[10:11], v45, v7
	v_cmp_gt_f32_e64 s[14:15], v44, v6
	s_and_b64 s[0:1], s[18:19], s[0:1]
	s_and_b64 s[16:17], s[16:17], vcc
	s_or_b64 vcc, s[14:15], s[16:17]
	s_or_b64 s[0:1], s[10:11], s[0:1]
	v_addc_co_u32_e64 v13, s[0:1], 0, v13, s[0:1]
	v_addc_co_u32_e32 v12, vcc, 0, v12, vcc
	v_cmp_lt_u32_e32 vcc, 28, v2
	v_cmp_lt_u32_e64 s[0:1], 29, v5
	v_cmp_eq_f32_e64 s[16:17], v46, v6
	v_cmp_eq_f32_e64 s[18:19], v47, v7
	v_cmp_gt_f32_e64 s[10:11], v47, v7
	v_cmp_gt_f32_e64 s[14:15], v46, v6
	s_and_b64 s[0:1], s[18:19], s[0:1]
	s_and_b64 s[16:17], s[16:17], vcc
	s_or_b64 vcc, s[14:15], s[16:17]
	s_or_b64 s[0:1], s[10:11], s[0:1]
	v_addc_co_u32_e64 v13, s[0:1], 0, v13, s[0:1]
	v_addc_co_u32_e32 v12, vcc, 0, v12, vcc
	v_cmp_lt_u32_e32 vcc, 30, v2
	v_cmp_lt_u32_e64 s[0:1], 31, v5
	v_cmp_eq_f32_e64 s[16:17], v48, v6
	v_cmp_eq_f32_e64 s[18:19], v49, v7
	v_cmp_gt_f32_e64 s[10:11], v49, v7
	v_cmp_gt_f32_e64 s[14:15], v48, v6
	s_and_b64 s[0:1], s[18:19], s[0:1]
	s_and_b64 s[16:17], s[16:17], vcc
	s_or_b64 vcc, s[14:15], s[16:17]
	s_or_b64 s[0:1], s[10:11], s[0:1]
	v_addc_co_u32_e64 v13, s[0:1], 0, v13, s[0:1]
	v_addc_co_u32_e32 v12, vcc, 0, v12, vcc
	ds_read_b32 v6, v14 offset:4
	s_mov_b32 s2, 1
	s_mov_b32 s6, 0
	v_mov_b32_e32 v14, 0
	v_mov_b32_e32 v15, 0
	s_waitcnt lgkmcnt(0)
; __device__ __forceinline__ void attn_item(const P& p, Frame& F, const bool is_s, const int b, const int g, const int c) {
;     ...
;                 { const int q = tid2 >> 3, jg = tid2 & 7; unsigned bits = 0u;
;                   for (int jj = 0; jj < 4; ++jj) { const int j = jg * 4 + jj; const float vj = IMP[q * 33 + j]; int rank = 0;
; #pragma nounroll
;                       for (int i = 0; i < 32; ++i) { const float vi = IMP[q * 33 + i]; rank += (vi > vj || (vi == vj && i < j)) ? 1 : 0; }
;                       if (rank < 16) bits |= 1u << j; }
	v_mov_b32_e32 v7, v6
	s_mov_b32 s7, 0
	v_cmp_le_u32_e32 vcc, 0, v2
	v_cmp_le_u32_e64 s[0:1], 1, v5
	v_cmp_eq_f32_e64 s[16:17], v18, v6
	v_cmp_eq_f32_e64 s[18:19], v19, v7
	v_cmp_gt_f32_e64 s[10:11], v19, v7
	v_cmp_gt_f32_e64 s[14:15], v18, v6
	s_and_b64 s[0:1], s[18:19], s[0:1]
	s_and_b64 s[16:17], s[16:17], vcc
	s_or_b64 vcc, s[14:15], s[16:17]
	s_or_b64 s[0:1], s[10:11], s[0:1]
	v_addc_co_u32_e64 v15, s[0:1], 0, v15, s[0:1]
	v_addc_co_u32_e32 v14, vcc, 0, v14, vcc
	v_cmp_le_u32_e32 vcc, 2, v2
	v_cmp_le_u32_e64 s[0:1], 3, v5
	v_cmp_eq_f32_e64 s[16:17], v20, v6
	v_cmp_eq_f32_e64 s[18:19], v21, v7
	v_cmp_gt_f32_e64 s[10:11], v21, v7
	v_cmp_gt_f32_e64 s[14:15], v20, v6
	s_and_b64 s[0:1], s[18:19], s[0:1]
	s_and_b64 s[16:17], s[16:17], vcc
	s_or_b64 vcc, s[14:15], s[16:17]
	s_or_b64 s[0:1], s[10:11], s[0:1]
	v_addc_co_u32_e64 v15, s[0:1], 0, v15, s[0:1]
	v_addc_co_u32_e32 v14, vcc, 0, v14, vcc
	v_cmp_le_u32_e32 vcc, 4, v2
	v_cmp_le_u32_e64 s[0:1], 5, v5
	v_cmp_eq_f32_e64 s[16:17], v22, v6
	v_cmp_eq_f32_e64 s[18:19], v23, v7
	v_cmp_gt_f32_e64 s[10:11], v23, v7
	v_cmp_gt_f32_e64 s[14:15], v22, v6
	s_and_b64 s[0:1], s[18:19], s[0:1]
	s_and_b64 s[16:17], s[16:17], vcc
	s_or_b64 vcc, s[14:15], s[16:17]
	s_or_b64 s[0:1], s[10:11], s[0:1]
	v_addc_co_u32_e64 v15, s[0:1], 0, v15, s[0:1]
	v_addc_co_u32_e32 v14, vcc, 0, v14, vcc
	v_cmp_le_u32_e32 vcc, 6, v2
	v_cmp_le_u32_e64 s[0:1], 7, v5
	v_cmp_eq_f32_e64 s[16:17], v24, v6
	v_cmp_eq_f32_e64 s[18:19], v25, v7
	v_cmp_gt_f32_e64 s[10:11], v25, v7
	v_cmp_gt_f32_e64 s[14:15], v24, v6
	s_and_b64 s[0:1], s[18:19], s[0:1]
	s_and_b64 s[16:17], s[16:17], vcc
	s_or_b64 vcc, s[14:15], s[16:17]
	s_or_b64 s[0:1], s[10:11], s[0:1]
	v_addc_co_u32_e64 v15, s[0:1], 0, v15, s[0:1]
	v_addc_co_u32_e32 v14, vcc, 0, v14, vcc
	v_cmp_le_u32_e32 vcc, 8, v2
	v_cmp_le_u32_e64 s[0:1], 9, v5
	v_cmp_eq_f32_e64 s[16:17], v26, v6
	v_cmp_eq_f32_e64 s[18:19], v27, v7
	v_cmp_gt_f32_e64 s[10:11], v27, v7
	v_cmp_gt_f32_e64 s[14:15], v26, v6
	s_and_b64 s[0:1], s[18:19], s[0:1]
	s_and_b64 s[16:17], s[16:17], vcc
	s_or_b64 vcc, s[14:15], s[16:17]
	s_or_b64 s[0:1], s[10:11], s[0:1]
	v_addc_co_u32_e64 v15, s[0:1], 0, v15, s[0:1]
	v_addc_co_u32_e32 v14, vcc, 0, v14, vcc
	v_cmp_le_u32_e32 vcc, 10, v2
	v_cmp_le_u32_e64 s[0:1], 11, v5
	v_cmp_eq_f32_e64 s[16:17], v28, v6
	v_cmp_eq_f32_e64 s[18:19], v29, v7
	v_cmp_gt_f32_e64 s[10:11], v29, v7
	v_cmp_gt_f32_e64 s[14:15], v28, v6
	s_and_b64 s[0:1], s[18:19], s[0:1]
	s_and_b64 s[16:17], s[16:17], vcc
	s_or_b64 vcc, s[14:15], s[16:17]
	s_or_b64 s[0:1], s[10:11], s[0:1]
	v_addc_co_u32_e64 v15, s[0:1], 0, v15, s[0:1]
	v_addc_co_u32_e32 v14, vcc, 0, v14, vcc
	v_cmp_le_u32_e32 vcc, 12, v2
	v_cmp_le_u32_e64 s[0:1], 13, v5
	v_cmp_eq_f32_e64 s[16:17], v30, v6
	v_cmp_eq_f32_e64 s[18:19], v31, v7
	v_cmp_gt_f32_e64 s[10:11], v31, v7
	v_cmp_gt_f32_e64 s[14:15], v30, v6
	s_and_b64 s[0:1], s[18:19], s[0:1]
	s_and_b64 s[16:17], s[16:17], vcc
	s_or_b64 vcc, s[14:15], s[16:17]
	s_or_b64 s[0:1], s[10:11], s[0:1]
	v_addc_co_u32_e64 v15, s[0:1], 0, v15, s[0:1]
	v_addc_co_u32_e32 v14, vcc, 0, v14, vcc
	v_cmp_le_u32_e32 vcc, 14, v2
	v_cmp_le_u32_e64 s[0:1], 15, v5
	v_cmp_eq_f32_e64 s[16:17], v32, v6
	v_cmp_eq_f32_e64 s[18:19], v33, v7
	v_cmp_gt_f32_e64 s[10:11], v33, v7
	v_cmp_gt_f32_e64 s[14:15], v32, v6
	s_and_b64 s[0:1], s[18:19], s[0:1]
	s_and_b64 s[16:17], s[16:17], vcc
	s_or_b64 vcc, s[14:15], s[16:17]
	s_or_b64 s[0:1], s[10:11], s[0:1]
	v_addc_co_u32_e64 v15, s[0:1], 0, v15, s[0:1]
	v_addc_co_u32_e32 v14, vcc, 0, v14, vcc
	v_cmp_le_u32_e32 vcc, 16, v2
	v_cmp_le_u32_e64 s[0:1], 17, v5
	v_cmp_eq_f32_e64 s[16:17], v34, v6
	v_cmp_eq_f32_e64 s[18:19], v35, v7
	v_cmp_gt_f32_e64 s[10:11], v35, v7
	v_cmp_gt_f32_e64 s[14:15], v34, v6
	s_and_b64 s[0:1], s[18:19], s[0:1]
	s_and_b64 s[16:17], s[16:17], vcc
	s_or_b64 vcc, s[14:15], s[16:17]
	s_or_b64 s[0:1], s[10:11], s[0:1]
	v_addc_co_u32_e64 v15, s[0:1], 0, v15, s[0:1]
	v_addc_co_u32_e32 v14, vcc, 0, v14, vcc
	v_cmp_le_u32_e32 vcc, 18, v2
	v_cmp_le_u32_e64 s[0:1], 19, v5
	v_cmp_eq_f32_e64 s[16:17], v36, v6
	v_cmp_eq_f32_e64 s[18:19], v37, v7
	v_cmp_gt_f32_e64 s[10:11], v37, v7
	v_cmp_gt_f32_e64 s[14:15], v36, v6
	s_and_b64 s[0:1], s[18:19], s[0:1]
	s_and_b64 s[16:17], s[16:17], vcc
	s_or_b64 vcc, s[14:15], s[16:17]
	s_or_b64 s[0:1], s[10:11], s[0:1]
	v_addc_co_u32_e64 v15, s[0:1], 0, v15, s[0:1]
	v_addc_co_u32_e32 v14, vcc, 0, v14, vcc
	v_cmp_le_u32_e32 vcc, 20, v2
	v_cmp_le_u32_e64 s[0:1], 21, v5
	v_cmp_eq_f32_e64 s[16:17], v38, v6
	v_cmp_eq_f32_e64 s[18:19], v39, v7
	v_cmp_gt_f32_e64 s[10:11], v39, v7
	v_cmp_gt_f32_e64 s[14:15], v38, v6
	s_and_b64 s[0:1], s[18:19], s[0:1]
	s_and_b64 s[16:17], s[16:17], vcc
	s_or_b64 vcc, s[14:15], s[16:17]
	s_or_b64 s[0:1], s[10:11], s[0:1]
	v_addc_co_u32_e64 v15, s[0:1], 0, v15, s[0:1]
	v_addc_co_u32_e32 v14, vcc, 0, v14, vcc
	v_cmp_le_u32_e32 vcc, 22, v2
	v_cmp_le_u32_e64 s[0:1], 23, v5
	v_cmp_eq_f32_e64 s[16:17], v40, v6
	v_cmp_eq_f32_e64 s[18:19], v41, v7
	v_cmp_gt_f32_e64 s[10:11], v41, v7
	v_cmp_gt_f32_e64 s[14:15], v40, v6
	s_and_b64 s[0:1], s[18:19], s[0:1]
	s_and_b64 s[16:17], s[16:17], vcc
	s_or_b64 vcc, s[14:15], s[16:17]
	s_or_b64 s[0:1], s[10:11], s[0:1]
	v_addc_co_u32_e64 v15, s[0:1], 0, v15, s[0:1]
	v_addc_co_u32_e32 v14, vcc, 0, v14, vcc
	v_cmp_le_u32_e32 vcc, 24, v2
	v_cmp_le_u32_e64 s[0:1], 25, v5
	v_cmp_eq_f32_e64 s[16:17], v42, v6
	v_cmp_eq_f32_e64 s[18:19], v43, v7
	v_cmp_gt_f32_e64 s[10:11], v43, v7
	v_cmp_gt_f32_e64 s[14:15], v42, v6
	s_and_b64 s[0:1], s[18:19], s[0:1]
	s_and_b64 s[16:17], s[16:17], vcc
	s_or_b64 vcc, s[14:15], s[16:17]
	s_or_b64 s[0:1], s[10:11], s[0:1]
	v_addc_co_u32_e64 v15, s[0:1], 0, v15, s[0:1]
; __device__ __forceinline__ void attn_item(const P& p, Frame& F, const bool is_s, const int b, const int g, const int c) {
;     ...
;                 { const int q = tid2 >> 3, jg = tid2 & 7; unsigned bits = 0u;
;                   for (int jj = 0; jj < 4; ++jj) { const int j = jg * 4 + jj; const float vj = IMP[q * 33 + j]; int rank = 0;
; #pragma nounroll
;                       for (int i = 0; i < 32; ++i) { const float vi = IMP[q * 33 + i]; rank += (vi > vj || (vi == vj && i < j)) ? 1 : 0; }
;                       if (rank < 16) bits |= 1u << j; }
	v_addc_co_u32_e32 v14, vcc, 0, v14, vcc
	v_cmp_le_u32_e32 vcc, 26, v2
	v_cmp_le_u32_e64 s[0:1], 27, v5
	v_cmp_eq_f32_e64 s[16:17], v44, v6
	v_cmp_eq_f32_e64 s[18:19], v45, v7
	v_cmp_gt_f32_e64 s[10:11], v45, v7
	v_cmp_gt_f32_e64 s[14:15], v44, v6
	s_and_b64 s[0:1], s[18:19], s[0:1]
	s_and_b64 s[16:17], s[16:17], vcc
	s_or_b64 vcc, s[14:15], s[16:17]
	s_or_b64 s[0:1], s[10:11], s[0:1]
	v_addc_co_u32_e64 v15, s[0:1], 0, v15, s[0:1]
	v_addc_co_u32_e32 v14, vcc, 0, v14, vcc
	v_cmp_le_u32_e32 vcc, 28, v2
	v_cmp_le_u32_e64 s[0:1], 29, v5
	v_cmp_eq_f32_e64 s[16:17], v46, v6
	v_cmp_eq_f32_e64 s[18:19], v47, v7
	v_cmp_gt_f32_e64 s[10:11], v47, v7
	v_cmp_gt_f32_e64 s[14:15], v46, v6
	s_and_b64 s[0:1], s[18:19], s[0:1]
	s_and_b64 s[16:17], s[16:17], vcc
	s_or_b64 vcc, s[14:15], s[16:17]
	s_or_b64 s[0:1], s[10:11], s[0:1]
	v_addc_co_u32_e64 v15, s[0:1], 0, v15, s[0:1]
	v_addc_co_u32_e32 v14, vcc, 0, v14, vcc
	v_cmp_le_u32_e32 vcc, 30, v2
	v_cmp_le_u32_e64 s[0:1], 31, v5
	v_cmp_eq_f32_e64 s[16:17], v48, v6
	v_cmp_eq_f32_e64 s[18:19], v49, v7
	v_cmp_gt_f32_e64 s[10:11], v49, v7
	v_cmp_gt_f32_e64 s[14:15], v48, v6
	s_and_b64 s[0:1], s[18:19], s[0:1]
	s_and_b64 s[16:17], s[16:17], vcc
	s_or_b64 vcc, s[14:15], s[16:17]
	s_or_b64 s[0:1], s[10:11], s[0:1]
	v_addc_co_u32_e64 v15, s[0:1], 0, v15, s[0:1]
	v_addc_co_u32_e32 v14, vcc, 0, v14, vcc
	ds_read_b32 v6, v8
	v_mov_b32_e32 v8, v4
	v_mov_b32_e32 v5, v4
	s_mov_b32 s2, 1
	s_mov_b32 s6, 0
	s_waitcnt lgkmcnt(0)
	v_mov_b32_e32 v7, v6
	v_mov_b32_e32 v16, 0
	v_mov_b32_e32 v17, 0
	s_mov_b32 s7, 0
	v_cmp_lt_u32_e32 vcc, 0, v8
	v_cmp_lt_u32_e64 s[0:1], 1, v5
	v_cmp_eq_f32_e64 s[16:17], v18, v6
	v_cmp_eq_f32_e64 s[18:19], v19, v7
	v_cmp_gt_f32_e64 s[10:11], v19, v7
	v_cmp_gt_f32_e64 s[14:15], v18, v6
	s_and_b64 s[0:1], s[18:19], s[0:1]
	s_and_b64 s[16:17], s[16:17], vcc
	s_or_b64 vcc, s[14:15], s[16:17]
	s_or_b64 s[0:1], s[10:11], s[0:1]
	v_addc_co_u32_e64 v17, s[0:1], 0, v17, s[0:1]
	v_addc_co_u32_e32 v16, vcc, 0, v16, vcc
	v_cmp_lt_u32_e32 vcc, 2, v8
	v_cmp_lt_u32_e64 s[0:1], 3, v5
	v_cmp_eq_f32_e64 s[16:17], v20, v6
	v_cmp_eq_f32_e64 s[18:19], v21, v7
	v_cmp_gt_f32_e64 s[10:11], v21, v7
	v_cmp_gt_f32_e64 s[14:15], v20, v6
	s_and_b64 s[0:1], s[18:19], s[0:1]
	s_and_b64 s[16:17], s[16:17], vcc
	s_or_b64 vcc, s[14:15], s[16:17]
	s_or_b64 s[0:1], s[10:11], s[0:1]
	v_addc_co_u32_e64 v17, s[0:1], 0, v17, s[0:1]
	v_addc_co_u32_e32 v16, vcc, 0, v16, vcc
	v_cmp_lt_u32_e32 vcc, 4, v8
	v_cmp_lt_u32_e64 s[0:1], 5, v5
	v_cmp_eq_f32_e64 s[16:17], v22, v6
	v_cmp_eq_f32_e64 s[18:19], v23, v7
	v_cmp_gt_f32_e64 s[10:11], v23, v7
	v_cmp_gt_f32_e64 s[14:15], v22, v6
	s_and_b64 s[0:1], s[18:19], s[0:1]
	s_and_b64 s[16:17], s[16:17], vcc
	s_or_b64 vcc, s[14:15], s[16:17]
	s_or_b64 s[0:1], s[10:11], s[0:1]
	v_addc_co_u32_e64 v17, s[0:1], 0, v17, s[0:1]
	v_addc_co_u32_e32 v16, vcc, 0, v16, vcc
	v_cmp_lt_u32_e32 vcc, 6, v8
	v_cmp_lt_u32_e64 s[0:1], 7, v5
	v_cmp_eq_f32_e64 s[16:17], v24, v6
	v_cmp_eq_f32_e64 s[18:19], v25, v7
	v_cmp_gt_f32_e64 s[10:11], v25, v7
	v_cmp_gt_f32_e64 s[14:15], v24, v6
	s_and_b64 s[0:1], s[18:19], s[0:1]
	s_and_b64 s[16:17], s[16:17], vcc
	s_or_b64 vcc, s[14:15], s[16:17]
	s_or_b64 s[0:1], s[10:11], s[0:1]
	v_addc_co_u32_e64 v17, s[0:1], 0, v17, s[0:1]
	v_addc_co_u32_e32 v16, vcc, 0, v16, vcc
	v_cmp_lt_u32_e32 vcc, 8, v8
	v_cmp_lt_u32_e64 s[0:1], 9, v5
	v_cmp_eq_f32_e64 s[16:17], v26, v6
	v_cmp_eq_f32_e64 s[18:19], v27, v7
	v_cmp_gt_f32_e64 s[10:11], v27, v7
	v_cmp_gt_f32_e64 s[14:15], v26, v6
	s_and_b64 s[0:1], s[18:19], s[0:1]
	s_and_b64 s[16:17], s[16:17], vcc
	s_or_b64 vcc, s[14:15], s[16:17]
	s_or_b64 s[0:1], s[10:11], s[0:1]
	v_addc_co_u32_e64 v17, s[0:1], 0, v17, s[0:1]
	v_addc_co_u32_e32 v16, vcc, 0, v16, vcc
	v_cmp_lt_u32_e32 vcc, 10, v8
	v_cmp_lt_u32_e64 s[0:1], 11, v5
	v_cmp_eq_f32_e64 s[16:17], v28, v6
	v_cmp_eq_f32_e64 s[18:19], v29, v7
	v_cmp_gt_f32_e64 s[10:11], v29, v7
	v_cmp_gt_f32_e64 s[14:15], v28, v6
	s_and_b64 s[0:1], s[18:19], s[0:1]
	s_and_b64 s[16:17], s[16:17], vcc
	s_or_b64 vcc, s[14:15], s[16:17]
	s_or_b64 s[0:1], s[10:11], s[0:1]
	v_addc_co_u32_e64 v17, s[0:1], 0, v17, s[0:1]
	v_addc_co_u32_e32 v16, vcc, 0, v16, vcc
	v_cmp_lt_u32_e32 vcc, 12, v8
	v_cmp_lt_u32_e64 s[0:1], 13, v5
	v_cmp_eq_f32_e64 s[16:17], v30, v6
	v_cmp_eq_f32_e64 s[18:19], v31, v7
	v_cmp_gt_f32_e64 s[10:11], v31, v7
	v_cmp_gt_f32_e64 s[14:15], v30, v6
	s_and_b64 s[0:1], s[18:19], s[0:1]
	s_and_b64 s[16:17], s[16:17], vcc
	s_or_b64 vcc, s[14:15], s[16:17]
	s_or_b64 s[0:1], s[10:11], s[0:1]
	v_addc_co_u32_e64 v17, s[0:1], 0, v17, s[0:1]
	v_addc_co_u32_e32 v16, vcc, 0, v16, vcc
	v_cmp_lt_u32_e32 vcc, 14, v8
	v_cmp_lt_u32_e64 s[0:1], 15, v5
	v_cmp_eq_f32_e64 s[16:17], v32, v6
	v_cmp_eq_f32_e64 s[18:19], v33, v7
	v_cmp_gt_f32_e64 s[10:11], v33, v7
	v_cmp_gt_f32_e64 s[14:15], v32, v6
	s_and_b64 s[0:1], s[18:19], s[0:1]
	s_and_b64 s[16:17], s[16:17], vcc
	s_or_b64 vcc, s[14:15], s[16:17]
	s_or_b64 s[0:1], s[10:11], s[0:1]
	v_addc_co_u32_e64 v17, s[0:1], 0, v17, s[0:1]
	v_addc_co_u32_e32 v16, vcc, 0, v16, vcc
	v_cmp_lt_u32_e32 vcc, 16, v8
	v_cmp_lt_u32_e64 s[0:1], 17, v5
	v_cmp_eq_f32_e64 s[16:17], v34, v6
	v_cmp_eq_f32_e64 s[18:19], v35, v7
	v_cmp_gt_f32_e64 s[10:11], v35, v7
	v_cmp_gt_f32_e64 s[14:15], v34, v6
	s_and_b64 s[0:1], s[18:19], s[0:1]
	s_and_b64 s[16:17], s[16:17], vcc
	s_or_b64 vcc, s[14:15], s[16:17]
	s_or_b64 s[0:1], s[10:11], s[0:1]
	v_addc_co_u32_e64 v17, s[0:1], 0, v17, s[0:1]
	v_addc_co_u32_e32 v16, vcc, 0, v16, vcc
	v_cmp_lt_u32_e32 vcc, 18, v8
	v_cmp_lt_u32_e64 s[0:1], 19, v5
	v_cmp_eq_f32_e64 s[16:17], v36, v6
	v_cmp_eq_f32_e64 s[18:19], v37, v7
	v_cmp_gt_f32_e64 s[10:11], v37, v7
; __device__ __forceinline__ void attn_item(const P& p, Frame& F, const bool is_s, const int b, const int g, const int c) {
;     ...
;                 { const int q = tid2 >> 3, jg = tid2 & 7; unsigned bits = 0u;
;                   for (int jj = 0; jj < 4; ++jj) { const int j = jg * 4 + jj; const float vj = IMP[q * 33 + j]; int rank = 0;
; #pragma nounroll
;                       for (int i = 0; i < 32; ++i) { const float vi = IMP[q * 33 + i]; rank += (vi > vj || (vi == vj && i < j)) ? 1 : 0; }
;                       if (rank < 16) bits |= 1u << j; }
	v_cmp_gt_f32_e64 s[14:15], v36, v6
	s_and_b64 s[0:1], s[18:19], s[0:1]
	s_and_b64 s[16:17], s[16:17], vcc
	s_or_b64 vcc, s[14:15], s[16:17]
	s_or_b64 s[0:1], s[10:11], s[0:1]
	v_addc_co_u32_e64 v17, s[0:1], 0, v17, s[0:1]
	v_addc_co_u32_e32 v16, vcc, 0, v16, vcc
	v_cmp_lt_u32_e32 vcc, 20, v8
	v_cmp_lt_u32_e64 s[0:1], 21, v5
	v_cmp_eq_f32_e64 s[16:17], v38, v6
	v_cmp_eq_f32_e64 s[18:19], v39, v7
	v_cmp_gt_f32_e64 s[10:11], v39, v7
	v_cmp_gt_f32_e64 s[14:15], v38, v6
	s_and_b64 s[0:1], s[18:19], s[0:1]
	s_and_b64 s[16:17], s[16:17], vcc
	s_or_b64 vcc, s[14:15], s[16:17]
	s_or_b64 s[0:1], s[10:11], s[0:1]
	v_addc_co_u32_e64 v17, s[0:1], 0, v17, s[0:1]
	v_addc_co_u32_e32 v16, vcc, 0, v16, vcc
	v_cmp_lt_u32_e32 vcc, 22, v8
	v_cmp_lt_u32_e64 s[0:1], 23, v5
	v_cmp_eq_f32_e64 s[16:17], v40, v6
	v_cmp_eq_f32_e64 s[18:19], v41, v7
	v_cmp_gt_f32_e64 s[10:11], v41, v7
	v_cmp_gt_f32_e64 s[14:15], v40, v6
	s_and_b64 s[0:1], s[18:19], s[0:1]
	s_and_b64 s[16:17], s[16:17], vcc
	s_or_b64 vcc, s[14:15], s[16:17]
	s_or_b64 s[0:1], s[10:11], s[0:1]
	v_addc_co_u32_e64 v17, s[0:1], 0, v17, s[0:1]
	v_addc_co_u32_e32 v16, vcc, 0, v16, vcc
	v_cmp_lt_u32_e32 vcc, 24, v8
	v_cmp_lt_u32_e64 s[0:1], 25, v5
	v_cmp_eq_f32_e64 s[16:17], v42, v6
	v_cmp_eq_f32_e64 s[18:19], v43, v7
	v_cmp_gt_f32_e64 s[10:11], v43, v7
	v_cmp_gt_f32_e64 s[14:15], v42, v6
	s_and_b64 s[0:1], s[18:19], s[0:1]
	s_and_b64 s[16:17], s[16:17], vcc
	s_or_b64 vcc, s[14:15], s[16:17]
	s_or_b64 s[0:1], s[10:11], s[0:1]
	v_addc_co_u32_e64 v17, s[0:1], 0, v17, s[0:1]
	v_addc_co_u32_e32 v16, vcc, 0, v16, vcc
	v_cmp_lt_u32_e32 vcc, 26, v8
	v_cmp_lt_u32_e64 s[0:1], 27, v5
	v_cmp_eq_f32_e64 s[16:17], v44, v6
	v_cmp_eq_f32_e64 s[18:19], v45, v7
	v_cmp_gt_f32_e64 s[10:11], v45, v7
	v_cmp_gt_f32_e64 s[14:15], v44, v6
	s_and_b64 s[0:1], s[18:19], s[0:1]
	s_and_b64 s[16:17], s[16:17], vcc
	s_or_b64 vcc, s[14:15], s[16:17]
	s_or_b64 s[0:1], s[10:11], s[0:1]
	v_addc_co_u32_e64 v17, s[0:1], 0, v17, s[0:1]
	v_addc_co_u32_e32 v16, vcc, 0, v16, vcc
	v_cmp_lt_u32_e32 vcc, 28, v8
	v_cmp_lt_u32_e64 s[0:1], 29, v5
	v_cmp_eq_f32_e64 s[16:17], v46, v6
	v_cmp_eq_f32_e64 s[18:19], v47, v7
	v_cmp_gt_f32_e64 s[10:11], v47, v7
	v_cmp_gt_f32_e64 s[14:15], v46, v6
	s_and_b64 s[0:1], s[18:19], s[0:1]
	s_and_b64 s[16:17], s[16:17], vcc
	s_or_b64 vcc, s[14:15], s[16:17]
	s_or_b64 s[0:1], s[10:11], s[0:1]
	v_addc_co_u32_e64 v17, s[0:1], 0, v17, s[0:1]
	v_addc_co_u32_e32 v16, vcc, 0, v16, vcc
	v_cmp_lt_u32_e32 vcc, 30, v8
	v_cmp_lt_u32_e64 s[0:1], 31, v5
	v_cmp_eq_f32_e64 s[16:17], v48, v6
	v_cmp_eq_f32_e64 s[18:19], v49, v7
	v_cmp_gt_f32_e64 s[10:11], v49, v7
	v_cmp_gt_f32_e64 s[14:15], v48, v6
	s_and_b64 s[0:1], s[18:19], s[0:1]
	s_and_b64 s[16:17], s[16:17], vcc
	s_or_b64 vcc, s[14:15], s[16:17]
	s_or_b64 s[0:1], s[10:11], s[0:1]
	v_addc_co_u32_e64 v17, s[0:1], 0, v17, s[0:1]
	v_addc_co_u32_e32 v16, vcc, 0, v16, vcc
	v_lshl_add_u32 v4, v1, 2, v11
	ds_read_b32 v4, v4
	v_mov_b32_e32 v6, v1
	s_mov_b32 s2, 1
	s_mov_b32 s6, 0
	v_mov_b32_e32 v7, 0
	s_waitcnt lgkmcnt(0)
	v_mov_b32_e32 v5, v4
	v_mov_b32_e32 v8, 0
	s_mov_b32 s7, 0
	v_cmp_lt_u32_e32 vcc, 0, v6
	v_cmp_lt_u32_e64 s[0:1], 1, v1
	v_cmp_eq_f32_e64 s[16:17], v18, v4
	v_cmp_eq_f32_e64 s[18:19], v19, v5
	v_cmp_gt_f32_e64 s[10:11], v19, v5
	v_cmp_gt_f32_e64 s[14:15], v18, v4
	s_and_b64 s[0:1], s[18:19], s[0:1]
	s_and_b64 s[16:17], s[16:17], vcc
	s_or_b64 vcc, s[14:15], s[16:17]
	s_or_b64 s[0:1], s[10:11], s[0:1]
	v_addc_co_u32_e64 v8, s[0:1], 0, v8, s[0:1]
	v_addc_co_u32_e32 v7, vcc, 0, v7, vcc
	v_cmp_lt_u32_e32 vcc, 2, v6
	v_cmp_lt_u32_e64 s[0:1], 3, v1
	v_cmp_eq_f32_e64 s[16:17], v20, v4
	v_cmp_eq_f32_e64 s[18:19], v21, v5
	v_cmp_gt_f32_e64 s[10:11], v21, v5
	v_cmp_gt_f32_e64 s[14:15], v20, v4
	s_and_b64 s[0:1], s[18:19], s[0:1]
	s_and_b64 s[16:17], s[16:17], vcc
	s_or_b64 vcc, s[14:15], s[16:17]
	s_or_b64 s[0:1], s[10:11], s[0:1]
	v_addc_co_u32_e64 v8, s[0:1], 0, v8, s[0:1]
	v_addc_co_u32_e32 v7, vcc, 0, v7, vcc
	v_cmp_lt_u32_e32 vcc, 4, v6
	v_cmp_lt_u32_e64 s[0:1], 5, v1
	v_cmp_eq_f32_e64 s[16:17], v22, v4
	v_cmp_eq_f32_e64 s[18:19], v23, v5
	v_cmp_gt_f32_e64 s[10:11], v23, v5
	v_cmp_gt_f32_e64 s[14:15], v22, v4
	s_and_b64 s[0:1], s[18:19], s[0:1]
	s_and_b64 s[16:17], s[16:17], vcc
	s_or_b64 vcc, s[14:15], s[16:17]
	s_or_b64 s[0:1], s[10:11], s[0:1]
	v_addc_co_u32_e64 v8, s[0:1], 0, v8, s[0:1]
	v_addc_co_u32_e32 v7, vcc, 0, v7, vcc
	v_cmp_lt_u32_e32 vcc, 6, v6
	v_cmp_lt_u32_e64 s[0:1], 7, v1
	v_cmp_eq_f32_e64 s[16:17], v24, v4
	v_cmp_eq_f32_e64 s[18:19], v25, v5
	v_cmp_gt_f32_e64 s[10:11], v25, v5
	v_cmp_gt_f32_e64 s[14:15], v24, v4
	s_and_b64 s[0:1], s[18:19], s[0:1]
	s_and_b64 s[16:17], s[16:17], vcc
	s_or_b64 vcc, s[14:15], s[16:17]
	s_or_b64 s[0:1], s[10:11], s[0:1]
	v_addc_co_u32_e64 v8, s[0:1], 0, v8, s[0:1]
	v_addc_co_u32_e32 v7, vcc, 0, v7, vcc
	v_cmp_lt_u32_e32 vcc, 8, v6
	v_cmp_lt_u32_e64 s[0:1], 9, v1
	v_cmp_eq_f32_e64 s[16:17], v26, v4
	v_cmp_eq_f32_e64 s[18:19], v27, v5
	v_cmp_gt_f32_e64 s[10:11], v27, v5
	v_cmp_gt_f32_e64 s[14:15], v26, v4
	s_and_b64 s[0:1], s[18:19], s[0:1]
	s_and_b64 s[16:17], s[16:17], vcc
	s_or_b64 vcc, s[14:15], s[16:17]
	s_or_b64 s[0:1], s[10:11], s[0:1]
	v_addc_co_u32_e64 v8, s[0:1], 0, v8, s[0:1]
	v_addc_co_u32_e32 v7, vcc, 0, v7, vcc
	v_cmp_lt_u32_e32 vcc, 10, v6
	v_cmp_lt_u32_e64 s[0:1], 11, v1
	v_cmp_eq_f32_e64 s[16:17], v28, v4
	v_cmp_eq_f32_e64 s[18:19], v29, v5
	v_cmp_gt_f32_e64 s[10:11], v29, v5
; __device__ __forceinline__ void attn_item(const P& p, Frame& F, const bool is_s, const int b, const int g, const int c) {
;     ...
;                 { const int q = tid2 >> 3, jg = tid2 & 7; unsigned bits = 0u;
;                   for (int jj = 0; jj < 4; ++jj) { const int j = jg * 4 + jj; const float vj = IMP[q * 33 + j]; int rank = 0;
; #pragma nounroll
;                       for (int i = 0; i < 32; ++i) { const float vi = IMP[q * 33 + i]; rank += (vi > vj || (vi == vj && i < j)) ? 1 : 0; }
;                       if (rank < 16) bits |= 1u << j; }
;                   if (bits) atomicOr((unsigned*)&SELM[q], bits); }
;                 __syncthreads();
;                 selm = SELM[iq];
	v_cmp_gt_f32_e64 s[14:15], v28, v4
	s_and_b64 s[0:1], s[18:19], s[0:1]
	s_and_b64 s[16:17], s[16:17], vcc
	s_or_b64 vcc, s[14:15], s[16:17]
	s_or_b64 s[0:1], s[10:11], s[0:1]
	v_addc_co_u32_e64 v8, s[0:1], 0, v8, s[0:1]
	v_addc_co_u32_e32 v7, vcc, 0, v7, vcc
	v_cmp_lt_u32_e32 vcc, 12, v6
	v_cmp_lt_u32_e64 s[0:1], 13, v1
	v_cmp_eq_f32_e64 s[16:17], v30, v4
	v_cmp_eq_f32_e64 s[18:19], v31, v5
	v_cmp_gt_f32_e64 s[10:11], v31, v5
	v_cmp_gt_f32_e64 s[14:15], v30, v4
	s_and_b64 s[0:1], s[18:19], s[0:1]
	s_and_b64 s[16:17], s[16:17], vcc
	s_or_b64 vcc, s[14:15], s[16:17]
	s_or_b64 s[0:1], s[10:11], s[0:1]
	v_addc_co_u32_e64 v8, s[0:1], 0, v8, s[0:1]
	v_addc_co_u32_e32 v7, vcc, 0, v7, vcc
	v_cmp_lt_u32_e32 vcc, 14, v6
	v_cmp_lt_u32_e64 s[0:1], 15, v1
	v_cmp_eq_f32_e64 s[16:17], v32, v4
	v_cmp_eq_f32_e64 s[18:19], v33, v5
	v_cmp_gt_f32_e64 s[10:11], v33, v5
	v_cmp_gt_f32_e64 s[14:15], v32, v4
	s_and_b64 s[0:1], s[18:19], s[0:1]
	s_and_b64 s[16:17], s[16:17], vcc
	s_or_b64 vcc, s[14:15], s[16:17]
	s_or_b64 s[0:1], s[10:11], s[0:1]
	v_addc_co_u32_e64 v8, s[0:1], 0, v8, s[0:1]
	v_addc_co_u32_e32 v7, vcc, 0, v7, vcc
	v_cmp_lt_u32_e32 vcc, 16, v6
	v_cmp_lt_u32_e64 s[0:1], 17, v1
	v_cmp_eq_f32_e64 s[16:17], v34, v4
	v_cmp_eq_f32_e64 s[18:19], v35, v5
	v_cmp_gt_f32_e64 s[10:11], v35, v5
	v_cmp_gt_f32_e64 s[14:15], v34, v4
	s_and_b64 s[0:1], s[18:19], s[0:1]
	s_and_b64 s[16:17], s[16:17], vcc
	s_or_b64 vcc, s[14:15], s[16:17]
	s_or_b64 s[0:1], s[10:11], s[0:1]
	v_addc_co_u32_e64 v8, s[0:1], 0, v8, s[0:1]
	v_addc_co_u32_e32 v7, vcc, 0, v7, vcc
	v_cmp_lt_u32_e32 vcc, 18, v6
	v_cmp_lt_u32_e64 s[0:1], 19, v1
	v_cmp_eq_f32_e64 s[16:17], v36, v4
	v_cmp_eq_f32_e64 s[18:19], v37, v5
	v_cmp_gt_f32_e64 s[10:11], v37, v5
	v_cmp_gt_f32_e64 s[14:15], v36, v4
	s_and_b64 s[0:1], s[18:19], s[0:1]
	s_and_b64 s[16:17], s[16:17], vcc
	s_or_b64 vcc, s[14:15], s[16:17]
	s_or_b64 s[0:1], s[10:11], s[0:1]
	v_addc_co_u32_e64 v8, s[0:1], 0, v8, s[0:1]
	v_addc_co_u32_e32 v7, vcc, 0, v7, vcc
	v_cmp_lt_u32_e32 vcc, 20, v6
	v_cmp_lt_u32_e64 s[0:1], 21, v1
	v_cmp_eq_f32_e64 s[16:17], v38, v4
	v_cmp_eq_f32_e64 s[18:19], v39, v5
	v_cmp_gt_f32_e64 s[10:11], v39, v5
	v_cmp_gt_f32_e64 s[14:15], v38, v4
	s_and_b64 s[0:1], s[18:19], s[0:1]
	s_and_b64 s[16:17], s[16:17], vcc
	s_or_b64 vcc, s[14:15], s[16:17]
	s_or_b64 s[0:1], s[10:11], s[0:1]
	v_addc_co_u32_e64 v8, s[0:1], 0, v8, s[0:1]
	v_addc_co_u32_e32 v7, vcc, 0, v7, vcc
	v_cmp_lt_u32_e32 vcc, 22, v6
	v_cmp_lt_u32_e64 s[0:1], 23, v1
	v_cmp_eq_f32_e64 s[16:17], v40, v4
	v_cmp_eq_f32_e64 s[18:19], v41, v5
	v_cmp_gt_f32_e64 s[10:11], v41, v5
	v_cmp_gt_f32_e64 s[14:15], v40, v4
	s_and_b64 s[0:1], s[18:19], s[0:1]
	s_and_b64 s[16:17], s[16:17], vcc
	s_or_b64 vcc, s[14:15], s[16:17]
	s_or_b64 s[0:1], s[10:11], s[0:1]
	v_addc_co_u32_e64 v8, s[0:1], 0, v8, s[0:1]
	v_addc_co_u32_e32 v7, vcc, 0, v7, vcc
	v_cmp_lt_u32_e32 vcc, 24, v6
	v_cmp_lt_u32_e64 s[0:1], 25, v1
	v_cmp_eq_f32_e64 s[16:17], v42, v4
	v_cmp_eq_f32_e64 s[18:19], v43, v5
	v_cmp_gt_f32_e64 s[10:11], v43, v5
	v_cmp_gt_f32_e64 s[14:15], v42, v4
	s_and_b64 s[0:1], s[18:19], s[0:1]
	s_and_b64 s[16:17], s[16:17], vcc
	s_or_b64 vcc, s[14:15], s[16:17]
	s_or_b64 s[0:1], s[10:11], s[0:1]
	v_addc_co_u32_e64 v8, s[0:1], 0, v8, s[0:1]
	v_addc_co_u32_e32 v7, vcc, 0, v7, vcc
	v_cmp_lt_u32_e32 vcc, 26, v6
	v_cmp_lt_u32_e64 s[0:1], 27, v1
	v_cmp_eq_f32_e64 s[16:17], v44, v4
	v_cmp_eq_f32_e64 s[18:19], v45, v5
	v_cmp_gt_f32_e64 s[10:11], v45, v5
	v_cmp_gt_f32_e64 s[14:15], v44, v4
	s_and_b64 s[0:1], s[18:19], s[0:1]
	s_and_b64 s[16:17], s[16:17], vcc
	s_or_b64 vcc, s[14:15], s[16:17]
	s_or_b64 s[0:1], s[10:11], s[0:1]
	v_addc_co_u32_e64 v8, s[0:1], 0, v8, s[0:1]
	v_addc_co_u32_e32 v7, vcc, 0, v7, vcc
	v_cmp_lt_u32_e32 vcc, 28, v6
	v_cmp_lt_u32_e64 s[0:1], 29, v1
	v_cmp_eq_f32_e64 s[16:17], v46, v4
	v_cmp_eq_f32_e64 s[18:19], v47, v5
	v_cmp_gt_f32_e64 s[10:11], v47, v5
	v_cmp_gt_f32_e64 s[14:15], v46, v4
	s_and_b64 s[0:1], s[18:19], s[0:1]
	s_and_b64 s[16:17], s[16:17], vcc
	s_or_b64 vcc, s[14:15], s[16:17]
	s_or_b64 s[0:1], s[10:11], s[0:1]
	v_addc_co_u32_e64 v8, s[0:1], 0, v8, s[0:1]
	v_addc_co_u32_e32 v7, vcc, 0, v7, vcc
	v_cmp_lt_u32_e32 vcc, 30, v6
	v_cmp_lt_u32_e64 s[0:1], 31, v1
	v_cmp_eq_f32_e64 s[16:17], v48, v4
	v_cmp_eq_f32_e64 s[18:19], v49, v5
	v_cmp_gt_f32_e64 s[10:11], v49, v5
	v_cmp_gt_f32_e64 s[14:15], v48, v4
	s_and_b64 s[0:1], s[18:19], s[0:1]
	s_and_b64 s[16:17], s[16:17], vcc
	s_or_b64 vcc, s[14:15], s[16:17]
	s_or_b64 s[0:1], s[10:11], s[0:1]
	v_addc_co_u32_e64 v8, s[0:1], 0, v8, s[0:1]
	v_addc_co_u32_e32 v7, vcc, 0, v7, vcc
	v_add_u32_e32 v1, v12, v13
	v_add_u32_e32 v4, v14, v15
	v_lshlrev_b32_e64 v5, v2, 1
	v_cmp_gt_u32_e32 vcc, 16, v1
	v_add_u32_e32 v6, v16, v17
	s_nop 0
	v_cndmask_b32_e32 v1, 0, v5, vcc
	v_lshlrev_b32_e64 v5, v2, 2
	v_cmp_gt_u32_e32 vcc, 16, v4
	s_nop 1
	v_cndmask_b32_e32 v4, 0, v5, vcc
	v_or_b32_e32 v1, v4, v1
	v_lshlrev_b32_e64 v4, v2, 4
	v_add_u32_e32 v5, v7, v8
	v_cmp_gt_u32_e32 vcc, 16, v6
	v_lshlrev_b32_e64 v2, v2, 8
	s_nop 0
	v_cndmask_b32_e32 v4, 0, v4, vcc
	v_cmp_gt_u32_e32 vcc, 16, v5
	s_nop 1
	v_cndmask_b32_e32 v2, 0, v2, vcc
	v_or3_b32 v1, v1, v4, v2
	v_cmp_ne_u32_e32 vcc, 0, v1
	s_and_saveexec_b64 s[0:1], vcc
	v_lshl_add_u32 v2, v10, 2, 0
	v_add_u32_e32 v2, 0x19000, v2
	ds_or_b32 v2, v1
	s_or_b64 exec, exec, s[0:1]
	s_waitcnt lgkmcnt(0)
	s_barrier
	ds_read_b32 v1, v231
	s_mov_b64 s[0:1], 0

; __device__ __forceinline__ unsigned pk2(float lo, float hi) { const bfx2 b = __builtin_convertvector((f32x2){lo, hi}, bfx2); return __builtin_bit_cast(unsigned, b); }
; __device__ __forceinline__ float bflo(unsigned w) { return __uint_as_float(w << 16); }
; __device__ __forceinline__ float bfhi(unsigned w) { return __uint_as_float(w & 0xffff0000u); }
; #define PKP(var) unsigned char* var; { int l_ = threadIdx.x; asm volatile("" : "+v"(l_)); var = ws + WS_PARK + (size_t)(item8 + (l_ >> 6)) * 8192 + (l_ & 63) * 16; }
; __device__ __forceinline__ void attn_item(const P& p, Frame& F, const bool is_s, const int b, const int g, const int c) {
;     ...
;             if (ph == 3) { const float lt = l + __shfl_xor(l, 32); const float sc = lt > 0.f ? NGt[(size_t)mrow * 32 + 1 * 8 + h] / lt : 0.f;
;                 if (qvalid) { PKP(PK);
; #pragma unroll
;                     for (int dt = 0; dt < 4; ++dt)
; #pragma unroll
;                         for (int hf = 0; hf < 2; ++hf) { u32x4* yp = (u32x4*)(PK + (2 * dt + hf) * 1024); const u32x4 o = *yp; u32x4 w;
;                             w.x = pk2(bflo(o.x) + ot[dt][8 * hf + 0] * sc, bfhi(o.x) + ot[dt][8 * hf + 1] * sc); w.y = pk2(bflo(o.y) + ot[dt][8 * hf + 2] * sc, bfhi(o.y) + ot[dt][8 * hf + 3] * sc);
;                             w.z = pk2(bflo(o.z) + ot[dt][8 * hf + 4] * sc, bfhi(o.z) + ot[dt][8 * hf + 5] * sc); w.w = pk2(bflo(o.w) + ot[dt][8 * hf + 6] * sc, bfhi(o.w) + ot[dt][8 * hf + 7] * sc); *yp = w; } } }
.LBB0_2003:
	s_cmp_gt_u32 s5, 1
	s_cselect_b64 s[16:17], -1, 0
	s_cmp_lt_u32 s5, 2
	s_cselect_b64 s[18:19], -1, 0
	s_and_b64 vcc, exec, s[18:19]
	s_cbranch_vccnz .LBB0_2011
	s_cmp_lg_u32 s5, 3
	s_cbranch_scc1 .LBB0_2010
	v_mov_b32_e32 v8, 0
	s_and_saveexec_b64 s[0:1], s[22:23]
	v_mov_b32_e32 v1, v0
	v_readlane_b32 s2, v252, 13
	v_ashrrev_i32_e32 v2, 6, v1
	v_readlane_b32 s6, v254, 49
	v_add_u32_e32 v4, s2, v2
	v_ashrrev_i32_e32 v5, 31, v4
	v_lshlrev_b64 v[4:5], 13, v[4:5]
	v_readlane_b32 s7, v254, 50
	v_lshlrev_b32_e32 v1, 4, v1
	v_and_b32_e32 v2, 0x3f0, v1
	v_lshl_add_u64 v[4:5], s[6:7], 0, v[4:5]
	s_movk_i32 s2, 0x1000
	v_lshl_add_u64 v[4:5], v[4:5], 0, v[2:3]
	s_nop 0
	v_add_co_u32_e32 v10, vcc, s2, v4
	s_nop 1
	v_addc_co_u32_e32 v11, vcc, 0, v5, vcc
	global_load_dword v2, v[202:203], off offset:32
	global_load_dwordx4 v[114:117], v[4:5], off
	global_load_dwordx4 v[118:121], v[4:5], off offset:1024
	global_load_dwordx4 v[122:125], v[4:5], off offset:2048
	global_load_dwordx4 v[126:129], v[4:5], off offset:3072
	global_load_dwordx4 v[130:133], v[10:11], off
	global_load_dwordx4 v[134:137], v[10:11], off offset:1024
	global_load_dwordx4 v[138:141], v[10:11], off offset:2048
	global_load_dwordx4 v[142:145], v[10:11], off offset:3072
	s_or_b64 exec, exec, s[0:1]
	v_and_b32_e32 v7, 64, v221
	v_xor_b32_e32 v1, 32, v221
	v_add_u32_e32 v7, 64, v7
	v_cmp_lt_i32_e32 vcc, v1, v7
	s_nop 1
	v_cndmask_b32_e32 v1, v221, v1, vcc
	v_lshlrev_b32_e32 v1, 2, v1
	ds_bpermute_b32 v1, v1, v240
	s_waitcnt lgkmcnt(0)
	v_add_f32_e32 v1, v240, v1
	v_cmp_lt_f32_e32 vcc, 0, v1
	s_and_saveexec_b64 s[0:1], vcc
	s_waitcnt vmcnt(0)
	v_div_scale_f32 v12, s[6:7], v1, v1, v2
	v_rcp_f32_e32 v13, v12
	v_div_scale_f32 v14, vcc, v2, v1, v2
	v_fma_f32 v15, -v12, v13, 1.0
	v_fmac_f32_e32 v13, v15, v13
	v_mul_f32_e32 v15, v14, v13
	v_fma_f32 v8, -v12, v15, v14
	v_fmac_f32_e32 v15, v8, v13
	v_fma_f32 v12, -v12, v15, v14
	v_div_fmas_f32 v12, v12, v13, v15
	v_div_fixup_f32 v8, v12, v1, v2
	s_or_b64 exec, exec, s[0:1]
	s_and_saveexec_b64 s[0:1], s[22:23]
	s_cbranch_execz .LBB0_2009
; __device__ __forceinline__ unsigned pk2(float lo, float hi) { const bfx2 b = __builtin_convertvector((f32x2){lo, hi}, bfx2); return __builtin_bit_cast(unsigned, b); }
; __device__ __forceinline__ float bflo(unsigned w) { return __uint_as_float(w << 16); }
; __device__ __forceinline__ float bfhi(unsigned w) { return __uint_as_float(w & 0xffff0000u); }
; __device__ __forceinline__ void attn_item(const P& p, Frame& F, const bool is_s, const int b, const int g, const int c) {
;     ...
;                         for (int hf = 0; hf < 2; ++hf) { u32x4* yp = (u32x4*)(PK + (2 * dt + hf) * 1024); const u32x4 o = *yp; u32x4 w;
;                             w.x = pk2(bflo(o.x) + ot[dt][8 * hf + 0] * sc, bfhi(o.x) + ot[dt][8 * hf + 1] * sc); w.y = pk2(bflo(o.y) + ot[dt][8 * hf + 2] * sc, bfhi(o.y) + ot[dt][8 * hf + 3] * sc);
;                             w.z = pk2(bflo(o.z) + ot[dt][8 * hf + 4] * sc, bfhi(o.z) + ot[dt][8 * hf + 5] * sc); w.w = pk2(bflo(o.w) + ot[dt][8 * hf + 6] * sc, bfhi(o.w) + ot[dt][8 * hf + 7] * sc); *yp = w; } } }
	s_waitcnt vmcnt(0)
	v_lshlrev_b32_e32 v6, 16, v114
	v_and_b32_e32 v7, 0xffff0000, v114
	v_fma_f32 v6, v66, v8, v6
	v_fma_f32 v7, v67, v8, v7
	s_nop 0
	v_cvt_pk_bf16_f32 v114, v6, v7
	v_lshlrev_b32_e32 v12, 16, v115
	v_and_b32_e32 v13, 0xffff0000, v115
	v_fma_f32 v12, v68, v8, v12
	v_fma_f32 v13, v69, v8, v13
	s_nop 0
	v_cvt_pk_bf16_f32 v115, v12, v13
	v_lshlrev_b32_e32 v14, 16, v116
	v_and_b32_e32 v15, 0xffff0000, v116
	v_fma_f32 v14, v70, v8, v14
	v_fma_f32 v15, v71, v8, v15
	s_nop 0
	v_cvt_pk_bf16_f32 v116, v14, v15
	v_lshlrev_b32_e32 v16, 16, v117
	v_and_b32_e32 v17, 0xffff0000, v117
	v_fma_f32 v16, v72, v8, v16
	v_fma_f32 v17, v73, v8, v17
	s_nop 0
	v_cvt_pk_bf16_f32 v117, v16, v17
	global_store_dwordx4 v[4:5], v[114:117], off
	v_lshlrev_b32_e32 v6, 16, v118
	v_and_b32_e32 v7, 0xffff0000, v118
	v_fma_f32 v6, v74, v8, v6
	v_fma_f32 v7, v75, v8, v7
	s_nop 0
	v_cvt_pk_bf16_f32 v118, v6, v7
	v_lshlrev_b32_e32 v12, 16, v119
	v_and_b32_e32 v13, 0xffff0000, v119
	v_fma_f32 v12, v76, v8, v12
	v_fma_f32 v13, v77, v8, v13
	s_nop 0
	v_cvt_pk_bf16_f32 v119, v12, v13
	v_lshlrev_b32_e32 v14, 16, v120
	v_and_b32_e32 v15, 0xffff0000, v120
	v_fma_f32 v14, v78, v8, v14
	v_fma_f32 v15, v79, v8, v15
	s_nop 0
	v_cvt_pk_bf16_f32 v120, v14, v15
	v_lshlrev_b32_e32 v16, 16, v121
	v_and_b32_e32 v17, 0xffff0000, v121
	v_fma_f32 v16, v80, v8, v16
	v_fma_f32 v17, v81, v8, v17
	s_nop 0
	v_cvt_pk_bf16_f32 v121, v16, v17
	global_store_dwordx4 v[4:5], v[118:121], off offset:1024
	v_lshlrev_b32_e32 v6, 16, v122
	v_and_b32_e32 v7, 0xffff0000, v122
	v_fma_f32 v6, v50, v8, v6
	v_fma_f32 v7, v51, v8, v7
	s_nop 0
	v_cvt_pk_bf16_f32 v122, v6, v7
	v_lshlrev_b32_e32 v12, 16, v123
	v_and_b32_e32 v13, 0xffff0000, v123
	v_fma_f32 v12, v52, v8, v12
	v_fma_f32 v13, v53, v8, v13
	s_nop 0
	v_cvt_pk_bf16_f32 v123, v12, v13
	v_lshlrev_b32_e32 v14, 16, v124
	v_and_b32_e32 v15, 0xffff0000, v124
	v_fma_f32 v14, v54, v8, v14
	v_fma_f32 v15, v55, v8, v15
	s_nop 0
	v_cvt_pk_bf16_f32 v124, v14, v15
	v_lshlrev_b32_e32 v16, 16, v125
	v_and_b32_e32 v17, 0xffff0000, v125
	v_fma_f32 v16, v56, v8, v16
	v_fma_f32 v17, v57, v8, v17
	s_nop 0
	v_cvt_pk_bf16_f32 v125, v16, v17
	global_store_dwordx4 v[4:5], v[122:125], off offset:2048
	v_lshlrev_b32_e32 v6, 16, v126
	v_and_b32_e32 v7, 0xffff0000, v126
	v_fma_f32 v6, v58, v8, v6
	v_fma_f32 v7, v59, v8, v7
	s_nop 0
	v_cvt_pk_bf16_f32 v126, v6, v7
	v_lshlrev_b32_e32 v12, 16, v127
	v_and_b32_e32 v13, 0xffff0000, v127
	v_fma_f32 v12, v60, v8, v12
	v_fma_f32 v13, v61, v8, v13
	s_nop 0
	v_cvt_pk_bf16_f32 v127, v12, v13
	v_lshlrev_b32_e32 v14, 16, v128
	v_and_b32_e32 v15, 0xffff0000, v128
	v_fma_f32 v14, v62, v8, v14
	v_fma_f32 v15, v63, v8, v15
	s_nop 0
	v_cvt_pk_bf16_f32 v128, v14, v15
	v_lshlrev_b32_e32 v16, 16, v129
	v_and_b32_e32 v17, 0xffff0000, v129
	v_fma_f32 v16, v64, v8, v16
	v_fma_f32 v17, v65, v8, v17
	s_nop 0
	v_cvt_pk_bf16_f32 v129, v16, v17
	global_store_dwordx4 v[4:5], v[126:129], off offset:3072
	v_lshlrev_b32_e32 v6, 16, v130
	v_and_b32_e32 v7, 0xffff0000, v130
	v_fma_f32 v6, v34, v8, v6
	v_fma_f32 v7, v35, v8, v7
	s_nop 0
	v_cvt_pk_bf16_f32 v130, v6, v7
	v_lshlrev_b32_e32 v12, 16, v131
	v_and_b32_e32 v13, 0xffff0000, v131
	v_fma_f32 v12, v36, v8, v12
	v_fma_f32 v13, v37, v8, v13
	s_nop 0
	v_cvt_pk_bf16_f32 v131, v12, v13
	v_lshlrev_b32_e32 v14, 16, v132
	v_and_b32_e32 v15, 0xffff0000, v132
	v_fma_f32 v14, v38, v8, v14
	v_fma_f32 v15, v39, v8, v15
	s_nop 0
	v_cvt_pk_bf16_f32 v132, v14, v15
	v_lshlrev_b32_e32 v16, 16, v133
	v_and_b32_e32 v17, 0xffff0000, v133
	v_fma_f32 v16, v40, v8, v16
	v_fma_f32 v17, v41, v8, v17
	s_nop 0
	v_cvt_pk_bf16_f32 v133, v16, v17
	global_store_dwordx4 v[10:11], v[130:133], off
	v_lshlrev_b32_e32 v6, 16, v134
	v_and_b32_e32 v7, 0xffff0000, v134
	v_fma_f32 v6, v42, v8, v6
	v_fma_f32 v7, v43, v8, v7
	s_nop 0
	v_cvt_pk_bf16_f32 v134, v6, v7
	v_lshlrev_b32_e32 v12, 16, v135
	v_and_b32_e32 v13, 0xffff0000, v135
	v_fma_f32 v12, v44, v8, v12
	v_fma_f32 v13, v45, v8, v13
	s_nop 0
	v_cvt_pk_bf16_f32 v135, v12, v13
	v_lshlrev_b32_e32 v14, 16, v136
	v_and_b32_e32 v15, 0xffff0000, v136
	v_fma_f32 v14, v46, v8, v14
	v_fma_f32 v15, v47, v8, v15
	s_nop 0
	v_cvt_pk_bf16_f32 v136, v14, v15
	v_lshlrev_b32_e32 v16, 16, v137
	v_and_b32_e32 v17, 0xffff0000, v137
	v_fma_f32 v16, v48, v8, v16
	v_fma_f32 v17, v49, v8, v17
	s_nop 0
	v_cvt_pk_bf16_f32 v137, v16, v17
	global_store_dwordx4 v[10:11], v[134:137], off offset:1024
	v_lshlrev_b32_e32 v6, 16, v138
	v_and_b32_e32 v7, 0xffff0000, v138
	v_fma_f32 v6, v18, v8, v6
	v_fma_f32 v7, v19, v8, v7
	s_nop 0
	v_cvt_pk_bf16_f32 v138, v6, v7
	v_lshlrev_b32_e32 v12, 16, v139
	v_and_b32_e32 v13, 0xffff0000, v139
	v_fma_f32 v12, v20, v8, v12
	v_fma_f32 v13, v21, v8, v13
	s_nop 0
	v_cvt_pk_bf16_f32 v139, v12, v13
	v_lshlrev_b32_e32 v14, 16, v140
	v_and_b32_e32 v15, 0xffff0000, v140
	v_fma_f32 v14, v22, v8, v14
	v_fma_f32 v15, v23, v8, v15
	s_nop 0
	v_cvt_pk_bf16_f32 v140, v14, v15
	v_lshlrev_b32_e32 v16, 16, v141
	v_and_b32_e32 v17, 0xffff0000, v141
	v_fma_f32 v16, v24, v8, v16
	v_fma_f32 v17, v25, v8, v17
	s_nop 0
	v_cvt_pk_bf16_f32 v141, v16, v17
	global_store_dwordx4 v[10:11], v[138:141], off offset:2048
	v_lshlrev_b32_e32 v6, 16, v142
	v_and_b32_e32 v7, 0xffff0000, v142
	v_fma_f32 v6, v26, v8, v6
	v_fma_f32 v7, v27, v8, v7
	s_nop 0
	v_cvt_pk_bf16_f32 v142, v6, v7
	v_lshlrev_b32_e32 v12, 16, v143
	v_and_b32_e32 v13, 0xffff0000, v143
	v_fma_f32 v12, v28, v8, v12
	v_fma_f32 v13, v29, v8, v13
	s_nop 0
	v_cvt_pk_bf16_f32 v143, v12, v13
	v_lshlrev_b32_e32 v14, 16, v144
	v_and_b32_e32 v15, 0xffff0000, v144
	v_fma_f32 v14, v30, v8, v14
	v_fma_f32 v15, v31, v8, v15
	s_nop 0
	v_cvt_pk_bf16_f32 v144, v14, v15
	v_lshlrev_b32_e32 v16, 16, v145
	v_and_b32_e32 v17, 0xffff0000, v145
	v_fma_f32 v16, v32, v8, v16
	v_fma_f32 v17, v33, v8, v17
	s_nop 0
	v_cvt_pk_bf16_f32 v145, v16, v17
	global_store_dwordx4 v[10:11], v[142:145], off offset:3072

; #define LAS __attribute__((address_space(3)))
; template <int MODE> ...
;     ...
;         } else if (interior) {
;             const LAS float* bp = btab + (t - kp0 - (32 * nt + 4 * half));
; #pragma unroll
;             for (int rg = 0; rg < 4; ++rg) { float bv[4];
; #pragma unroll
;                 for (int r4 = 0; r4 < 4; ++r4) bv[r4] = *(bp - (8 * rg + r4));
; #pragma unroll
;                 for (int r4 = 0; r4 < 4; ++r4) asm volatile("" : "+v"(bv[r4]));
; #pragma unroll
;                 for (int r4 = 0; r4 < 4; ++r4) { const int r = 4 * rg + r4; const float s2 = st[r] * SC + bv[r4]; st[r] = s2; mloc = fmaxf(mloc, s2); } }
;             if (!lanevalid) mloc = NEG_S;
.LBB0_2110:
	s_andn2_saveexec_b64 s[94:95], s[94:95]
	s_cbranch_execz .LBB0_2112
	v_add_u32_e32 v16, s26, v242
	v_sub_u32_e32 v16, v228, v16
	v_lshl_add_u32 v216, v16, 2, s58
	v_add_u32_e32 v216, 0x8794, v216
	ds_read2_b32 v[114:115], v216 offset0:26 offset1:27
	ds_read2_b32 v[116:117], v216 offset0:24 offset1:25
	ds_read2_b32 v[118:119], v216 offset0:18 offset1:19
	ds_read2_b32 v[120:121], v216 offset0:16 offset1:17
	ds_read2_b32 v[122:123], v216 offset0:10 offset1:11
	ds_read2_b32 v[124:125], v216 offset0:8 offset1:9
	ds_read2_b32 v[126:127], v216 offset0:2 offset1:3
	ds_read2_b32 v[128:129], v216 offset0:0 offset1:1
	s_waitcnt lgkmcnt(7)
	v_fma_f32 v16, v146, s82, v115
	v_fma_f32 v17, v147, s82, v114
	s_waitcnt lgkmcnt(6)
	v_fma_f32 v206, v148, s82, v117
	v_fma_f32 v207, v149, s82, v116
	s_waitcnt lgkmcnt(5)
	v_fma_f32 v210, v150, s82, v119
	v_fma_f32 v211, v151, s82, v118
	v_max3_f32 v146, v16, s55, v17
	s_waitcnt lgkmcnt(4)
	v_fma_f32 v208, v152, s82, v121
	v_fma_f32 v209, v153, s82, v120
	v_max3_f32 v146, v146, v206, v207
	s_waitcnt lgkmcnt(3)
	v_fma_f32 v212, v154, s82, v123
	v_fma_f32 v213, v155, s82, v122
	v_max3_f32 v146, v146, v210, v211
	s_waitcnt lgkmcnt(2)
	v_fma_f32 v214, v156, s82, v125
	v_fma_f32 v215, v157, s82, v124
	v_max3_f32 v146, v146, v208, v209
	s_waitcnt lgkmcnt(1)
	v_fma_f32 v216, v158, s82, v127
	v_fma_f32 v217, v159, s82, v126
	v_max3_f32 v146, v146, v212, v213
	s_waitcnt lgkmcnt(0)
	v_fma_f32 v218, v160, s82, v129
	v_fma_f32 v219, v161, s82, v128
	v_max3_f32 v146, v146, v214, v215
	v_max3_f32 v146, v146, v216, v217
	v_max3_f32 v146, v146, v218, v219
	v_cndmask_b32_e64 v246, v224, v146, s[74:75]

; template <int MODE> ...
;     ...
;         if (far) { const float bfar = btab[1023];
; #pragma unroll
;             for (int r = 0; r < 16; ++r) { const float s2 = st[r] * SC + bfar; st[r] = s2; mloc = fmaxf(mloc, s2); }
;             if (!lanevalid) mloc = NEG_S;
;     ...
;         if (MODE == 0) {
;             mloc = fmaxf(mloc, __shfl_xor(mloc, 32));
;             const float mnew = mloc > m + 8.0f ? mloc : m;
;             if (__ballot(mnew != m) != 0ull) { const float alpha = __builtin_amdgcn_exp2f(m - mnew); m = mnew; l *= alpha;
; #pragma unroll
;                 for (int dt = 0; dt < 4; ++dt)
; #pragma unroll
;                     for (int i = 0; i < 16; ++i) ot[dt][i] *= alpha; }
.LBB0_2113:
	s_andn2_saveexec_b64 s[70:71], s[80:81]
	s_cbranch_execz .LBB0_2115
	v_mov_b32_e32 v16, s58
	ds_read_b32 v218, v16 offset:38908
	s_waitcnt lgkmcnt(0)
	s_nop 3
	v_fma_f32 v16, v146, s82, v218
	v_fma_f32 v17, v147, s82, v218
	v_fma_f32 v206, v148, s82, v218
	v_fma_f32 v207, v149, s82, v218
	v_max3_f32 v146, v16, s55, v17
	v_fma_f32 v210, v150, s82, v218
	v_fma_f32 v211, v151, s82, v218
	v_max3_f32 v146, v146, v206, v207
	v_fma_f32 v208, v152, s82, v218
	v_fma_f32 v209, v153, s82, v218
	v_max3_f32 v146, v146, v210, v211
	v_fma_f32 v212, v154, s82, v218
	v_fma_f32 v213, v155, s82, v218
	v_max3_f32 v146, v146, v208, v209
	v_max3_f32 v146, v146, v212, v213
	v_fma_f32 v214, v156, s82, v218
	v_fma_f32 v215, v157, s82, v218
	v_fma_f32 v216, v158, s82, v218
	v_fma_f32 v217, v159, s82, v218
	v_max3_f32 v146, v146, v214, v215
	v_max3_f32 v146, v146, v216, v217
	v_fma_f32 v219, v161, s82, v218
	v_fma_f32 v218, v160, s82, v218
	s_nop 0
	v_max3_f32 v146, v146, v218, v219
	v_cndmask_b32_e64 v246, v224, v146, s[74:75]
.LBB0_2115:
	s_or_b64 exec, exec, s[70:71]
	s_nop 5
	v_mov_b32_e32 v146, v246
	v_add_f32_e32 v148, 0x41000000, v245
	s_nop 0
	v_permlane32_swap_b32_e32 v146, v246
	v_max_f32_e32 v146, v146, v246
	v_cmp_gt_f32_e32 vcc, v146, v148
	s_nop 1
	v_cndmask_b32_e32 v146, v245, v146, vcc
	v_cmp_neq_f32_e32 vcc, v146, v245
	s_cbranch_vccz .LBB0_2117
	v_sub_f32_e32 v147, v245, v146
	v_exp_f32_e32 v148, v147
	s_nop 0
	v_mul_f32_e32 v243, v243, v148
	v_mul_f32_e32 v80, v80, v148
	v_mul_f32_e32 v81, v81, v148
	v_mul_f32_e32 v78, v78, v148
	v_mul_f32_e32 v79, v79, v148
	v_mul_f32_e32 v76, v76, v148
	v_mul_f32_e32 v77, v77, v148
	v_mul_f32_e32 v74, v74, v148
	v_mul_f32_e32 v75, v75, v148
	v_mul_f32_e32 v72, v72, v148
	v_mul_f32_e32 v73, v73, v148
	v_mul_f32_e32 v70, v70, v148
	v_mul_f32_e32 v71, v71, v148
	v_mul_f32_e32 v68, v68, v148
	v_mul_f32_e32 v69, v69, v148
	v_mul_f32_e32 v66, v66, v148
	v_mul_f32_e32 v67, v67, v148
	v_mul_f32_e32 v64, v64, v148
	v_mul_f32_e32 v65, v65, v148
	v_mul_f32_e32 v62, v62, v148
	v_mul_f32_e32 v63, v63, v148
	v_mul_f32_e32 v60, v60, v148
	v_mul_f32_e32 v61, v61, v148
	v_mul_f32_e32 v58, v58, v148
	v_mul_f32_e32 v59, v59, v148
	v_mul_f32_e32 v56, v56, v148
	v_mul_f32_e32 v57, v57, v148
	v_mul_f32_e32 v54, v54, v148
	v_mul_f32_e32 v55, v55, v148
	v_mul_f32_e32 v52, v52, v148
	v_mul_f32_e32 v53, v53, v148
	v_mul_f32_e32 v50, v50, v148
	v_mul_f32_e32 v51, v51, v148
	v_mul_f32_e32 v48, v48, v148
	v_mul_f32_e32 v49, v49, v148
	v_mul_f32_e32 v46, v46, v148
	v_mul_f32_e32 v47, v47, v148
	v_mul_f32_e32 v44, v44, v148
	v_mul_f32_e32 v45, v45, v148
	v_mul_f32_e32 v42, v42, v148
	v_mul_f32_e32 v43, v43, v148
	v_mul_f32_e32 v40, v40, v148
	v_mul_f32_e32 v41, v41, v148
	v_mul_f32_e32 v38, v38, v148
	v_mul_f32_e32 v39, v39, v148
	v_mul_f32_e32 v36, v36, v148
	v_mul_f32_e32 v37, v37, v148
	v_mul_f32_e32 v34, v34, v148
	v_mul_f32_e32 v35, v35, v148
	v_mul_f32_e32 v32, v32, v148
	v_mul_f32_e32 v33, v33, v148
	v_mul_f32_e32 v30, v30, v148
	v_mul_f32_e32 v31, v31, v148
	v_mul_f32_e32 v28, v28, v148
	v_mul_f32_e32 v29, v29, v148
	v_mul_f32_e32 v26, v26, v148
	v_mul_f32_e32 v27, v27, v148
	v_mul_f32_e32 v24, v24, v148
	v_mul_f32_e32 v25, v25, v148
	v_mul_f32_e32 v22, v22, v148
	v_mul_f32_e32 v23, v23, v148
	v_mul_f32_e32 v20, v20, v148
	v_mul_f32_e32 v21, v21, v148
	v_mul_f32_e32 v18, v18, v148
	v_mul_f32_e32 v19, v19, v148
	s_branch .LBB0_2118

; #define LAS __attribute__((address_space(3)))
; template <int MODE> ...
;     ...
;         } else if (interior) {
;             const LAS float* bp = btab + (t - kp0 - (32 * nt + 4 * half));
; #pragma unroll
;             for (int rg = 0; rg < 4; ++rg) { float bv[4];
; #pragma unroll
;                 for (int r4 = 0; r4 < 4; ++r4) bv[r4] = *(bp - (8 * rg + r4));
; #pragma unroll
;                 for (int r4 = 0; r4 < 4; ++r4) asm volatile("" : "+v"(bv[r4]));
; #pragma unroll
;                 for (int r4 = 0; r4 < 4; ++r4) { const int r = 4 * rg + r4; const float s2 = st[r] * SC + bv[r4]; st[r] = s2; mloc = fmaxf(mloc, s2); } }
;             if (!lanevalid) mloc = NEG_S;
.LBB0_2130:
	s_andn2_saveexec_b64 s[70:71], s[94:95]
	s_cbranch_execz .LBB0_2132
	v_add_u32_e32 v82, s6, v242
	v_sub_u32_e32 v82, v228, v82
	v_lshl_add_u32 v96, v82, 2, s58
	v_add_u32_e32 v82, 0x87fc, v96
	ds_read2_b32 v[82:83], v82 offset1:1
	v_add_u32_e32 v84, 0x87f4, v96
	ds_read2_b32 v[84:85], v84 offset1:1
	s_waitcnt lgkmcnt(1)
	v_add_u32_e32 v86, 0x87dc, v96
	v_mov_b32_e32 v114, v83
	v_mov_b32_e32 v115, v82
	s_waitcnt lgkmcnt(0)
	ds_read2_b32 v[86:87], v86 offset1:1
	v_add_u32_e32 v88, 0x87d4, v96
	v_fma_f32 v82, v98, s82, v114
	v_fma_f32 v83, v99, s82, v115
	v_mov_b32_e32 v98, v85
	v_mov_b32_e32 v99, v84
	ds_read2_b32 v[88:89], v88 offset1:1
	s_waitcnt lgkmcnt(1)
	v_add_u32_e32 v90, 0x87bc, v96
	v_fma_f32 v84, v100, s82, v98
	v_fma_f32 v85, v101, s82, v99
	v_mov_b32_e32 v98, v87
	v_mov_b32_e32 v99, v86
	s_waitcnt lgkmcnt(0)
	ds_read2_b32 v[90:91], v90 offset1:1
	v_add_u32_e32 v92, 0x87b4, v96
	v_fma_f32 v86, v102, s82, v98
	v_fma_f32 v87, v103, s82, v99
	v_mov_b32_e32 v98, v89
	v_mov_b32_e32 v99, v88
	ds_read2_b32 v[92:93], v92 offset1:1
	s_waitcnt lgkmcnt(1)
	v_add_u32_e32 v94, 0x879c, v96
	v_fma_f32 v88, v104, s82, v98
	v_fma_f32 v89, v105, s82, v99
	v_mov_b32_e32 v98, v91
	v_mov_b32_e32 v99, v90
	s_waitcnt lgkmcnt(0)
	ds_read2_b32 v[94:95], v94 offset1:1
	v_add_u32_e32 v96, 0x8794, v96
	v_fma_f32 v90, v106, s82, v98
	v_fma_f32 v91, v107, s82, v99
	v_mov_b32_e32 v98, v93
	v_mov_b32_e32 v99, v92
	ds_read2_b32 v[96:97], v96 offset1:1
	s_waitcnt lgkmcnt(1)
	v_fma_f32 v92, v108, s82, v98
	v_fma_f32 v93, v109, s82, v99
	v_mov_b32_e32 v98, v95
	v_mov_b32_e32 v99, v94
	s_waitcnt lgkmcnt(0)
	v_fma_f32 v94, v110, s82, v98
	v_fma_f32 v95, v111, s82, v99
	v_mov_b32_e32 v98, v97
	v_mov_b32_e32 v99, v96
	v_fma_f32 v96, v112, s82, v98
	v_fma_f32 v97, v113, s82, v99

; template <int MODE> ...
;     ...
;         if (far) { const float bfar = btab[1023];
; #pragma unroll
;             for (int r = 0; r < 16; ++r) { const float s2 = st[r] * SC + bfar; st[r] = s2; mloc = fmaxf(mloc, s2); }
;             if (!lanevalid) mloc = NEG_S;
;     ...
;             if (impwrite) {
;                 const float meff = lanevalid ? m : 3.0e30f;
; #pragma unroll
;                 for (int r = 0; r < 16; r += 2) { const float p0 = __builtin_amdgcn_exp2f(st[r] - meff) * invl, p1 = __builtin_amdgcn_exp2f(st[r + 1] - meff) * invl;
;                     imp_row[jbase + 16 * nt + ((r & 3) >> 1) + 4 * (r >> 2) + 2 * half] = p0 + p1; }
;             }
.LBB0_2135:
	v_mov_b32_e32 v82, s58
	ds_read_b32 v82, v82 offset:38908
	s_waitcnt lgkmcnt(0)
	s_nop 3
	v_fma_f32 v96, v112, s82, v82
	v_fma_f32 v97, v113, s82, v82
	v_fma_f32 v94, v110, s82, v82
	v_fma_f32 v95, v111, s82, v82
	v_fma_f32 v92, v108, s82, v82
	v_fma_f32 v93, v109, s82, v82
	v_fma_f32 v90, v106, s82, v82
	v_fma_f32 v91, v107, s82, v82
	v_fma_f32 v88, v104, s82, v82
	v_fma_f32 v89, v105, s82, v82
	v_fma_f32 v86, v102, s82, v82
	v_fma_f32 v87, v103, s82, v82
	v_fma_f32 v84, v100, s82, v82
	v_fma_f32 v85, v101, s82, v82
	v_fma_f32 v83, v99, s82, v82
	v_fma_f32 v82, v98, s82, v82
	s_or_b64 exec, exec, s[6:7]
	s_and_saveexec_b64 s[70:71], s[22:23]
	s_cbranch_execz .LBB0_2126
.LBB0_2136:
	v_sub_f32_e32 v83, v83, v16
	s_nop 1
	v_exp_f32_e32 v98, v83
	v_sub_f32_e32 v83, v84, v16
	v_sub_f32_e32 v84, v85, v16
	v_sub_f32_e32 v82, v82, v16
	v_exp_f32_e32 v99, v84
	v_exp_f32_e32 v82, v82
	v_exp_f32_e32 v83, v83
	v_lshl_add_u32 v100, s27, 6, v17
	v_mul_f32_e32 v84, v204, v98
	v_mul_f32_e32 v85, v205, v99
	s_nop 0
	v_fma_f32 v82, v204, v82, v84
	v_fma_f32 v83, v205, v83, v85
	ds_write2_b32 v100, v82, v83 offset1:1
	v_sub_f32_e32 v83, v87, v16
	v_sub_f32_e32 v85, v89, v16
	v_sub_f32_e32 v82, v86, v16
	v_exp_f32_e32 v84, v83
	v_sub_f32_e32 v83, v88, v16
	v_exp_f32_e32 v85, v85
	v_exp_f32_e32 v82, v82
	v_exp_f32_e32 v83, v83
	v_mul_f32_e32 v84, v204, v84
	v_mul_f32_e32 v85, v205, v85
	s_nop 0
	v_fma_f32 v82, v204, v82, v84
	v_fma_f32 v83, v205, v83, v85
	ds_write2_b32 v100, v82, v83 offset0:4 offset1:5
	v_sub_f32_e32 v83, v91, v16
	v_sub_f32_e32 v85, v93, v16
	v_sub_f32_e32 v82, v90, v16
	v_exp_f32_e32 v84, v83
	v_sub_f32_e32 v83, v92, v16
	v_exp_f32_e32 v85, v85
	v_exp_f32_e32 v82, v82
	v_exp_f32_e32 v83, v83
	v_mul_f32_e32 v84, v204, v84
	v_mul_f32_e32 v85, v205, v85
	s_nop 0
	v_fma_f32 v82, v204, v82, v84
	v_fma_f32 v83, v205, v83, v85
	ds_write2_b32 v100, v82, v83 offset0:8 offset1:9
	v_sub_f32_e32 v83, v95, v16
	v_sub_f32_e32 v85, v97, v16
	v_sub_f32_e32 v82, v94, v16
	v_exp_f32_e32 v84, v83
	v_sub_f32_e32 v83, v96, v16
	v_exp_f32_e32 v85, v85
	v_exp_f32_e32 v82, v82
	v_exp_f32_e32 v83, v83
	v_mul_f32_e32 v84, v204, v84
	v_mul_f32_e32 v85, v205, v85
	s_nop 0
	v_fma_f32 v82, v204, v82, v84
	v_fma_f32 v83, v205, v83, v85
	ds_write2_b32 v100, v82, v83 offset0:12 offset1:13
	s_branch .LBB0_2126

; __device__ __forceinline__ unsigned pk2(float lo, float hi) { const bfx2 b = __builtin_convertvector((f32x2){lo, hi}, bfx2); return __builtin_bit_cast(unsigned, b); }
; __device__ __forceinline__ float bflo(unsigned w) { return __uint_as_float(w << 16); }
; __device__ __forceinline__ float bfhi(unsigned w) { return __uint_as_float(w & 0xffff0000u); }
; #define PKP(var) unsigned char* var; { int l_ = threadIdx.x; asm volatile("" : "+v"(l_)); var = ws + WS_PARK + (size_t)(item8 + (l_ >> 6)) * 8192 + (l_ & 63) * 16; }
; __device__ __forceinline__ void attn_item(const P& p, Frame& F, const bool is_s, const int b, const int g, const int c) {
;     ...
;     { const float lt = l + __shfl_xor(l, 32); const float sc = lt > 0.f ? NGt[(size_t)mrow * 32 + 2 * 8 + h] / lt : 0.f;
;       if (qvalid) { PKP(PK);
; #pragma unroll
;           for (int dt = 0; dt < 4; ++dt)
; #pragma unroll
;               for (int hf = 0; hf < 2; ++hf) { const u32x4 o4 = *(const u32x4*)(PK + (2 * dt + hf) * 1024);
; #pragma unroll
;                   for (int rr = 0; rr < 2; ++rr) { const int r4 = 2 * hf + rr; const int d0 = 32 * dt + 8 * r4 + 4 * half; const u32x2 o = rr ? (u32x2){o4.z, o4.w} : (u32x2){o4.x, o4.y};
;                       u32x2 w; w.x = pk2(bflo(o.x) + ot[dt][4 * r4 + 0] * sc, bfhi(o.x) + ot[dt][4 * r4 + 1] * sc); w.y = pk2(bflo(o.y) + ot[dt][4 * r4 + 2] * sc, bfhi(o.y) + ot[dt][4 * r4 + 3] * sc);
;                       *(u32x2*)(YN + (size_t)mrow * 1024 + h * 128 + d0) = w; } } } }
.LBB0_2141:
	s_waitcnt vmcnt(0)
	s_and_saveexec_b64 s[0:1], s[22:23]
	v_mov_b32_e32 v1, v0
	v_readlane_b32 s2, v252, 13
	v_ashrrev_i32_e32 v2, 6, v1
	v_lshlrev_b32_e32 v1, 4, v1
	v_add_u32_e32 v6, s2, v2
	v_ashrrev_i32_e32 v7, 31, v6
	v_readlane_b32 s2, v254, 49
	v_lshlrev_b64 v[6:7], 13, v[6:7]
	v_readlane_b32 s3, v254, 50
	v_and_b32_e32 v2, 0x3f0, v1
	s_nop 0
	v_lshl_add_u64 v[6:7], s[2:3], 0, v[6:7]
	v_lshl_add_u64 v[8:9], v[6:7], 0, v[2:3]
	s_movk_i32 s2, 0x1000
	s_nop 0
	v_add_co_u32_e32 v10, vcc, s2, v8
	s_nop 1
	v_addc_co_u32_e32 v11, vcc, 0, v9, vcc
	global_load_dword v16, v[202:203], off offset:64
	global_load_dwordx4 v[114:117], v[8:9], off
	global_load_dwordx4 v[118:121], v[8:9], off offset:1024
	global_load_dwordx4 v[122:125], v[8:9], off offset:2048
	global_load_dwordx4 v[126:129], v[8:9], off offset:3072
	global_load_dwordx4 v[130:133], v[10:11], off
	global_load_dwordx4 v[134:137], v[10:11], off offset:1024
	global_load_dwordx4 v[138:141], v[10:11], off offset:2048
	global_load_dwordx4 v[142:145], v[10:11], off offset:3072
	v_readlane_b32 s2, v252, 23
	v_readlane_b32 s3, v252, 24
	v_lshlrev_b32_e32 v2, 1, v229
	s_nop 1
	v_lshl_add_u64 v[6:7], s[2:3], 0, v[200:201]
	v_readlane_b32 s2, v252, 45
	s_nop 1
	s_lshl_b32 s44, s2, 1
	s_nop 0
	v_lshl_add_u64 v[6:7], v[6:7], 0, s[44:45]
	v_lshl_add_u64 v[6:7], v[6:7], 0, v[2:3]
	s_or_b64 exec, exec, s[0:1]
	v_and_b32_e32 v13, 64, v221
	v_xor_b32_e32 v1, 32, v221
	v_add_u32_e32 v13, 64, v13
	v_cmp_lt_i32_e32 vcc, v1, v13
	v_mov_b32_e32 v4, 0
	s_nop 0
	v_cndmask_b32_e32 v1, v221, v1, vcc
	v_lshlrev_b32_e32 v1, 2, v1
	ds_bpermute_b32 v1, v1, v240
	s_waitcnt lgkmcnt(0)
	v_add_f32_e32 v1, v240, v1
	v_cmp_lt_f32_e32 vcc, 0, v1
	s_and_saveexec_b64 s[0:1], vcc
	s_waitcnt vmcnt(0)
	v_div_scale_f32 v4, s[2:3], v1, v1, v16
	v_rcp_f32_e32 v5, v4
	v_div_scale_f32 v12, vcc, v16, v1, v16
	v_fma_f32 v13, -v4, v5, 1.0
	v_fmac_f32_e32 v5, v13, v5
	v_mul_f32_e32 v13, v12, v5
	v_fma_f32 v14, -v4, v13, v12
	v_fmac_f32_e32 v13, v14, v5
	v_fma_f32 v4, -v4, v13, v12
	v_div_fmas_f32 v4, v4, v5, v13
	v_div_fixup_f32 v4, v4, v1, v16
	s_or_b64 exec, exec, s[0:1]
	s_and_saveexec_b64 s[0:1], s[22:23]
	v_readlane_b32 s79, v252, 40
	s_mov_b32 s33, 0x58000
	s_movk_i32 s40, 0x5800
	s_mov_b32 s41, 0x16000
	s_mov_b32 s42, 0x2c000
	s_mov_b32 s43, 0x42000
	s_mov_b32 s46, 0x6e000
	s_mov_b32 s47, 0x84000
	s_mov_b32 s50, 0x9a000
	s_mov_b32 s51, 0xb0000
	s_mov_b32 s52, 0xc6000
	s_mov_b32 s53, 0xdc000
	s_mov_b32 s56, 0xf2000
	s_mov_b32 s57, 0x108000
	v_readlane_b32 s90, v252, 43
	v_readlane_b32 s81, v252, 39
	s_cbranch_execz .LBB0_2145
; __device__ __forceinline__ unsigned pk2(float lo, float hi) { const bfx2 b = __builtin_convertvector((f32x2){lo, hi}, bfx2); return __builtin_bit_cast(unsigned, b); }
; __device__ __forceinline__ float bflo(unsigned w) { return __uint_as_float(w << 16); }
; __device__ __forceinline__ float bfhi(unsigned w) { return __uint_as_float(w & 0xffff0000u); }
; __device__ __forceinline__ void attn_item(const P& p, Frame& F, const bool is_s, const int b, const int g, const int c) {
;     ...
;               for (int hf = 0; hf < 2; ++hf) { const u32x4 o4 = *(const u32x4*)(PK + (2 * dt + hf) * 1024);
; #pragma unroll
;                   for (int rr = 0; rr < 2; ++rr) { const int r4 = 2 * hf + rr; const int d0 = 32 * dt + 8 * r4 + 4 * half; const u32x2 o = rr ? (u32x2){o4.z, o4.w} : (u32x2){o4.x, o4.y};
;                       u32x2 w; w.x = pk2(bflo(o.x) + ot[dt][4 * r4 + 0] * sc, bfhi(o.x) + ot[dt][4 * r4 + 1] * sc); w.y = pk2(bflo(o.y) + ot[dt][4 * r4 + 2] * sc, bfhi(o.y) + ot[dt][4 * r4 + 3] * sc);
;                       *(u32x2*)(YN + (size_t)mrow * 1024 + h * 128 + d0) = w; } } } }
	s_waitcnt vmcnt(0)
	v_lshlrev_b32_e32 v12, 16, v114
	v_and_b32_e32 v13, 0xffff0000, v114
	v_fma_f32 v12, v66, v4, v12
	v_fma_f32 v13, v67, v4, v13
	s_nop 0
	v_cvt_pk_bf16_f32 v114, v12, v13
	v_lshlrev_b32_e32 v14, 16, v115
	v_and_b32_e32 v15, 0xffff0000, v115
	v_fma_f32 v14, v68, v4, v14
	v_fma_f32 v15, v69, v4, v15
	s_nop 0
	v_cvt_pk_bf16_f32 v115, v14, v15
	global_store_dwordx2 v[6:7], v[114:115], off
	v_lshlrev_b32_e32 v16, 16, v116
	v_and_b32_e32 v17, 0xffff0000, v116
	v_fma_f32 v16, v70, v4, v16
	v_fma_f32 v17, v71, v4, v17
	s_nop 0
	v_cvt_pk_bf16_f32 v116, v16, v17
	v_lshlrev_b32_e32 v12, 16, v117
	v_and_b32_e32 v13, 0xffff0000, v117
	v_fma_f32 v12, v72, v4, v12
	v_fma_f32 v13, v73, v4, v13
	s_nop 0
	v_cvt_pk_bf16_f32 v117, v12, v13
	global_store_dwordx2 v[6:7], v[116:117], off offset:16
	v_lshlrev_b32_e32 v14, 16, v118
	v_and_b32_e32 v15, 0xffff0000, v118
	v_fma_f32 v14, v74, v4, v14
	v_fma_f32 v15, v75, v4, v15
	s_nop 0
	v_cvt_pk_bf16_f32 v118, v14, v15
	v_lshlrev_b32_e32 v16, 16, v119
	v_and_b32_e32 v17, 0xffff0000, v119
	v_fma_f32 v16, v76, v4, v16
	v_fma_f32 v17, v77, v4, v17
	s_nop 0
	v_cvt_pk_bf16_f32 v119, v16, v17
	global_store_dwordx2 v[6:7], v[118:119], off offset:32
	v_lshlrev_b32_e32 v12, 16, v120
	v_and_b32_e32 v13, 0xffff0000, v120
	v_fma_f32 v12, v78, v4, v12
	v_fma_f32 v13, v79, v4, v13
	s_nop 0
	v_cvt_pk_bf16_f32 v120, v12, v13
	v_lshlrev_b32_e32 v14, 16, v121
	v_and_b32_e32 v15, 0xffff0000, v121
	v_fma_f32 v14, v80, v4, v14
	v_fma_f32 v15, v81, v4, v15
	s_nop 0
	v_cvt_pk_bf16_f32 v121, v14, v15
	global_store_dwordx2 v[6:7], v[120:121], off offset:48
	v_lshlrev_b32_e32 v16, 16, v122
	v_and_b32_e32 v17, 0xffff0000, v122
	v_fma_f32 v16, v50, v4, v16
	v_fma_f32 v17, v51, v4, v17
	s_nop 0
	v_cvt_pk_bf16_f32 v122, v16, v17
	v_lshlrev_b32_e32 v12, 16, v123
	v_and_b32_e32 v13, 0xffff0000, v123
	v_fma_f32 v12, v52, v4, v12
	v_fma_f32 v13, v53, v4, v13
	s_nop 0
	v_cvt_pk_bf16_f32 v123, v12, v13
	global_store_dwordx2 v[6:7], v[122:123], off offset:64
	v_lshlrev_b32_e32 v14, 16, v124
	v_and_b32_e32 v15, 0xffff0000, v124
	v_fma_f32 v14, v54, v4, v14
	v_fma_f32 v15, v55, v4, v15
	s_nop 0
	v_cvt_pk_bf16_f32 v124, v14, v15
	v_lshlrev_b32_e32 v16, 16, v125
	v_and_b32_e32 v17, 0xffff0000, v125
	v_fma_f32 v16, v56, v4, v16
	v_fma_f32 v17, v57, v4, v17
	s_nop 0
	v_cvt_pk_bf16_f32 v125, v16, v17
	global_store_dwordx2 v[6:7], v[124:125], off offset:80
	v_lshlrev_b32_e32 v12, 16, v126
	v_and_b32_e32 v13, 0xffff0000, v126
	v_fma_f32 v12, v58, v4, v12
	v_fma_f32 v13, v59, v4, v13
	s_nop 0
	v_cvt_pk_bf16_f32 v126, v12, v13
	v_lshlrev_b32_e32 v14, 16, v127
	v_and_b32_e32 v15, 0xffff0000, v127
	v_fma_f32 v14, v60, v4, v14
	v_fma_f32 v15, v61, v4, v15
	s_nop 0
	v_cvt_pk_bf16_f32 v127, v14, v15
	global_store_dwordx2 v[6:7], v[126:127], off offset:96
	v_lshlrev_b32_e32 v16, 16, v128
	v_and_b32_e32 v17, 0xffff0000, v128
	v_fma_f32 v16, v62, v4, v16
	v_fma_f32 v17, v63, v4, v17
	s_nop 0
	v_cvt_pk_bf16_f32 v128, v16, v17
	v_lshlrev_b32_e32 v12, 16, v129
	v_and_b32_e32 v13, 0xffff0000, v129
	v_fma_f32 v12, v64, v4, v12
	v_fma_f32 v13, v65, v4, v13
	s_nop 0
	v_cvt_pk_bf16_f32 v129, v12, v13
	global_store_dwordx2 v[6:7], v[128:129], off offset:112
	v_lshlrev_b32_e32 v14, 16, v130
	v_and_b32_e32 v15, 0xffff0000, v130
	v_fma_f32 v14, v34, v4, v14
	v_fma_f32 v15, v35, v4, v15
	s_nop 0
	v_cvt_pk_bf16_f32 v130, v14, v15
	v_lshlrev_b32_e32 v16, 16, v131
	v_and_b32_e32 v17, 0xffff0000, v131
	v_fma_f32 v16, v36, v4, v16
	v_fma_f32 v17, v37, v4, v17
	s_nop 0
	v_cvt_pk_bf16_f32 v131, v16, v17
	global_store_dwordx2 v[6:7], v[130:131], off offset:128
	v_lshlrev_b32_e32 v12, 16, v132
	v_and_b32_e32 v13, 0xffff0000, v132
	v_fma_f32 v12, v38, v4, v12
	v_fma_f32 v13, v39, v4, v13
	s_nop 0
	v_cvt_pk_bf16_f32 v132, v12, v13
	v_lshlrev_b32_e32 v14, 16, v133
	v_and_b32_e32 v15, 0xffff0000, v133
	v_fma_f32 v14, v40, v4, v14
	v_fma_f32 v15, v41, v4, v15
	s_nop 0
	v_cvt_pk_bf16_f32 v133, v14, v15
	global_store_dwordx2 v[6:7], v[132:133], off offset:144
	v_lshlrev_b32_e32 v16, 16, v134
	v_and_b32_e32 v17, 0xffff0000, v134
	v_fma_f32 v16, v42, v4, v16
	v_fma_f32 v17, v43, v4, v17
	s_nop 0
	v_cvt_pk_bf16_f32 v134, v16, v17
	v_lshlrev_b32_e32 v12, 16, v135
	v_and_b32_e32 v13, 0xffff0000, v135
	v_fma_f32 v12, v44, v4, v12
	v_fma_f32 v13, v45, v4, v13
	s_nop 0
	v_cvt_pk_bf16_f32 v135, v12, v13
	global_store_dwordx2 v[6:7], v[134:135], off offset:160
	v_lshlrev_b32_e32 v14, 16, v136
	v_and_b32_e32 v15, 0xffff0000, v136
	v_fma_f32 v14, v46, v4, v14
	v_fma_f32 v15, v47, v4, v15
	s_nop 0
	v_cvt_pk_bf16_f32 v136, v14, v15
	v_lshlrev_b32_e32 v16, 16, v137
	v_and_b32_e32 v17, 0xffff0000, v137
	v_fma_f32 v16, v48, v4, v16
	v_fma_f32 v17, v49, v4, v17
	s_nop 0
	v_cvt_pk_bf16_f32 v137, v16, v17
	global_store_dwordx2 v[6:7], v[136:137], off offset:176
	v_lshlrev_b32_e32 v12, 16, v138
	v_and_b32_e32 v13, 0xffff0000, v138
	v_fma_f32 v12, v18, v4, v12
	v_fma_f32 v13, v19, v4, v13
	s_nop 0
	v_cvt_pk_bf16_f32 v138, v12, v13
	v_lshlrev_b32_e32 v14, 16, v139
	v_and_b32_e32 v15, 0xffff0000, v139
	v_fma_f32 v14, v20, v4, v14
	v_fma_f32 v15, v21, v4, v15
	s_nop 0
	v_cvt_pk_bf16_f32 v139, v14, v15
	global_store_dwordx2 v[6:7], v[138:139], off offset:192
	v_lshlrev_b32_e32 v16, 16, v140
	v_and_b32_e32 v17, 0xffff0000, v140
	v_fma_f32 v16, v22, v4, v16
	v_fma_f32 v17, v23, v4, v17
	s_nop 0
	v_cvt_pk_bf16_f32 v140, v16, v17
	v_lshlrev_b32_e32 v12, 16, v141
	v_and_b32_e32 v13, 0xffff0000, v141
	v_fma_f32 v12, v24, v4, v12
	v_fma_f32 v13, v25, v4, v13
	s_nop 0
	v_cvt_pk_bf16_f32 v141, v12, v13
	global_store_dwordx2 v[6:7], v[140:141], off offset:208
	v_lshlrev_b32_e32 v14, 16, v142
	v_and_b32_e32 v15, 0xffff0000, v142
	v_fma_f32 v14, v26, v4, v14
	v_fma_f32 v15, v27, v4, v15
	s_nop 0
	v_cvt_pk_bf16_f32 v142, v14, v15
	v_lshlrev_b32_e32 v16, 16, v143
	v_and_b32_e32 v17, 0xffff0000, v143
	v_fma_f32 v16, v28, v4, v16
	v_fma_f32 v17, v29, v4, v17
	s_nop 0
	v_cvt_pk_bf16_f32 v143, v16, v17
	global_store_dwordx2 v[6:7], v[142:143], off offset:224
	v_lshlrev_b32_e32 v12, 16, v144
	v_and_b32_e32 v13, 0xffff0000, v144
	v_fma_f32 v12, v30, v4, v12
	v_fma_f32 v13, v31, v4, v13
	s_nop 0
	v_cvt_pk_bf16_f32 v144, v12, v13
	v_lshlrev_b32_e32 v14, 16, v145
	v_and_b32_e32 v15, 0xffff0000, v145
	v_fma_f32 v14, v32, v4, v14
	v_fma_f32 v15, v33, v4, v15
	s_nop 0
	v_cvt_pk_bf16_f32 v145, v14, v15
	global_store_dwordx2 v[6:7], v[144:145], off offset:240
